# attention v8: local rounds process both query rows of the pair together (shared K / V^T fragment reads, the two softmax chains interleaved)
# speedup vs baseline: 1.0100x; 1.0031x over previous
; __device__ __forceinline__ void attn_phase(const Params& P, char* smem_raw) {
;   u16* sm_k = reinterpret_cast<u16*>(smem_raw);
;   u16* sm_vt = sm_k + 128 * LDSS;
;   u16* sm_p = sm_vt + 64 * 136;
;   float* sm_rpb = reinterpret_cast<float*>(sm_p + 4 * 16 * 136);
;   const int tid = VTID, lane = tid & 63, wid = tid >> 6;
;   const u16* QKV = P.zq;
;   const u16* VTX = P.zf;
;   const u16* VTC = reinterpret_cast<const u16*>(P.summ);
;   uint4 kreg[4], vreg[4];
;   bf16x8 qn[2];
;     ...
;   int dco[4][4];
; #pragma unroll
;   for (int reg = 0; reg < 4; ++reg) {
;     const int c = wid * 16 + (lane >> 4) * 4 + reg;
;     const int cs = min(max(c - 8, 0), 48);
; #pragma unroll
;     for (int q4 = 0; q4 < 4; ++q4) {
;       const int kc = q4 * 16 + (lane & 15);
;       dco[reg][q4] = (kc >= cs && kc < cs + 16) ? (kc - c + 15) : 465;
;     }
;   }
;   int t = VBID;
;   __syncthreads();
;   if (t < 8192) {
;     const int h0 = t & 15;
;     for (int idx = tid; idx < 930; idx += VTHR) sm_rpb[idx] = (idx < 465) ? P.rpb[h0 * 465 + idx] * 1.4426950408889634f : -1e30f;
;     ATT_ISSUE(t, 0)
;     ATT_QLOAD(t)
;   }
.LBB0_1489:
	s_cmp_gt_i32 s34, 12
	s_cselect_b64 s[0:1], -1, 0
	s_cmp_lt_i32 s35, 13
	s_cselect_b64 s[4:5], -1, 0
	s_or_b64 s[0:1], s[0:1], s[4:5]
	s_and_b64 vcc, exec, s[0:1]
	s_cbranch_vccnz .LBB0_1555
	s_waitcnt vmcnt(5)
	v_lshl_add_u32 v109, s2, 1, v153
	s_movk_i32 s0, 0x2000
	v_mov_b32_e32 v0, v153
	v_cmp_gt_i32_e32 vcc, s0, v109
	s_barrier
	s_and_saveexec_b64 s[42:43], vcc
	s_cbranch_execz .LBB0_1501
	v_readlane_b32 s0, v252, 0
	v_readlane_b32 s1, v252, 1
	v_readfirstlane_b32 s3, v153
	s_nop 3
	s_sub_u32 s0, s0, 0x170
	s_subb_u32 s1, s1, 0
	s_load_dwordx2 s[12:13], s[0:1], 0xb8
	s_load_dwordx2 s[8:9], s[0:1], 0x130
	s_load_dwordx4 s[4:7], s[0:1], 0x148
	s_load_dwordx2 s[10:11], s[0:1], 0x158
	s_lshl_b32 s100, s2, 1
	s_add_u32 s3, s100, s3
	s_and_b32 s101, s3, 15
	s_lshl_b32 s3, s3, 8
	s_waitcnt lgkmcnt(0)
	s_lshl_b32 s100, s101, 7
	s_add_u32 s4, s4, s100
	s_addc_u32 s5, s5, 0
	s_add_u32 s10, s10, s100
	s_addc_u32 s11, s11, 0
	s_lshl_b32 s100, s101, 20
	s_add_u32 s6, s6, s100
	s_addc_u32 s7, s7, 0
	s_lshl_b32 s100, s101, 15
	s_add_u32 s8, s8, s100
	s_addc_u32 s9, s9, 0
	s_mul_i32 s100, s101, 0x744
	s_add_u32 s12, s12, s100
	s_addc_u32 s13, s13, 0
	v_and_b32_e32 v112, 0xff, v152
	v_and_b32_e32 v113, 63, v152
	v_bfe_u32 v114, v152, 6, 2
	v_lshrrev_b32_e32 v115, 4, v113
	v_and_b32_e32 v116, 15, v113
	v_mul_u32_u24_e32 v117, 0x12000, v153
	v_add_u32_e32 v117, 16, v117
	v_and_b32_e32 v118, 7, v116
	v_lshrrev_b32_e32 v119, 1, v114
	v_add_u32_e32 v119, v119, v114
	v_lshlrev_b32_e32 v119, 3, v119
	v_xor_b32_e32 v121, v115, v118
	v_lshl_add_u32 v122, v116, 7, v117
	v_lshl_add_u32 v149, v121, 4, v122
	v_xor_b32_e32 v121, 4, v121
	v_lshl_add_u32 v224, v121, 4, v122
	v_lshl_add_u32 v144, v119, 7, v149
	v_lshl_add_u32 v145, v119, 7, v224
	v_lshl_add_u32 v124, v116, 8, v117
	v_add_u32_e32 v124, 0x4000, v124
	v_lshrrev_b32_e32 v123, 2, v119
	v_add_u32_e32 v125, 0, v115
	v_xor_b32_e32 v125, v125, v116
	v_lshl_add_u32 v225, v125, 4, v124
	v_add_u32_e32 v125, 4, v115
	v_xor_b32_e32 v125, v125, v116
	v_lshl_add_u32 v226, v125, 4, v124
	v_add_u32_e32 v125, 8, v115
	v_xor_b32_e32 v125, v125, v116
	v_lshl_add_u32 v227, v125, 4, v124
	v_add_u32_e32 v125, 12, v115
	v_xor_b32_e32 v125, v125, v116
	v_lshl_add_u32 v228, v125, 4, v124
	v_add3_u32 v125, v123, 0, v115
	v_xor_b32_e32 v125, v125, v116
	v_lshl_add_u32 v146, v125, 4, v124
	v_add3_u32 v125, v123, 4, v115
	v_xor_b32_e32 v125, v125, v116
	v_lshl_add_u32 v147, v125, 4, v124
	v_lshrrev_b32_e32 v126, 3, v112
	v_and_b32_e32 v127, 7, v112
	v_and_b32_e32 v128, 7, v126
	v_xor_b32_e32 v128, v127, v128
	v_lshl_add_u32 v125, v126, 7, v117
	v_lshl_add_u32 v150, v128, 4, v125
	v_lshrrev_b32_e32 v129, 4, v112
	v_and_b32_e32 v130, 15, v112
	v_and_b32_e32 v125, 7, v130
	v_lshlrev_b32_e32 v125, 1, v125
	v_xor_b32_e32 v125, v125, v129
	v_lshl_add_u32 v128, v129, 8, v117
	v_lshl_add_u32 v151, v125, 4, v128
	v_xor_b32_e32 v125, 1, v125
	v_lshl_add_u32 v229, v125, 4, v128
	v_lshrrev_b32_e32 v125, 3, v130
	v_lshl_add_u32 v151, v125, 3, v151
	v_lshl_add_u32 v229, v125, 3, v229
	v_add_u32_e32 v151, 0x4000, v151
	v_add_u32_e32 v229, 0x4000, v229
	v_mul_u32_u24_e32 v125, 0x1800, v126
	v_lshl_add_u32 v154, v127, 4, v125
	v_add_u32_e32 v155, 0x30000, v154
	v_add_u32_e32 v156, 0x60000, v154
	v_add_u32_e32 v157, 0x90000, v154
	v_lshlrev_b32_e32 v125, 14, v129
	v_lshl_add_u32 v158, v130, 4, v125
	v_add_u32_e32 v159, 0x40000, v158
	v_add_u32_e32 v160, 0x80000, v158
	v_add_u32_e32 v161, 0xc0000, v158
	v_lshlrev_b32_e32 v125, 9, v129
	v_lshl_add_u32 v162, v130, 4, v125
	v_add_u32_e32 v163, 0x2000, v162
	v_add_u32_e32 v164, 0x4000, v162
	v_add_u32_e32 v165, 0x6000, v162
	v_lshl_add_u32 v131, v114, 4, v116
	v_mul_u32_u24_e32 v125, 0x1800, v131
	v_lshl_add_u32 v166, v115, 4, v125
	v_lshlrev_b32_e32 v125, 11, v131
	v_lshl_add_u32 v167, v115, 3, v125
	v_sub_u32_e64 v132, v131, 8 clamp
	v_min_u32_e32 v132, 48, v132
	v_mov_b32_e32 v210, 0x7c
	v_lshl_add_u32 v133, v115, 2, v119
	v_add_u32_e32 v134, 0, v133
	v_sub_u32_e32 v135, v134, v132
	v_cmp_gt_u32_e32 vcc, 16, v135
	v_sub_u32_e32 v136, v134, v131
	v_lshlrev_b32_e32 v136, 2, v136
	v_add_u32_e32 v136, 60, v136
	v_cndmask_b32_e32 v168, v210, v136, vcc
	v_add_u32_e32 v134, 1, v133
	v_sub_u32_e32 v135, v134, v132
	v_cmp_gt_u32_e32 vcc, 16, v135
	v_sub_u32_e32 v136, v134, v131
	v_lshlrev_b32_e32 v136, 2, v136
	v_add_u32_e32 v136, 60, v136
	v_cndmask_b32_e32 v169, v210, v136, vcc
	v_add_u32_e32 v134, 2, v133
	v_sub_u32_e32 v135, v134, v132
	v_cmp_gt_u32_e32 vcc, 16, v135
	v_sub_u32_e32 v136, v134, v131
	v_lshlrev_b32_e32 v136, 2, v136
	v_add_u32_e32 v136, 60, v136
	v_cndmask_b32_e32 v170, v210, v136, vcc
	v_add_u32_e32 v134, 3, v133
	v_sub_u32_e32 v135, v134, v132
	v_cmp_gt_u32_e32 vcc, 16, v135
	v_sub_u32_e32 v136, v134, v131
	v_lshlrev_b32_e32 v136, 2, v136
	v_add_u32_e32 v136, 60, v136
	v_cndmask_b32_e32 v171, v210, v136, vcc
	v_add_u32_e32 v134, 16, v133
	v_sub_u32_e32 v135, v134, v132
	v_cmp_gt_u32_e32 vcc, 16, v135
	v_sub_u32_e32 v136, v134, v131
	v_lshlrev_b32_e32 v136, 2, v136
	v_add_u32_e32 v136, 60, v136
	v_cndmask_b32_e32 v172, v210, v136, vcc
	v_add_u32_e32 v134, 17, v133
	v_sub_u32_e32 v135, v134, v132
	v_cmp_gt_u32_e32 vcc, 16, v135
	v_sub_u32_e32 v136, v134, v131
	v_lshlrev_b32_e32 v136, 2, v136
	v_add_u32_e32 v136, 60, v136
	v_cndmask_b32_e32 v173, v210, v136, vcc
	v_add_u32_e32 v134, 18, v133
	v_sub_u32_e32 v135, v134, v132
	v_cmp_gt_u32_e32 vcc, 16, v135
	v_sub_u32_e32 v136, v134, v131
	v_lshlrev_b32_e32 v136, 2, v136
	v_add_u32_e32 v136, 60, v136
	v_cndmask_b32_e32 v174, v210, v136, vcc
	v_add_u32_e32 v134, 19, v133
	v_sub_u32_e32 v135, v134, v132
	v_cmp_gt_u32_e32 vcc, 16, v135
	v_sub_u32_e32 v136, v134, v131
	v_lshlrev_b32_e32 v136, 2, v136
	v_add_u32_e32 v136, 60, v136
	v_cndmask_b32_e32 v175, v210, v136, vcc
	v_mov_b32_e32 v143, 0xf149f2ca
	v_mov_b32_e32 v137, v112
	v_lshrrev_b32_e32 v138, 5, v137
	v_and_b32_e32 v139, 31, v137
	v_mul_u32_u24_e32 v140, 31, v138
	v_add_u32_e32 v140, v140, v139
	v_min_u32_e32 v140, 0x1d0, v140
	v_lshlrev_b32_e32 v140, 2, v140
	global_load_dword v141, v140, s[12:13]
	v_lshl_add_u32 v142, v137, 2, v117
	v_add_u32_e32 v142, 0x10000, v142
	v_cmp_eq_u32_e32 vcc, 31, v139
	s_waitcnt vmcnt(0)
; __device__ __forceinline__ void attn_phase(const Params& P, char* smem_raw) {
;     ...
;   int dco[4][4];
; #pragma unroll
;   for (int reg = 0; reg < 4; ++reg) {
;     const int c = wid * 16 + (lane >> 4) * 4 + reg;
;     const int cs = min(max(c - 8, 0), 48);
; #pragma unroll
;     for (int q4 = 0; q4 < 4; ++q4) {
;       const int kc = q4 * 16 + (lane & 15);
;       dco[reg][q4] = (kc >= cs && kc < cs + 16) ? (kc - c + 15) : 465;
;     }
;   }
;   int t = VBID;
;   __syncthreads();
;   if (t < 8192) {
;     const int h0 = t & 15;
;     for (int idx = tid; idx < 930; idx += VTHR) sm_rpb[idx] = (idx < 465) ? P.rpb[h0 * 465 + idx] * 1.4426950408889634f : -1e30f;
;     ATT_ISSUE(t, 0)
;     ATT_QLOAD(t)
;   }
;   for (; t < 8192; t += VGRID) {
;     const int h = t & 15, r = (t >> 4) & 127, b = t >> 11;
;     const int rs = min(max(r - 4, 0), 120);
;     bf16x8 qf[2];
;     qf[0] = qn[0]; qf[1] = qn[1];
;     f32x4 o[4];
; #pragma unroll
;     for (int td = 0; td < 4; ++td) o[td] = f32x4{0.f, 0.f, 0.f, 0.f};
;     float mrow[4], lrow[4];
; #pragma unroll
;     for (int reg = 0; reg < 4; ++reg) { mrow[reg] = -1e30f; lrow[reg] = 0.f; }
	v_mul_f32_e32 v141, 0x3fb8aa3b, v141
	v_cndmask_b32_e32 v141, v141, v143, vcc
	ds_write_b32 v142, v141
	v_add_u32_e32 v137, 0x100, v112
	v_lshrrev_b32_e32 v138, 5, v137
	v_and_b32_e32 v139, 31, v137
	v_mul_u32_u24_e32 v140, 31, v138
	v_add_u32_e32 v140, v140, v139
	v_min_u32_e32 v140, 0x1d0, v140
	v_lshlrev_b32_e32 v140, 2, v140
	global_load_dword v141, v140, s[12:13]
	v_lshl_add_u32 v142, v137, 2, v117
	v_add_u32_e32 v142, 0x10000, v142
	v_cmp_eq_u32_e32 vcc, 31, v139
	s_waitcnt vmcnt(0)
	v_mul_f32_e32 v141, 0x3fb8aa3b, v141
	v_cndmask_b32_e32 v141, v141, v143, vcc
	ds_write_b32 v142, v141
	s_and_b32 s0, s3, 0xff
	s_lshr_b32 s1, s0, 1
	s_and_b32 s0, s0, 1
	s_lshl_b32 s0, s0, 5
	s_lshr_b32 vcc_lo, s3, 12
	s_add_u32 s0, s0, vcc_lo
	s_lshl_b32 s0, s0, 1
	s_sub_i32 vcc_lo, s0, 4
	s_max_i32 vcc_lo, vcc_lo, 0
	s_min_i32 vcc_lo, vcc_lo, 0x78
	s_lshl_b32 vcc_hi, s1, 13
	s_add_u32 s20, vcc_lo, 8
	s_min_u32 s20, s20, 0x7e
	s_sub_u32 s20, s20, vcc_lo
	s_lshl_b32 s21, s20, 7
	s_mul_i32 s20, s20, 0x60000
	s_lshl_b32 m0, vcc_lo, 6
	s_add_u32 m0, m0, vcc_hi
	s_mul_i32 m0, m0, 0x1800
	s_add_u32 s12, s4, m0
	s_addc_u32 s13, s5, 0
	s_lshl_b32 m0, s1, 24
	s_lshl_b32 s100, vcc_lo, 7
	s_add_u32 m0, m0, s100
	s_add_u32 s14, s6, m0
	s_addc_u32 s15, s7, 0
	s_lshl_b32 m0, s0, 6
	s_add_u32 m0, m0, vcc_hi
	s_mul_i32 m0, m0, 0x1800
	s_add_u32 s100, s4, m0
	s_addc_u32 s101, s5, 0
	global_load_dwordx4 v[64:67], v166, s[100:101]
	global_load_dwordx4 v[68:71], v166, s[100:101] offset:64
	s_add_u32 s100, s100, 0x60000
	s_addc_u32 s101, s101, 0
	global_load_dwordx4 v[230:233], v166, s[100:101]
	global_load_dwordx4 v[234:237], v166, s[100:101] offset:64
	s_and_b32 s0, s3, 0xff
	s_lshr_b32 s1, s0, 1
	s_and_b32 s0, s0, 1
	s_lshl_b32 s0, s0, 5
	s_lshr_b32 vcc_lo, s3, 12
	s_add_u32 s0, s0, vcc_lo
	s_lshl_b32 s0, s0, 1
	s_sub_i32 vcc_lo, s0, 4
	s_max_i32 vcc_lo, vcc_lo, 0
	s_min_i32 vcc_lo, vcc_lo, 0x78
	s_lshl_b32 vcc_hi, s1, 13
	s_sub_i32 vcc_lo, vcc_lo, s0
	s_add_i32 vcc_lo, vcc_lo, 4
	s_lshl_b32 vcc_lo, vcc_lo, 7
	s_bfe_u32 m0, s3, 0x10008
	s_mul_i32 m0, m0, 0x12000
	s_add_i32 vcc_lo, vcc_lo, m0
	s_add_i32 vcc_lo, vcc_lo, 0x10010
	v_add_u32_e32 v184, vcc_lo, v168
	v_add_u32_e32 v185, vcc_lo, v169
	v_add_u32_e32 v186, vcc_lo, v170
	v_add_u32_e32 v187, vcc_lo, v171
	v_add_u32_e32 v188, vcc_lo, v172
	v_add_u32_e32 v189, vcc_lo, v173
	v_add_u32_e32 v190, vcc_lo, v174
	v_add_u32_e32 v191, vcc_lo, v175
	s_add_u32 s100, s12, 0x0
	s_addc_u32 s101, s13, 0
	s_add_u32 s0, s14, 0x0
	s_addc_u32 s1, s15, 0
	global_load_dwordx4 v[80:83], v154, s[100:101] offset:2048
	global_load_dwordx4 v[96:99], v158, s[0:1]
	global_load_dwordx4 v[84:87], v155, s[100:101] offset:2048
	global_load_dwordx4 v[100:103], v159, s[0:1]
	global_load_dwordx4 v[88:91], v156, s[100:101] offset:2048
	global_load_dwordx4 v[104:107], v160, s[0:1]
	global_load_dwordx4 v[92:95], v157, s[100:101] offset:2048
	global_load_dwordx4 v[108:111], v161, s[0:1]
	v_mov_b32_e32 v200, 0xf149f2ca
	v_mov_b32_e32 v201, 0
	v_mov_b32_e32 v32, 0
	v_mov_b32_e32 v33, 0
	v_mov_b32_e32 v34, 0
	v_mov_b32_e32 v35, 0
	v_mov_b32_e32 v36, 0
	v_mov_b32_e32 v37, 0
	v_mov_b32_e32 v38, 0
	v_mov_b32_e32 v39, 0
	v_mov_b32_e32 v40, 0
	v_mov_b32_e32 v41, 0
	v_mov_b32_e32 v42, 0
	v_mov_b32_e32 v43, 0
	v_mov_b32_e32 v44, 0
	v_mov_b32_e32 v45, 0
	v_mov_b32_e32 v46, 0
	v_mov_b32_e32 v47, 0
	v_mov_b32_e32 v246, 0xf149f2ca
	v_mov_b32_e32 v247, 0
	v_mov_b32_e32 v176, 0
	v_mov_b32_e32 v177, 0
	v_mov_b32_e32 v178, 0
	v_mov_b32_e32 v179, 0
	v_mov_b32_e32 v180, 0
	v_mov_b32_e32 v181, 0
	v_mov_b32_e32 v182, 0
	v_mov_b32_e32 v183, 0
	v_mov_b32_e32 v192, 0
	v_mov_b32_e32 v193, 0
	v_mov_b32_e32 v194, 0
	v_mov_b32_e32 v195, 0
	v_mov_b32_e32 v196, 0
	v_mov_b32_e32 v197, 0
	v_mov_b32_e32 v198, 0
	v_mov_b32_e32 v199, 0
	s_waitcnt vmcnt(0)
	ds_write_b128 v150, v[80:83] offset:0
	ds_write_b128 v150, v[84:87] offset:4096
	ds_write_b128 v150, v[88:91] offset:8192
	ds_write_b128 v150, v[92:95] offset:12288
	ds_write_b64 v151, v[96:97] offset:0
	ds_write_b64 v229, v[98:99] offset:0
	ds_write_b64 v151, v[100:101] offset:4096
	ds_write_b64 v229, v[102:103] offset:4096
	ds_write_b64 v151, v[104:105] offset:8192
	ds_write_b64 v229, v[106:107] offset:8192
	ds_write_b64 v151, v[108:109] offset:12288
	ds_write_b64 v229, v[110:111] offset:12288
	s_add_u32 s100, s12, 0xc0000
	s_addc_u32 s101, s13, 0
	s_add_u32 s0, s14, 0x100
	s_addc_u32 s1, s15, 0
	global_load_dwordx4 v[80:83], v154, s[100:101] offset:2048
	global_load_dwordx4 v[96:99], v158, s[0:1]
	global_load_dwordx4 v[84:87], v155, s[100:101] offset:2048
	global_load_dwordx4 v[100:103], v159, s[0:1]
	global_load_dwordx4 v[88:91], v156, s[100:101] offset:2048
	global_load_dwordx4 v[104:107], v160, s[0:1]
	global_load_dwordx4 v[92:95], v157, s[100:101] offset:2048
	global_load_dwordx4 v[108:111], v161, s[0:1]
	s_waitcnt lgkmcnt(0)
	s_barrier
	s_and_b32 s0, s3, 0xff
	s_lshr_b32 s1, s0, 1
	s_and_b32 s0, s0, 1
	s_lshl_b32 s0, s0, 5
	s_lshr_b32 vcc_lo, s3, 12
	s_add_u32 s0, s0, vcc_lo
	s_lshl_b32 s0, s0, 1
	s_sub_i32 vcc_lo, s0, 4
	s_max_i32 vcc_lo, vcc_lo, 0
	s_min_i32 vcc_lo, vcc_lo, 0x78
	s_lshl_b32 vcc_hi, s1, 13
	s_sub_i32 s18, s0, 3
	s_max_i32 s18, s18, 0
	s_min_i32 s18, s18, 0x78
	s_sub_i32 s18, vcc_lo, s18
	ds_read_b32 v0, v184 offset:384
	ds_read_b32 v1, v185 offset:384
	ds_read_b32 v2, v186 offset:384
	ds_read_b32 v3, v187 offset:384
	ds_read_b32 v4, v184 offset:512
	ds_read_b32 v5, v185 offset:512
	ds_read_b32 v6, v186 offset:512
	ds_read_b32 v7, v187 offset:512
	ds_read_b32 v8, v188 offset:384
	ds_read_b32 v9, v189 offset:384
	ds_read_b32 v10, v190 offset:384
	ds_read_b32 v11, v191 offset:384
	ds_read_b32 v12, v188 offset:512
	ds_read_b32 v13, v189 offset:512
	ds_read_b32 v14, v190 offset:512
	ds_read_b32 v15, v191 offset:512
	s_cmp_eq_u32 s18, 0
	s_cbranch_scc1 .Lmy_att_b0_0
	v_mov_b32_e32 v16, 0xf149f2ca
	v_mov_b32_e32 v17, 0xf149f2ca
	v_mov_b32_e32 v18, 0xf149f2ca
	v_mov_b32_e32 v19, 0xf149f2ca
	v_mov_b32_e32 v24, 0xf149f2ca
	v_mov_b32_e32 v25, 0xf149f2ca
	v_mov_b32_e32 v26, 0xf149f2ca
	v_mov_b32_e32 v27, 0xf149f2ca
	s_branch .Lmy_att_b1_0
; __device__ __forceinline__ void attn_phase(const Params& P, char* smem_raw) {
;     ...
;     for (int ck = 0; ck < 6; ++ck) {
;       int lane_c = lane;
;       asm volatile("" : "+v"(lane_c));
;       __syncthreads();
; #pragma unroll
;       for (int i = 0; i < 4; ++i) {
;         const int idx = tid + 256 * i;
;         *reinterpret_cast<uint4*>(&sm_k[(idx >> 3) * LDSS + (idx & 7) * 8]) = kreg[i];
;         *reinterpret_cast<uint4*>(&sm_vt[(idx >> 4) * 136 + (idx & 15) * 8]) = vreg[i];
;       }
;       __syncthreads();
;       f32x4 sacc[8];
; #pragma unroll
;       for (int t8 = 0; t8 < 8; ++t8) sacc[t8] = f32x4{0.f, 0.f, 0.f, 0.f};
; #pragma unroll
;       for (int s = 0; s < 2; ++s)
; #pragma unroll
;         for (int t8 = 0; t8 < 8; ++t8) {
;           const bf16x8 kf = *reinterpret_cast<const bf16x8*>(&sm_k[(t8 * 16 + (lane_c & 15)) * LDSS + s * 32 + (lane_c >> 4) * 8]);
;           sacc[t8] = __builtin_amdgcn_mfma_f32_16x16x32_bf16(qf[s], kf, sacc[t8], 0, 0, 0);
;         }
;       if (ck < 5) {
;         ATT_ISSUE(t, ck + 1)
;       } else if (t + VGRID < 8192) {
;         ATT_ISSUE(t + VGRID, 0)
;         ATT_QLOAD(t + VGRID)
;       }
;       if (ck < 4) {
;         const float* rb0 = sm_rpb + (rs + ck * 2 - r + 7) * 31;
; #pragma unroll
;         for (int t8 = 0; t8 < 8; ++t8)
; #pragma unroll
;           for (int reg = 0; reg < 4; ++reg)
;             sacc[t8][reg] += rb0[(t8 >> 2) * 31 + dco[reg][t8 & 3]];
;       }
; #pragma unroll
;       for (int reg = 0; reg < 4; ++reg) {
;         float mx = sacc[0][reg];
; #pragma unroll
;         for (int t8 = 1; t8 < 8; ++t8) mx = fmaxf(mx, sacc[t8][reg]);
;         mx = row16_max(mx);
;         const float mnew = fmaxf(mrow[reg], mx);
;         const float alpha = __builtin_amdgcn_exp2f(mrow[reg] - mnew);
;         mrow[reg] = mnew;
;         float rsum = 0.f;
; #pragma unroll
;         for (int t8 = 0; t8 < 8; ++t8) {
;           const float p = __builtin_amdgcn_exp2f(sacc[t8][reg] - mnew);
;           rsum += p;
;           sm_p[(wid * 16 + (lane_c >> 4) * 4 + reg) * 136 + t8 * 16 + (lane_c & 15)] = f2bf(p);
;         }
;         rsum = row16_sum(rsum);
;         lrow[reg] = lrow[reg] * alpha + rsum;
; #pragma unroll
;         for (int td = 0; td < 4; ++td) o[td][reg] *= alpha;
;       }
.Lmy_att_b0_0:
	ds_read_b32 v16, v184 offset:256
	ds_read_b32 v17, v185 offset:256
	ds_read_b32 v18, v186 offset:256
	ds_read_b32 v19, v187 offset:256
	ds_read_b32 v24, v188 offset:256
	ds_read_b32 v25, v189 offset:256
	ds_read_b32 v26, v190 offset:256
	ds_read_b32 v27, v191 offset:256
.Lmy_att_b1_0:
	ds_read_b32 v20, v184 offset:384
	ds_read_b32 v21, v185 offset:384
	ds_read_b32 v22, v186 offset:384
	ds_read_b32 v23, v187 offset:384
	ds_read_b32 v28, v188 offset:384
	ds_read_b32 v29, v189 offset:384
	ds_read_b32 v30, v190 offset:384
	ds_read_b32 v31, v191 offset:384
	s_waitcnt lgkmcnt(0)
	s_waitcnt vmcnt(0)
.Lmy_att_tile:
	s_barrier
	ds_read_b128 v[112:115], v144 offset:0
	ds_read_b128 v[116:119], v145 offset:0
	ds_read_b128 v[120:123], v144 offset:8192
	ds_read_b128 v[124:127], v145 offset:8192
	ds_read_b128 v[128:131], v144 offset:2048
	ds_read_b128 v[132:135], v145 offset:2048
	ds_read_b128 v[136:139], v144 offset:10240
	ds_read_b128 v[140:143], v145 offset:10240
	s_waitcnt lgkmcnt(7)
	v_mfma_f32_16x16x32_bf16 v[0:3], v[112:115], v[64:67], v[0:3]
	v_mfma_f32_16x16x32_bf16 v[16:19], v[112:115], v[230:233], v[16:19]
	s_waitcnt lgkmcnt(6)
	v_mfma_f32_16x16x32_bf16 v[0:3], v[116:119], v[68:71], v[0:3]
	v_mfma_f32_16x16x32_bf16 v[16:19], v[116:119], v[234:237], v[16:19]
	s_waitcnt lgkmcnt(5)
	v_mfma_f32_16x16x32_bf16 v[4:7], v[120:123], v[64:67], v[4:7]
	v_mfma_f32_16x16x32_bf16 v[20:23], v[120:123], v[230:233], v[20:23]
	s_waitcnt lgkmcnt(4)
	v_mfma_f32_16x16x32_bf16 v[4:7], v[124:127], v[68:71], v[4:7]
	v_mfma_f32_16x16x32_bf16 v[20:23], v[124:127], v[234:237], v[20:23]
	s_waitcnt lgkmcnt(3)
	v_mfma_f32_16x16x32_bf16 v[8:11], v[128:131], v[64:67], v[8:11]
	v_mfma_f32_16x16x32_bf16 v[24:27], v[128:131], v[230:233], v[24:27]
	s_waitcnt lgkmcnt(2)
	v_mfma_f32_16x16x32_bf16 v[8:11], v[132:135], v[68:71], v[8:11]
	v_mfma_f32_16x16x32_bf16 v[24:27], v[132:135], v[234:237], v[24:27]
	s_waitcnt lgkmcnt(1)
	v_mfma_f32_16x16x32_bf16 v[12:15], v[136:139], v[64:67], v[12:15]
	v_mfma_f32_16x16x32_bf16 v[28:31], v[136:139], v[230:233], v[28:31]
	s_waitcnt lgkmcnt(0)
	v_mfma_f32_16x16x32_bf16 v[12:15], v[140:143], v[68:71], v[12:15]
	v_mfma_f32_16x16x32_bf16 v[28:31], v[140:143], v[234:237], v[28:31]
	s_nop 7
	v_max3_f32 v203, v0, v1, v2
	v_max3_f32 v206, v16, v17, v18
	v_max3_f32 v203, v203, v3, v4
	v_max3_f32 v206, v206, v19, v20
	v_max3_f32 v203, v203, v5, v6
	v_max3_f32 v206, v206, v21, v22
	v_max3_f32 v203, v203, v7, v8
	v_max3_f32 v206, v206, v23, v24
	v_max3_f32 v203, v203, v9, v10
	v_max3_f32 v206, v206, v25, v26
	v_max3_f32 v203, v203, v11, v12
	v_max3_f32 v206, v206, v27, v28
	v_max3_f32 v203, v203, v13, v14
	v_max3_f32 v206, v206, v29, v30
	v_max_f32_e32 v203, v203, v15
	v_max_f32_e32 v206, v206, v31
	v_mov_b32_e32 v205, v203
	v_mov_b32_e32 v207, v206
	s_nop 1
	v_permlane16_swap_b32_e32 v203, v205
	v_permlane16_swap_b32_e32 v206, v207
	v_max_f32_e32 v203, v203, v205
	v_max_f32_e32 v206, v206, v207
	v_mov_b32_e32 v205, v203
	v_mov_b32_e32 v207, v206
	s_nop 1
	v_permlane32_swap_b32_e32 v203, v205
	v_permlane32_swap_b32_e32 v206, v207
	v_max_f32_e32 v203, v203, v205
	v_max_f32_e32 v206, v206, v207
	v_max_f32_e32 v218, v200, v203
	v_max_f32_e32 v208, v246, v206
	v_sub_f32_e32 v220, v200, v218
	v_sub_f32_e32 v248, v246, v208
	v_mov_b32_e32 v219, v218
	v_mov_b32_e32 v209, v208
	v_exp_f32_e32 v220, v220
	v_exp_f32_e32 v248, v248
	v_mov_b32_e32 v200, v218
	v_mov_b32_e32 v246, v208
	v_pk_add_f32 v[0:1], v[0:1], v[218:219] neg_lo:[0,1] neg_hi:[0,1]
	v_pk_add_f32 v[16:17], v[16:17], v[208:209] neg_lo:[0,1] neg_hi:[0,1]
	v_pk_add_f32 v[2:3], v[2:3], v[218:219] neg_lo:[0,1] neg_hi:[0,1]
	v_pk_add_f32 v[18:19], v[18:19], v[208:209] neg_lo:[0,1] neg_hi:[0,1]
	v_pk_add_f32 v[4:5], v[4:5], v[218:219] neg_lo:[0,1] neg_hi:[0,1]
	v_pk_add_f32 v[20:21], v[20:21], v[208:209] neg_lo:[0,1] neg_hi:[0,1]
	v_pk_add_f32 v[6:7], v[6:7], v[218:219] neg_lo:[0,1] neg_hi:[0,1]
	v_pk_add_f32 v[22:23], v[22:23], v[208:209] neg_lo:[0,1] neg_hi:[0,1]
	v_pk_add_f32 v[8:9], v[8:9], v[218:219] neg_lo:[0,1] neg_hi:[0,1]
	v_pk_add_f32 v[24:25], v[24:25], v[208:209] neg_lo:[0,1] neg_hi:[0,1]
	v_pk_add_f32 v[10:11], v[10:11], v[218:219] neg_lo:[0,1] neg_hi:[0,1]
	v_pk_add_f32 v[26:27], v[26:27], v[208:209] neg_lo:[0,1] neg_hi:[0,1]
	v_pk_add_f32 v[12:13], v[12:13], v[218:219] neg_lo:[0,1] neg_hi:[0,1]
	v_pk_add_f32 v[28:29], v[28:29], v[208:209] neg_lo:[0,1] neg_hi:[0,1]
	v_pk_add_f32 v[14:15], v[14:15], v[218:219] neg_lo:[0,1] neg_hi:[0,1]
	v_pk_add_f32 v[30:31], v[30:31], v[208:209] neg_lo:[0,1] neg_hi:[0,1]
	v_exp_f32_e32 v0, v0
	s_waitcnt vmcnt(8)
; __device__ __forceinline__ void attn_phase(const Params& P, char* smem_raw) {
;     ...
;     for (int ck = 0; ck < 6; ++ck) {
;       int lane_c = lane;
;       asm volatile("" : "+v"(lane_c));
;       __syncthreads();
; #pragma unroll
;       for (int i = 0; i < 4; ++i) {
;         const int idx = tid + 256 * i;
;         *reinterpret_cast<uint4*>(&sm_k[(idx >> 3) * LDSS + (idx & 7) * 8]) = kreg[i];
;         *reinterpret_cast<uint4*>(&sm_vt[(idx >> 4) * 136 + (idx & 15) * 8]) = vreg[i];
;       }
;       __syncthreads();
;       f32x4 sacc[8];
; #pragma unroll
;       for (int t8 = 0; t8 < 8; ++t8) sacc[t8] = f32x4{0.f, 0.f, 0.f, 0.f};
; #pragma unroll
;       for (int s = 0; s < 2; ++s)
; #pragma unroll
;         for (int t8 = 0; t8 < 8; ++t8) {
;           const bf16x8 kf = *reinterpret_cast<const bf16x8*>(&sm_k[(t8 * 16 + (lane_c & 15)) * LDSS + s * 32 + (lane_c >> 4) * 8]);
;           sacc[t8] = __builtin_amdgcn_mfma_f32_16x16x32_bf16(qf[s], kf, sacc[t8], 0, 0, 0);
;         }
;       if (ck < 5) {
;         ATT_ISSUE(t, ck + 1)
;       } else if (t + VGRID < 8192) {
;         ATT_ISSUE(t + VGRID, 0)
;         ATT_QLOAD(t + VGRID)
;       }
;       if (ck < 4) {
;         const float* rb0 = sm_rpb + (rs + ck * 2 - r + 7) * 31;
; #pragma unroll
;         for (int t8 = 0; t8 < 8; ++t8)
; #pragma unroll
;           for (int reg = 0; reg < 4; ++reg)
;             sacc[t8][reg] += rb0[(t8 >> 2) * 31 + dco[reg][t8 & 3]];
;       }
; #pragma unroll
;       for (int reg = 0; reg < 4; ++reg) {
;         float mx = sacc[0][reg];
; #pragma unroll
;         for (int t8 = 1; t8 < 8; ++t8) mx = fmaxf(mx, sacc[t8][reg]);
;         mx = row16_max(mx);
;         const float mnew = fmaxf(mrow[reg], mx);
;         const float alpha = __builtin_amdgcn_exp2f(mrow[reg] - mnew);
;         mrow[reg] = mnew;
;         float rsum = 0.f;
; #pragma unroll
;         for (int t8 = 0; t8 < 8; ++t8) {
;           const float p = __builtin_amdgcn_exp2f(sacc[t8][reg] - mnew);
;           rsum += p;
;           sm_p[(wid * 16 + (lane_c >> 4) * 4 + reg) * 136 + t8 * 16 + (lane_c & 15)] = f2bf(p);
;         }
;         rsum = row16_sum(rsum);
;         lrow[reg] = lrow[reg] * alpha + rsum;
; #pragma unroll
;         for (int td = 0; td < 4; ++td) o[td][reg] *= alpha;
;       }
;       asm volatile("s_waitcnt lgkmcnt(0)" ::: "memory");
; #pragma unroll
;       for (int s4 = 0; s4 < 4; ++s4) {
	v_exp_f32_e32 v1, v1
	ds_write_b128 v150, v[80:83] offset:32768
	v_exp_f32_e32 v2, v2
	ds_write_b128 v150, v[84:87] offset:36864
	v_exp_f32_e32 v3, v3
	ds_write_b128 v150, v[88:91] offset:40960
	v_exp_f32_e32 v4, v4
	ds_write_b128 v150, v[92:95] offset:45056
	v_exp_f32_e32 v5, v5
	ds_write_b64 v151, v[96:97] offset:32768
	v_exp_f32_e32 v6, v6
	ds_write_b64 v229, v[98:99] offset:32768
	v_exp_f32_e32 v7, v7
	ds_write_b64 v151, v[100:101] offset:36864
	v_exp_f32_e32 v8, v8
	ds_write_b64 v229, v[102:103] offset:36864
	v_exp_f32_e32 v9, v9
	ds_write_b64 v151, v[104:105] offset:40960
	v_exp_f32_e32 v10, v10
	ds_write_b64 v229, v[106:107] offset:40960
	v_exp_f32_e32 v11, v11
	ds_write_b64 v151, v[108:109] offset:45056
	v_exp_f32_e32 v12, v12
	ds_write_b64 v229, v[110:111] offset:45056
	v_exp_f32_e32 v13, v13
	s_add_u32 s100, s12, 0x180000
	v_exp_f32_e32 v14, v14
	s_addc_u32 s101, s13, 0
	v_exp_f32_e32 v15, v15
	s_add_u32 s0, s14, 0x200
	v_exp_f32_e32 v16, v16
	s_addc_u32 s1, s15, 0
	v_exp_f32_e32 v17, v17
	global_load_dwordx4 v[80:83], v154, s[100:101] offset:2048
	v_exp_f32_e32 v18, v18
	global_load_dwordx4 v[96:99], v158, s[0:1]
	v_exp_f32_e32 v19, v19
	global_load_dwordx4 v[84:87], v155, s[100:101] offset:2048
	v_exp_f32_e32 v20, v20
	global_load_dwordx4 v[100:103], v159, s[0:1]
	v_exp_f32_e32 v21, v21
	global_load_dwordx4 v[88:91], v156, s[100:101] offset:2048
	v_exp_f32_e32 v22, v22
	global_load_dwordx4 v[104:107], v160, s[0:1]
	v_exp_f32_e32 v23, v23
	global_load_dwordx4 v[92:95], v157, s[100:101] offset:2048
	v_exp_f32_e32 v24, v24
	global_load_dwordx4 v[108:111], v161, s[0:1]
	v_exp_f32_e32 v25, v25
	v_exp_f32_e32 v26, v26
	v_exp_f32_e32 v27, v27
	v_exp_f32_e32 v28, v28
	v_exp_f32_e32 v29, v29
	v_exp_f32_e32 v30, v30
	v_exp_f32_e32 v31, v31
	s_and_b32 s0, s3, 0xff
	s_lshr_b32 s1, s0, 1
	s_and_b32 s0, s0, 1
	s_lshl_b32 s0, s0, 5
	s_lshr_b32 vcc_lo, s3, 12
	s_add_u32 s0, s0, vcc_lo
	s_lshl_b32 s0, s0, 1
	s_sub_i32 vcc_lo, s0, 4
	s_max_i32 vcc_lo, vcc_lo, 0
	s_min_i32 vcc_lo, vcc_lo, 0x78
	s_lshl_b32 vcc_hi, s1, 13
	s_sub_i32 s19, s0, 3
	s_max_i32 s19, s19, 0
	s_min_i32 s19, s19, 0x78
	s_sub_i32 s19, vcc_lo, s19
	s_lshl_b32 m0, s1, 8
	s_add_u32 m0, m0, 0x8000
	s_mul_i32 m0, m0, 0x1800
	s_add_u32 s16, s4, m0
	s_addc_u32 s17, s5, 0
	s_lshl_b32 m0, s1, 19
	s_add_u32 s36, s8, m0
	s_addc_u32 s37, s9, 0
	s_lshl_b32 m0, s0, 6
	s_add_u32 m0, m0, vcc_hi
	s_lshl_b32 m0, m0, 11
	s_add_u32 s98, s10, m0
	s_addc_u32 s99, s11, 0
	ds_read_b128 v[112:115], v146 offset:0
	ds_read_b128 v[116:119], v146 offset:4096
	ds_read_b128 v[120:123], v146 offset:8192
	ds_read_b128 v[124:127], v146 offset:12288
	ds_read_b128 v[128:131], v147 offset:0
	ds_read_b128 v[132:135], v147 offset:4096
	ds_read_b128 v[136:139], v147 offset:8192
	ds_read_b128 v[140:143], v147 offset:12288
	v_mov_b32_e32 v221, v220
	v_mov_b32_e32 v249, v248
	v_pk_add_f32 v[222:223], v[0:1], v[2:3]
	v_pk_add_f32 v[250:251], v[16:17], v[18:19]
	v_pk_add_f32 v[222:223], v[222:223], v[4:5]
	v_pk_add_f32 v[250:251], v[250:251], v[20:21]
	v_pk_add_f32 v[222:223], v[222:223], v[6:7]
	v_pk_add_f32 v[250:251], v[250:251], v[22:23]
	v_pk_add_f32 v[222:223], v[222:223], v[8:9]
	v_pk_add_f32 v[250:251], v[250:251], v[24:25]
	v_pk_add_f32 v[222:223], v[222:223], v[10:11]
	v_pk_add_f32 v[250:251], v[250:251], v[26:27]
	v_pk_add_f32 v[222:223], v[222:223], v[12:13]
	v_pk_add_f32 v[250:251], v[250:251], v[28:29]
	v_pk_add_f32 v[222:223], v[222:223], v[14:15]
	v_pk_add_f32 v[250:251], v[250:251], v[30:31]
	v_pk_mul_f32 v[32:33], v[32:33], v[220:221]
	v_pk_mul_f32 v[34:35], v[34:35], v[220:221]
	v_pk_mul_f32 v[176:177], v[176:177], v[248:249]
	v_pk_mul_f32 v[178:179], v[178:179], v[248:249]
	v_pk_mul_f32 v[36:37], v[36:37], v[220:221]
	v_pk_mul_f32 v[38:39], v[38:39], v[220:221]
	v_pk_mul_f32 v[180:181], v[180:181], v[248:249]
	v_pk_mul_f32 v[182:183], v[182:183], v[248:249]
	v_pk_mul_f32 v[40:41], v[40:41], v[220:221]
	v_pk_mul_f32 v[42:43], v[42:43], v[220:221]
	v_pk_mul_f32 v[192:193], v[192:193], v[248:249]
	v_pk_mul_f32 v[194:195], v[194:195], v[248:249]
	v_pk_mul_f32 v[44:45], v[44:45], v[220:221]
	v_pk_mul_f32 v[46:47], v[46:47], v[220:221]
	v_pk_mul_f32 v[196:197], v[196:197], v[248:249]
	v_pk_mul_f32 v[198:199], v[198:199], v[248:249]
	v_add_f32_e32 v203, v222, v223
	v_add_f32_e32 v206, v250, v251
	v_fma_f32 v201, v201, v220, v203
	v_fma_f32 v247, v247, v248, v206
	v_cvt_pk_bf16_f32 v48, v0, v1
	v_cvt_pk_bf16_f32 v49, v2, v3
	v_cvt_pk_bf16_f32 v50, v4, v5
	v_cvt_pk_bf16_f32 v51, v6, v7
	v_cvt_pk_bf16_f32 v56, v16, v17
	v_cvt_pk_bf16_f32 v57, v18, v19
	v_cvt_pk_bf16_f32 v58, v20, v21
	v_cvt_pk_bf16_f32 v59, v22, v23
	v_cvt_pk_bf16_f32 v52, v8, v9
	v_cvt_pk_bf16_f32 v53, v10, v11
	v_cvt_pk_bf16_f32 v54, v12, v13
	v_cvt_pk_bf16_f32 v55, v14, v15
	v_cvt_pk_bf16_f32 v60, v24, v25
	v_cvt_pk_bf16_f32 v61, v26, v27
	v_cvt_pk_bf16_f32 v62, v28, v29
	v_cvt_pk_bf16_f32 v63, v30, v31
	s_waitcnt lgkmcnt(7)
	v_mfma_f32_16x16x32_bf16 v[32:35], v[112:115], v[48:51], v[32:35]
	v_mfma_f32_16x16x32_bf16 v[176:179], v[112:115], v[56:59], v[176:179]
	s_waitcnt lgkmcnt(6)
	v_mfma_f32_16x16x32_bf16 v[36:39], v[116:119], v[48:51], v[36:39]
	v_mfma_f32_16x16x32_bf16 v[180:183], v[116:119], v[56:59], v[180:183]
	s_waitcnt lgkmcnt(5)
	v_mfma_f32_16x16x32_bf16 v[40:43], v[120:123], v[48:51], v[40:43]
	v_mfma_f32_16x16x32_bf16 v[192:195], v[120:123], v[56:59], v[192:195]
	s_waitcnt lgkmcnt(4)
	v_mfma_f32_16x16x32_bf16 v[44:47], v[124:127], v[48:51], v[44:47]
	v_mfma_f32_16x16x32_bf16 v[196:199], v[124:127], v[56:59], v[196:199]
	s_waitcnt lgkmcnt(3)
	v_mfma_f32_16x16x32_bf16 v[32:35], v[128:131], v[52:55], v[32:35]
	v_mfma_f32_16x16x32_bf16 v[176:179], v[128:131], v[60:63], v[176:179]
	s_waitcnt lgkmcnt(2)
; __device__ __forceinline__ void attn_phase(const Params& P, char* smem_raw) {
;     ...
;     for (int ck = 0; ck < 6; ++ck) {
;       int lane_c = lane;
;       asm volatile("" : "+v"(lane_c));
;       __syncthreads();
; #pragma unroll
;       for (int i = 0; i < 4; ++i) {
;         const int idx = tid + 256 * i;
;         *reinterpret_cast<uint4*>(&sm_k[(idx >> 3) * LDSS + (idx & 7) * 8]) = kreg[i];
;         *reinterpret_cast<uint4*>(&sm_vt[(idx >> 4) * 136 + (idx & 15) * 8]) = vreg[i];
;       }
;       __syncthreads();
;       f32x4 sacc[8];
; #pragma unroll
;       for (int t8 = 0; t8 < 8; ++t8) sacc[t8] = f32x4{0.f, 0.f, 0.f, 0.f};
; #pragma unroll
;       for (int s = 0; s < 2; ++s)
; #pragma unroll
;         for (int t8 = 0; t8 < 8; ++t8) {
;           const bf16x8 kf = *reinterpret_cast<const bf16x8*>(&sm_k[(t8 * 16 + (lane_c & 15)) * LDSS + s * 32 + (lane_c >> 4) * 8]);
;           sacc[t8] = __builtin_amdgcn_mfma_f32_16x16x32_bf16(qf[s], kf, sacc[t8], 0, 0, 0);
;         }
;       if (ck < 5) {
;         ATT_ISSUE(t, ck + 1)
;       } else if (t + VGRID < 8192) {
;         ATT_ISSUE(t + VGRID, 0)
;         ATT_QLOAD(t + VGRID)
;       }
;       if (ck < 4) {
;         const float* rb0 = sm_rpb + (rs + ck * 2 - r + 7) * 31;
; #pragma unroll
;         for (int t8 = 0; t8 < 8; ++t8)
; #pragma unroll
;           for (int reg = 0; reg < 4; ++reg)
;             sacc[t8][reg] += rb0[(t8 >> 2) * 31 + dco[reg][t8 & 3]];
;       }
; #pragma unroll
;       for (int reg = 0; reg < 4; ++reg) {
;         float mx = sacc[0][reg];
; #pragma unroll
;         for (int t8 = 1; t8 < 8; ++t8) mx = fmaxf(mx, sacc[t8][reg]);
;         mx = row16_max(mx);
;         const float mnew = fmaxf(mrow[reg], mx);
;         const float alpha = __builtin_amdgcn_exp2f(mrow[reg] - mnew);
;         mrow[reg] = mnew;
;         float rsum = 0.f;
; #pragma unroll
;         for (int t8 = 0; t8 < 8; ++t8) {
;           const float p = __builtin_amdgcn_exp2f(sacc[t8][reg] - mnew);
;           rsum += p;
;           sm_p[(wid * 16 + (lane_c >> 4) * 4 + reg) * 136 + t8 * 16 + (lane_c & 15)] = f2bf(p);
;         }
;         rsum = row16_sum(rsum);
;         lrow[reg] = lrow[reg] * alpha + rsum;
; #pragma unroll
;         for (int td = 0; td < 4; ++td) o[td][reg] *= alpha;
;       }
;       asm volatile("s_waitcnt lgkmcnt(0)" ::: "memory");
; #pragma unroll
;       for (int s4 = 0; s4 < 4; ++s4) {
	v_mfma_f32_16x16x32_bf16 v[36:39], v[132:135], v[52:55], v[36:39]
	v_mfma_f32_16x16x32_bf16 v[180:183], v[132:135], v[60:63], v[180:183]
	s_waitcnt lgkmcnt(1)
	v_mfma_f32_16x16x32_bf16 v[40:43], v[136:139], v[52:55], v[40:43]
	v_mfma_f32_16x16x32_bf16 v[192:195], v[136:139], v[60:63], v[192:195]
	s_waitcnt lgkmcnt(0)
	v_mfma_f32_16x16x32_bf16 v[44:47], v[140:143], v[52:55], v[44:47]
	v_mfma_f32_16x16x32_bf16 v[196:199], v[140:143], v[60:63], v[196:199]
	ds_read_b32 v0, v184 offset:640
	ds_read_b32 v1, v185 offset:640
	ds_read_b32 v2, v186 offset:640
	ds_read_b32 v3, v187 offset:640
	ds_read_b32 v4, v184 offset:768
	ds_read_b32 v5, v185 offset:768
	ds_read_b32 v6, v186 offset:768
	ds_read_b32 v7, v187 offset:768
	ds_read_b32 v8, v188 offset:640
	ds_read_b32 v9, v189 offset:640
	ds_read_b32 v10, v190 offset:640
	ds_read_b32 v11, v191 offset:640
	ds_read_b32 v12, v188 offset:768
	ds_read_b32 v13, v189 offset:768
	ds_read_b32 v14, v190 offset:768
	ds_read_b32 v15, v191 offset:768
	ds_read_b32 v16, v184 offset:512
	ds_read_b32 v17, v185 offset:512
	ds_read_b32 v18, v186 offset:512
	ds_read_b32 v19, v187 offset:512
	ds_read_b32 v20, v184 offset:640
	ds_read_b32 v21, v185 offset:640
	ds_read_b32 v22, v186 offset:640
	ds_read_b32 v23, v187 offset:640
	ds_read_b32 v24, v188 offset:512
	ds_read_b32 v25, v189 offset:512
	ds_read_b32 v26, v190 offset:512
	ds_read_b32 v27, v191 offset:512
	ds_read_b32 v28, v188 offset:640
	ds_read_b32 v29, v189 offset:640
	ds_read_b32 v30, v190 offset:640
	ds_read_b32 v31, v191 offset:640
	s_waitcnt lgkmcnt(0)
	s_barrier
	ds_read_b128 v[112:115], v144 offset:32768
	ds_read_b128 v[116:119], v145 offset:32768
	ds_read_b128 v[120:123], v144 offset:40960
	ds_read_b128 v[124:127], v145 offset:40960
	ds_read_b128 v[128:131], v144 offset:34816
	ds_read_b128 v[132:135], v145 offset:34816
	ds_read_b128 v[136:139], v144 offset:43008
	ds_read_b128 v[140:143], v145 offset:43008
	s_waitcnt lgkmcnt(7)
	v_mfma_f32_16x16x32_bf16 v[0:3], v[112:115], v[64:67], v[0:3]
	v_mfma_f32_16x16x32_bf16 v[16:19], v[112:115], v[230:233], v[16:19]
	s_waitcnt lgkmcnt(6)
	v_mfma_f32_16x16x32_bf16 v[0:3], v[116:119], v[68:71], v[0:3]
	v_mfma_f32_16x16x32_bf16 v[16:19], v[116:119], v[234:237], v[16:19]
	s_waitcnt lgkmcnt(5)
	v_mfma_f32_16x16x32_bf16 v[4:7], v[120:123], v[64:67], v[4:7]
	v_mfma_f32_16x16x32_bf16 v[20:23], v[120:123], v[230:233], v[20:23]
	s_waitcnt lgkmcnt(4)
	v_mfma_f32_16x16x32_bf16 v[4:7], v[124:127], v[68:71], v[4:7]
	v_mfma_f32_16x16x32_bf16 v[20:23], v[124:127], v[234:237], v[20:23]
	s_waitcnt lgkmcnt(3)
	v_mfma_f32_16x16x32_bf16 v[8:11], v[128:131], v[64:67], v[8:11]
	v_mfma_f32_16x16x32_bf16 v[24:27], v[128:131], v[230:233], v[24:27]
	s_waitcnt lgkmcnt(2)
	v_mfma_f32_16x16x32_bf16 v[8:11], v[132:135], v[68:71], v[8:11]
	v_mfma_f32_16x16x32_bf16 v[24:27], v[132:135], v[234:237], v[24:27]
	s_waitcnt lgkmcnt(1)
	v_mfma_f32_16x16x32_bf16 v[12:15], v[136:139], v[64:67], v[12:15]
	v_mfma_f32_16x16x32_bf16 v[28:31], v[136:139], v[230:233], v[28:31]
	s_waitcnt lgkmcnt(0)
	v_mfma_f32_16x16x32_bf16 v[12:15], v[140:143], v[68:71], v[12:15]
	v_mfma_f32_16x16x32_bf16 v[28:31], v[140:143], v[234:237], v[28:31]
	s_nop 7
	v_max3_f32 v203, v0, v1, v2
	v_max3_f32 v206, v16, v17, v18
	v_max3_f32 v203, v203, v3, v4
	v_max3_f32 v206, v206, v19, v20
	v_max3_f32 v203, v203, v5, v6
	v_max3_f32 v206, v206, v21, v22
	v_max3_f32 v203, v203, v7, v8
	v_max3_f32 v206, v206, v23, v24
	v_max3_f32 v203, v203, v9, v10
	v_max3_f32 v206, v206, v25, v26
	v_max3_f32 v203, v203, v11, v12
	v_max3_f32 v206, v206, v27, v28
	v_max3_f32 v203, v203, v13, v14
	v_max3_f32 v206, v206, v29, v30
	v_max_f32_e32 v203, v203, v15
	v_max_f32_e32 v206, v206, v31
	v_mov_b32_e32 v205, v203
	v_mov_b32_e32 v207, v206
	s_nop 1
	v_permlane16_swap_b32_e32 v203, v205
	v_permlane16_swap_b32_e32 v206, v207
	v_max_f32_e32 v203, v203, v205
	v_max_f32_e32 v206, v206, v207
	v_mov_b32_e32 v205, v203
	v_mov_b32_e32 v207, v206
	s_nop 1
	v_permlane32_swap_b32_e32 v203, v205
	v_permlane32_swap_b32_e32 v206, v207
	v_max_f32_e32 v203, v203, v205
	v_max_f32_e32 v206, v206, v207
	v_max_f32_e32 v218, v200, v203
	v_max_f32_e32 v208, v246, v206
	v_sub_f32_e32 v220, v200, v218
	v_sub_f32_e32 v248, v246, v208
	v_mov_b32_e32 v219, v218
	v_mov_b32_e32 v209, v208
	v_exp_f32_e32 v220, v220
	v_exp_f32_e32 v248, v248
	v_mov_b32_e32 v200, v218
	v_mov_b32_e32 v246, v208
	v_pk_add_f32 v[0:1], v[0:1], v[218:219] neg_lo:[0,1] neg_hi:[0,1]
	v_pk_add_f32 v[16:17], v[16:17], v[208:209] neg_lo:[0,1] neg_hi:[0,1]
	v_pk_add_f32 v[2:3], v[2:3], v[218:219] neg_lo:[0,1] neg_hi:[0,1]
	v_pk_add_f32 v[18:19], v[18:19], v[208:209] neg_lo:[0,1] neg_hi:[0,1]
	v_pk_add_f32 v[4:5], v[4:5], v[218:219] neg_lo:[0,1] neg_hi:[0,1]
	v_pk_add_f32 v[20:21], v[20:21], v[208:209] neg_lo:[0,1] neg_hi:[0,1]
	v_pk_add_f32 v[6:7], v[6:7], v[218:219] neg_lo:[0,1] neg_hi:[0,1]
	v_pk_add_f32 v[22:23], v[22:23], v[208:209] neg_lo:[0,1] neg_hi:[0,1]
	v_pk_add_f32 v[8:9], v[8:9], v[218:219] neg_lo:[0,1] neg_hi:[0,1]
	v_pk_add_f32 v[24:25], v[24:25], v[208:209] neg_lo:[0,1] neg_hi:[0,1]
	v_pk_add_f32 v[10:11], v[10:11], v[218:219] neg_lo:[0,1] neg_hi:[0,1]
	v_pk_add_f32 v[26:27], v[26:27], v[208:209] neg_lo:[0,1] neg_hi:[0,1]
	v_pk_add_f32 v[12:13], v[12:13], v[218:219] neg_lo:[0,1] neg_hi:[0,1]
	v_pk_add_f32 v[28:29], v[28:29], v[208:209] neg_lo:[0,1] neg_hi:[0,1]
	v_pk_add_f32 v[14:15], v[14:15], v[218:219] neg_lo:[0,1] neg_hi:[0,1]
	v_pk_add_f32 v[30:31], v[30:31], v[208:209] neg_lo:[0,1] neg_hi:[0,1]
	v_exp_f32_e32 v0, v0
	s_waitcnt vmcnt(0)
; __device__ __forceinline__ void attn_phase(const Params& P, char* smem_raw) {
;     ...
;     for (int ck = 0; ck < 6; ++ck) {
;       int lane_c = lane;
;       asm volatile("" : "+v"(lane_c));
;       __syncthreads();
; #pragma unroll
;       for (int i = 0; i < 4; ++i) {
;         const int idx = tid + 256 * i;
;         *reinterpret_cast<uint4*>(&sm_k[(idx >> 3) * LDSS + (idx & 7) * 8]) = kreg[i];
;         *reinterpret_cast<uint4*>(&sm_vt[(idx >> 4) * 136 + (idx & 15) * 8]) = vreg[i];
;       }
;       __syncthreads();
;       f32x4 sacc[8];
; #pragma unroll
;       for (int t8 = 0; t8 < 8; ++t8) sacc[t8] = f32x4{0.f, 0.f, 0.f, 0.f};
; #pragma unroll
;       for (int s = 0; s < 2; ++s)
; #pragma unroll
;         for (int t8 = 0; t8 < 8; ++t8) {
;           const bf16x8 kf = *reinterpret_cast<const bf16x8*>(&sm_k[(t8 * 16 + (lane_c & 15)) * LDSS + s * 32 + (lane_c >> 4) * 8]);
;           sacc[t8] = __builtin_amdgcn_mfma_f32_16x16x32_bf16(qf[s], kf, sacc[t8], 0, 0, 0);
;         }
;       if (ck < 5) {
;         ATT_ISSUE(t, ck + 1)
;       } else if (t + VGRID < 8192) {
;         ATT_ISSUE(t + VGRID, 0)
;         ATT_QLOAD(t + VGRID)
;       }
;       if (ck < 4) {
;         const float* rb0 = sm_rpb + (rs + ck * 2 - r + 7) * 31;
; #pragma unroll
;         for (int t8 = 0; t8 < 8; ++t8)
; #pragma unroll
;           for (int reg = 0; reg < 4; ++reg)
;             sacc[t8][reg] += rb0[(t8 >> 2) * 31 + dco[reg][t8 & 3]];
;       }
; #pragma unroll
;       for (int reg = 0; reg < 4; ++reg) {
;         float mx = sacc[0][reg];
; #pragma unroll
;         for (int t8 = 1; t8 < 8; ++t8) mx = fmaxf(mx, sacc[t8][reg]);
;         mx = row16_max(mx);
;         const float mnew = fmaxf(mrow[reg], mx);
;         const float alpha = __builtin_amdgcn_exp2f(mrow[reg] - mnew);
;         mrow[reg] = mnew;
;         float rsum = 0.f;
; #pragma unroll
;         for (int t8 = 0; t8 < 8; ++t8) {
;           const float p = __builtin_amdgcn_exp2f(sacc[t8][reg] - mnew);
;           rsum += p;
;           sm_p[(wid * 16 + (lane_c >> 4) * 4 + reg) * 136 + t8 * 16 + (lane_c & 15)] = f2bf(p);
;         }
;         rsum = row16_sum(rsum);
;         lrow[reg] = lrow[reg] * alpha + rsum;
; #pragma unroll
;         for (int td = 0; td < 4; ++td) o[td][reg] *= alpha;
;       }
;       asm volatile("s_waitcnt lgkmcnt(0)" ::: "memory");
; #pragma unroll
;       for (int s4 = 0; s4 < 4; ++s4) {
	v_exp_f32_e32 v1, v1
	ds_write_b128 v150, v[80:83] offset:0
	v_exp_f32_e32 v2, v2
	ds_write_b128 v150, v[84:87] offset:4096
	v_exp_f32_e32 v3, v3
	ds_write_b128 v150, v[88:91] offset:8192
	v_exp_f32_e32 v4, v4
	ds_write_b128 v150, v[92:95] offset:12288
	v_exp_f32_e32 v5, v5
	ds_write_b64 v151, v[96:97] offset:0
	v_exp_f32_e32 v6, v6
	ds_write_b64 v229, v[98:99] offset:0
	v_exp_f32_e32 v7, v7
	ds_write_b64 v151, v[100:101] offset:4096
	v_exp_f32_e32 v8, v8
	ds_write_b64 v229, v[102:103] offset:4096
	v_exp_f32_e32 v9, v9
	ds_write_b64 v151, v[104:105] offset:8192
	v_exp_f32_e32 v10, v10
	ds_write_b64 v229, v[106:107] offset:8192
	v_exp_f32_e32 v11, v11
	ds_write_b64 v151, v[108:109] offset:12288
	v_exp_f32_e32 v12, v12
	ds_write_b64 v229, v[110:111] offset:12288
	v_exp_f32_e32 v13, v13
	s_add_u32 s100, s12, 0x240000
	v_exp_f32_e32 v14, v14
	s_addc_u32 s101, s13, 0
	v_exp_f32_e32 v15, v15
	s_add_u32 s0, s14, 0x300
	v_exp_f32_e32 v16, v16
	s_addc_u32 s1, s15, 0
	v_exp_f32_e32 v17, v17
	global_load_dwordx4 v[80:83], v154, s[100:101] offset:2048
	v_exp_f32_e32 v18, v18
	global_load_dwordx4 v[96:99], v158, s[0:1]
	v_exp_f32_e32 v19, v19
	global_load_dwordx4 v[84:87], v155, s[100:101] offset:2048
	v_exp_f32_e32 v20, v20
	global_load_dwordx4 v[100:103], v159, s[0:1]
	v_exp_f32_e32 v21, v21
	global_load_dwordx4 v[88:91], v156, s[100:101] offset:2048
	v_exp_f32_e32 v22, v22
	global_load_dwordx4 v[104:107], v160, s[0:1]
	v_exp_f32_e32 v23, v23
	global_load_dwordx4 v[92:95], v157, s[100:101] offset:2048
	v_exp_f32_e32 v24, v24
	global_load_dwordx4 v[108:111], v161, s[0:1]
	v_exp_f32_e32 v25, v25
	v_exp_f32_e32 v26, v26
	v_exp_f32_e32 v27, v27
	v_exp_f32_e32 v28, v28
	v_exp_f32_e32 v29, v29
	v_exp_f32_e32 v30, v30
	v_exp_f32_e32 v31, v31
	ds_read_b128 v[112:115], v146 offset:32768
	ds_read_b128 v[116:119], v146 offset:36864
	ds_read_b128 v[120:123], v146 offset:40960
	ds_read_b128 v[124:127], v146 offset:45056
	ds_read_b128 v[128:131], v147 offset:32768
	ds_read_b128 v[132:135], v147 offset:36864
	ds_read_b128 v[136:139], v147 offset:40960
	ds_read_b128 v[140:143], v147 offset:45056
	v_mov_b32_e32 v221, v220
	v_mov_b32_e32 v249, v248
	v_pk_add_f32 v[222:223], v[0:1], v[2:3]
	v_pk_add_f32 v[250:251], v[16:17], v[18:19]
	v_pk_add_f32 v[222:223], v[222:223], v[4:5]
	v_pk_add_f32 v[250:251], v[250:251], v[20:21]
	v_pk_add_f32 v[222:223], v[222:223], v[6:7]
	v_pk_add_f32 v[250:251], v[250:251], v[22:23]
	v_pk_add_f32 v[222:223], v[222:223], v[8:9]
	v_pk_add_f32 v[250:251], v[250:251], v[24:25]
	v_pk_add_f32 v[222:223], v[222:223], v[10:11]
	v_pk_add_f32 v[250:251], v[250:251], v[26:27]
	v_pk_add_f32 v[222:223], v[222:223], v[12:13]
	v_pk_add_f32 v[250:251], v[250:251], v[28:29]
	v_pk_add_f32 v[222:223], v[222:223], v[14:15]
	v_pk_add_f32 v[250:251], v[250:251], v[30:31]
	v_pk_mul_f32 v[32:33], v[32:33], v[220:221]
	v_pk_mul_f32 v[34:35], v[34:35], v[220:221]
	v_pk_mul_f32 v[176:177], v[176:177], v[248:249]
	v_pk_mul_f32 v[178:179], v[178:179], v[248:249]
	v_pk_mul_f32 v[36:37], v[36:37], v[220:221]
	v_pk_mul_f32 v[38:39], v[38:39], v[220:221]
	v_pk_mul_f32 v[180:181], v[180:181], v[248:249]
	v_pk_mul_f32 v[182:183], v[182:183], v[248:249]
	v_pk_mul_f32 v[40:41], v[40:41], v[220:221]
	v_pk_mul_f32 v[42:43], v[42:43], v[220:221]
	v_pk_mul_f32 v[192:193], v[192:193], v[248:249]
	v_pk_mul_f32 v[194:195], v[194:195], v[248:249]
	v_pk_mul_f32 v[44:45], v[44:45], v[220:221]
	v_pk_mul_f32 v[46:47], v[46:47], v[220:221]
	v_pk_mul_f32 v[196:197], v[196:197], v[248:249]
	v_pk_mul_f32 v[198:199], v[198:199], v[248:249]
	v_add_f32_e32 v203, v222, v223
	v_add_f32_e32 v206, v250, v251
	v_fma_f32 v201, v201, v220, v203
	v_fma_f32 v247, v247, v248, v206
	v_cvt_pk_bf16_f32 v48, v0, v1
	v_cvt_pk_bf16_f32 v49, v2, v3
	v_cvt_pk_bf16_f32 v50, v4, v5
	v_cvt_pk_bf16_f32 v51, v6, v7
	v_cvt_pk_bf16_f32 v56, v16, v17
	v_cvt_pk_bf16_f32 v57, v18, v19
	v_cvt_pk_bf16_f32 v58, v20, v21
	v_cvt_pk_bf16_f32 v59, v22, v23
	v_cvt_pk_bf16_f32 v52, v8, v9
	v_cvt_pk_bf16_f32 v53, v10, v11
	v_cvt_pk_bf16_f32 v54, v12, v13
	v_cvt_pk_bf16_f32 v55, v14, v15
	v_cvt_pk_bf16_f32 v60, v24, v25
	v_cvt_pk_bf16_f32 v61, v26, v27
	v_cvt_pk_bf16_f32 v62, v28, v29
	v_cvt_pk_bf16_f32 v63, v30, v31
	s_waitcnt lgkmcnt(7)
	v_mfma_f32_16x16x32_bf16 v[32:35], v[112:115], v[48:51], v[32:35]
	v_mfma_f32_16x16x32_bf16 v[176:179], v[112:115], v[56:59], v[176:179]
	s_waitcnt lgkmcnt(6)
	v_mfma_f32_16x16x32_bf16 v[36:39], v[116:119], v[48:51], v[36:39]
	v_mfma_f32_16x16x32_bf16 v[180:183], v[116:119], v[56:59], v[180:183]
	s_waitcnt lgkmcnt(5)
	v_mfma_f32_16x16x32_bf16 v[40:43], v[120:123], v[48:51], v[40:43]
	v_mfma_f32_16x16x32_bf16 v[192:195], v[120:123], v[56:59], v[192:195]
	s_waitcnt lgkmcnt(4)
	v_mfma_f32_16x16x32_bf16 v[44:47], v[124:127], v[48:51], v[44:47]
	v_mfma_f32_16x16x32_bf16 v[196:199], v[124:127], v[56:59], v[196:199]
	s_waitcnt lgkmcnt(3)
	v_mfma_f32_16x16x32_bf16 v[32:35], v[128:131], v[52:55], v[32:35]
	v_mfma_f32_16x16x32_bf16 v[176:179], v[128:131], v[60:63], v[176:179]
	s_waitcnt lgkmcnt(2)
	v_mfma_f32_16x16x32_bf16 v[36:39], v[132:135], v[52:55], v[36:39]
	v_mfma_f32_16x16x32_bf16 v[180:183], v[132:135], v[60:63], v[180:183]
	s_waitcnt lgkmcnt(1)
	v_mfma_f32_16x16x32_bf16 v[40:43], v[136:139], v[52:55], v[40:43]
	v_mfma_f32_16x16x32_bf16 v[192:195], v[136:139], v[60:63], v[192:195]
	s_waitcnt lgkmcnt(0)
	v_mfma_f32_16x16x32_bf16 v[44:47], v[140:143], v[52:55], v[44:47]
	v_mfma_f32_16x16x32_bf16 v[196:199], v[140:143], v[60:63], v[196:199]
	ds_read_b32 v0, v184 offset:896
	ds_read_b32 v1, v185 offset:896
	ds_read_b32 v2, v186 offset:896
	ds_read_b32 v3, v187 offset:896
	ds_read_b32 v4, v184 offset:1024
	ds_read_b32 v5, v185 offset:1024
	ds_read_b32 v6, v186 offset:1024
	ds_read_b32 v7, v187 offset:1024
	ds_read_b32 v8, v188 offset:896
	ds_read_b32 v9, v189 offset:896
	ds_read_b32 v10, v190 offset:896
	ds_read_b32 v11, v191 offset:896
	ds_read_b32 v12, v188 offset:1024
	ds_read_b32 v13, v189 offset:1024
	ds_read_b32 v14, v190 offset:1024
	ds_read_b32 v15, v191 offset:1024
	ds_read_b32 v16, v184 offset:768
	ds_read_b32 v17, v185 offset:768
	ds_read_b32 v18, v186 offset:768
	ds_read_b32 v19, v187 offset:768
	ds_read_b32 v20, v184 offset:896
	ds_read_b32 v21, v185 offset:896
	ds_read_b32 v22, v186 offset:896
	ds_read_b32 v23, v187 offset:896
	ds_read_b32 v24, v188 offset:768
	ds_read_b32 v25, v189 offset:768
	ds_read_b32 v26, v190 offset:768
	ds_read_b32 v27, v191 offset:768
	ds_read_b32 v28, v188 offset:896
	ds_read_b32 v29, v189 offset:896
	ds_read_b32 v30, v190 offset:896
	ds_read_b32 v31, v191 offset:896
	s_waitcnt lgkmcnt(0)
	s_barrier
; __device__ __forceinline__ void attn_phase(const Params& P, char* smem_raw) {
;     ...
;     for (int ck = 0; ck < 6; ++ck) {
;       int lane_c = lane;
;       asm volatile("" : "+v"(lane_c));
;       __syncthreads();
; #pragma unroll
;       for (int i = 0; i < 4; ++i) {
;         const int idx = tid + 256 * i;
;         *reinterpret_cast<uint4*>(&sm_k[(idx >> 3) * LDSS + (idx & 7) * 8]) = kreg[i];
;         *reinterpret_cast<uint4*>(&sm_vt[(idx >> 4) * 136 + (idx & 15) * 8]) = vreg[i];
;       }
;       __syncthreads();
;       f32x4 sacc[8];
; #pragma unroll
;       for (int t8 = 0; t8 < 8; ++t8) sacc[t8] = f32x4{0.f, 0.f, 0.f, 0.f};
; #pragma unroll
;       for (int s = 0; s < 2; ++s)
; #pragma unroll
;         for (int t8 = 0; t8 < 8; ++t8) {
;           const bf16x8 kf = *reinterpret_cast<const bf16x8*>(&sm_k[(t8 * 16 + (lane_c & 15)) * LDSS + s * 32 + (lane_c >> 4) * 8]);
;           sacc[t8] = __builtin_amdgcn_mfma_f32_16x16x32_bf16(qf[s], kf, sacc[t8], 0, 0, 0);
;         }
;       if (ck < 5) {
;         ATT_ISSUE(t, ck + 1)
;       } else if (t + VGRID < 8192) {
;         ATT_ISSUE(t + VGRID, 0)
;         ATT_QLOAD(t + VGRID)
;       }
;       if (ck < 4) {
;         const float* rb0 = sm_rpb + (rs + ck * 2 - r + 7) * 31;
; #pragma unroll
;         for (int t8 = 0; t8 < 8; ++t8)
; #pragma unroll
;           for (int reg = 0; reg < 4; ++reg)
;             sacc[t8][reg] += rb0[(t8 >> 2) * 31 + dco[reg][t8 & 3]];
;       }
; #pragma unroll
;       for (int reg = 0; reg < 4; ++reg) {
;         float mx = sacc[0][reg];
; #pragma unroll
;         for (int t8 = 1; t8 < 8; ++t8) mx = fmaxf(mx, sacc[t8][reg]);
;         mx = row16_max(mx);
;         const float mnew = fmaxf(mrow[reg], mx);
;         const float alpha = __builtin_amdgcn_exp2f(mrow[reg] - mnew);
;         mrow[reg] = mnew;
;         float rsum = 0.f;
; #pragma unroll
;         for (int t8 = 0; t8 < 8; ++t8) {
;           const float p = __builtin_amdgcn_exp2f(sacc[t8][reg] - mnew);
;           rsum += p;
;           sm_p[(wid * 16 + (lane_c >> 4) * 4 + reg) * 136 + t8 * 16 + (lane_c & 15)] = f2bf(p);
;         }
;         rsum = row16_sum(rsum);
;         lrow[reg] = lrow[reg] * alpha + rsum;
; #pragma unroll
;         for (int td = 0; td < 4; ++td) o[td][reg] *= alpha;
;       }
;       asm volatile("s_waitcnt lgkmcnt(0)" ::: "memory");
; #pragma unroll
;       for (int s4 = 0; s4 < 4; ++s4) {
	ds_read_b128 v[112:115], v144 offset:0
	ds_read_b128 v[116:119], v145 offset:0
	ds_read_b128 v[120:123], v144 offset:8192
	ds_read_b128 v[124:127], v145 offset:8192
	ds_read_b128 v[128:131], v144 offset:2048
	ds_read_b128 v[132:135], v145 offset:2048
	ds_read_b128 v[136:139], v144 offset:10240
	ds_read_b128 v[140:143], v145 offset:10240
	s_waitcnt lgkmcnt(7)
	v_mfma_f32_16x16x32_bf16 v[0:3], v[112:115], v[64:67], v[0:3]
	v_mfma_f32_16x16x32_bf16 v[16:19], v[112:115], v[230:233], v[16:19]
	s_waitcnt lgkmcnt(6)
	v_mfma_f32_16x16x32_bf16 v[0:3], v[116:119], v[68:71], v[0:3]
	v_mfma_f32_16x16x32_bf16 v[16:19], v[116:119], v[234:237], v[16:19]
	s_waitcnt lgkmcnt(5)
	v_mfma_f32_16x16x32_bf16 v[4:7], v[120:123], v[64:67], v[4:7]
	v_mfma_f32_16x16x32_bf16 v[20:23], v[120:123], v[230:233], v[20:23]
	s_waitcnt lgkmcnt(4)
	v_mfma_f32_16x16x32_bf16 v[4:7], v[124:127], v[68:71], v[4:7]
	v_mfma_f32_16x16x32_bf16 v[20:23], v[124:127], v[234:237], v[20:23]
	s_waitcnt lgkmcnt(3)
	v_mfma_f32_16x16x32_bf16 v[8:11], v[128:131], v[64:67], v[8:11]
	v_mfma_f32_16x16x32_bf16 v[24:27], v[128:131], v[230:233], v[24:27]
	s_waitcnt lgkmcnt(2)
	v_mfma_f32_16x16x32_bf16 v[8:11], v[132:135], v[68:71], v[8:11]
	v_mfma_f32_16x16x32_bf16 v[24:27], v[132:135], v[234:237], v[24:27]
	s_waitcnt lgkmcnt(1)
	v_mfma_f32_16x16x32_bf16 v[12:15], v[136:139], v[64:67], v[12:15]
	v_mfma_f32_16x16x32_bf16 v[28:31], v[136:139], v[230:233], v[28:31]
	s_waitcnt lgkmcnt(0)
	v_mfma_f32_16x16x32_bf16 v[12:15], v[140:143], v[68:71], v[12:15]
	v_mfma_f32_16x16x32_bf16 v[28:31], v[140:143], v[234:237], v[28:31]
	s_nop 7
	v_max3_f32 v203, v0, v1, v2
	v_max3_f32 v206, v16, v17, v18
	v_max3_f32 v203, v203, v3, v4
	v_max3_f32 v206, v206, v19, v20
	v_max3_f32 v203, v203, v5, v6
	v_max3_f32 v206, v206, v21, v22
	v_max3_f32 v203, v203, v7, v8
	v_max3_f32 v206, v206, v23, v24
	v_max3_f32 v203, v203, v9, v10
	v_max3_f32 v206, v206, v25, v26
	v_max3_f32 v203, v203, v11, v12
	v_max3_f32 v206, v206, v27, v28
	v_max3_f32 v203, v203, v13, v14
	v_max3_f32 v206, v206, v29, v30
	v_max_f32_e32 v203, v203, v15
	v_max_f32_e32 v206, v206, v31
	v_mov_b32_e32 v205, v203
	v_mov_b32_e32 v207, v206
	s_nop 1
	v_permlane16_swap_b32_e32 v203, v205
	v_permlane16_swap_b32_e32 v206, v207
	v_max_f32_e32 v203, v203, v205
	v_max_f32_e32 v206, v206, v207
	v_mov_b32_e32 v205, v203
	v_mov_b32_e32 v207, v206
	s_nop 1
	v_permlane32_swap_b32_e32 v203, v205
	v_permlane32_swap_b32_e32 v206, v207
	v_max_f32_e32 v203, v203, v205
	v_max_f32_e32 v206, v206, v207
	v_max_f32_e32 v218, v200, v203
	v_max_f32_e32 v208, v246, v206
	v_sub_f32_e32 v220, v200, v218
	v_sub_f32_e32 v248, v246, v208
	v_mov_b32_e32 v219, v218
	v_mov_b32_e32 v209, v208
	v_exp_f32_e32 v220, v220
	v_exp_f32_e32 v248, v248
	v_mov_b32_e32 v200, v218
	v_mov_b32_e32 v246, v208
	v_pk_add_f32 v[0:1], v[0:1], v[218:219] neg_lo:[0,1] neg_hi:[0,1]
	v_pk_add_f32 v[16:17], v[16:17], v[208:209] neg_lo:[0,1] neg_hi:[0,1]
	v_pk_add_f32 v[2:3], v[2:3], v[218:219] neg_lo:[0,1] neg_hi:[0,1]
	v_pk_add_f32 v[18:19], v[18:19], v[208:209] neg_lo:[0,1] neg_hi:[0,1]
	v_pk_add_f32 v[4:5], v[4:5], v[218:219] neg_lo:[0,1] neg_hi:[0,1]
	v_pk_add_f32 v[20:21], v[20:21], v[208:209] neg_lo:[0,1] neg_hi:[0,1]
	v_pk_add_f32 v[6:7], v[6:7], v[218:219] neg_lo:[0,1] neg_hi:[0,1]
	v_pk_add_f32 v[22:23], v[22:23], v[208:209] neg_lo:[0,1] neg_hi:[0,1]
	v_pk_add_f32 v[8:9], v[8:9], v[218:219] neg_lo:[0,1] neg_hi:[0,1]
	v_pk_add_f32 v[24:25], v[24:25], v[208:209] neg_lo:[0,1] neg_hi:[0,1]
	v_pk_add_f32 v[10:11], v[10:11], v[218:219] neg_lo:[0,1] neg_hi:[0,1]
	v_pk_add_f32 v[26:27], v[26:27], v[208:209] neg_lo:[0,1] neg_hi:[0,1]
	v_pk_add_f32 v[12:13], v[12:13], v[218:219] neg_lo:[0,1] neg_hi:[0,1]
	v_pk_add_f32 v[28:29], v[28:29], v[208:209] neg_lo:[0,1] neg_hi:[0,1]
	v_pk_add_f32 v[14:15], v[14:15], v[218:219] neg_lo:[0,1] neg_hi:[0,1]
	v_pk_add_f32 v[30:31], v[30:31], v[208:209] neg_lo:[0,1] neg_hi:[0,1]
	v_exp_f32_e32 v0, v0
	s_waitcnt vmcnt(0)
	v_exp_f32_e32 v1, v1
	ds_write_b128 v150, v[80:83] offset:32768
	v_exp_f32_e32 v2, v2
	ds_write_b128 v150, v[84:87] offset:36864
	v_exp_f32_e32 v3, v3
	ds_write_b128 v150, v[88:91] offset:40960
	v_exp_f32_e32 v4, v4
	ds_write_b128 v150, v[92:95] offset:45056
	v_exp_f32_e32 v5, v5
	ds_write_b64 v151, v[96:97] offset:32768
	v_exp_f32_e32 v6, v6
	ds_write_b64 v229, v[98:99] offset:32768
	v_exp_f32_e32 v7, v7
	ds_write_b64 v151, v[100:101] offset:36864
	v_exp_f32_e32 v8, v8
	ds_write_b64 v229, v[102:103] offset:36864
	v_exp_f32_e32 v9, v9
	ds_write_b64 v151, v[104:105] offset:40960
	v_exp_f32_e32 v10, v10
	ds_write_b64 v229, v[106:107] offset:40960
	v_exp_f32_e32 v11, v11
	ds_write_b64 v151, v[108:109] offset:45056
	v_exp_f32_e32 v12, v12
	ds_write_b64 v229, v[110:111] offset:45056
	v_exp_f32_e32 v13, v13
	s_add_u32 s100, s12, s20
	v_exp_f32_e32 v14, v14
	s_addc_u32 s101, s13, 0
	v_exp_f32_e32 v15, v15
	s_add_u32 s0, s14, s21
	v_exp_f32_e32 v16, v16
	s_addc_u32 s1, s15, 0
	v_exp_f32_e32 v17, v17
	global_load_dwordx4 v[80:83], v154, s[100:101] offset:2048
	v_exp_f32_e32 v18, v18
	global_load_dwordx4 v[96:99], v158, s[0:1]
	v_exp_f32_e32 v19, v19
	global_load_dwordx4 v[84:87], v155, s[100:101] offset:2048
	v_exp_f32_e32 v20, v20
	global_load_dwordx4 v[100:103], v159, s[0:1]
	v_exp_f32_e32 v21, v21
	global_load_dwordx4 v[88:91], v156, s[100:101] offset:2048
	v_exp_f32_e32 v22, v22
	global_load_dwordx4 v[104:107], v160, s[0:1]
	v_exp_f32_e32 v23, v23
	global_load_dwordx4 v[92:95], v157, s[100:101] offset:2048
	v_exp_f32_e32 v24, v24
	global_load_dwordx4 v[108:111], v161, s[0:1]
	v_exp_f32_e32 v25, v25
	v_exp_f32_e32 v26, v26
	v_exp_f32_e32 v27, v27
	v_exp_f32_e32 v28, v28
; __device__ __forceinline__ void attn_phase(const Params& P, char* smem_raw) {
;     ...
;     for (int ck = 0; ck < 6; ++ck) {
;       int lane_c = lane;
;       asm volatile("" : "+v"(lane_c));
;       __syncthreads();
; #pragma unroll
;       for (int i = 0; i < 4; ++i) {
;         const int idx = tid + 256 * i;
;         *reinterpret_cast<uint4*>(&sm_k[(idx >> 3) * LDSS + (idx & 7) * 8]) = kreg[i];
;         *reinterpret_cast<uint4*>(&sm_vt[(idx >> 4) * 136 + (idx & 15) * 8]) = vreg[i];
;       }
;       __syncthreads();
;       f32x4 sacc[8];
; #pragma unroll
;       for (int t8 = 0; t8 < 8; ++t8) sacc[t8] = f32x4{0.f, 0.f, 0.f, 0.f};
; #pragma unroll
;       for (int s = 0; s < 2; ++s)
; #pragma unroll
;         for (int t8 = 0; t8 < 8; ++t8) {
;           const bf16x8 kf = *reinterpret_cast<const bf16x8*>(&sm_k[(t8 * 16 + (lane_c & 15)) * LDSS + s * 32 + (lane_c >> 4) * 8]);
;           sacc[t8] = __builtin_amdgcn_mfma_f32_16x16x32_bf16(qf[s], kf, sacc[t8], 0, 0, 0);
;         }
;       if (ck < 5) {
;         ATT_ISSUE(t, ck + 1)
;       } else if (t + VGRID < 8192) {
;         ATT_ISSUE(t + VGRID, 0)
;         ATT_QLOAD(t + VGRID)
;       }
;       if (ck < 4) {
;         const float* rb0 = sm_rpb + (rs + ck * 2 - r + 7) * 31;
; #pragma unroll
;         for (int t8 = 0; t8 < 8; ++t8)
; #pragma unroll
;           for (int reg = 0; reg < 4; ++reg)
;             sacc[t8][reg] += rb0[(t8 >> 2) * 31 + dco[reg][t8 & 3]];
;       }
; #pragma unroll
;       for (int reg = 0; reg < 4; ++reg) {
;         float mx = sacc[0][reg];
; #pragma unroll
;         for (int t8 = 1; t8 < 8; ++t8) mx = fmaxf(mx, sacc[t8][reg]);
;         mx = row16_max(mx);
;         const float mnew = fmaxf(mrow[reg], mx);
;         const float alpha = __builtin_amdgcn_exp2f(mrow[reg] - mnew);
;         mrow[reg] = mnew;
;         float rsum = 0.f;
; #pragma unroll
;         for (int t8 = 0; t8 < 8; ++t8) {
;           const float p = __builtin_amdgcn_exp2f(sacc[t8][reg] - mnew);
;           rsum += p;
;           sm_p[(wid * 16 + (lane_c >> 4) * 4 + reg) * 136 + t8 * 16 + (lane_c & 15)] = f2bf(p);
;         }
;         rsum = row16_sum(rsum);
;         lrow[reg] = lrow[reg] * alpha + rsum;
; #pragma unroll
;         for (int td = 0; td < 4; ++td) o[td][reg] *= alpha;
;       }
;       asm volatile("s_waitcnt lgkmcnt(0)" ::: "memory");
; #pragma unroll
;       for (int s4 = 0; s4 < 4; ++s4) {
	v_exp_f32_e32 v29, v29
	v_exp_f32_e32 v30, v30
	v_exp_f32_e32 v31, v31
	ds_read_b128 v[112:115], v146 offset:0
	ds_read_b128 v[116:119], v146 offset:4096
	ds_read_b128 v[120:123], v146 offset:8192
	ds_read_b128 v[124:127], v146 offset:12288
	ds_read_b128 v[128:131], v147 offset:0
	ds_read_b128 v[132:135], v147 offset:4096
	ds_read_b128 v[136:139], v147 offset:8192
	ds_read_b128 v[140:143], v147 offset:12288
	v_mov_b32_e32 v221, v220
	v_mov_b32_e32 v249, v248
	v_pk_add_f32 v[222:223], v[0:1], v[2:3]
	v_pk_add_f32 v[250:251], v[16:17], v[18:19]
	v_pk_add_f32 v[222:223], v[222:223], v[4:5]
	v_pk_add_f32 v[250:251], v[250:251], v[20:21]
	v_pk_add_f32 v[222:223], v[222:223], v[6:7]
	v_pk_add_f32 v[250:251], v[250:251], v[22:23]
	v_pk_add_f32 v[222:223], v[222:223], v[8:9]
	v_pk_add_f32 v[250:251], v[250:251], v[24:25]
	v_pk_add_f32 v[222:223], v[222:223], v[10:11]
	v_pk_add_f32 v[250:251], v[250:251], v[26:27]
	v_pk_add_f32 v[222:223], v[222:223], v[12:13]
	v_pk_add_f32 v[250:251], v[250:251], v[28:29]
	v_pk_add_f32 v[222:223], v[222:223], v[14:15]
	v_pk_add_f32 v[250:251], v[250:251], v[30:31]
	v_pk_mul_f32 v[32:33], v[32:33], v[220:221]
	v_pk_mul_f32 v[34:35], v[34:35], v[220:221]
	v_pk_mul_f32 v[176:177], v[176:177], v[248:249]
	v_pk_mul_f32 v[178:179], v[178:179], v[248:249]
	v_pk_mul_f32 v[36:37], v[36:37], v[220:221]
	v_pk_mul_f32 v[38:39], v[38:39], v[220:221]
	v_pk_mul_f32 v[180:181], v[180:181], v[248:249]
	v_pk_mul_f32 v[182:183], v[182:183], v[248:249]
	v_pk_mul_f32 v[40:41], v[40:41], v[220:221]
	v_pk_mul_f32 v[42:43], v[42:43], v[220:221]
	v_pk_mul_f32 v[192:193], v[192:193], v[248:249]
	v_pk_mul_f32 v[194:195], v[194:195], v[248:249]
	v_pk_mul_f32 v[44:45], v[44:45], v[220:221]
	v_pk_mul_f32 v[46:47], v[46:47], v[220:221]
	v_pk_mul_f32 v[196:197], v[196:197], v[248:249]
	v_pk_mul_f32 v[198:199], v[198:199], v[248:249]
	v_add_f32_e32 v203, v222, v223
	v_add_f32_e32 v206, v250, v251
	v_fma_f32 v201, v201, v220, v203
	v_fma_f32 v247, v247, v248, v206
	v_cvt_pk_bf16_f32 v48, v0, v1
	v_cvt_pk_bf16_f32 v49, v2, v3
	v_cvt_pk_bf16_f32 v50, v4, v5
	v_cvt_pk_bf16_f32 v51, v6, v7
	v_cvt_pk_bf16_f32 v56, v16, v17
	v_cvt_pk_bf16_f32 v57, v18, v19
	v_cvt_pk_bf16_f32 v58, v20, v21
	v_cvt_pk_bf16_f32 v59, v22, v23
	v_cvt_pk_bf16_f32 v52, v8, v9
	v_cvt_pk_bf16_f32 v53, v10, v11
	v_cvt_pk_bf16_f32 v54, v12, v13
	v_cvt_pk_bf16_f32 v55, v14, v15
	v_cvt_pk_bf16_f32 v60, v24, v25
	v_cvt_pk_bf16_f32 v61, v26, v27
	v_cvt_pk_bf16_f32 v62, v28, v29
	v_cvt_pk_bf16_f32 v63, v30, v31
	s_waitcnt lgkmcnt(7)
	v_mfma_f32_16x16x32_bf16 v[32:35], v[112:115], v[48:51], v[32:35]
	v_mfma_f32_16x16x32_bf16 v[176:179], v[112:115], v[56:59], v[176:179]
	s_waitcnt lgkmcnt(6)
	v_mfma_f32_16x16x32_bf16 v[36:39], v[116:119], v[48:51], v[36:39]
	v_mfma_f32_16x16x32_bf16 v[180:183], v[116:119], v[56:59], v[180:183]
	s_waitcnt lgkmcnt(5)
	v_mfma_f32_16x16x32_bf16 v[40:43], v[120:123], v[48:51], v[40:43]
	v_mfma_f32_16x16x32_bf16 v[192:195], v[120:123], v[56:59], v[192:195]
	s_waitcnt lgkmcnt(4)
	v_mfma_f32_16x16x32_bf16 v[44:47], v[124:127], v[48:51], v[44:47]
	v_mfma_f32_16x16x32_bf16 v[196:199], v[124:127], v[56:59], v[196:199]
	s_waitcnt lgkmcnt(3)
	v_mfma_f32_16x16x32_bf16 v[32:35], v[128:131], v[52:55], v[32:35]
	v_mfma_f32_16x16x32_bf16 v[176:179], v[128:131], v[60:63], v[176:179]
	s_waitcnt lgkmcnt(2)
	v_mfma_f32_16x16x32_bf16 v[36:39], v[132:135], v[52:55], v[36:39]
	v_mfma_f32_16x16x32_bf16 v[180:183], v[132:135], v[60:63], v[180:183]
	s_waitcnt lgkmcnt(1)
	v_mfma_f32_16x16x32_bf16 v[40:43], v[136:139], v[52:55], v[40:43]
	v_mfma_f32_16x16x32_bf16 v[192:195], v[136:139], v[60:63], v[192:195]
	s_waitcnt lgkmcnt(0)
	v_mfma_f32_16x16x32_bf16 v[44:47], v[140:143], v[52:55], v[44:47]
	v_mfma_f32_16x16x32_bf16 v[196:199], v[140:143], v[60:63], v[196:199]
	ds_read_b32 v0, v184 offset:1152
	ds_read_b32 v1, v185 offset:1152
	ds_read_b32 v2, v186 offset:1152
	ds_read_b32 v3, v187 offset:1152
	ds_read_b32 v4, v184 offset:1280
	ds_read_b32 v5, v185 offset:1280
	ds_read_b32 v6, v186 offset:1280
	ds_read_b32 v7, v187 offset:1280
	ds_read_b32 v8, v188 offset:1152
	ds_read_b32 v9, v189 offset:1152
	ds_read_b32 v10, v190 offset:1152
	ds_read_b32 v11, v191 offset:1152
	ds_read_b32 v12, v188 offset:1280
	ds_read_b32 v13, v189 offset:1280
	ds_read_b32 v14, v190 offset:1280
	ds_read_b32 v15, v191 offset:1280
	ds_read_b32 v16, v184 offset:1024
	ds_read_b32 v17, v185 offset:1024
	ds_read_b32 v18, v186 offset:1024
	ds_read_b32 v19, v187 offset:1024
	ds_read_b32 v20, v184 offset:1152
	ds_read_b32 v21, v185 offset:1152
	ds_read_b32 v22, v186 offset:1152
	ds_read_b32 v23, v187 offset:1152
	ds_read_b32 v24, v188 offset:1024
	ds_read_b32 v25, v189 offset:1024
	ds_read_b32 v26, v190 offset:1024
	ds_read_b32 v27, v191 offset:1024
	ds_read_b32 v28, v188 offset:1152
	ds_read_b32 v29, v189 offset:1152
	ds_read_b32 v30, v190 offset:1152
	ds_read_b32 v31, v191 offset:1152
	s_waitcnt lgkmcnt(0)
	s_barrier
; __device__ __forceinline__ void attn_phase(const Params& P, char* smem_raw) {
;     ...
;     for (int ck = 0; ck < 6; ++ck) {
;       int lane_c = lane;
;       asm volatile("" : "+v"(lane_c));
;       __syncthreads();
; #pragma unroll
;       for (int i = 0; i < 4; ++i) {
;         const int idx = tid + 256 * i;
;         *reinterpret_cast<uint4*>(&sm_k[(idx >> 3) * LDSS + (idx & 7) * 8]) = kreg[i];
;         *reinterpret_cast<uint4*>(&sm_vt[(idx >> 4) * 136 + (idx & 15) * 8]) = vreg[i];
;       }
;       __syncthreads();
;       f32x4 sacc[8];
; #pragma unroll
;       for (int t8 = 0; t8 < 8; ++t8) sacc[t8] = f32x4{0.f, 0.f, 0.f, 0.f};
; #pragma unroll
;       for (int s = 0; s < 2; ++s)
; #pragma unroll
;         for (int t8 = 0; t8 < 8; ++t8) {
;           const bf16x8 kf = *reinterpret_cast<const bf16x8*>(&sm_k[(t8 * 16 + (lane_c & 15)) * LDSS + s * 32 + (lane_c >> 4) * 8]);
;           sacc[t8] = __builtin_amdgcn_mfma_f32_16x16x32_bf16(qf[s], kf, sacc[t8], 0, 0, 0);
;         }
;       if (ck < 5) {
;         ATT_ISSUE(t, ck + 1)
;       } else if (t + VGRID < 8192) {
;         ATT_ISSUE(t + VGRID, 0)
;         ATT_QLOAD(t + VGRID)
;       }
;       if (ck < 4) {
;         const float* rb0 = sm_rpb + (rs + ck * 2 - r + 7) * 31;
; #pragma unroll
;         for (int t8 = 0; t8 < 8; ++t8)
; #pragma unroll
;           for (int reg = 0; reg < 4; ++reg)
;             sacc[t8][reg] += rb0[(t8 >> 2) * 31 + dco[reg][t8 & 3]];
;       }
; #pragma unroll
;       for (int reg = 0; reg < 4; ++reg) {
;         float mx = sacc[0][reg];
; #pragma unroll
;         for (int t8 = 1; t8 < 8; ++t8) mx = fmaxf(mx, sacc[t8][reg]);
;         mx = row16_max(mx);
;         const float mnew = fmaxf(mrow[reg], mx);
;         const float alpha = __builtin_amdgcn_exp2f(mrow[reg] - mnew);
;         mrow[reg] = mnew;
;         float rsum = 0.f;
; #pragma unroll
;         for (int t8 = 0; t8 < 8; ++t8) {
;           const float p = __builtin_amdgcn_exp2f(sacc[t8][reg] - mnew);
;           rsum += p;
;           sm_p[(wid * 16 + (lane_c >> 4) * 4 + reg) * 136 + t8 * 16 + (lane_c & 15)] = f2bf(p);
;         }
;         rsum = row16_sum(rsum);
;         lrow[reg] = lrow[reg] * alpha + rsum;
; #pragma unroll
;         for (int td = 0; td < 4; ++td) o[td][reg] *= alpha;
;       }
;       asm volatile("s_waitcnt lgkmcnt(0)" ::: "memory");
; #pragma unroll
;       for (int s4 = 0; s4 < 4; ++s4) {
	ds_read_b128 v[112:115], v144 offset:32768
	ds_read_b128 v[116:119], v145 offset:32768
	ds_read_b128 v[120:123], v144 offset:40960
	ds_read_b128 v[124:127], v145 offset:40960
	ds_read_b128 v[128:131], v144 offset:34816
	ds_read_b128 v[132:135], v145 offset:34816
	ds_read_b128 v[136:139], v144 offset:43008
	ds_read_b128 v[140:143], v145 offset:43008
	s_waitcnt lgkmcnt(7)
	v_mfma_f32_16x16x32_bf16 v[0:3], v[112:115], v[64:67], v[0:3]
	v_mfma_f32_16x16x32_bf16 v[16:19], v[112:115], v[230:233], v[16:19]
	s_waitcnt lgkmcnt(6)
	v_mfma_f32_16x16x32_bf16 v[0:3], v[116:119], v[68:71], v[0:3]
	v_mfma_f32_16x16x32_bf16 v[16:19], v[116:119], v[234:237], v[16:19]
	s_waitcnt lgkmcnt(5)
	v_mfma_f32_16x16x32_bf16 v[4:7], v[120:123], v[64:67], v[4:7]
	v_mfma_f32_16x16x32_bf16 v[20:23], v[120:123], v[230:233], v[20:23]
	s_waitcnt lgkmcnt(4)
	v_mfma_f32_16x16x32_bf16 v[4:7], v[124:127], v[68:71], v[4:7]
	v_mfma_f32_16x16x32_bf16 v[20:23], v[124:127], v[234:237], v[20:23]
	s_waitcnt lgkmcnt(3)
	v_mfma_f32_16x16x32_bf16 v[8:11], v[128:131], v[64:67], v[8:11]
	v_mfma_f32_16x16x32_bf16 v[24:27], v[128:131], v[230:233], v[24:27]
	s_waitcnt lgkmcnt(2)
	v_mfma_f32_16x16x32_bf16 v[8:11], v[132:135], v[68:71], v[8:11]
	v_mfma_f32_16x16x32_bf16 v[24:27], v[132:135], v[234:237], v[24:27]
	s_waitcnt lgkmcnt(1)
	v_mfma_f32_16x16x32_bf16 v[12:15], v[136:139], v[64:67], v[12:15]
	v_mfma_f32_16x16x32_bf16 v[28:31], v[136:139], v[230:233], v[28:31]
	s_waitcnt lgkmcnt(0)
	v_mfma_f32_16x16x32_bf16 v[12:15], v[140:143], v[68:71], v[12:15]
	v_mfma_f32_16x16x32_bf16 v[28:31], v[140:143], v[234:237], v[28:31]
	s_nop 7
	v_max3_f32 v203, v0, v1, v2
	v_max3_f32 v206, v16, v17, v18
	v_max3_f32 v203, v203, v3, v4
	v_max3_f32 v206, v206, v19, v20
	v_max3_f32 v203, v203, v5, v6
	v_max3_f32 v206, v206, v21, v22
	v_max3_f32 v203, v203, v7, v8
	v_max3_f32 v206, v206, v23, v24
	v_max3_f32 v203, v203, v9, v10
	v_max3_f32 v206, v206, v25, v26
	v_max3_f32 v203, v203, v11, v12
	v_max3_f32 v206, v206, v27, v28
	v_max3_f32 v203, v203, v13, v14
	v_max3_f32 v206, v206, v29, v30
	v_max_f32_e32 v203, v203, v15
	v_max_f32_e32 v206, v206, v31
	v_mov_b32_e32 v205, v203
	v_mov_b32_e32 v207, v206
	s_nop 1
	v_permlane16_swap_b32_e32 v203, v205
	v_permlane16_swap_b32_e32 v206, v207
	v_max_f32_e32 v203, v203, v205
	v_max_f32_e32 v206, v206, v207
	v_mov_b32_e32 v205, v203
	v_mov_b32_e32 v207, v206
	s_nop 1
	v_permlane32_swap_b32_e32 v203, v205
	v_permlane32_swap_b32_e32 v206, v207
	v_max_f32_e32 v203, v203, v205
	v_max_f32_e32 v206, v206, v207
	v_max_f32_e32 v218, v200, v203
	v_max_f32_e32 v208, v246, v206
	v_sub_f32_e32 v220, v200, v218
	v_sub_f32_e32 v248, v246, v208
	v_mov_b32_e32 v219, v218
	v_mov_b32_e32 v209, v208
	v_exp_f32_e32 v220, v220
	v_exp_f32_e32 v248, v248
	v_mov_b32_e32 v200, v218
	v_mov_b32_e32 v246, v208
	v_pk_add_f32 v[0:1], v[0:1], v[218:219] neg_lo:[0,1] neg_hi:[0,1]
	v_pk_add_f32 v[16:17], v[16:17], v[208:209] neg_lo:[0,1] neg_hi:[0,1]
	v_pk_add_f32 v[2:3], v[2:3], v[218:219] neg_lo:[0,1] neg_hi:[0,1]
	v_pk_add_f32 v[18:19], v[18:19], v[208:209] neg_lo:[0,1] neg_hi:[0,1]
	v_pk_add_f32 v[4:5], v[4:5], v[218:219] neg_lo:[0,1] neg_hi:[0,1]
	v_pk_add_f32 v[20:21], v[20:21], v[208:209] neg_lo:[0,1] neg_hi:[0,1]
	v_pk_add_f32 v[6:7], v[6:7], v[218:219] neg_lo:[0,1] neg_hi:[0,1]
	v_pk_add_f32 v[22:23], v[22:23], v[208:209] neg_lo:[0,1] neg_hi:[0,1]
	v_pk_add_f32 v[8:9], v[8:9], v[218:219] neg_lo:[0,1] neg_hi:[0,1]
	v_pk_add_f32 v[24:25], v[24:25], v[208:209] neg_lo:[0,1] neg_hi:[0,1]
	v_pk_add_f32 v[10:11], v[10:11], v[218:219] neg_lo:[0,1] neg_hi:[0,1]
	v_pk_add_f32 v[26:27], v[26:27], v[208:209] neg_lo:[0,1] neg_hi:[0,1]
	v_pk_add_f32 v[12:13], v[12:13], v[218:219] neg_lo:[0,1] neg_hi:[0,1]
	v_pk_add_f32 v[28:29], v[28:29], v[208:209] neg_lo:[0,1] neg_hi:[0,1]
	v_pk_add_f32 v[14:15], v[14:15], v[218:219] neg_lo:[0,1] neg_hi:[0,1]
	v_pk_add_f32 v[30:31], v[30:31], v[208:209] neg_lo:[0,1] neg_hi:[0,1]
	v_exp_f32_e32 v0, v0
	s_waitcnt vmcnt(0)
	v_exp_f32_e32 v1, v1
	ds_write_b128 v150, v[80:83] offset:0
	v_exp_f32_e32 v2, v2
	ds_write_b128 v150, v[84:87] offset:4096
	v_exp_f32_e32 v3, v3
	ds_write_b128 v150, v[88:91] offset:8192
	v_exp_f32_e32 v4, v4
	ds_write_b128 v150, v[92:95] offset:12288
	v_exp_f32_e32 v5, v5
	ds_write_b64 v151, v[96:97] offset:0
	v_exp_f32_e32 v6, v6
	ds_write_b64 v229, v[98:99] offset:0
	v_exp_f32_e32 v7, v7
	ds_write_b64 v151, v[100:101] offset:4096
	v_exp_f32_e32 v8, v8
	ds_write_b64 v229, v[102:103] offset:4096
	v_exp_f32_e32 v9, v9
	ds_write_b64 v151, v[104:105] offset:8192
	v_exp_f32_e32 v10, v10
	ds_write_b64 v229, v[106:107] offset:8192
	v_exp_f32_e32 v11, v11
	ds_write_b64 v151, v[108:109] offset:12288
	v_exp_f32_e32 v12, v12
	ds_write_b64 v229, v[110:111] offset:12288
	v_exp_f32_e32 v13, v13
	s_add_u32 s100, s16, 0x0
	v_exp_f32_e32 v14, v14
	s_addc_u32 s101, s17, 0
	v_exp_f32_e32 v15, v15
	s_add_u32 s0, s36, 0x0
	v_exp_f32_e32 v16, v16
	s_addc_u32 s1, s37, 0
	v_exp_f32_e32 v17, v17
	global_load_dwordx4 v[80:83], v154, s[100:101] offset:2048
	v_exp_f32_e32 v18, v18
	global_load_dwordx4 v[96:99], v162, s[0:1]
	v_exp_f32_e32 v19, v19
	global_load_dwordx4 v[84:87], v155, s[100:101] offset:2048
	v_exp_f32_e32 v20, v20
	global_load_dwordx4 v[100:103], v163, s[0:1]
	v_exp_f32_e32 v21, v21
	global_load_dwordx4 v[88:91], v156, s[100:101] offset:2048
	v_exp_f32_e32 v22, v22
	global_load_dwordx4 v[104:107], v164, s[0:1]
	v_exp_f32_e32 v23, v23
	global_load_dwordx4 v[92:95], v157, s[100:101] offset:2048
	v_exp_f32_e32 v24, v24
	global_load_dwordx4 v[108:111], v165, s[0:1]
	v_exp_f32_e32 v25, v25
	v_exp_f32_e32 v26, v26
	v_exp_f32_e32 v27, v27
	v_exp_f32_e32 v28, v28
; __device__ __forceinline__ void attn_phase(const Params& P, char* smem_raw) {
;     ...
;     for (int ck = 0; ck < 6; ++ck) {
;       int lane_c = lane;
;       asm volatile("" : "+v"(lane_c));
;       __syncthreads();
; #pragma unroll
;       for (int i = 0; i < 4; ++i) {
;         const int idx = tid + 256 * i;
;         *reinterpret_cast<uint4*>(&sm_k[(idx >> 3) * LDSS + (idx & 7) * 8]) = kreg[i];
;         *reinterpret_cast<uint4*>(&sm_vt[(idx >> 4) * 136 + (idx & 15) * 8]) = vreg[i];
;       }
;       __syncthreads();
;       f32x4 sacc[8];
; #pragma unroll
;       for (int t8 = 0; t8 < 8; ++t8) sacc[t8] = f32x4{0.f, 0.f, 0.f, 0.f};
; #pragma unroll
;       for (int s = 0; s < 2; ++s)
; #pragma unroll
;         for (int t8 = 0; t8 < 8; ++t8) {
;           const bf16x8 kf = *reinterpret_cast<const bf16x8*>(&sm_k[(t8 * 16 + (lane_c & 15)) * LDSS + s * 32 + (lane_c >> 4) * 8]);
;           sacc[t8] = __builtin_amdgcn_mfma_f32_16x16x32_bf16(qf[s], kf, sacc[t8], 0, 0, 0);
;         }
;       if (ck < 5) {
;         ATT_ISSUE(t, ck + 1)
;       } else if (t + VGRID < 8192) {
;         ATT_ISSUE(t + VGRID, 0)
;         ATT_QLOAD(t + VGRID)
;       }
;       if (ck < 4) {
;         const float* rb0 = sm_rpb + (rs + ck * 2 - r + 7) * 31;
; #pragma unroll
;         for (int t8 = 0; t8 < 8; ++t8)
; #pragma unroll
;           for (int reg = 0; reg < 4; ++reg)
;             sacc[t8][reg] += rb0[(t8 >> 2) * 31 + dco[reg][t8 & 3]];
;       }
; #pragma unroll
;       for (int reg = 0; reg < 4; ++reg) {
;         float mx = sacc[0][reg];
; #pragma unroll
;         for (int t8 = 1; t8 < 8; ++t8) mx = fmaxf(mx, sacc[t8][reg]);
;         mx = row16_max(mx);
;         const float mnew = fmaxf(mrow[reg], mx);
;         const float alpha = __builtin_amdgcn_exp2f(mrow[reg] - mnew);
;         mrow[reg] = mnew;
;         float rsum = 0.f;
; #pragma unroll
;         for (int t8 = 0; t8 < 8; ++t8) {
;           const float p = __builtin_amdgcn_exp2f(sacc[t8][reg] - mnew);
;           rsum += p;
;           sm_p[(wid * 16 + (lane_c >> 4) * 4 + reg) * 136 + t8 * 16 + (lane_c & 15)] = f2bf(p);
;         }
;         rsum = row16_sum(rsum);
;         lrow[reg] = lrow[reg] * alpha + rsum;
; #pragma unroll
;         for (int td = 0; td < 4; ++td) o[td][reg] *= alpha;
;       }
;       asm volatile("s_waitcnt lgkmcnt(0)" ::: "memory");
; #pragma unroll
;       for (int s4 = 0; s4 < 4; ++s4) {
	v_exp_f32_e32 v29, v29
	v_exp_f32_e32 v30, v30
	v_exp_f32_e32 v31, v31
	ds_read_b128 v[112:115], v146 offset:32768
	ds_read_b128 v[116:119], v146 offset:36864
	ds_read_b128 v[120:123], v146 offset:40960
	ds_read_b128 v[124:127], v146 offset:45056
	ds_read_b128 v[128:131], v147 offset:32768
	ds_read_b128 v[132:135], v147 offset:36864
	ds_read_b128 v[136:139], v147 offset:40960
	ds_read_b128 v[140:143], v147 offset:45056
	v_mov_b32_e32 v221, v220
	v_mov_b32_e32 v249, v248
	v_pk_add_f32 v[222:223], v[0:1], v[2:3]
	v_pk_add_f32 v[250:251], v[16:17], v[18:19]
	v_pk_add_f32 v[222:223], v[222:223], v[4:5]
	v_pk_add_f32 v[250:251], v[250:251], v[20:21]
	v_pk_add_f32 v[222:223], v[222:223], v[6:7]
	v_pk_add_f32 v[250:251], v[250:251], v[22:23]
	v_pk_add_f32 v[222:223], v[222:223], v[8:9]
	v_pk_add_f32 v[250:251], v[250:251], v[24:25]
	v_pk_add_f32 v[222:223], v[222:223], v[10:11]
	v_pk_add_f32 v[250:251], v[250:251], v[26:27]
	v_pk_add_f32 v[222:223], v[222:223], v[12:13]
	v_pk_add_f32 v[250:251], v[250:251], v[28:29]
	v_pk_add_f32 v[222:223], v[222:223], v[14:15]
	v_pk_add_f32 v[250:251], v[250:251], v[30:31]
	v_pk_mul_f32 v[32:33], v[32:33], v[220:221]
	v_pk_mul_f32 v[34:35], v[34:35], v[220:221]
	v_pk_mul_f32 v[176:177], v[176:177], v[248:249]
	v_pk_mul_f32 v[178:179], v[178:179], v[248:249]
	v_pk_mul_f32 v[36:37], v[36:37], v[220:221]
	v_pk_mul_f32 v[38:39], v[38:39], v[220:221]
	v_pk_mul_f32 v[180:181], v[180:181], v[248:249]
	v_pk_mul_f32 v[182:183], v[182:183], v[248:249]
	v_pk_mul_f32 v[40:41], v[40:41], v[220:221]
	v_pk_mul_f32 v[42:43], v[42:43], v[220:221]
	v_pk_mul_f32 v[192:193], v[192:193], v[248:249]
	v_pk_mul_f32 v[194:195], v[194:195], v[248:249]
	v_pk_mul_f32 v[44:45], v[44:45], v[220:221]
	v_pk_mul_f32 v[46:47], v[46:47], v[220:221]
	v_pk_mul_f32 v[196:197], v[196:197], v[248:249]
	v_pk_mul_f32 v[198:199], v[198:199], v[248:249]
	v_add_f32_e32 v203, v222, v223
	v_add_f32_e32 v206, v250, v251
	v_fma_f32 v201, v201, v220, v203
	v_fma_f32 v247, v247, v248, v206
	v_cvt_pk_bf16_f32 v48, v0, v1
	v_cvt_pk_bf16_f32 v49, v2, v3
	v_cvt_pk_bf16_f32 v50, v4, v5
	v_cvt_pk_bf16_f32 v51, v6, v7
	v_cvt_pk_bf16_f32 v56, v16, v17
	v_cvt_pk_bf16_f32 v57, v18, v19
	v_cvt_pk_bf16_f32 v58, v20, v21
	v_cvt_pk_bf16_f32 v59, v22, v23
	v_cvt_pk_bf16_f32 v52, v8, v9
	v_cvt_pk_bf16_f32 v53, v10, v11
	v_cvt_pk_bf16_f32 v54, v12, v13
	v_cvt_pk_bf16_f32 v55, v14, v15
	v_cvt_pk_bf16_f32 v60, v24, v25
	v_cvt_pk_bf16_f32 v61, v26, v27
	v_cvt_pk_bf16_f32 v62, v28, v29
	v_cvt_pk_bf16_f32 v63, v30, v31
	s_waitcnt lgkmcnt(7)
	v_mfma_f32_16x16x32_bf16 v[32:35], v[112:115], v[48:51], v[32:35]
	v_mfma_f32_16x16x32_bf16 v[176:179], v[112:115], v[56:59], v[176:179]
	s_waitcnt lgkmcnt(6)
	v_mfma_f32_16x16x32_bf16 v[36:39], v[116:119], v[48:51], v[36:39]
	v_mfma_f32_16x16x32_bf16 v[180:183], v[116:119], v[56:59], v[180:183]
	s_waitcnt lgkmcnt(5)
	v_mfma_f32_16x16x32_bf16 v[40:43], v[120:123], v[48:51], v[40:43]
	v_mfma_f32_16x16x32_bf16 v[192:195], v[120:123], v[56:59], v[192:195]
	s_waitcnt lgkmcnt(4)
	v_mfma_f32_16x16x32_bf16 v[44:47], v[124:127], v[48:51], v[44:47]
	v_mfma_f32_16x16x32_bf16 v[196:199], v[124:127], v[56:59], v[196:199]
	s_waitcnt lgkmcnt(3)
	v_mfma_f32_16x16x32_bf16 v[32:35], v[128:131], v[52:55], v[32:35]
	v_mfma_f32_16x16x32_bf16 v[176:179], v[128:131], v[60:63], v[176:179]
	s_waitcnt lgkmcnt(2)
	v_mfma_f32_16x16x32_bf16 v[36:39], v[132:135], v[52:55], v[36:39]
	v_mfma_f32_16x16x32_bf16 v[180:183], v[132:135], v[60:63], v[180:183]
	s_waitcnt lgkmcnt(1)
	v_mfma_f32_16x16x32_bf16 v[40:43], v[136:139], v[52:55], v[40:43]
	v_mfma_f32_16x16x32_bf16 v[192:195], v[136:139], v[60:63], v[192:195]
	s_waitcnt lgkmcnt(0)
	v_mfma_f32_16x16x32_bf16 v[44:47], v[140:143], v[52:55], v[44:47]
	v_mfma_f32_16x16x32_bf16 v[196:199], v[140:143], v[60:63], v[196:199]
	s_waitcnt lgkmcnt(0)
	s_barrier
	s_cmp_eq_u32 s19, 0
	s_cbranch_scc1 .Lmy_att_s4_1
	ds_read_b32 v0, v184 offset:1280
	ds_read_b32 v1, v185 offset:1280
	ds_read_b32 v2, v186 offset:1280
	ds_read_b32 v3, v187 offset:1280
	ds_read_b32 v8, v188 offset:1280
	ds_read_b32 v9, v189 offset:1280
	ds_read_b32 v10, v190 offset:1280
	ds_read_b32 v11, v191 offset:1280
	v_mov_b32_e32 v4, 0xf149f2ca
	v_mov_b32_e32 v5, 0xf149f2ca
	v_mov_b32_e32 v6, 0xf149f2ca
	v_mov_b32_e32 v7, 0xf149f2ca
	v_mov_b32_e32 v12, 0xf149f2ca
	v_mov_b32_e32 v13, 0xf149f2ca
	v_mov_b32_e32 v14, 0xf149f2ca
	v_mov_b32_e32 v15, 0xf149f2ca
	ds_read_b128 v[112:115], v144 offset:0
	ds_read_b128 v[116:119], v145 offset:0
	ds_read_b128 v[120:123], v144 offset:8192
	ds_read_b128 v[124:127], v145 offset:8192
	ds_read_b128 v[128:131], v144 offset:2048
	ds_read_b128 v[132:135], v145 offset:2048
	ds_read_b128 v[136:139], v144 offset:10240
	ds_read_b128 v[140:143], v145 offset:10240
	s_waitcnt lgkmcnt(7)
	v_mfma_f32_16x16x32_bf16 v[0:3], v[112:115], v[230:233], v[0:3]
	s_waitcnt lgkmcnt(6)
	v_mfma_f32_16x16x32_bf16 v[0:3], v[116:119], v[234:237], v[0:3]
	s_waitcnt lgkmcnt(5)
	v_mfma_f32_16x16x32_bf16 v[4:7], v[120:123], v[230:233], v[4:7]
	s_waitcnt lgkmcnt(4)
	v_mfma_f32_16x16x32_bf16 v[4:7], v[124:127], v[234:237], v[4:7]
	s_waitcnt lgkmcnt(3)
	v_mfma_f32_16x16x32_bf16 v[8:11], v[128:131], v[230:233], v[8:11]
	s_waitcnt lgkmcnt(2)
	v_mfma_f32_16x16x32_bf16 v[8:11], v[132:135], v[234:237], v[8:11]
	s_waitcnt lgkmcnt(1)
	v_mfma_f32_16x16x32_bf16 v[12:15], v[136:139], v[230:233], v[12:15]
	s_waitcnt lgkmcnt(0)
; __device__ __forceinline__ void attn_phase(const Params& P, char* smem_raw) {
;     ...
;     for (int ck = 0; ck < 6; ++ck) {
;       int lane_c = lane;
;       asm volatile("" : "+v"(lane_c));
;       __syncthreads();
; #pragma unroll
;       for (int i = 0; i < 4; ++i) {
;         const int idx = tid + 256 * i;
;         *reinterpret_cast<uint4*>(&sm_k[(idx >> 3) * LDSS + (idx & 7) * 8]) = kreg[i];
;         *reinterpret_cast<uint4*>(&sm_vt[(idx >> 4) * 136 + (idx & 15) * 8]) = vreg[i];
;       }
;       __syncthreads();
;       f32x4 sacc[8];
; #pragma unroll
;       for (int t8 = 0; t8 < 8; ++t8) sacc[t8] = f32x4{0.f, 0.f, 0.f, 0.f};
; #pragma unroll
;       for (int s = 0; s < 2; ++s)
; #pragma unroll
;         for (int t8 = 0; t8 < 8; ++t8) {
;           const bf16x8 kf = *reinterpret_cast<const bf16x8*>(&sm_k[(t8 * 16 + (lane_c & 15)) * LDSS + s * 32 + (lane_c >> 4) * 8]);
;           sacc[t8] = __builtin_amdgcn_mfma_f32_16x16x32_bf16(qf[s], kf, sacc[t8], 0, 0, 0);
;         }
;       if (ck < 5) {
;         ATT_ISSUE(t, ck + 1)
;       } else if (t + VGRID < 8192) {
;         ATT_ISSUE(t + VGRID, 0)
;         ATT_QLOAD(t + VGRID)
;       }
;       if (ck < 4) {
;         const float* rb0 = sm_rpb + (rs + ck * 2 - r + 7) * 31;
; #pragma unroll
;         for (int t8 = 0; t8 < 8; ++t8)
; #pragma unroll
;           for (int reg = 0; reg < 4; ++reg)
;             sacc[t8][reg] += rb0[(t8 >> 2) * 31 + dco[reg][t8 & 3]];
;       }
; #pragma unroll
;       for (int reg = 0; reg < 4; ++reg) {
;         float mx = sacc[0][reg];
; #pragma unroll
;         for (int t8 = 1; t8 < 8; ++t8) mx = fmaxf(mx, sacc[t8][reg]);
;         mx = row16_max(mx);
;         const float mnew = fmaxf(mrow[reg], mx);
;         const float alpha = __builtin_amdgcn_exp2f(mrow[reg] - mnew);
;         mrow[reg] = mnew;
;         float rsum = 0.f;
; #pragma unroll
;         for (int t8 = 0; t8 < 8; ++t8) {
;           const float p = __builtin_amdgcn_exp2f(sacc[t8][reg] - mnew);
;           rsum += p;
;           sm_p[(wid * 16 + (lane_c >> 4) * 4 + reg) * 136 + t8 * 16 + (lane_c & 15)] = f2bf(p);
;         }
;         rsum = row16_sum(rsum);
;         lrow[reg] = lrow[reg] * alpha + rsum;
; #pragma unroll
;         for (int td = 0; td < 4; ++td) o[td][reg] *= alpha;
;       }
;       asm volatile("s_waitcnt lgkmcnt(0)" ::: "memory");
; #pragma unroll
;       for (int s4 = 0; s4 < 4; ++s4) {
	v_mfma_f32_16x16x32_bf16 v[12:15], v[140:143], v[234:237], v[12:15]
	s_nop 7
	v_max3_f32 v203, v0, v1, v2
	v_max3_f32 v203, v203, v3, v4
	v_max3_f32 v203, v203, v5, v6
	v_max3_f32 v203, v203, v7, v8
	v_max3_f32 v203, v203, v9, v10
	v_max3_f32 v203, v203, v11, v12
	v_max3_f32 v203, v203, v13, v14
	v_max_f32_e32 v203, v203, v15
	v_mov_b32_e32 v205, v203
	s_nop 1
	v_permlane16_swap_b32_e32 v203, v205
	v_max_f32_e32 v203, v203, v205
	v_mov_b32_e32 v205, v203
	s_nop 1
	v_permlane32_swap_b32_e32 v203, v205
	v_max_f32_e32 v203, v203, v205
	v_max_f32_e32 v218, v246, v203
	v_sub_f32_e32 v220, v246, v218
	v_mov_b32_e32 v219, v218
	v_exp_f32_e32 v220, v220
	v_mov_b32_e32 v246, v218
	v_pk_add_f32 v[0:1], v[0:1], v[218:219] neg_lo:[0,1] neg_hi:[0,1]
	v_pk_add_f32 v[2:3], v[2:3], v[218:219] neg_lo:[0,1] neg_hi:[0,1]
	v_pk_add_f32 v[4:5], v[4:5], v[218:219] neg_lo:[0,1] neg_hi:[0,1]
	v_pk_add_f32 v[6:7], v[6:7], v[218:219] neg_lo:[0,1] neg_hi:[0,1]
	v_pk_add_f32 v[8:9], v[8:9], v[218:219] neg_lo:[0,1] neg_hi:[0,1]
	v_pk_add_f32 v[10:11], v[10:11], v[218:219] neg_lo:[0,1] neg_hi:[0,1]
	v_pk_add_f32 v[12:13], v[12:13], v[218:219] neg_lo:[0,1] neg_hi:[0,1]
	v_pk_add_f32 v[14:15], v[14:15], v[218:219] neg_lo:[0,1] neg_hi:[0,1]
	v_exp_f32_e32 v0, v0
	s_waitcnt vmcnt(0)
	v_exp_f32_e32 v1, v1
	ds_write_b128 v150, v[80:83] offset:32768
	v_exp_f32_e32 v2, v2
	ds_write_b128 v150, v[84:87] offset:36864
	v_exp_f32_e32 v3, v3
	ds_write_b128 v150, v[88:91] offset:40960
	v_exp_f32_e32 v4, v4
	ds_write_b128 v150, v[92:95] offset:45056
	v_exp_f32_e32 v5, v5
	ds_write_b64 v151, v[96:97] offset:32768
	v_exp_f32_e32 v6, v6
	ds_write_b64 v229, v[98:99] offset:32768
	v_exp_f32_e32 v7, v7
	ds_write_b64 v151, v[100:101] offset:36864
	v_exp_f32_e32 v8, v8
	ds_write_b64 v229, v[102:103] offset:36864
	v_exp_f32_e32 v9, v9
	ds_write_b64 v151, v[104:105] offset:40960
	v_exp_f32_e32 v10, v10
	ds_write_b64 v229, v[106:107] offset:40960
	v_exp_f32_e32 v11, v11
	ds_write_b64 v151, v[108:109] offset:45056
	v_exp_f32_e32 v12, v12
	ds_write_b64 v229, v[110:111] offset:45056
	v_exp_f32_e32 v13, v13
	s_add_u32 s100, s16, 0xc0000
	v_exp_f32_e32 v14, v14
	s_addc_u32 s101, s17, 0
	v_exp_f32_e32 v15, v15
	s_add_u32 s0, s36, 0x100
	s_addc_u32 s1, s37, 0
	global_load_dwordx4 v[80:83], v154, s[100:101] offset:2048
	global_load_dwordx4 v[96:99], v162, s[0:1]
	global_load_dwordx4 v[84:87], v155, s[100:101] offset:2048
	global_load_dwordx4 v[100:103], v163, s[0:1]
	global_load_dwordx4 v[88:91], v156, s[100:101] offset:2048
	global_load_dwordx4 v[104:107], v164, s[0:1]
	global_load_dwordx4 v[92:95], v157, s[100:101] offset:2048
	global_load_dwordx4 v[108:111], v165, s[0:1]
	s_and_b32 s0, s3, 0xff
	s_add_u32 s0, s0, 1
	s_min_u32 s0, s0, 7
	s_lshr_b32 s1, s0, 1
	s_and_b32 s0, s0, 1
	s_lshl_b32 s0, s0, 5
	s_lshr_b32 vcc_lo, s3, 12
	s_add_u32 s0, s0, vcc_lo
	s_lshl_b32 s0, s0, 1
	s_sub_i32 vcc_lo, s0, 4
	s_max_i32 vcc_lo, vcc_lo, 0
	s_min_i32 vcc_lo, vcc_lo, 0x78
	s_lshl_b32 vcc_hi, s1, 13
	s_add_u32 s20, vcc_lo, 8
	s_min_u32 s20, s20, 0x7e
	s_sub_u32 s20, s20, vcc_lo
	s_lshl_b32 s21, s20, 7
	s_mul_i32 s20, s20, 0x60000
	s_lshl_b32 m0, vcc_lo, 6
	s_add_u32 m0, m0, vcc_hi
	s_mul_i32 m0, m0, 0x1800
	s_add_u32 s12, s4, m0
	s_addc_u32 s13, s5, 0
	s_lshl_b32 m0, s1, 24
	s_lshl_b32 s100, vcc_lo, 7
	s_add_u32 m0, m0, s100
	s_add_u32 s14, s6, m0
	s_addc_u32 s15, s7, 0
	s_lshl_b32 m0, s0, 6
	s_add_u32 m0, m0, vcc_hi
	s_mul_i32 m0, m0, 0x1800
	s_add_u32 s100, s4, m0
	s_addc_u32 s101, s5, 0
	global_load_dwordx4 v[72:75], v166, s[100:101]
	global_load_dwordx4 v[76:79], v166, s[100:101] offset:64
	s_add_u32 s100, s100, 0x60000
	s_addc_u32 s101, s101, 0
	global_load_dwordx4 v[238:241], v166, s[100:101]
	global_load_dwordx4 v[242:245], v166, s[100:101] offset:64
	ds_read_b128 v[112:115], v146 offset:0
	ds_read_b128 v[116:119], v146 offset:4096
	ds_read_b128 v[120:123], v146 offset:8192
	ds_read_b128 v[124:127], v146 offset:12288
	ds_read_b128 v[128:131], v147 offset:0
	ds_read_b128 v[132:135], v147 offset:4096
	ds_read_b128 v[136:139], v147 offset:8192
	ds_read_b128 v[140:143], v147 offset:12288
	v_mov_b32_e32 v221, v220
	v_pk_add_f32 v[222:223], v[0:1], v[2:3]
	v_pk_add_f32 v[222:223], v[222:223], v[4:5]
	v_pk_add_f32 v[222:223], v[222:223], v[6:7]
	v_pk_add_f32 v[222:223], v[222:223], v[8:9]
	v_pk_add_f32 v[222:223], v[222:223], v[10:11]
	v_pk_add_f32 v[222:223], v[222:223], v[12:13]
	v_pk_add_f32 v[222:223], v[222:223], v[14:15]
	v_pk_mul_f32 v[176:177], v[176:177], v[220:221]
	v_pk_mul_f32 v[178:179], v[178:179], v[220:221]
	v_pk_mul_f32 v[180:181], v[180:181], v[220:221]
	v_pk_mul_f32 v[182:183], v[182:183], v[220:221]
	v_pk_mul_f32 v[192:193], v[192:193], v[220:221]
	v_pk_mul_f32 v[194:195], v[194:195], v[220:221]
	v_pk_mul_f32 v[196:197], v[196:197], v[220:221]
	v_pk_mul_f32 v[198:199], v[198:199], v[220:221]
	v_add_f32_e32 v203, v222, v223
	v_fma_f32 v247, v247, v220, v203
	v_cvt_pk_bf16_f32 v48, v0, v1
	v_cvt_pk_bf16_f32 v49, v2, v3
	v_cvt_pk_bf16_f32 v50, v4, v5
	v_cvt_pk_bf16_f32 v51, v6, v7
	v_cvt_pk_bf16_f32 v52, v8, v9
	v_cvt_pk_bf16_f32 v53, v10, v11
	v_cvt_pk_bf16_f32 v54, v12, v13
	v_cvt_pk_bf16_f32 v55, v14, v15
	s_waitcnt lgkmcnt(7)
	v_mfma_f32_16x16x32_bf16 v[176:179], v[112:115], v[48:51], v[176:179]
	s_waitcnt lgkmcnt(6)
	v_mfma_f32_16x16x32_bf16 v[180:183], v[116:119], v[48:51], v[180:183]
	s_waitcnt lgkmcnt(5)
	v_mfma_f32_16x16x32_bf16 v[192:195], v[120:123], v[48:51], v[192:195]
	s_waitcnt lgkmcnt(4)
	v_mfma_f32_16x16x32_bf16 v[196:199], v[124:127], v[48:51], v[196:199]
	s_waitcnt lgkmcnt(3)
	v_mfma_f32_16x16x32_bf16 v[176:179], v[128:131], v[52:55], v[176:179]
	s_waitcnt lgkmcnt(2)
	v_mfma_f32_16x16x32_bf16 v[180:183], v[132:135], v[52:55], v[180:183]
	s_waitcnt lgkmcnt(1)
	v_mfma_f32_16x16x32_bf16 v[192:195], v[136:139], v[52:55], v[192:195]
	s_waitcnt lgkmcnt(0)
	v_mfma_f32_16x16x32_bf16 v[196:199], v[140:143], v[52:55], v[196:199]
	s_branch .Lmy_att_e4_1

; __device__ __forceinline__ void attn_phase(const Params& P, char* smem_raw) {
;     ...
;     for (int ck = 0; ck < 6; ++ck) {
;       int lane_c = lane;
;       asm volatile("" : "+v"(lane_c));
;       __syncthreads();
; #pragma unroll
;       for (int i = 0; i < 4; ++i) {
;         const int idx = tid + 256 * i;
;         *reinterpret_cast<uint4*>(&sm_k[(idx >> 3) * LDSS + (idx & 7) * 8]) = kreg[i];
;         *reinterpret_cast<uint4*>(&sm_vt[(idx >> 4) * 136 + (idx & 15) * 8]) = vreg[i];
;       }
;       __syncthreads();
;       f32x4 sacc[8];
; #pragma unroll
;       for (int t8 = 0; t8 < 8; ++t8) sacc[t8] = f32x4{0.f, 0.f, 0.f, 0.f};
; #pragma unroll
;       for (int s = 0; s < 2; ++s)
; #pragma unroll
;         for (int t8 = 0; t8 < 8; ++t8) {
;           const bf16x8 kf = *reinterpret_cast<const bf16x8*>(&sm_k[(t8 * 16 + (lane_c & 15)) * LDSS + s * 32 + (lane_c >> 4) * 8]);
;           sacc[t8] = __builtin_amdgcn_mfma_f32_16x16x32_bf16(qf[s], kf, sacc[t8], 0, 0, 0);
;         }
;       if (ck < 5) {
;         ATT_ISSUE(t, ck + 1)
;       } else if (t + VGRID < 8192) {
;         ATT_ISSUE(t + VGRID, 0)
;         ATT_QLOAD(t + VGRID)
;       }
;       if (ck < 4) {
;         const float* rb0 = sm_rpb + (rs + ck * 2 - r + 7) * 31;
; #pragma unroll
;         for (int t8 = 0; t8 < 8; ++t8)
; #pragma unroll
;           for (int reg = 0; reg < 4; ++reg)
;             sacc[t8][reg] += rb0[(t8 >> 2) * 31 + dco[reg][t8 & 3]];
;       }
; #pragma unroll
;       for (int reg = 0; reg < 4; ++reg) {
;         float mx = sacc[0][reg];
; #pragma unroll
;         for (int t8 = 1; t8 < 8; ++t8) mx = fmaxf(mx, sacc[t8][reg]);
;         mx = row16_max(mx);
;         const float mnew = fmaxf(mrow[reg], mx);
;         const float alpha = __builtin_amdgcn_exp2f(mrow[reg] - mnew);
;         mrow[reg] = mnew;
;         float rsum = 0.f;
; #pragma unroll
;         for (int t8 = 0; t8 < 8; ++t8) {
;           const float p = __builtin_amdgcn_exp2f(sacc[t8][reg] - mnew);
;           rsum += p;
;           sm_p[(wid * 16 + (lane_c >> 4) * 4 + reg) * 136 + t8 * 16 + (lane_c & 15)] = f2bf(p);
;         }
;         rsum = row16_sum(rsum);
;         lrow[reg] = lrow[reg] * alpha + rsum;
; #pragma unroll
;         for (int td = 0; td < 4; ++td) o[td][reg] *= alpha;
;       }
.Lmy_att_e4_1:
	s_waitcnt lgkmcnt(0)
	s_barrier
	ds_read_b128 v[112:115], v149 offset:32768
	ds_read_b128 v[116:119], v224 offset:32768
	ds_read_b128 v[120:123], v149 offset:40960
	ds_read_b128 v[124:127], v224 offset:40960
	ds_read_b128 v[128:131], v149 offset:34816
	ds_read_b128 v[132:135], v224 offset:34816
	ds_read_b128 v[136:139], v149 offset:43008
	ds_read_b128 v[140:143], v224 offset:43008
	s_waitcnt lgkmcnt(7)
	v_mfma_f32_16x16x32_bf16 v[0:3], v[112:115], v[64:67], 0
	ds_read_b128 v[112:115], v149 offset:36864
	s_waitcnt lgkmcnt(7)
	v_mfma_f32_16x16x32_bf16 v[0:3], v[116:119], v[68:71], v[0:3]
	ds_read_b128 v[116:119], v224 offset:36864
	s_waitcnt lgkmcnt(7)
	v_mfma_f32_16x16x32_bf16 v[4:7], v[120:123], v[64:67], 0
	ds_read_b128 v[120:123], v149 offset:45056
	s_waitcnt lgkmcnt(7)
	v_mfma_f32_16x16x32_bf16 v[4:7], v[124:127], v[68:71], v[4:7]
	ds_read_b128 v[124:127], v224 offset:45056
	s_waitcnt lgkmcnt(7)
	v_mfma_f32_16x16x32_bf16 v[8:11], v[128:131], v[64:67], 0
	ds_read_b128 v[128:131], v149 offset:38912
	s_waitcnt lgkmcnt(7)
	v_mfma_f32_16x16x32_bf16 v[8:11], v[132:135], v[68:71], v[8:11]
	ds_read_b128 v[132:135], v224 offset:38912
	s_waitcnt lgkmcnt(7)
	v_mfma_f32_16x16x32_bf16 v[12:15], v[136:139], v[64:67], 0
	ds_read_b128 v[136:139], v149 offset:47104
	s_waitcnt lgkmcnt(7)
	v_mfma_f32_16x16x32_bf16 v[12:15], v[140:143], v[68:71], v[12:15]
	ds_read_b128 v[140:143], v224 offset:47104
	s_waitcnt lgkmcnt(7)
	v_mfma_f32_16x16x32_bf16 v[16:19], v[112:115], v[64:67], 0
	s_waitcnt lgkmcnt(6)
	v_mfma_f32_16x16x32_bf16 v[16:19], v[116:119], v[68:71], v[16:19]
	s_waitcnt lgkmcnt(5)
	v_mfma_f32_16x16x32_bf16 v[20:23], v[120:123], v[64:67], 0
	s_waitcnt lgkmcnt(4)
	v_mfma_f32_16x16x32_bf16 v[20:23], v[124:127], v[68:71], v[20:23]
	s_waitcnt lgkmcnt(3)
	v_mfma_f32_16x16x32_bf16 v[24:27], v[128:131], v[64:67], 0
	s_waitcnt lgkmcnt(2)
	v_mfma_f32_16x16x32_bf16 v[24:27], v[132:135], v[68:71], v[24:27]
	s_waitcnt lgkmcnt(1)
	v_mfma_f32_16x16x32_bf16 v[28:31], v[136:139], v[64:67], 0
	s_waitcnt lgkmcnt(0)
	v_mfma_f32_16x16x32_bf16 v[28:31], v[140:143], v[68:71], v[28:31]
	s_nop 7
	v_max3_f32 v203, v0, v1, v2
	v_max3_f32 v203, v203, v3, v4
	v_max3_f32 v203, v203, v5, v6
	v_max3_f32 v203, v203, v7, v8
	v_max3_f32 v203, v203, v9, v10
	v_max3_f32 v203, v203, v11, v12
	v_max3_f32 v203, v203, v13, v14
	v_max3_f32 v203, v203, v15, v16
	v_max3_f32 v203, v203, v17, v18
	v_max3_f32 v203, v203, v19, v20
	v_max3_f32 v203, v203, v21, v22
	v_max3_f32 v203, v203, v23, v24
	v_max3_f32 v203, v203, v25, v26
	v_max3_f32 v203, v203, v27, v28
	v_max3_f32 v203, v203, v29, v30
	v_max_f32_e32 v203, v203, v31
	v_mov_b32_e32 v205, v203
	s_nop 1
	v_permlane16_swap_b32_e32 v203, v205
	v_max_f32_e32 v203, v203, v205
	v_mov_b32_e32 v205, v203
	s_nop 1
	v_permlane32_swap_b32_e32 v203, v205
	v_max_f32_e32 v203, v203, v205
	v_max_f32_e32 v218, v200, v203
	v_sub_f32_e32 v220, v200, v218
	v_mov_b32_e32 v219, v218
	v_exp_f32_e32 v220, v220
	v_mov_b32_e32 v200, v218
	v_pk_add_f32 v[0:1], v[0:1], v[218:219] neg_lo:[0,1] neg_hi:[0,1]
	v_pk_add_f32 v[2:3], v[2:3], v[218:219] neg_lo:[0,1] neg_hi:[0,1]
	v_pk_add_f32 v[4:5], v[4:5], v[218:219] neg_lo:[0,1] neg_hi:[0,1]
	v_pk_add_f32 v[6:7], v[6:7], v[218:219] neg_lo:[0,1] neg_hi:[0,1]
	v_pk_add_f32 v[8:9], v[8:9], v[218:219] neg_lo:[0,1] neg_hi:[0,1]
	v_pk_add_f32 v[10:11], v[10:11], v[218:219] neg_lo:[0,1] neg_hi:[0,1]
	v_pk_add_f32 v[12:13], v[12:13], v[218:219] neg_lo:[0,1] neg_hi:[0,1]
	v_pk_add_f32 v[14:15], v[14:15], v[218:219] neg_lo:[0,1] neg_hi:[0,1]
	v_pk_add_f32 v[16:17], v[16:17], v[218:219] neg_lo:[0,1] neg_hi:[0,1]
	v_pk_add_f32 v[18:19], v[18:19], v[218:219] neg_lo:[0,1] neg_hi:[0,1]
	v_pk_add_f32 v[20:21], v[20:21], v[218:219] neg_lo:[0,1] neg_hi:[0,1]
	v_pk_add_f32 v[22:23], v[22:23], v[218:219] neg_lo:[0,1] neg_hi:[0,1]
	v_pk_add_f32 v[24:25], v[24:25], v[218:219] neg_lo:[0,1] neg_hi:[0,1]
	v_pk_add_f32 v[26:27], v[26:27], v[218:219] neg_lo:[0,1] neg_hi:[0,1]
	v_pk_add_f32 v[28:29], v[28:29], v[218:219] neg_lo:[0,1] neg_hi:[0,1]
	v_pk_add_f32 v[30:31], v[30:31], v[218:219] neg_lo:[0,1] neg_hi:[0,1]
	v_exp_f32_e32 v0, v0
	s_waitcnt vmcnt(4)
	v_exp_f32_e32 v1, v1
	ds_write_b128 v150, v[80:83] offset:0
	v_exp_f32_e32 v2, v2
	ds_write_b128 v150, v[84:87] offset:4096
	v_exp_f32_e32 v3, v3
	ds_write_b128 v150, v[88:91] offset:8192
	v_exp_f32_e32 v4, v4
	ds_write_b128 v150, v[92:95] offset:12288
	v_exp_f32_e32 v5, v5
	ds_write_b64 v151, v[96:97] offset:0
	v_exp_f32_e32 v6, v6
	ds_write_b64 v229, v[98:99] offset:0
	v_exp_f32_e32 v7, v7
	ds_write_b64 v151, v[100:101] offset:4096
	v_exp_f32_e32 v8, v8
	ds_write_b64 v229, v[102:103] offset:4096
	v_exp_f32_e32 v9, v9
	ds_write_b64 v151, v[104:105] offset:8192
	v_exp_f32_e32 v10, v10
	ds_write_b64 v229, v[106:107] offset:8192
	v_exp_f32_e32 v11, v11
	ds_write_b64 v151, v[108:109] offset:12288
	v_exp_f32_e32 v12, v12
	ds_write_b64 v229, v[110:111] offset:12288
	v_exp_f32_e32 v13, v13
	s_add_u32 s100, s12, 0x0
	v_exp_f32_e32 v14, v14
	s_addc_u32 s101, s13, 0
	v_exp_f32_e32 v15, v15
	s_add_u32 s0, s14, 0x0
	v_exp_f32_e32 v16, v16
	s_addc_u32 s1, s15, 0
	v_exp_f32_e32 v17, v17
	global_load_dwordx4 v[80:83], v154, s[100:101] offset:2048
	v_exp_f32_e32 v18, v18
	global_load_dwordx4 v[96:99], v158, s[0:1]
	v_exp_f32_e32 v19, v19
	global_load_dwordx4 v[84:87], v155, s[100:101] offset:2048
	v_exp_f32_e32 v20, v20
	global_load_dwordx4 v[100:103], v159, s[0:1]
	v_exp_f32_e32 v21, v21
	global_load_dwordx4 v[88:91], v156, s[100:101] offset:2048
	v_exp_f32_e32 v22, v22
	global_load_dwordx4 v[104:107], v160, s[0:1]
	v_exp_f32_e32 v23, v23
	global_load_dwordx4 v[92:95], v157, s[100:101] offset:2048
; __device__ __forceinline__ void attn_phase(const Params& P, char* smem_raw) {
;     ...
;     for (int ck = 0; ck < 6; ++ck) {
;       int lane_c = lane;
;       asm volatile("" : "+v"(lane_c));
;       __syncthreads();
; #pragma unroll
;       for (int i = 0; i < 4; ++i) {
;         const int idx = tid + 256 * i;
;         *reinterpret_cast<uint4*>(&sm_k[(idx >> 3) * LDSS + (idx & 7) * 8]) = kreg[i];
;         *reinterpret_cast<uint4*>(&sm_vt[(idx >> 4) * 136 + (idx & 15) * 8]) = vreg[i];
;       }
;       __syncthreads();
;       f32x4 sacc[8];
; #pragma unroll
;       for (int t8 = 0; t8 < 8; ++t8) sacc[t8] = f32x4{0.f, 0.f, 0.f, 0.f};
; #pragma unroll
;       for (int s = 0; s < 2; ++s)
; #pragma unroll
;         for (int t8 = 0; t8 < 8; ++t8) {
;           const bf16x8 kf = *reinterpret_cast<const bf16x8*>(&sm_k[(t8 * 16 + (lane_c & 15)) * LDSS + s * 32 + (lane_c >> 4) * 8]);
;           sacc[t8] = __builtin_amdgcn_mfma_f32_16x16x32_bf16(qf[s], kf, sacc[t8], 0, 0, 0);
;         }
;       if (ck < 5) {
;         ATT_ISSUE(t, ck + 1)
;       } else if (t + VGRID < 8192) {
;         ATT_ISSUE(t + VGRID, 0)
;         ATT_QLOAD(t + VGRID)
;       }
;       if (ck < 4) {
;         const float* rb0 = sm_rpb + (rs + ck * 2 - r + 7) * 31;
; #pragma unroll
;         for (int t8 = 0; t8 < 8; ++t8)
; #pragma unroll
;           for (int reg = 0; reg < 4; ++reg)
;             sacc[t8][reg] += rb0[(t8 >> 2) * 31 + dco[reg][t8 & 3]];
;       }
; #pragma unroll
;       for (int reg = 0; reg < 4; ++reg) {
;         float mx = sacc[0][reg];
; #pragma unroll
;         for (int t8 = 1; t8 < 8; ++t8) mx = fmaxf(mx, sacc[t8][reg]);
;         mx = row16_max(mx);
;         const float mnew = fmaxf(mrow[reg], mx);
;         const float alpha = __builtin_amdgcn_exp2f(mrow[reg] - mnew);
;         mrow[reg] = mnew;
;         float rsum = 0.f;
; #pragma unroll
;         for (int t8 = 0; t8 < 8; ++t8) {
;           const float p = __builtin_amdgcn_exp2f(sacc[t8][reg] - mnew);
;           rsum += p;
;           sm_p[(wid * 16 + (lane_c >> 4) * 4 + reg) * 136 + t8 * 16 + (lane_c & 15)] = f2bf(p);
;         }
;         rsum = row16_sum(rsum);
;         lrow[reg] = lrow[reg] * alpha + rsum;
; #pragma unroll
;         for (int td = 0; td < 4; ++td) o[td][reg] *= alpha;
;       }
;       asm volatile("s_waitcnt lgkmcnt(0)" ::: "memory");
; #pragma unroll
;       for (int s4 = 0; s4 < 4; ++s4) {
	v_exp_f32_e32 v24, v24
	global_load_dwordx4 v[108:111], v161, s[0:1]
	v_exp_f32_e32 v25, v25
	v_exp_f32_e32 v26, v26
	v_exp_f32_e32 v27, v27
	v_exp_f32_e32 v28, v28
	v_exp_f32_e32 v29, v29
	v_exp_f32_e32 v30, v30
	v_exp_f32_e32 v31, v31
	s_and_b32 s0, s3, 0xff
	s_add_u32 s0, s0, 1
	s_min_u32 s0, s0, 7
	s_lshr_b32 s1, s0, 1
	s_and_b32 s0, s0, 1
	s_lshl_b32 s0, s0, 5
	s_lshr_b32 vcc_lo, s3, 12
	s_add_u32 s0, s0, vcc_lo
	s_lshl_b32 s0, s0, 1
	s_sub_i32 vcc_lo, s0, 4
	s_max_i32 vcc_lo, vcc_lo, 0
	s_min_i32 vcc_lo, vcc_lo, 0x78
	s_lshl_b32 vcc_hi, s1, 13
	s_sub_i32 vcc_lo, vcc_lo, s0
	s_add_i32 vcc_lo, vcc_lo, 4
	s_lshl_b32 vcc_lo, vcc_lo, 7
	s_bfe_u32 m0, s3, 0x10008
	s_mul_i32 m0, m0, 0x12000
	s_add_i32 vcc_lo, vcc_lo, m0
	s_add_i32 vcc_lo, vcc_lo, 0x10010
	v_add_u32_e32 v184, vcc_lo, v168
	v_add_u32_e32 v185, vcc_lo, v169
	v_add_u32_e32 v186, vcc_lo, v170
	v_add_u32_e32 v187, vcc_lo, v171
	v_add_u32_e32 v188, vcc_lo, v172
	v_add_u32_e32 v189, vcc_lo, v173
	v_add_u32_e32 v190, vcc_lo, v174
	v_add_u32_e32 v191, vcc_lo, v175
	s_and_b32 s0, s3, 0xff
	s_add_u32 s0, s0, 1
	s_min_u32 s0, s0, 7
	s_lshr_b32 s1, s0, 1
	s_and_b32 s0, s0, 1
	s_lshl_b32 s0, s0, 5
	s_lshr_b32 vcc_lo, s3, 12
	s_add_u32 s0, s0, vcc_lo
	s_lshl_b32 s0, s0, 1
	s_sub_i32 vcc_lo, s0, 4
	s_max_i32 vcc_lo, vcc_lo, 0
	s_min_i32 vcc_lo, vcc_lo, 0x78
	s_lshl_b32 vcc_hi, s1, 13
	s_sub_i32 s18, s0, 3
	s_max_i32 s18, s18, 0
	s_min_i32 s18, s18, 0x78
	s_sub_i32 s18, vcc_lo, s18
	ds_read_b128 v[112:115], v225 offset:32768
	ds_read_b128 v[116:119], v225 offset:36864
	ds_read_b128 v[120:123], v225 offset:40960
	ds_read_b128 v[124:127], v225 offset:45056
	ds_read_b128 v[128:131], v226 offset:32768
	ds_read_b128 v[132:135], v226 offset:36864
	ds_read_b128 v[136:139], v226 offset:40960
	ds_read_b128 v[140:143], v226 offset:45056
	v_mov_b32_e32 v221, v220
	v_pk_add_f32 v[222:223], v[0:1], v[2:3]
	v_pk_add_f32 v[222:223], v[222:223], v[4:5]
	v_pk_add_f32 v[222:223], v[222:223], v[6:7]
	v_pk_add_f32 v[222:223], v[222:223], v[8:9]
	v_pk_add_f32 v[222:223], v[222:223], v[10:11]
	v_pk_add_f32 v[222:223], v[222:223], v[12:13]
	v_pk_add_f32 v[222:223], v[222:223], v[14:15]
	v_pk_add_f32 v[222:223], v[222:223], v[16:17]
	v_pk_add_f32 v[222:223], v[222:223], v[18:19]
	v_pk_add_f32 v[222:223], v[222:223], v[20:21]
	v_pk_add_f32 v[222:223], v[222:223], v[22:23]
	v_pk_add_f32 v[222:223], v[222:223], v[24:25]
	v_pk_add_f32 v[222:223], v[222:223], v[26:27]
	v_pk_add_f32 v[222:223], v[222:223], v[28:29]
	v_pk_add_f32 v[222:223], v[222:223], v[30:31]
	v_pk_mul_f32 v[32:33], v[32:33], v[220:221]
	v_pk_mul_f32 v[34:35], v[34:35], v[220:221]
	v_pk_mul_f32 v[36:37], v[36:37], v[220:221]
	v_pk_mul_f32 v[38:39], v[38:39], v[220:221]
	v_pk_mul_f32 v[40:41], v[40:41], v[220:221]
	v_pk_mul_f32 v[42:43], v[42:43], v[220:221]
	v_pk_mul_f32 v[44:45], v[44:45], v[220:221]
	v_pk_mul_f32 v[46:47], v[46:47], v[220:221]
	v_add_f32_e32 v203, v222, v223
	v_fma_f32 v201, v201, v220, v203
	v_cvt_pk_bf16_f32 v48, v0, v1
	v_cvt_pk_bf16_f32 v49, v2, v3
	v_cvt_pk_bf16_f32 v50, v4, v5
	v_cvt_pk_bf16_f32 v51, v6, v7
	v_cvt_pk_bf16_f32 v52, v8, v9
	v_cvt_pk_bf16_f32 v53, v10, v11
	v_cvt_pk_bf16_f32 v54, v12, v13
	v_cvt_pk_bf16_f32 v55, v14, v15
	v_cvt_pk_bf16_f32 v56, v16, v17
	v_cvt_pk_bf16_f32 v57, v18, v19
	v_cvt_pk_bf16_f32 v58, v20, v21
	v_cvt_pk_bf16_f32 v59, v22, v23
	v_cvt_pk_bf16_f32 v60, v24, v25
	v_cvt_pk_bf16_f32 v61, v26, v27
	v_cvt_pk_bf16_f32 v62, v28, v29
	v_cvt_pk_bf16_f32 v63, v30, v31
	s_waitcnt lgkmcnt(7)
	v_mfma_f32_16x16x32_bf16 v[32:35], v[112:115], v[48:51], v[32:35]
	ds_read_b128 v[112:115], v227 offset:32768
	s_waitcnt lgkmcnt(7)
	v_mfma_f32_16x16x32_bf16 v[36:39], v[116:119], v[48:51], v[36:39]
	ds_read_b128 v[116:119], v227 offset:36864
	s_waitcnt lgkmcnt(7)
	v_mfma_f32_16x16x32_bf16 v[40:43], v[120:123], v[48:51], v[40:43]
	ds_read_b128 v[120:123], v227 offset:40960
	s_waitcnt lgkmcnt(7)
	v_mfma_f32_16x16x32_bf16 v[44:47], v[124:127], v[48:51], v[44:47]
	ds_read_b128 v[124:127], v227 offset:45056
	s_waitcnt lgkmcnt(7)
	v_mfma_f32_16x16x32_bf16 v[32:35], v[128:131], v[52:55], v[32:35]
	ds_read_b128 v[128:131], v228 offset:32768
	s_waitcnt lgkmcnt(7)
	v_mfma_f32_16x16x32_bf16 v[36:39], v[132:135], v[52:55], v[36:39]
	ds_read_b128 v[132:135], v228 offset:36864
	s_waitcnt lgkmcnt(7)
	v_mfma_f32_16x16x32_bf16 v[40:43], v[136:139], v[52:55], v[40:43]
	ds_read_b128 v[136:139], v228 offset:40960
	s_waitcnt lgkmcnt(7)
	v_mfma_f32_16x16x32_bf16 v[44:47], v[140:143], v[52:55], v[44:47]
	ds_read_b128 v[140:143], v228 offset:45056
	s_waitcnt lgkmcnt(7)
	v_mfma_f32_16x16x32_bf16 v[32:35], v[112:115], v[56:59], v[32:35]
	s_waitcnt lgkmcnt(6)
	v_mfma_f32_16x16x32_bf16 v[36:39], v[116:119], v[56:59], v[36:39]
	s_waitcnt lgkmcnt(5)
	v_mfma_f32_16x16x32_bf16 v[40:43], v[120:123], v[56:59], v[40:43]
	s_waitcnt lgkmcnt(4)
	v_mfma_f32_16x16x32_bf16 v[44:47], v[124:127], v[56:59], v[44:47]
	s_waitcnt lgkmcnt(3)
	v_mfma_f32_16x16x32_bf16 v[32:35], v[128:131], v[60:63], v[32:35]
	s_waitcnt lgkmcnt(2)
	v_mfma_f32_16x16x32_bf16 v[36:39], v[132:135], v[60:63], v[36:39]
	s_waitcnt lgkmcnt(1)
	v_mfma_f32_16x16x32_bf16 v[40:43], v[136:139], v[60:63], v[40:43]
	s_waitcnt lgkmcnt(0)
	v_mfma_f32_16x16x32_bf16 v[44:47], v[140:143], v[60:63], v[44:47]
	ds_read_b128 v[112:115], v149 offset:32768
	ds_read_b128 v[116:119], v224 offset:32768
	ds_read_b128 v[120:123], v149 offset:40960
	ds_read_b128 v[124:127], v224 offset:40960
	ds_read_b128 v[128:131], v149 offset:34816
	ds_read_b128 v[132:135], v224 offset:34816
	ds_read_b128 v[136:139], v149 offset:43008
	ds_read_b128 v[140:143], v224 offset:43008
	s_waitcnt lgkmcnt(7)
; __device__ __forceinline__ void attn_phase(const Params& P, char* smem_raw) {
;     ...
;     for (int ck = 0; ck < 6; ++ck) {
;       int lane_c = lane;
;       asm volatile("" : "+v"(lane_c));
;       __syncthreads();
; #pragma unroll
;       for (int i = 0; i < 4; ++i) {
;         const int idx = tid + 256 * i;
;         *reinterpret_cast<uint4*>(&sm_k[(idx >> 3) * LDSS + (idx & 7) * 8]) = kreg[i];
;         *reinterpret_cast<uint4*>(&sm_vt[(idx >> 4) * 136 + (idx & 15) * 8]) = vreg[i];
;       }
;       __syncthreads();
;       f32x4 sacc[8];
; #pragma unroll
;       for (int t8 = 0; t8 < 8; ++t8) sacc[t8] = f32x4{0.f, 0.f, 0.f, 0.f};
; #pragma unroll
;       for (int s = 0; s < 2; ++s)
; #pragma unroll
;         for (int t8 = 0; t8 < 8; ++t8) {
;           const bf16x8 kf = *reinterpret_cast<const bf16x8*>(&sm_k[(t8 * 16 + (lane_c & 15)) * LDSS + s * 32 + (lane_c >> 4) * 8]);
;           sacc[t8] = __builtin_amdgcn_mfma_f32_16x16x32_bf16(qf[s], kf, sacc[t8], 0, 0, 0);
;         }
;       if (ck < 5) {
;         ATT_ISSUE(t, ck + 1)
;       } else if (t + VGRID < 8192) {
;         ATT_ISSUE(t + VGRID, 0)
;         ATT_QLOAD(t + VGRID)
;       }
;       if (ck < 4) {
;         const float* rb0 = sm_rpb + (rs + ck * 2 - r + 7) * 31;
; #pragma unroll
;         for (int t8 = 0; t8 < 8; ++t8)
; #pragma unroll
;           for (int reg = 0; reg < 4; ++reg)
;             sacc[t8][reg] += rb0[(t8 >> 2) * 31 + dco[reg][t8 & 3]];
;       }
; #pragma unroll
;       for (int reg = 0; reg < 4; ++reg) {
;         float mx = sacc[0][reg];
; #pragma unroll
;         for (int t8 = 1; t8 < 8; ++t8) mx = fmaxf(mx, sacc[t8][reg]);
;         mx = row16_max(mx);
;         const float mnew = fmaxf(mrow[reg], mx);
;         const float alpha = __builtin_amdgcn_exp2f(mrow[reg] - mnew);
;         mrow[reg] = mnew;
;         float rsum = 0.f;
; #pragma unroll
;         for (int t8 = 0; t8 < 8; ++t8) {
;           const float p = __builtin_amdgcn_exp2f(sacc[t8][reg] - mnew);
;           rsum += p;
;           sm_p[(wid * 16 + (lane_c >> 4) * 4 + reg) * 136 + t8 * 16 + (lane_c & 15)] = f2bf(p);
;         }
;         rsum = row16_sum(rsum);
;         lrow[reg] = lrow[reg] * alpha + rsum;
; #pragma unroll
;         for (int td = 0; td < 4; ++td) o[td][reg] *= alpha;
;       }
;       asm volatile("s_waitcnt lgkmcnt(0)" ::: "memory");
; #pragma unroll
;       for (int s4 = 0; s4 < 4; ++s4) {
	v_mfma_f32_16x16x32_bf16 v[0:3], v[112:115], v[230:233], 0
	ds_read_b128 v[112:115], v149 offset:36864
	s_waitcnt lgkmcnt(7)
	v_mfma_f32_16x16x32_bf16 v[0:3], v[116:119], v[234:237], v[0:3]
	ds_read_b128 v[116:119], v224 offset:36864
	s_waitcnt lgkmcnt(7)
	v_mfma_f32_16x16x32_bf16 v[4:7], v[120:123], v[230:233], 0
	ds_read_b128 v[120:123], v149 offset:45056
	s_waitcnt lgkmcnt(7)
	v_mfma_f32_16x16x32_bf16 v[4:7], v[124:127], v[234:237], v[4:7]
	ds_read_b128 v[124:127], v224 offset:45056
	s_waitcnt lgkmcnt(7)
	v_mfma_f32_16x16x32_bf16 v[8:11], v[128:131], v[230:233], 0
	ds_read_b128 v[128:131], v149 offset:38912
	s_waitcnt lgkmcnt(7)
	v_mfma_f32_16x16x32_bf16 v[8:11], v[132:135], v[234:237], v[8:11]
	ds_read_b128 v[132:135], v224 offset:38912
	s_waitcnt lgkmcnt(7)
	v_mfma_f32_16x16x32_bf16 v[12:15], v[136:139], v[230:233], 0
	ds_read_b128 v[136:139], v149 offset:47104
	s_waitcnt lgkmcnt(7)
	v_mfma_f32_16x16x32_bf16 v[12:15], v[140:143], v[234:237], v[12:15]
	ds_read_b128 v[140:143], v224 offset:47104
	s_waitcnt lgkmcnt(7)
	v_mfma_f32_16x16x32_bf16 v[16:19], v[112:115], v[230:233], 0
	s_waitcnt lgkmcnt(6)
	v_mfma_f32_16x16x32_bf16 v[16:19], v[116:119], v[234:237], v[16:19]
	s_waitcnt lgkmcnt(5)
	v_mfma_f32_16x16x32_bf16 v[20:23], v[120:123], v[230:233], 0
	s_waitcnt lgkmcnt(4)
	v_mfma_f32_16x16x32_bf16 v[20:23], v[124:127], v[234:237], v[20:23]
	s_waitcnt lgkmcnt(3)
	v_mfma_f32_16x16x32_bf16 v[24:27], v[128:131], v[230:233], 0
	s_waitcnt lgkmcnt(2)
	v_mfma_f32_16x16x32_bf16 v[24:27], v[132:135], v[234:237], v[24:27]
	s_waitcnt lgkmcnt(1)
	v_mfma_f32_16x16x32_bf16 v[28:31], v[136:139], v[230:233], 0
	s_waitcnt lgkmcnt(0)
	v_mfma_f32_16x16x32_bf16 v[28:31], v[140:143], v[234:237], v[28:31]
	s_nop 7
	v_max3_f32 v203, v0, v1, v2
	v_max3_f32 v203, v203, v3, v4
	v_max3_f32 v203, v203, v5, v6
	v_max3_f32 v203, v203, v7, v8
	v_max3_f32 v203, v203, v9, v10
	v_max3_f32 v203, v203, v11, v12
	v_max3_f32 v203, v203, v13, v14
	v_max3_f32 v203, v203, v15, v16
	v_max3_f32 v203, v203, v17, v18
	v_max3_f32 v203, v203, v19, v20
	v_max3_f32 v203, v203, v21, v22
	v_max3_f32 v203, v203, v23, v24
	v_max3_f32 v203, v203, v25, v26
	v_max3_f32 v203, v203, v27, v28
	v_max3_f32 v203, v203, v29, v30
	v_max_f32_e32 v203, v203, v31
	v_mov_b32_e32 v205, v203
	s_nop 1
	v_permlane16_swap_b32_e32 v203, v205
	v_max_f32_e32 v203, v203, v205
	v_mov_b32_e32 v205, v203
	s_nop 1
	v_permlane32_swap_b32_e32 v203, v205
	v_max_f32_e32 v203, v203, v205
	v_max_f32_e32 v218, v246, v203
	v_sub_f32_e32 v220, v246, v218
	v_mov_b32_e32 v219, v218
	v_exp_f32_e32 v220, v220
	v_mov_b32_e32 v246, v218
	v_pk_add_f32 v[0:1], v[0:1], v[218:219] neg_lo:[0,1] neg_hi:[0,1]
	v_pk_add_f32 v[2:3], v[2:3], v[218:219] neg_lo:[0,1] neg_hi:[0,1]
	v_pk_add_f32 v[4:5], v[4:5], v[218:219] neg_lo:[0,1] neg_hi:[0,1]
	v_pk_add_f32 v[6:7], v[6:7], v[218:219] neg_lo:[0,1] neg_hi:[0,1]
	v_pk_add_f32 v[8:9], v[8:9], v[218:219] neg_lo:[0,1] neg_hi:[0,1]
	v_pk_add_f32 v[10:11], v[10:11], v[218:219] neg_lo:[0,1] neg_hi:[0,1]
	v_pk_add_f32 v[12:13], v[12:13], v[218:219] neg_lo:[0,1] neg_hi:[0,1]
	v_pk_add_f32 v[14:15], v[14:15], v[218:219] neg_lo:[0,1] neg_hi:[0,1]
	v_pk_add_f32 v[16:17], v[16:17], v[218:219] neg_lo:[0,1] neg_hi:[0,1]
	v_pk_add_f32 v[18:19], v[18:19], v[218:219] neg_lo:[0,1] neg_hi:[0,1]
	v_pk_add_f32 v[20:21], v[20:21], v[218:219] neg_lo:[0,1] neg_hi:[0,1]
	v_pk_add_f32 v[22:23], v[22:23], v[218:219] neg_lo:[0,1] neg_hi:[0,1]
	v_pk_add_f32 v[24:25], v[24:25], v[218:219] neg_lo:[0,1] neg_hi:[0,1]
	v_pk_add_f32 v[26:27], v[26:27], v[218:219] neg_lo:[0,1] neg_hi:[0,1]
	v_pk_add_f32 v[28:29], v[28:29], v[218:219] neg_lo:[0,1] neg_hi:[0,1]
	v_pk_add_f32 v[30:31], v[30:31], v[218:219] neg_lo:[0,1] neg_hi:[0,1]
	v_exp_f32_e32 v0, v0
	v_exp_f32_e32 v1, v1
	v_exp_f32_e32 v2, v2
	v_exp_f32_e32 v3, v3
	v_exp_f32_e32 v4, v4
	v_exp_f32_e32 v5, v5
	v_exp_f32_e32 v6, v6
	v_exp_f32_e32 v7, v7
	v_exp_f32_e32 v8, v8
	v_exp_f32_e32 v9, v9
	v_exp_f32_e32 v10, v10
	v_exp_f32_e32 v11, v11
	v_exp_f32_e32 v12, v12
	v_exp_f32_e32 v13, v13
	v_exp_f32_e32 v14, v14
	v_exp_f32_e32 v15, v15
	v_exp_f32_e32 v16, v16
	v_exp_f32_e32 v17, v17
	v_exp_f32_e32 v18, v18
	v_exp_f32_e32 v19, v19
	v_exp_f32_e32 v20, v20
	v_exp_f32_e32 v21, v21
	v_exp_f32_e32 v22, v22
	v_exp_f32_e32 v23, v23
	v_exp_f32_e32 v24, v24
	v_exp_f32_e32 v25, v25
	v_exp_f32_e32 v26, v26
	v_exp_f32_e32 v27, v27
	v_exp_f32_e32 v28, v28
	v_exp_f32_e32 v29, v29
	v_exp_f32_e32 v30, v30
	v_exp_f32_e32 v31, v31
	ds_read_b128 v[112:115], v225 offset:32768
	ds_read_b128 v[116:119], v225 offset:36864
	ds_read_b128 v[120:123], v225 offset:40960
	ds_read_b128 v[124:127], v225 offset:45056
	ds_read_b128 v[128:131], v226 offset:32768
	ds_read_b128 v[132:135], v226 offset:36864
	ds_read_b128 v[136:139], v226 offset:40960
	ds_read_b128 v[140:143], v226 offset:45056
	v_mov_b32_e32 v221, v220
	v_pk_add_f32 v[222:223], v[0:1], v[2:3]
	v_pk_add_f32 v[222:223], v[222:223], v[4:5]
	v_pk_add_f32 v[222:223], v[222:223], v[6:7]
	v_pk_add_f32 v[222:223], v[222:223], v[8:9]
	v_pk_add_f32 v[222:223], v[222:223], v[10:11]
	v_pk_add_f32 v[222:223], v[222:223], v[12:13]
	v_pk_add_f32 v[222:223], v[222:223], v[14:15]
	v_pk_add_f32 v[222:223], v[222:223], v[16:17]
	v_pk_add_f32 v[222:223], v[222:223], v[18:19]
	v_pk_add_f32 v[222:223], v[222:223], v[20:21]
	v_pk_add_f32 v[222:223], v[222:223], v[22:23]
	v_pk_add_f32 v[222:223], v[222:223], v[24:25]
	v_pk_add_f32 v[222:223], v[222:223], v[26:27]
	v_pk_add_f32 v[222:223], v[222:223], v[28:29]
	v_pk_add_f32 v[222:223], v[222:223], v[30:31]
	v_pk_mul_f32 v[176:177], v[176:177], v[220:221]
	v_pk_mul_f32 v[178:179], v[178:179], v[220:221]
	v_pk_mul_f32 v[180:181], v[180:181], v[220:221]
	v_pk_mul_f32 v[182:183], v[182:183], v[220:221]
	v_pk_mul_f32 v[192:193], v[192:193], v[220:221]
	v_pk_mul_f32 v[194:195], v[194:195], v[220:221]
	v_pk_mul_f32 v[196:197], v[196:197], v[220:221]
	v_pk_mul_f32 v[198:199], v[198:199], v[220:221]
	v_add_f32_e32 v203, v222, v223
	v_fma_f32 v247, v247, v220, v203
	v_cvt_pk_bf16_f32 v48, v0, v1
	v_cvt_pk_bf16_f32 v49, v2, v3
	v_cvt_pk_bf16_f32 v50, v4, v5
	v_cvt_pk_bf16_f32 v51, v6, v7
	v_cvt_pk_bf16_f32 v52, v8, v9
	v_cvt_pk_bf16_f32 v53, v10, v11
	v_cvt_pk_bf16_f32 v54, v12, v13
	v_cvt_pk_bf16_f32 v55, v14, v15
	v_cvt_pk_bf16_f32 v56, v16, v17
	v_cvt_pk_bf16_f32 v57, v18, v19
	v_cvt_pk_bf16_f32 v58, v20, v21
	v_cvt_pk_bf16_f32 v59, v22, v23
	v_cvt_pk_bf16_f32 v60, v24, v25
	v_cvt_pk_bf16_f32 v61, v26, v27
	v_cvt_pk_bf16_f32 v62, v28, v29
	v_cvt_pk_bf16_f32 v63, v30, v31
	s_waitcnt lgkmcnt(7)
; __device__ __forceinline__ void attn_phase(const Params& P, char* smem_raw) {
;     ...
;     for (int ck = 0; ck < 6; ++ck) {
;       int lane_c = lane;
;       asm volatile("" : "+v"(lane_c));
;       __syncthreads();
; #pragma unroll
;       for (int i = 0; i < 4; ++i) {
;         const int idx = tid + 256 * i;
;         *reinterpret_cast<uint4*>(&sm_k[(idx >> 3) * LDSS + (idx & 7) * 8]) = kreg[i];
;         *reinterpret_cast<uint4*>(&sm_vt[(idx >> 4) * 136 + (idx & 15) * 8]) = vreg[i];
;       }
;       __syncthreads();
;       f32x4 sacc[8];
; #pragma unroll
;       for (int t8 = 0; t8 < 8; ++t8) sacc[t8] = f32x4{0.f, 0.f, 0.f, 0.f};
; #pragma unroll
;       for (int s = 0; s < 2; ++s)
; #pragma unroll
;         for (int t8 = 0; t8 < 8; ++t8) {
;           const bf16x8 kf = *reinterpret_cast<const bf16x8*>(&sm_k[(t8 * 16 + (lane_c & 15)) * LDSS + s * 32 + (lane_c >> 4) * 8]);
;           sacc[t8] = __builtin_amdgcn_mfma_f32_16x16x32_bf16(qf[s], kf, sacc[t8], 0, 0, 0);
;         }
;       if (ck < 5) {
;         ATT_ISSUE(t, ck + 1)
;       } else if (t + VGRID < 8192) {
;         ATT_ISSUE(t + VGRID, 0)
;         ATT_QLOAD(t + VGRID)
;       }
;       if (ck < 4) {
;         const float* rb0 = sm_rpb + (rs + ck * 2 - r + 7) * 31;
; #pragma unroll
;         for (int t8 = 0; t8 < 8; ++t8)
; #pragma unroll
;           for (int reg = 0; reg < 4; ++reg)
;             sacc[t8][reg] += rb0[(t8 >> 2) * 31 + dco[reg][t8 & 3]];
;       }
; #pragma unroll
;       for (int reg = 0; reg < 4; ++reg) {
;         float mx = sacc[0][reg];
; #pragma unroll
;         for (int t8 = 1; t8 < 8; ++t8) mx = fmaxf(mx, sacc[t8][reg]);
;         mx = row16_max(mx);
;         const float mnew = fmaxf(mrow[reg], mx);
;         const float alpha = __builtin_amdgcn_exp2f(mrow[reg] - mnew);
;         mrow[reg] = mnew;
;         float rsum = 0.f;
; #pragma unroll
;         for (int t8 = 0; t8 < 8; ++t8) {
;           const float p = __builtin_amdgcn_exp2f(sacc[t8][reg] - mnew);
;           rsum += p;
;           sm_p[(wid * 16 + (lane_c >> 4) * 4 + reg) * 136 + t8 * 16 + (lane_c & 15)] = f2bf(p);
;         }
;         rsum = row16_sum(rsum);
;         lrow[reg] = lrow[reg] * alpha + rsum;
; #pragma unroll
;         for (int td = 0; td < 4; ++td) o[td][reg] *= alpha;
;       }
;       asm volatile("s_waitcnt lgkmcnt(0)" ::: "memory");
; #pragma unroll
;       for (int s4 = 0; s4 < 4; ++s4) {
	v_mfma_f32_16x16x32_bf16 v[176:179], v[112:115], v[48:51], v[176:179]
	ds_read_b128 v[112:115], v227 offset:32768
	s_waitcnt lgkmcnt(7)
	v_mfma_f32_16x16x32_bf16 v[180:183], v[116:119], v[48:51], v[180:183]
	ds_read_b128 v[116:119], v227 offset:36864
	s_waitcnt lgkmcnt(7)
	v_mfma_f32_16x16x32_bf16 v[192:195], v[120:123], v[48:51], v[192:195]
	ds_read_b128 v[120:123], v227 offset:40960
	s_waitcnt lgkmcnt(7)
	v_mfma_f32_16x16x32_bf16 v[196:199], v[124:127], v[48:51], v[196:199]
	ds_read_b128 v[124:127], v227 offset:45056
	s_waitcnt lgkmcnt(7)
	v_mfma_f32_16x16x32_bf16 v[176:179], v[128:131], v[52:55], v[176:179]
	ds_read_b128 v[128:131], v228 offset:32768
	s_waitcnt lgkmcnt(7)
	v_mfma_f32_16x16x32_bf16 v[180:183], v[132:135], v[52:55], v[180:183]
	ds_read_b128 v[132:135], v228 offset:36864
	s_waitcnt lgkmcnt(7)
	v_mfma_f32_16x16x32_bf16 v[192:195], v[136:139], v[52:55], v[192:195]
	ds_read_b128 v[136:139], v228 offset:40960
	s_waitcnt lgkmcnt(7)
	v_mfma_f32_16x16x32_bf16 v[196:199], v[140:143], v[52:55], v[196:199]
	ds_read_b128 v[140:143], v228 offset:45056
	s_waitcnt lgkmcnt(7)
	v_mfma_f32_16x16x32_bf16 v[176:179], v[112:115], v[56:59], v[176:179]
	s_waitcnt lgkmcnt(6)
	v_mfma_f32_16x16x32_bf16 v[180:183], v[116:119], v[56:59], v[180:183]
	s_waitcnt lgkmcnt(5)
	v_mfma_f32_16x16x32_bf16 v[192:195], v[120:123], v[56:59], v[192:195]
	s_waitcnt lgkmcnt(4)
	v_mfma_f32_16x16x32_bf16 v[196:199], v[124:127], v[56:59], v[196:199]
	s_waitcnt lgkmcnt(3)
	v_mfma_f32_16x16x32_bf16 v[176:179], v[128:131], v[60:63], v[176:179]
	s_waitcnt lgkmcnt(2)
	v_mfma_f32_16x16x32_bf16 v[180:183], v[132:135], v[60:63], v[180:183]
	s_waitcnt lgkmcnt(1)
	v_mfma_f32_16x16x32_bf16 v[192:195], v[136:139], v[60:63], v[192:195]
	s_waitcnt lgkmcnt(0)
	v_mfma_f32_16x16x32_bf16 v[196:199], v[140:143], v[60:63], v[196:199]
	s_waitcnt lgkmcnt(0)
	s_barrier
	ds_read_b128 v[112:115], v149 offset:0
	ds_read_b128 v[116:119], v224 offset:0
	ds_read_b128 v[120:123], v149 offset:8192
	ds_read_b128 v[124:127], v224 offset:8192
	ds_read_b128 v[128:131], v149 offset:2048
	ds_read_b128 v[132:135], v224 offset:2048
	ds_read_b128 v[136:139], v149 offset:10240
	ds_read_b128 v[140:143], v224 offset:10240
	s_waitcnt lgkmcnt(7)
	v_mfma_f32_16x16x32_bf16 v[0:3], v[112:115], v[64:67], 0
	ds_read_b128 v[112:115], v149 offset:4096
	s_waitcnt lgkmcnt(7)
	v_mfma_f32_16x16x32_bf16 v[0:3], v[116:119], v[68:71], v[0:3]
	ds_read_b128 v[116:119], v224 offset:4096
	s_waitcnt lgkmcnt(7)
	v_mfma_f32_16x16x32_bf16 v[4:7], v[120:123], v[64:67], 0
	ds_read_b128 v[120:123], v149 offset:12288
	s_waitcnt lgkmcnt(7)
	v_mfma_f32_16x16x32_bf16 v[4:7], v[124:127], v[68:71], v[4:7]
	ds_read_b128 v[124:127], v224 offset:12288
	s_waitcnt lgkmcnt(7)
	v_mfma_f32_16x16x32_bf16 v[8:11], v[128:131], v[64:67], 0
	ds_read_b128 v[128:131], v149 offset:6144
	s_waitcnt lgkmcnt(7)
	v_mfma_f32_16x16x32_bf16 v[8:11], v[132:135], v[68:71], v[8:11]
	ds_read_b128 v[132:135], v224 offset:6144
	s_waitcnt lgkmcnt(7)
	v_mfma_f32_16x16x32_bf16 v[12:15], v[136:139], v[64:67], 0
	ds_read_b128 v[136:139], v149 offset:14336
	s_waitcnt lgkmcnt(7)
	v_mfma_f32_16x16x32_bf16 v[12:15], v[140:143], v[68:71], v[12:15]
	ds_read_b128 v[140:143], v224 offset:14336
	s_waitcnt lgkmcnt(7)
	v_mfma_f32_16x16x32_bf16 v[16:19], v[112:115], v[64:67], 0
	s_waitcnt lgkmcnt(6)
	v_mfma_f32_16x16x32_bf16 v[16:19], v[116:119], v[68:71], v[16:19]
	s_waitcnt lgkmcnt(5)
	v_mfma_f32_16x16x32_bf16 v[20:23], v[120:123], v[64:67], 0
	s_waitcnt lgkmcnt(4)
	v_mfma_f32_16x16x32_bf16 v[20:23], v[124:127], v[68:71], v[20:23]
	s_waitcnt lgkmcnt(3)
	v_mfma_f32_16x16x32_bf16 v[24:27], v[128:131], v[64:67], 0
	s_waitcnt lgkmcnt(2)
	v_mfma_f32_16x16x32_bf16 v[24:27], v[132:135], v[68:71], v[24:27]
	s_waitcnt lgkmcnt(1)
	v_mfma_f32_16x16x32_bf16 v[28:31], v[136:139], v[64:67], 0
	s_waitcnt lgkmcnt(0)
	v_mfma_f32_16x16x32_bf16 v[28:31], v[140:143], v[68:71], v[28:31]
	s_nop 7
	v_max3_f32 v203, v0, v1, v2
	v_max3_f32 v203, v203, v3, v4
	v_max3_f32 v203, v203, v5, v6
	v_max3_f32 v203, v203, v7, v8
	v_max3_f32 v203, v203, v9, v10
	v_max3_f32 v203, v203, v11, v12
	v_max3_f32 v203, v203, v13, v14
	v_max3_f32 v203, v203, v15, v16
	v_max3_f32 v203, v203, v17, v18
	v_max3_f32 v203, v203, v19, v20
	v_max3_f32 v203, v203, v21, v22
	v_max3_f32 v203, v203, v23, v24
	v_max3_f32 v203, v203, v25, v26
	v_max3_f32 v203, v203, v27, v28
	v_max3_f32 v203, v203, v29, v30
	v_max_f32_e32 v203, v203, v31
	v_mov_b32_e32 v205, v203
	s_nop 1
	v_permlane16_swap_b32_e32 v203, v205
	v_max_f32_e32 v203, v203, v205
	v_mov_b32_e32 v205, v203
	s_nop 1
	v_permlane32_swap_b32_e32 v203, v205
	v_max_f32_e32 v203, v203, v205
	v_max_f32_e32 v218, v200, v203
	v_sub_f32_e32 v220, v200, v218
	v_mov_b32_e32 v219, v218
	v_exp_f32_e32 v220, v220
	v_mov_b32_e32 v200, v218
	v_pk_add_f32 v[0:1], v[0:1], v[218:219] neg_lo:[0,1] neg_hi:[0,1]
	v_pk_add_f32 v[2:3], v[2:3], v[218:219] neg_lo:[0,1] neg_hi:[0,1]
	v_pk_add_f32 v[4:5], v[4:5], v[218:219] neg_lo:[0,1] neg_hi:[0,1]
	v_pk_add_f32 v[6:7], v[6:7], v[218:219] neg_lo:[0,1] neg_hi:[0,1]
	v_pk_add_f32 v[8:9], v[8:9], v[218:219] neg_lo:[0,1] neg_hi:[0,1]
	v_pk_add_f32 v[10:11], v[10:11], v[218:219] neg_lo:[0,1] neg_hi:[0,1]
	v_pk_add_f32 v[12:13], v[12:13], v[218:219] neg_lo:[0,1] neg_hi:[0,1]
	v_pk_add_f32 v[14:15], v[14:15], v[218:219] neg_lo:[0,1] neg_hi:[0,1]
	v_pk_add_f32 v[16:17], v[16:17], v[218:219] neg_lo:[0,1] neg_hi:[0,1]
	v_pk_add_f32 v[18:19], v[18:19], v[218:219] neg_lo:[0,1] neg_hi:[0,1]
	v_pk_add_f32 v[20:21], v[20:21], v[218:219] neg_lo:[0,1] neg_hi:[0,1]
	v_pk_add_f32 v[22:23], v[22:23], v[218:219] neg_lo:[0,1] neg_hi:[0,1]
	v_pk_add_f32 v[24:25], v[24:25], v[218:219] neg_lo:[0,1] neg_hi:[0,1]
	v_pk_add_f32 v[26:27], v[26:27], v[218:219] neg_lo:[0,1] neg_hi:[0,1]
	v_pk_add_f32 v[28:29], v[28:29], v[218:219] neg_lo:[0,1] neg_hi:[0,1]
	v_pk_add_f32 v[30:31], v[30:31], v[218:219] neg_lo:[0,1] neg_hi:[0,1]
	v_exp_f32_e32 v0, v0
	s_waitcnt vmcnt(0)
; __device__ __forceinline__ void attn_phase(const Params& P, char* smem_raw) {
;     ...
;     for (int ck = 0; ck < 6; ++ck) {
;       int lane_c = lane;
;       asm volatile("" : "+v"(lane_c));
;       __syncthreads();
; #pragma unroll
;       for (int i = 0; i < 4; ++i) {
;         const int idx = tid + 256 * i;
;         *reinterpret_cast<uint4*>(&sm_k[(idx >> 3) * LDSS + (idx & 7) * 8]) = kreg[i];
;         *reinterpret_cast<uint4*>(&sm_vt[(idx >> 4) * 136 + (idx & 15) * 8]) = vreg[i];
;       }
;       __syncthreads();
;       f32x4 sacc[8];
; #pragma unroll
;       for (int t8 = 0; t8 < 8; ++t8) sacc[t8] = f32x4{0.f, 0.f, 0.f, 0.f};
; #pragma unroll
;       for (int s = 0; s < 2; ++s)
; #pragma unroll
;         for (int t8 = 0; t8 < 8; ++t8) {
;           const bf16x8 kf = *reinterpret_cast<const bf16x8*>(&sm_k[(t8 * 16 + (lane_c & 15)) * LDSS + s * 32 + (lane_c >> 4) * 8]);
;           sacc[t8] = __builtin_amdgcn_mfma_f32_16x16x32_bf16(qf[s], kf, sacc[t8], 0, 0, 0);
;         }
;       if (ck < 5) {
;         ATT_ISSUE(t, ck + 1)
;       } else if (t + VGRID < 8192) {
;         ATT_ISSUE(t + VGRID, 0)
;         ATT_QLOAD(t + VGRID)
;       }
;       if (ck < 4) {
;         const float* rb0 = sm_rpb + (rs + ck * 2 - r + 7) * 31;
; #pragma unroll
;         for (int t8 = 0; t8 < 8; ++t8)
; #pragma unroll
;           for (int reg = 0; reg < 4; ++reg)
;             sacc[t8][reg] += rb0[(t8 >> 2) * 31 + dco[reg][t8 & 3]];
;       }
; #pragma unroll
;       for (int reg = 0; reg < 4; ++reg) {
;         float mx = sacc[0][reg];
; #pragma unroll
;         for (int t8 = 1; t8 < 8; ++t8) mx = fmaxf(mx, sacc[t8][reg]);
;         mx = row16_max(mx);
;         const float mnew = fmaxf(mrow[reg], mx);
;         const float alpha = __builtin_amdgcn_exp2f(mrow[reg] - mnew);
;         mrow[reg] = mnew;
;         float rsum = 0.f;
; #pragma unroll
;         for (int t8 = 0; t8 < 8; ++t8) {
;           const float p = __builtin_amdgcn_exp2f(sacc[t8][reg] - mnew);
;           rsum += p;
;           sm_p[(wid * 16 + (lane_c >> 4) * 4 + reg) * 136 + t8 * 16 + (lane_c & 15)] = f2bf(p);
;         }
;         rsum = row16_sum(rsum);
;         lrow[reg] = lrow[reg] * alpha + rsum;
; #pragma unroll
;         for (int td = 0; td < 4; ++td) o[td][reg] *= alpha;
;       }
;       asm volatile("s_waitcnt lgkmcnt(0)" ::: "memory");
; #pragma unroll
;       for (int s4 = 0; s4 < 4; ++s4) {
	v_exp_f32_e32 v1, v1
	ds_write_b128 v150, v[80:83] offset:32768
	v_exp_f32_e32 v2, v2
	ds_write_b128 v150, v[84:87] offset:36864
	v_exp_f32_e32 v3, v3
	ds_write_b128 v150, v[88:91] offset:40960
	v_exp_f32_e32 v4, v4
	ds_write_b128 v150, v[92:95] offset:45056
	v_exp_f32_e32 v5, v5
	ds_write_b64 v151, v[96:97] offset:32768
	v_exp_f32_e32 v6, v6
	ds_write_b64 v229, v[98:99] offset:32768
	v_exp_f32_e32 v7, v7
	ds_write_b64 v151, v[100:101] offset:36864
	v_exp_f32_e32 v8, v8
	ds_write_b64 v229, v[102:103] offset:36864
	v_exp_f32_e32 v9, v9
	ds_write_b64 v151, v[104:105] offset:40960
	v_exp_f32_e32 v10, v10
	ds_write_b64 v229, v[106:107] offset:40960
	v_exp_f32_e32 v11, v11
	ds_write_b64 v151, v[108:109] offset:45056
	v_exp_f32_e32 v12, v12
	ds_write_b64 v229, v[110:111] offset:45056
	v_exp_f32_e32 v13, v13
	s_add_u32 s100, s12, 0xc0000
	v_exp_f32_e32 v14, v14
	s_addc_u32 s101, s13, 0
	v_exp_f32_e32 v15, v15
	s_add_u32 s0, s14, 0x100
	v_exp_f32_e32 v16, v16
	s_addc_u32 s1, s15, 0
	v_exp_f32_e32 v17, v17
	global_load_dwordx4 v[80:83], v154, s[100:101] offset:2048
	v_exp_f32_e32 v18, v18
	global_load_dwordx4 v[96:99], v158, s[0:1]
	v_exp_f32_e32 v19, v19
	global_load_dwordx4 v[84:87], v155, s[100:101] offset:2048
	v_exp_f32_e32 v20, v20
	global_load_dwordx4 v[100:103], v159, s[0:1]
	v_exp_f32_e32 v21, v21
	global_load_dwordx4 v[88:91], v156, s[100:101] offset:2048
	v_exp_f32_e32 v22, v22
	global_load_dwordx4 v[104:107], v160, s[0:1]
	v_exp_f32_e32 v23, v23
	global_load_dwordx4 v[92:95], v157, s[100:101] offset:2048
	v_exp_f32_e32 v24, v24
	global_load_dwordx4 v[108:111], v161, s[0:1]
	v_exp_f32_e32 v25, v25
	v_exp_f32_e32 v26, v26
	v_exp_f32_e32 v27, v27
	v_exp_f32_e32 v28, v28
	v_exp_f32_e32 v29, v29
	v_exp_f32_e32 v30, v30
	v_exp_f32_e32 v31, v31
	ds_read_b128 v[112:115], v225 offset:0
	ds_read_b128 v[116:119], v225 offset:4096
	ds_read_b128 v[120:123], v225 offset:8192
	ds_read_b128 v[124:127], v225 offset:12288
	ds_read_b128 v[128:131], v226 offset:0
	ds_read_b128 v[132:135], v226 offset:4096
	ds_read_b128 v[136:139], v226 offset:8192
	ds_read_b128 v[140:143], v226 offset:12288
	v_mov_b32_e32 v221, v220
	v_pk_add_f32 v[222:223], v[0:1], v[2:3]
	v_pk_add_f32 v[222:223], v[222:223], v[4:5]
	v_pk_add_f32 v[222:223], v[222:223], v[6:7]
	v_pk_add_f32 v[222:223], v[222:223], v[8:9]
	v_pk_add_f32 v[222:223], v[222:223], v[10:11]
	v_pk_add_f32 v[222:223], v[222:223], v[12:13]
	v_pk_add_f32 v[222:223], v[222:223], v[14:15]
	v_pk_add_f32 v[222:223], v[222:223], v[16:17]
	v_pk_add_f32 v[222:223], v[222:223], v[18:19]
	v_pk_add_f32 v[222:223], v[222:223], v[20:21]
	v_pk_add_f32 v[222:223], v[222:223], v[22:23]
	v_pk_add_f32 v[222:223], v[222:223], v[24:25]
	v_pk_add_f32 v[222:223], v[222:223], v[26:27]
	v_pk_add_f32 v[222:223], v[222:223], v[28:29]
	v_pk_add_f32 v[222:223], v[222:223], v[30:31]
	v_pk_mul_f32 v[32:33], v[32:33], v[220:221]
	v_pk_mul_f32 v[34:35], v[34:35], v[220:221]
	v_pk_mul_f32 v[36:37], v[36:37], v[220:221]
	v_pk_mul_f32 v[38:39], v[38:39], v[220:221]
	v_pk_mul_f32 v[40:41], v[40:41], v[220:221]
	v_pk_mul_f32 v[42:43], v[42:43], v[220:221]
	v_pk_mul_f32 v[44:45], v[44:45], v[220:221]
	v_pk_mul_f32 v[46:47], v[46:47], v[220:221]
	v_add_f32_e32 v203, v222, v223
	v_fma_f32 v201, v201, v220, v203
	v_cvt_pk_bf16_f32 v48, v0, v1
	v_cvt_pk_bf16_f32 v49, v2, v3
	v_cvt_pk_bf16_f32 v50, v4, v5
	v_cvt_pk_bf16_f32 v51, v6, v7
	v_cvt_pk_bf16_f32 v52, v8, v9
	v_cvt_pk_bf16_f32 v53, v10, v11
	v_cvt_pk_bf16_f32 v54, v12, v13
	v_cvt_pk_bf16_f32 v55, v14, v15
	v_cvt_pk_bf16_f32 v56, v16, v17
	v_cvt_pk_bf16_f32 v57, v18, v19
	v_cvt_pk_bf16_f32 v58, v20, v21
	v_cvt_pk_bf16_f32 v59, v22, v23
	v_cvt_pk_bf16_f32 v60, v24, v25
	v_cvt_pk_bf16_f32 v61, v26, v27
	v_cvt_pk_bf16_f32 v62, v28, v29
	v_cvt_pk_bf16_f32 v63, v30, v31
	s_waitcnt lgkmcnt(7)
	v_mfma_f32_16x16x32_bf16 v[32:35], v[112:115], v[48:51], v[32:35]
	ds_read_b128 v[112:115], v227 offset:0
	s_waitcnt lgkmcnt(7)
	v_mfma_f32_16x16x32_bf16 v[36:39], v[116:119], v[48:51], v[36:39]
	ds_read_b128 v[116:119], v227 offset:4096
	s_waitcnt lgkmcnt(7)
	v_mfma_f32_16x16x32_bf16 v[40:43], v[120:123], v[48:51], v[40:43]
	ds_read_b128 v[120:123], v227 offset:8192
	s_waitcnt lgkmcnt(7)
	v_mfma_f32_16x16x32_bf16 v[44:47], v[124:127], v[48:51], v[44:47]
	ds_read_b128 v[124:127], v227 offset:12288
	s_waitcnt lgkmcnt(7)
	v_mfma_f32_16x16x32_bf16 v[32:35], v[128:131], v[52:55], v[32:35]
	ds_read_b128 v[128:131], v228 offset:0
	s_waitcnt lgkmcnt(7)
	v_mfma_f32_16x16x32_bf16 v[36:39], v[132:135], v[52:55], v[36:39]
	ds_read_b128 v[132:135], v228 offset:4096
	s_waitcnt lgkmcnt(7)
	v_mfma_f32_16x16x32_bf16 v[40:43], v[136:139], v[52:55], v[40:43]
	ds_read_b128 v[136:139], v228 offset:8192
	s_waitcnt lgkmcnt(7)
	v_mfma_f32_16x16x32_bf16 v[44:47], v[140:143], v[52:55], v[44:47]
	ds_read_b128 v[140:143], v228 offset:12288
	s_waitcnt lgkmcnt(7)
	v_mfma_f32_16x16x32_bf16 v[32:35], v[112:115], v[56:59], v[32:35]
	s_waitcnt lgkmcnt(6)
	v_mfma_f32_16x16x32_bf16 v[36:39], v[116:119], v[56:59], v[36:39]
	s_waitcnt lgkmcnt(5)
	v_mfma_f32_16x16x32_bf16 v[40:43], v[120:123], v[56:59], v[40:43]
	s_waitcnt lgkmcnt(4)
	v_mfma_f32_16x16x32_bf16 v[44:47], v[124:127], v[56:59], v[44:47]
	s_waitcnt lgkmcnt(3)
	v_mfma_f32_16x16x32_bf16 v[32:35], v[128:131], v[60:63], v[32:35]
	s_waitcnt lgkmcnt(2)
	v_mfma_f32_16x16x32_bf16 v[36:39], v[132:135], v[60:63], v[36:39]
	s_waitcnt lgkmcnt(1)
	v_mfma_f32_16x16x32_bf16 v[40:43], v[136:139], v[60:63], v[40:43]
	s_waitcnt lgkmcnt(0)
; __device__ __forceinline__ void attn_phase(const Params& P, char* smem_raw) {
;     ...
;     for (int ck = 0; ck < 6; ++ck) {
;       int lane_c = lane;
;       asm volatile("" : "+v"(lane_c));
;       __syncthreads();
; #pragma unroll
;       for (int i = 0; i < 4; ++i) {
;         const int idx = tid + 256 * i;
;         *reinterpret_cast<uint4*>(&sm_k[(idx >> 3) * LDSS + (idx & 7) * 8]) = kreg[i];
;         *reinterpret_cast<uint4*>(&sm_vt[(idx >> 4) * 136 + (idx & 15) * 8]) = vreg[i];
;       }
;       __syncthreads();
;       f32x4 sacc[8];
; #pragma unroll
;       for (int t8 = 0; t8 < 8; ++t8) sacc[t8] = f32x4{0.f, 0.f, 0.f, 0.f};
; #pragma unroll
;       for (int s = 0; s < 2; ++s)
; #pragma unroll
;         for (int t8 = 0; t8 < 8; ++t8) {
;           const bf16x8 kf = *reinterpret_cast<const bf16x8*>(&sm_k[(t8 * 16 + (lane_c & 15)) * LDSS + s * 32 + (lane_c >> 4) * 8]);
;           sacc[t8] = __builtin_amdgcn_mfma_f32_16x16x32_bf16(qf[s], kf, sacc[t8], 0, 0, 0);
;         }
;       if (ck < 5) {
;         ATT_ISSUE(t, ck + 1)
;       } else if (t + VGRID < 8192) {
;         ATT_ISSUE(t + VGRID, 0)
;         ATT_QLOAD(t + VGRID)
;       }
;       if (ck < 4) {
;         const float* rb0 = sm_rpb + (rs + ck * 2 - r + 7) * 31;
; #pragma unroll
;         for (int t8 = 0; t8 < 8; ++t8)
; #pragma unroll
;           for (int reg = 0; reg < 4; ++reg)
;             sacc[t8][reg] += rb0[(t8 >> 2) * 31 + dco[reg][t8 & 3]];
;       }
; #pragma unroll
;       for (int reg = 0; reg < 4; ++reg) {
;         float mx = sacc[0][reg];
; #pragma unroll
;         for (int t8 = 1; t8 < 8; ++t8) mx = fmaxf(mx, sacc[t8][reg]);
;         mx = row16_max(mx);
;         const float mnew = fmaxf(mrow[reg], mx);
;         const float alpha = __builtin_amdgcn_exp2f(mrow[reg] - mnew);
;         mrow[reg] = mnew;
;         float rsum = 0.f;
; #pragma unroll
;         for (int t8 = 0; t8 < 8; ++t8) {
;           const float p = __builtin_amdgcn_exp2f(sacc[t8][reg] - mnew);
;           rsum += p;
;           sm_p[(wid * 16 + (lane_c >> 4) * 4 + reg) * 136 + t8 * 16 + (lane_c & 15)] = f2bf(p);
;         }
;         rsum = row16_sum(rsum);
;         lrow[reg] = lrow[reg] * alpha + rsum;
; #pragma unroll
;         for (int td = 0; td < 4; ++td) o[td][reg] *= alpha;
;       }
;       asm volatile("s_waitcnt lgkmcnt(0)" ::: "memory");
; #pragma unroll
;       for (int s4 = 0; s4 < 4; ++s4) {
	v_mfma_f32_16x16x32_bf16 v[44:47], v[140:143], v[60:63], v[44:47]
	ds_read_b128 v[112:115], v149 offset:0
	ds_read_b128 v[116:119], v224 offset:0
	ds_read_b128 v[120:123], v149 offset:8192
	ds_read_b128 v[124:127], v224 offset:8192
	ds_read_b128 v[128:131], v149 offset:2048
	ds_read_b128 v[132:135], v224 offset:2048
	ds_read_b128 v[136:139], v149 offset:10240
	ds_read_b128 v[140:143], v224 offset:10240
	s_waitcnt lgkmcnt(7)
	v_mfma_f32_16x16x32_bf16 v[0:3], v[112:115], v[230:233], 0
	ds_read_b128 v[112:115], v149 offset:4096
	s_waitcnt lgkmcnt(7)
	v_mfma_f32_16x16x32_bf16 v[0:3], v[116:119], v[234:237], v[0:3]
	ds_read_b128 v[116:119], v224 offset:4096
	s_waitcnt lgkmcnt(7)
	v_mfma_f32_16x16x32_bf16 v[4:7], v[120:123], v[230:233], 0
	ds_read_b128 v[120:123], v149 offset:12288
	s_waitcnt lgkmcnt(7)
	v_mfma_f32_16x16x32_bf16 v[4:7], v[124:127], v[234:237], v[4:7]
	ds_read_b128 v[124:127], v224 offset:12288
	s_waitcnt lgkmcnt(7)
	v_mfma_f32_16x16x32_bf16 v[8:11], v[128:131], v[230:233], 0
	ds_read_b128 v[128:131], v149 offset:6144
	s_waitcnt lgkmcnt(7)
	v_mfma_f32_16x16x32_bf16 v[8:11], v[132:135], v[234:237], v[8:11]
	ds_read_b128 v[132:135], v224 offset:6144
	s_waitcnt lgkmcnt(7)
	v_mfma_f32_16x16x32_bf16 v[12:15], v[136:139], v[230:233], 0
	ds_read_b128 v[136:139], v149 offset:14336
	s_waitcnt lgkmcnt(7)
	v_mfma_f32_16x16x32_bf16 v[12:15], v[140:143], v[234:237], v[12:15]
	ds_read_b128 v[140:143], v224 offset:14336
	s_waitcnt lgkmcnt(7)
	v_mfma_f32_16x16x32_bf16 v[16:19], v[112:115], v[230:233], 0
	s_waitcnt lgkmcnt(6)
	v_mfma_f32_16x16x32_bf16 v[16:19], v[116:119], v[234:237], v[16:19]
	s_waitcnt lgkmcnt(5)
	v_mfma_f32_16x16x32_bf16 v[20:23], v[120:123], v[230:233], 0
	s_waitcnt lgkmcnt(4)
	v_mfma_f32_16x16x32_bf16 v[20:23], v[124:127], v[234:237], v[20:23]
	s_waitcnt lgkmcnt(3)
	v_mfma_f32_16x16x32_bf16 v[24:27], v[128:131], v[230:233], 0
	s_waitcnt lgkmcnt(2)
	v_mfma_f32_16x16x32_bf16 v[24:27], v[132:135], v[234:237], v[24:27]
	s_waitcnt lgkmcnt(1)
	v_mfma_f32_16x16x32_bf16 v[28:31], v[136:139], v[230:233], 0
	s_waitcnt lgkmcnt(0)
	v_mfma_f32_16x16x32_bf16 v[28:31], v[140:143], v[234:237], v[28:31]
	s_nop 7
	v_max3_f32 v203, v0, v1, v2
	v_max3_f32 v203, v203, v3, v4
	v_max3_f32 v203, v203, v5, v6
	v_max3_f32 v203, v203, v7, v8
	v_max3_f32 v203, v203, v9, v10
	v_max3_f32 v203, v203, v11, v12
	v_max3_f32 v203, v203, v13, v14
	v_max3_f32 v203, v203, v15, v16
	v_max3_f32 v203, v203, v17, v18
	v_max3_f32 v203, v203, v19, v20
	v_max3_f32 v203, v203, v21, v22
	v_max3_f32 v203, v203, v23, v24
	v_max3_f32 v203, v203, v25, v26
	v_max3_f32 v203, v203, v27, v28
	v_max3_f32 v203, v203, v29, v30
	v_max_f32_e32 v203, v203, v31
	v_mov_b32_e32 v205, v203
	s_nop 1
	v_permlane16_swap_b32_e32 v203, v205
	v_max_f32_e32 v203, v203, v205
	v_mov_b32_e32 v205, v203
	s_nop 1
	v_permlane32_swap_b32_e32 v203, v205
	v_max_f32_e32 v203, v203, v205
	v_max_f32_e32 v218, v246, v203
	v_sub_f32_e32 v220, v246, v218
	v_mov_b32_e32 v219, v218
	v_exp_f32_e32 v220, v220
	v_mov_b32_e32 v246, v218
	v_pk_add_f32 v[0:1], v[0:1], v[218:219] neg_lo:[0,1] neg_hi:[0,1]
	v_pk_add_f32 v[2:3], v[2:3], v[218:219] neg_lo:[0,1] neg_hi:[0,1]
	v_pk_add_f32 v[4:5], v[4:5], v[218:219] neg_lo:[0,1] neg_hi:[0,1]
	v_pk_add_f32 v[6:7], v[6:7], v[218:219] neg_lo:[0,1] neg_hi:[0,1]
	v_pk_add_f32 v[8:9], v[8:9], v[218:219] neg_lo:[0,1] neg_hi:[0,1]
	v_pk_add_f32 v[10:11], v[10:11], v[218:219] neg_lo:[0,1] neg_hi:[0,1]
	v_pk_add_f32 v[12:13], v[12:13], v[218:219] neg_lo:[0,1] neg_hi:[0,1]
	v_pk_add_f32 v[14:15], v[14:15], v[218:219] neg_lo:[0,1] neg_hi:[0,1]
	v_pk_add_f32 v[16:17], v[16:17], v[218:219] neg_lo:[0,1] neg_hi:[0,1]
	v_pk_add_f32 v[18:19], v[18:19], v[218:219] neg_lo:[0,1] neg_hi:[0,1]
	v_pk_add_f32 v[20:21], v[20:21], v[218:219] neg_lo:[0,1] neg_hi:[0,1]
	v_pk_add_f32 v[22:23], v[22:23], v[218:219] neg_lo:[0,1] neg_hi:[0,1]
	v_pk_add_f32 v[24:25], v[24:25], v[218:219] neg_lo:[0,1] neg_hi:[0,1]
	v_pk_add_f32 v[26:27], v[26:27], v[218:219] neg_lo:[0,1] neg_hi:[0,1]
	v_pk_add_f32 v[28:29], v[28:29], v[218:219] neg_lo:[0,1] neg_hi:[0,1]
	v_pk_add_f32 v[30:31], v[30:31], v[218:219] neg_lo:[0,1] neg_hi:[0,1]
	v_exp_f32_e32 v0, v0
	v_exp_f32_e32 v1, v1
	v_exp_f32_e32 v2, v2
	v_exp_f32_e32 v3, v3
	v_exp_f32_e32 v4, v4
	v_exp_f32_e32 v5, v5
	v_exp_f32_e32 v6, v6
	v_exp_f32_e32 v7, v7
	v_exp_f32_e32 v8, v8
	v_exp_f32_e32 v9, v9
	v_exp_f32_e32 v10, v10
	v_exp_f32_e32 v11, v11
	v_exp_f32_e32 v12, v12
	v_exp_f32_e32 v13, v13
	v_exp_f32_e32 v14, v14
	v_exp_f32_e32 v15, v15
	v_exp_f32_e32 v16, v16
	v_exp_f32_e32 v17, v17
	v_exp_f32_e32 v18, v18
	v_exp_f32_e32 v19, v19
	v_exp_f32_e32 v20, v20
	v_exp_f32_e32 v21, v21
	v_exp_f32_e32 v22, v22
	v_exp_f32_e32 v23, v23
	v_exp_f32_e32 v24, v24
	v_exp_f32_e32 v25, v25
	v_exp_f32_e32 v26, v26
	v_exp_f32_e32 v27, v27
	v_exp_f32_e32 v28, v28
	v_exp_f32_e32 v29, v29
	v_exp_f32_e32 v30, v30
	v_exp_f32_e32 v31, v31
	ds_read_b128 v[112:115], v225 offset:0
	ds_read_b128 v[116:119], v225 offset:4096
	ds_read_b128 v[120:123], v225 offset:8192
	ds_read_b128 v[124:127], v225 offset:12288
	ds_read_b128 v[128:131], v226 offset:0
	ds_read_b128 v[132:135], v226 offset:4096
	ds_read_b128 v[136:139], v226 offset:8192
	ds_read_b128 v[140:143], v226 offset:12288
	v_mov_b32_e32 v221, v220
	v_pk_add_f32 v[222:223], v[0:1], v[2:3]
	v_pk_add_f32 v[222:223], v[222:223], v[4:5]
	v_pk_add_f32 v[222:223], v[222:223], v[6:7]
	v_pk_add_f32 v[222:223], v[222:223], v[8:9]
	v_pk_add_f32 v[222:223], v[222:223], v[10:11]
	v_pk_add_f32 v[222:223], v[222:223], v[12:13]
	v_pk_add_f32 v[222:223], v[222:223], v[14:15]
	v_pk_add_f32 v[222:223], v[222:223], v[16:17]
	v_pk_add_f32 v[222:223], v[222:223], v[18:19]
	v_pk_add_f32 v[222:223], v[222:223], v[20:21]
	v_pk_add_f32 v[222:223], v[222:223], v[22:23]
	v_pk_add_f32 v[222:223], v[222:223], v[24:25]
	v_pk_add_f32 v[222:223], v[222:223], v[26:27]
	v_pk_add_f32 v[222:223], v[222:223], v[28:29]
	v_pk_add_f32 v[222:223], v[222:223], v[30:31]
	v_pk_mul_f32 v[176:177], v[176:177], v[220:221]
	v_pk_mul_f32 v[178:179], v[178:179], v[220:221]
	v_pk_mul_f32 v[180:181], v[180:181], v[220:221]
	v_pk_mul_f32 v[182:183], v[182:183], v[220:221]
	v_pk_mul_f32 v[192:193], v[192:193], v[220:221]
	v_pk_mul_f32 v[194:195], v[194:195], v[220:221]
	v_pk_mul_f32 v[196:197], v[196:197], v[220:221]
	v_pk_mul_f32 v[198:199], v[198:199], v[220:221]
	v_add_f32_e32 v203, v222, v223
	v_fma_f32 v247, v247, v220, v203
	v_cvt_pk_bf16_f32 v48, v0, v1
	v_cvt_pk_bf16_f32 v49, v2, v3
	v_cvt_pk_bf16_f32 v50, v4, v5
	v_cvt_pk_bf16_f32 v51, v6, v7
	v_cvt_pk_bf16_f32 v52, v8, v9
	v_cvt_pk_bf16_f32 v53, v10, v11
	v_cvt_pk_bf16_f32 v54, v12, v13
	v_cvt_pk_bf16_f32 v55, v14, v15
	v_cvt_pk_bf16_f32 v56, v16, v17
	v_cvt_pk_bf16_f32 v57, v18, v19
	v_cvt_pk_bf16_f32 v58, v20, v21
	v_cvt_pk_bf16_f32 v59, v22, v23
	v_cvt_pk_bf16_f32 v60, v24, v25
	v_cvt_pk_bf16_f32 v61, v26, v27
	v_cvt_pk_bf16_f32 v62, v28, v29
	v_cvt_pk_bf16_f32 v63, v30, v31
	s_waitcnt lgkmcnt(7)
; __device__ __forceinline__ void attn_phase(const Params& P, char* smem_raw) {
;     ...
;     for (int ck = 0; ck < 6; ++ck) {
;       int lane_c = lane;
;       asm volatile("" : "+v"(lane_c));
;       __syncthreads();
; #pragma unroll
;       for (int i = 0; i < 4; ++i) {
;         const int idx = tid + 256 * i;
;         *reinterpret_cast<uint4*>(&sm_k[(idx >> 3) * LDSS + (idx & 7) * 8]) = kreg[i];
;         *reinterpret_cast<uint4*>(&sm_vt[(idx >> 4) * 136 + (idx & 15) * 8]) = vreg[i];
;       }
;       __syncthreads();
;       f32x4 sacc[8];
; #pragma unroll
;       for (int t8 = 0; t8 < 8; ++t8) sacc[t8] = f32x4{0.f, 0.f, 0.f, 0.f};
; #pragma unroll
;       for (int s = 0; s < 2; ++s)
; #pragma unroll
;         for (int t8 = 0; t8 < 8; ++t8) {
;           const bf16x8 kf = *reinterpret_cast<const bf16x8*>(&sm_k[(t8 * 16 + (lane_c & 15)) * LDSS + s * 32 + (lane_c >> 4) * 8]);
;           sacc[t8] = __builtin_amdgcn_mfma_f32_16x16x32_bf16(qf[s], kf, sacc[t8], 0, 0, 0);
;         }
;       if (ck < 5) {
;         ATT_ISSUE(t, ck + 1)
;       } else if (t + VGRID < 8192) {
;         ATT_ISSUE(t + VGRID, 0)
;         ATT_QLOAD(t + VGRID)
;       }
;       if (ck < 4) {
;         const float* rb0 = sm_rpb + (rs + ck * 2 - r + 7) * 31;
; #pragma unroll
;         for (int t8 = 0; t8 < 8; ++t8)
; #pragma unroll
;           for (int reg = 0; reg < 4; ++reg)
;             sacc[t8][reg] += rb0[(t8 >> 2) * 31 + dco[reg][t8 & 3]];
;       }
; #pragma unroll
;       for (int reg = 0; reg < 4; ++reg) {
;         float mx = sacc[0][reg];
; #pragma unroll
;         for (int t8 = 1; t8 < 8; ++t8) mx = fmaxf(mx, sacc[t8][reg]);
;         mx = row16_max(mx);
;         const float mnew = fmaxf(mrow[reg], mx);
;         const float alpha = __builtin_amdgcn_exp2f(mrow[reg] - mnew);
;         mrow[reg] = mnew;
;         float rsum = 0.f;
; #pragma unroll
;         for (int t8 = 0; t8 < 8; ++t8) {
;           const float p = __builtin_amdgcn_exp2f(sacc[t8][reg] - mnew);
;           rsum += p;
;           sm_p[(wid * 16 + (lane_c >> 4) * 4 + reg) * 136 + t8 * 16 + (lane_c & 15)] = f2bf(p);
;         }
;         rsum = row16_sum(rsum);
;         lrow[reg] = lrow[reg] * alpha + rsum;
; #pragma unroll
;         for (int td = 0; td < 4; ++td) o[td][reg] *= alpha;
;       }
;       asm volatile("s_waitcnt lgkmcnt(0)" ::: "memory");
; #pragma unroll
;       for (int s4 = 0; s4 < 4; ++s4) {
	v_mfma_f32_16x16x32_bf16 v[176:179], v[112:115], v[48:51], v[176:179]
	ds_read_b128 v[112:115], v227 offset:0
	s_waitcnt lgkmcnt(7)
	v_mfma_f32_16x16x32_bf16 v[180:183], v[116:119], v[48:51], v[180:183]
	ds_read_b128 v[116:119], v227 offset:4096
	s_waitcnt lgkmcnt(7)
	v_mfma_f32_16x16x32_bf16 v[192:195], v[120:123], v[48:51], v[192:195]
	ds_read_b128 v[120:123], v227 offset:8192
	s_waitcnt lgkmcnt(7)
	v_mfma_f32_16x16x32_bf16 v[196:199], v[124:127], v[48:51], v[196:199]
	ds_read_b128 v[124:127], v227 offset:12288
	s_waitcnt lgkmcnt(7)
	v_mfma_f32_16x16x32_bf16 v[176:179], v[128:131], v[52:55], v[176:179]
	ds_read_b128 v[128:131], v228 offset:0
	s_waitcnt lgkmcnt(7)
	v_mfma_f32_16x16x32_bf16 v[180:183], v[132:135], v[52:55], v[180:183]
	ds_read_b128 v[132:135], v228 offset:4096
	s_waitcnt lgkmcnt(7)
	v_mfma_f32_16x16x32_bf16 v[192:195], v[136:139], v[52:55], v[192:195]
	ds_read_b128 v[136:139], v228 offset:8192
	s_waitcnt lgkmcnt(7)
	v_mfma_f32_16x16x32_bf16 v[196:199], v[140:143], v[52:55], v[196:199]
	ds_read_b128 v[140:143], v228 offset:12288
	s_waitcnt lgkmcnt(7)
	v_mfma_f32_16x16x32_bf16 v[176:179], v[112:115], v[56:59], v[176:179]
	s_waitcnt lgkmcnt(6)
	v_mfma_f32_16x16x32_bf16 v[180:183], v[116:119], v[56:59], v[180:183]
	s_waitcnt lgkmcnt(5)
	v_mfma_f32_16x16x32_bf16 v[192:195], v[120:123], v[56:59], v[192:195]
	s_waitcnt lgkmcnt(4)
	v_mfma_f32_16x16x32_bf16 v[196:199], v[124:127], v[56:59], v[196:199]
	s_waitcnt lgkmcnt(3)
	v_mfma_f32_16x16x32_bf16 v[176:179], v[128:131], v[60:63], v[176:179]
	s_waitcnt lgkmcnt(2)
	v_mfma_f32_16x16x32_bf16 v[180:183], v[132:135], v[60:63], v[180:183]
	s_waitcnt lgkmcnt(1)
	v_mfma_f32_16x16x32_bf16 v[192:195], v[136:139], v[60:63], v[192:195]
	s_waitcnt lgkmcnt(0)
	v_mfma_f32_16x16x32_bf16 v[196:199], v[140:143], v[60:63], v[196:199]
	ds_read_b32 v0, v184 offset:384
	ds_read_b32 v1, v185 offset:384
	ds_read_b32 v2, v186 offset:384
	ds_read_b32 v3, v187 offset:384
	ds_read_b32 v4, v184 offset:512
	ds_read_b32 v5, v185 offset:512
	ds_read_b32 v6, v186 offset:512
	ds_read_b32 v7, v187 offset:512
	ds_read_b32 v8, v188 offset:384
	ds_read_b32 v9, v189 offset:384
	ds_read_b32 v10, v190 offset:384
	ds_read_b32 v11, v191 offset:384
	ds_read_b32 v12, v188 offset:512
	ds_read_b32 v13, v189 offset:512
	ds_read_b32 v14, v190 offset:512
	ds_read_b32 v15, v191 offset:512
	s_cmp_eq_u32 s18, 0
	s_cbranch_scc1 .Lmy_att_b0_2
	v_mov_b32_e32 v16, 0xf149f2ca
	v_mov_b32_e32 v17, 0xf149f2ca
	v_mov_b32_e32 v18, 0xf149f2ca
	v_mov_b32_e32 v19, 0xf149f2ca
	v_mov_b32_e32 v24, 0xf149f2ca
	v_mov_b32_e32 v25, 0xf149f2ca
	v_mov_b32_e32 v26, 0xf149f2ca
	v_mov_b32_e32 v27, 0xf149f2ca
	s_branch .Lmy_att_b1_2

; __device__ __forceinline__ void attn_phase(const Params& P, char* smem_raw) {
;     ...
;     for (int ck = 0; ck < 6; ++ck) {
;       int lane_c = lane;
;       asm volatile("" : "+v"(lane_c));
;       __syncthreads();
; #pragma unroll
;       for (int i = 0; i < 4; ++i) {
;         const int idx = tid + 256 * i;
;         *reinterpret_cast<uint4*>(&sm_k[(idx >> 3) * LDSS + (idx & 7) * 8]) = kreg[i];
;         *reinterpret_cast<uint4*>(&sm_vt[(idx >> 4) * 136 + (idx & 15) * 8]) = vreg[i];
;       }
;       __syncthreads();
;       f32x4 sacc[8];
; #pragma unroll
;       for (int t8 = 0; t8 < 8; ++t8) sacc[t8] = f32x4{0.f, 0.f, 0.f, 0.f};
; #pragma unroll
;       for (int s = 0; s < 2; ++s)
; #pragma unroll
;         for (int t8 = 0; t8 < 8; ++t8) {
;           const bf16x8 kf = *reinterpret_cast<const bf16x8*>(&sm_k[(t8 * 16 + (lane_c & 15)) * LDSS + s * 32 + (lane_c >> 4) * 8]);
;           sacc[t8] = __builtin_amdgcn_mfma_f32_16x16x32_bf16(qf[s], kf, sacc[t8], 0, 0, 0);
;         }
;       if (ck < 5) {
;         ATT_ISSUE(t, ck + 1)
;       } else if (t + VGRID < 8192) {
;         ATT_ISSUE(t + VGRID, 0)
;         ATT_QLOAD(t + VGRID)
;       }
;       if (ck < 4) {
;         const float* rb0 = sm_rpb + (rs + ck * 2 - r + 7) * 31;
; #pragma unroll
;         for (int t8 = 0; t8 < 8; ++t8)
; #pragma unroll
;           for (int reg = 0; reg < 4; ++reg)
;             sacc[t8][reg] += rb0[(t8 >> 2) * 31 + dco[reg][t8 & 3]];
;       }
; #pragma unroll
;       for (int reg = 0; reg < 4; ++reg) {
;         float mx = sacc[0][reg];
; #pragma unroll
;         for (int t8 = 1; t8 < 8; ++t8) mx = fmaxf(mx, sacc[t8][reg]);
;         mx = row16_max(mx);
;         const float mnew = fmaxf(mrow[reg], mx);
;         const float alpha = __builtin_amdgcn_exp2f(mrow[reg] - mnew);
;         mrow[reg] = mnew;
;         float rsum = 0.f;
; #pragma unroll
;         for (int t8 = 0; t8 < 8; ++t8) {
;           const float p = __builtin_amdgcn_exp2f(sacc[t8][reg] - mnew);
;           rsum += p;
;     ...
;     u16* Ob = P.cat + ((long)b * 8192 + r * 64) * 1024 + h * 64;
; #pragma unroll
;     for (int td = 0; td < 4; ++td)
; #pragma unroll
;       for (int reg = 0; reg < 4; ++reg) {
;         const int rowl = wid * 16 + (lane >> 4) * 4 + reg;
;         Ob[(unsigned)(rowl * 1024 + td * 16 + (lane & 15))] = f2bf(o[td][reg] * __builtin_amdgcn_rcpf(lrow[reg]));
;       }
.Lmy_att_b1_2:
	ds_read_b32 v20, v184 offset:384
	ds_read_b32 v21, v185 offset:384
	ds_read_b32 v22, v186 offset:384
	ds_read_b32 v23, v187 offset:384
	ds_read_b32 v28, v188 offset:384
	ds_read_b32 v29, v189 offset:384
	ds_read_b32 v30, v190 offset:384
	ds_read_b32 v31, v191 offset:384
	s_waitcnt lgkmcnt(0)
	v_mov_b32_e32 v205, v201
	s_nop 1
	v_permlane16_swap_b32_e32 v201, v205
	v_add_f32_e32 v201, v201, v205
	v_mov_b32_e32 v205, v201
	s_nop 1
	v_permlane32_swap_b32_e32 v201, v205
	v_add_f32_e32 v201, v201, v205
	v_rcp_f32_e32 v203, v201
	s_nop 7
	v_mul_f32_e32 v32, v32, v203
	v_mul_f32_e32 v33, v33, v203
	v_mul_f32_e32 v34, v34, v203
	v_mul_f32_e32 v35, v35, v203
	v_mul_f32_e32 v36, v36, v203
	v_mul_f32_e32 v37, v37, v203
	v_mul_f32_e32 v38, v38, v203
	v_mul_f32_e32 v39, v39, v203
	v_mul_f32_e32 v40, v40, v203
	v_mul_f32_e32 v41, v41, v203
	v_mul_f32_e32 v42, v42, v203
	v_mul_f32_e32 v43, v43, v203
	v_mul_f32_e32 v44, v44, v203
	v_mul_f32_e32 v45, v45, v203
	v_mul_f32_e32 v46, v46, v203
	v_mul_f32_e32 v47, v47, v203
	v_cvt_pk_bf16_f32 v210, v32, v33
	v_cvt_pk_bf16_f32 v211, v34, v35
	v_cvt_pk_bf16_f32 v212, v36, v37
	v_cvt_pk_bf16_f32 v213, v38, v39
	v_cvt_pk_bf16_f32 v214, v40, v41
	v_cvt_pk_bf16_f32 v215, v42, v43
	v_cvt_pk_bf16_f32 v216, v44, v45
	v_cvt_pk_bf16_f32 v217, v46, v47
	global_store_dwordx2 v167, v[210:211], s[98:99] offset:0
	global_store_dwordx2 v167, v[212:213], s[98:99] offset:32
	global_store_dwordx2 v167, v[214:215], s[98:99] offset:64
	global_store_dwordx2 v167, v[216:217], s[98:99] offset:96
	v_mov_b32_e32 v200, 0xf149f2ca
	v_mov_b32_e32 v201, 0
	v_mov_b32_e32 v32, 0
	v_mov_b32_e32 v33, 0
	v_mov_b32_e32 v34, 0
	v_mov_b32_e32 v35, 0
	v_mov_b32_e32 v36, 0
	v_mov_b32_e32 v37, 0
	v_mov_b32_e32 v38, 0
	v_mov_b32_e32 v39, 0
	v_mov_b32_e32 v40, 0
	v_mov_b32_e32 v41, 0
	v_mov_b32_e32 v42, 0
	v_mov_b32_e32 v43, 0
	v_mov_b32_e32 v44, 0
	v_mov_b32_e32 v45, 0
	v_mov_b32_e32 v46, 0
	v_mov_b32_e32 v47, 0
	v_mov_b32_e32 v64, v72
	v_mov_b32_e32 v65, v73
	v_mov_b32_e32 v66, v74
	v_mov_b32_e32 v67, v75
	v_mov_b32_e32 v68, v76
	v_mov_b32_e32 v69, v77
	v_mov_b32_e32 v70, v78
	v_mov_b32_e32 v71, v79
	v_mov_b32_e32 v205, v247
	s_nop 1
	v_permlane16_swap_b32_e32 v247, v205
	v_add_f32_e32 v247, v247, v205
	v_mov_b32_e32 v205, v247
	s_nop 1
	v_permlane32_swap_b32_e32 v247, v205
	v_add_f32_e32 v247, v247, v205
	v_rcp_f32_e32 v203, v247
	s_nop 7
	v_mul_f32_e32 v176, v176, v203
	v_mul_f32_e32 v177, v177, v203
	v_mul_f32_e32 v178, v178, v203
	v_mul_f32_e32 v179, v179, v203
	v_mul_f32_e32 v180, v180, v203
	v_mul_f32_e32 v181, v181, v203
	v_mul_f32_e32 v182, v182, v203
	v_mul_f32_e32 v183, v183, v203
	v_mul_f32_e32 v192, v192, v203
	v_mul_f32_e32 v193, v193, v203
	v_mul_f32_e32 v194, v194, v203
	v_mul_f32_e32 v195, v195, v203
	v_mul_f32_e32 v196, v196, v203
	v_mul_f32_e32 v197, v197, v203
	v_mul_f32_e32 v198, v198, v203
	v_mul_f32_e32 v199, v199, v203
	v_cvt_pk_bf16_f32 v210, v176, v177
	v_cvt_pk_bf16_f32 v211, v178, v179
	v_cvt_pk_bf16_f32 v212, v180, v181
	v_cvt_pk_bf16_f32 v213, v182, v183
	v_cvt_pk_bf16_f32 v214, v192, v193
	v_cvt_pk_bf16_f32 v215, v194, v195
	v_cvt_pk_bf16_f32 v216, v196, v197
	v_cvt_pk_bf16_f32 v217, v198, v199
	s_add_u32 s0, s98, 0x20000
	s_addc_u32 s1, s99, 0
	global_store_dwordx2 v167, v[210:211], s[0:1] offset:0
	global_store_dwordx2 v167, v[212:213], s[0:1] offset:32
	global_store_dwordx2 v167, v[214:215], s[0:1] offset:64
	global_store_dwordx2 v167, v[216:217], s[0:1] offset:96
	v_mov_b32_e32 v246, 0xf149f2ca
	v_mov_b32_e32 v247, 0
	v_mov_b32_e32 v176, 0
	v_mov_b32_e32 v177, 0
	v_mov_b32_e32 v178, 0
	v_mov_b32_e32 v179, 0
	v_mov_b32_e32 v180, 0
	v_mov_b32_e32 v181, 0
	v_mov_b32_e32 v182, 0
	v_mov_b32_e32 v183, 0
	v_mov_b32_e32 v192, 0
	v_mov_b32_e32 v193, 0
	v_mov_b32_e32 v194, 0
	v_mov_b32_e32 v195, 0
	v_mov_b32_e32 v196, 0
	v_mov_b32_e32 v197, 0
	v_mov_b32_e32 v198, 0
	v_mov_b32_e32 v199, 0
	v_mov_b32_e32 v230, v238
	v_mov_b32_e32 v231, v239
	v_mov_b32_e32 v232, v240
	v_mov_b32_e32 v233, v241
	v_mov_b32_e32 v234, v242
	v_mov_b32_e32 v235, v243
	v_mov_b32_e32 v236, v244
	v_mov_b32_e32 v237, v245
	s_add_u32 s3, s3, 1
	s_barrier
	ds_read_b128 v[112:115], v144 offset:32768
	ds_read_b128 v[116:119], v145 offset:32768
	ds_read_b128 v[120:123], v144 offset:40960
	ds_read_b128 v[124:127], v145 offset:40960
	ds_read_b128 v[128:131], v144 offset:34816
	ds_read_b128 v[132:135], v145 offset:34816
	ds_read_b128 v[136:139], v144 offset:43008
	ds_read_b128 v[140:143], v145 offset:43008
	s_waitcnt lgkmcnt(7)
	v_mfma_f32_16x16x32_bf16 v[0:3], v[112:115], v[64:67], v[0:3]
	v_mfma_f32_16x16x32_bf16 v[16:19], v[112:115], v[230:233], v[16:19]
	s_waitcnt lgkmcnt(6)
	v_mfma_f32_16x16x32_bf16 v[0:3], v[116:119], v[68:71], v[0:3]
	v_mfma_f32_16x16x32_bf16 v[16:19], v[116:119], v[234:237], v[16:19]
	s_waitcnt lgkmcnt(5)
	v_mfma_f32_16x16x32_bf16 v[4:7], v[120:123], v[64:67], v[4:7]
	v_mfma_f32_16x16x32_bf16 v[20:23], v[120:123], v[230:233], v[20:23]
	s_waitcnt lgkmcnt(4)
	v_mfma_f32_16x16x32_bf16 v[4:7], v[124:127], v[68:71], v[4:7]
	v_mfma_f32_16x16x32_bf16 v[20:23], v[124:127], v[234:237], v[20:23]
	s_waitcnt lgkmcnt(3)
	v_mfma_f32_16x16x32_bf16 v[8:11], v[128:131], v[64:67], v[8:11]
	v_mfma_f32_16x16x32_bf16 v[24:27], v[128:131], v[230:233], v[24:27]
	s_waitcnt lgkmcnt(2)
	v_mfma_f32_16x16x32_bf16 v[8:11], v[132:135], v[68:71], v[8:11]
	v_mfma_f32_16x16x32_bf16 v[24:27], v[132:135], v[234:237], v[24:27]
	s_waitcnt lgkmcnt(1)
	v_mfma_f32_16x16x32_bf16 v[12:15], v[136:139], v[64:67], v[12:15]
	v_mfma_f32_16x16x32_bf16 v[28:31], v[136:139], v[230:233], v[28:31]
	s_waitcnt lgkmcnt(0)
; __device__ __forceinline__ void attn_phase(const Params& P, char* smem_raw) {
;     ...
;     for (int ck = 0; ck < 6; ++ck) {
;       int lane_c = lane;
;       asm volatile("" : "+v"(lane_c));
;       __syncthreads();
; #pragma unroll
;       for (int i = 0; i < 4; ++i) {
;         const int idx = tid + 256 * i;
;         *reinterpret_cast<uint4*>(&sm_k[(idx >> 3) * LDSS + (idx & 7) * 8]) = kreg[i];
;         *reinterpret_cast<uint4*>(&sm_vt[(idx >> 4) * 136 + (idx & 15) * 8]) = vreg[i];
;       }
;       __syncthreads();
;       f32x4 sacc[8];
; #pragma unroll
;       for (int t8 = 0; t8 < 8; ++t8) sacc[t8] = f32x4{0.f, 0.f, 0.f, 0.f};
; #pragma unroll
;       for (int s = 0; s < 2; ++s)
; #pragma unroll
;         for (int t8 = 0; t8 < 8; ++t8) {
;           const bf16x8 kf = *reinterpret_cast<const bf16x8*>(&sm_k[(t8 * 16 + (lane_c & 15)) * LDSS + s * 32 + (lane_c >> 4) * 8]);
;           sacc[t8] = __builtin_amdgcn_mfma_f32_16x16x32_bf16(qf[s], kf, sacc[t8], 0, 0, 0);
;         }
;       if (ck < 5) {
;         ATT_ISSUE(t, ck + 1)
;       } else if (t + VGRID < 8192) {
;         ATT_ISSUE(t + VGRID, 0)
;         ATT_QLOAD(t + VGRID)
;       }
;       if (ck < 4) {
;         const float* rb0 = sm_rpb + (rs + ck * 2 - r + 7) * 31;
; #pragma unroll
;         for (int t8 = 0; t8 < 8; ++t8)
; #pragma unroll
;           for (int reg = 0; reg < 4; ++reg)
;             sacc[t8][reg] += rb0[(t8 >> 2) * 31 + dco[reg][t8 & 3]];
;       }
; #pragma unroll
;       for (int reg = 0; reg < 4; ++reg) {
;         float mx = sacc[0][reg];
; #pragma unroll
;         for (int t8 = 1; t8 < 8; ++t8) mx = fmaxf(mx, sacc[t8][reg]);
;         mx = row16_max(mx);
;         const float mnew = fmaxf(mrow[reg], mx);
;         const float alpha = __builtin_amdgcn_exp2f(mrow[reg] - mnew);
;         mrow[reg] = mnew;
;         float rsum = 0.f;
; #pragma unroll
;         for (int t8 = 0; t8 < 8; ++t8) {
;           const float p = __builtin_amdgcn_exp2f(sacc[t8][reg] - mnew);
;           rsum += p;
;           sm_p[(wid * 16 + (lane_c >> 4) * 4 + reg) * 136 + t8 * 16 + (lane_c & 15)] = f2bf(p);
;         }
;         rsum = row16_sum(rsum);
;         lrow[reg] = lrow[reg] * alpha + rsum;
; #pragma unroll
;         for (int td = 0; td < 4; ++td) o[td][reg] *= alpha;
;       }
;       asm volatile("s_waitcnt lgkmcnt(0)" ::: "memory");
; #pragma unroll
;       for (int s4 = 0; s4 < 4; ++s4) {
	v_mfma_f32_16x16x32_bf16 v[12:15], v[140:143], v[68:71], v[12:15]
	v_mfma_f32_16x16x32_bf16 v[28:31], v[140:143], v[234:237], v[28:31]
	s_nop 7
	v_max3_f32 v203, v0, v1, v2
	v_max3_f32 v206, v16, v17, v18
	v_max3_f32 v203, v203, v3, v4
	v_max3_f32 v206, v206, v19, v20
	v_max3_f32 v203, v203, v5, v6
	v_max3_f32 v206, v206, v21, v22
	v_max3_f32 v203, v203, v7, v8
	v_max3_f32 v206, v206, v23, v24
	v_max3_f32 v203, v203, v9, v10
	v_max3_f32 v206, v206, v25, v26
	v_max3_f32 v203, v203, v11, v12
	v_max3_f32 v206, v206, v27, v28
	v_max3_f32 v203, v203, v13, v14
	v_max3_f32 v206, v206, v29, v30
	v_max_f32_e32 v203, v203, v15
	v_max_f32_e32 v206, v206, v31
	v_mov_b32_e32 v205, v203
	v_mov_b32_e32 v207, v206
	s_nop 1
	v_permlane16_swap_b32_e32 v203, v205
	v_permlane16_swap_b32_e32 v206, v207
	v_max_f32_e32 v203, v203, v205
	v_max_f32_e32 v206, v206, v207
	v_mov_b32_e32 v205, v203
	v_mov_b32_e32 v207, v206
	s_nop 1
	v_permlane32_swap_b32_e32 v203, v205
	v_permlane32_swap_b32_e32 v206, v207
	v_max_f32_e32 v203, v203, v205
	v_max_f32_e32 v206, v206, v207
	v_max_f32_e32 v218, v200, v203
	v_max_f32_e32 v208, v246, v206
	v_sub_f32_e32 v220, v200, v218
	v_sub_f32_e32 v248, v246, v208
	v_mov_b32_e32 v219, v218
	v_mov_b32_e32 v209, v208
	v_exp_f32_e32 v220, v220
	v_exp_f32_e32 v248, v248
	v_mov_b32_e32 v200, v218
	v_mov_b32_e32 v246, v208
	v_pk_add_f32 v[0:1], v[0:1], v[218:219] neg_lo:[0,1] neg_hi:[0,1]
	v_pk_add_f32 v[16:17], v[16:17], v[208:209] neg_lo:[0,1] neg_hi:[0,1]
	v_pk_add_f32 v[2:3], v[2:3], v[218:219] neg_lo:[0,1] neg_hi:[0,1]
	v_pk_add_f32 v[18:19], v[18:19], v[208:209] neg_lo:[0,1] neg_hi:[0,1]
	v_pk_add_f32 v[4:5], v[4:5], v[218:219] neg_lo:[0,1] neg_hi:[0,1]
	v_pk_add_f32 v[20:21], v[20:21], v[208:209] neg_lo:[0,1] neg_hi:[0,1]
	v_pk_add_f32 v[6:7], v[6:7], v[218:219] neg_lo:[0,1] neg_hi:[0,1]
	v_pk_add_f32 v[22:23], v[22:23], v[208:209] neg_lo:[0,1] neg_hi:[0,1]
	v_pk_add_f32 v[8:9], v[8:9], v[218:219] neg_lo:[0,1] neg_hi:[0,1]
	v_pk_add_f32 v[24:25], v[24:25], v[208:209] neg_lo:[0,1] neg_hi:[0,1]
	v_pk_add_f32 v[10:11], v[10:11], v[218:219] neg_lo:[0,1] neg_hi:[0,1]
	v_pk_add_f32 v[26:27], v[26:27], v[208:209] neg_lo:[0,1] neg_hi:[0,1]
	v_pk_add_f32 v[12:13], v[12:13], v[218:219] neg_lo:[0,1] neg_hi:[0,1]
	v_pk_add_f32 v[28:29], v[28:29], v[208:209] neg_lo:[0,1] neg_hi:[0,1]
	v_pk_add_f32 v[14:15], v[14:15], v[218:219] neg_lo:[0,1] neg_hi:[0,1]
	v_pk_add_f32 v[30:31], v[30:31], v[208:209] neg_lo:[0,1] neg_hi:[0,1]
	v_exp_f32_e32 v0, v0
	s_waitcnt vmcnt(8)
	v_exp_f32_e32 v1, v1
	ds_write_b128 v150, v[80:83] offset:0
	v_exp_f32_e32 v2, v2
	ds_write_b128 v150, v[84:87] offset:4096
	v_exp_f32_e32 v3, v3
	ds_write_b128 v150, v[88:91] offset:8192
	v_exp_f32_e32 v4, v4
	ds_write_b128 v150, v[92:95] offset:12288
	v_exp_f32_e32 v5, v5
	ds_write_b64 v151, v[96:97] offset:0
	v_exp_f32_e32 v6, v6
	ds_write_b64 v229, v[98:99] offset:0
	v_exp_f32_e32 v7, v7
	ds_write_b64 v151, v[100:101] offset:4096
	v_exp_f32_e32 v8, v8
	ds_write_b64 v229, v[102:103] offset:4096
	v_exp_f32_e32 v9, v9
	ds_write_b64 v151, v[104:105] offset:8192
	v_exp_f32_e32 v10, v10
	ds_write_b64 v229, v[106:107] offset:8192
	v_exp_f32_e32 v11, v11
	ds_write_b64 v151, v[108:109] offset:12288
	v_exp_f32_e32 v12, v12
	ds_write_b64 v229, v[110:111] offset:12288
	v_exp_f32_e32 v13, v13
	s_add_u32 s100, s12, 0x180000
	v_exp_f32_e32 v14, v14
	s_addc_u32 s101, s13, 0
	v_exp_f32_e32 v15, v15
	s_add_u32 s0, s14, 0x200
	v_exp_f32_e32 v16, v16
	s_addc_u32 s1, s15, 0
	v_exp_f32_e32 v17, v17
	global_load_dwordx4 v[80:83], v154, s[100:101] offset:2048
	v_exp_f32_e32 v18, v18
	global_load_dwordx4 v[96:99], v158, s[0:1]
	v_exp_f32_e32 v19, v19
	global_load_dwordx4 v[84:87], v155, s[100:101] offset:2048
	v_exp_f32_e32 v20, v20
	global_load_dwordx4 v[100:103], v159, s[0:1]
	v_exp_f32_e32 v21, v21
	global_load_dwordx4 v[88:91], v156, s[100:101] offset:2048
	v_exp_f32_e32 v22, v22
	global_load_dwordx4 v[104:107], v160, s[0:1]
	v_exp_f32_e32 v23, v23
	global_load_dwordx4 v[92:95], v157, s[100:101] offset:2048
	v_exp_f32_e32 v24, v24
	global_load_dwordx4 v[108:111], v161, s[0:1]
	v_exp_f32_e32 v25, v25
	v_exp_f32_e32 v26, v26
	v_exp_f32_e32 v27, v27
	v_exp_f32_e32 v28, v28
	v_exp_f32_e32 v29, v29
	v_exp_f32_e32 v30, v30
	v_exp_f32_e32 v31, v31
	s_and_b32 s0, s3, 0xff
	s_lshr_b32 s1, s0, 1
	s_and_b32 s0, s0, 1
	s_lshl_b32 s0, s0, 5
	s_lshr_b32 vcc_lo, s3, 12
	s_add_u32 s0, s0, vcc_lo
	s_lshl_b32 s0, s0, 1
	s_sub_i32 vcc_lo, s0, 4
	s_max_i32 vcc_lo, vcc_lo, 0
	s_min_i32 vcc_lo, vcc_lo, 0x78
	s_lshl_b32 vcc_hi, s1, 13
	s_sub_i32 s19, s0, 3
	s_max_i32 s19, s19, 0
	s_min_i32 s19, s19, 0x78
	s_sub_i32 s19, vcc_lo, s19
	s_lshl_b32 m0, s1, 8
	s_add_u32 m0, m0, 0x8000
	s_mul_i32 m0, m0, 0x1800
	s_add_u32 s16, s4, m0
	s_addc_u32 s17, s5, 0
	s_lshl_b32 m0, s1, 19
	s_add_u32 s36, s8, m0
	s_addc_u32 s37, s9, 0
	s_lshl_b32 m0, s0, 6
	s_add_u32 m0, m0, vcc_hi
	s_lshl_b32 m0, m0, 11
	s_add_u32 s98, s10, m0
	s_addc_u32 s99, s11, 0
	ds_read_b128 v[112:115], v146 offset:32768
	ds_read_b128 v[116:119], v146 offset:36864
	ds_read_b128 v[120:123], v146 offset:40960
	ds_read_b128 v[124:127], v146 offset:45056
	ds_read_b128 v[128:131], v147 offset:32768
	ds_read_b128 v[132:135], v147 offset:36864
	ds_read_b128 v[136:139], v147 offset:40960
	ds_read_b128 v[140:143], v147 offset:45056
	v_mov_b32_e32 v221, v220
	v_mov_b32_e32 v249, v248
	v_pk_add_f32 v[222:223], v[0:1], v[2:3]
	v_pk_add_f32 v[250:251], v[16:17], v[18:19]
	v_pk_add_f32 v[222:223], v[222:223], v[4:5]
	v_pk_add_f32 v[250:251], v[250:251], v[20:21]
	v_pk_add_f32 v[222:223], v[222:223], v[6:7]
	v_pk_add_f32 v[250:251], v[250:251], v[22:23]
	v_pk_add_f32 v[222:223], v[222:223], v[8:9]
; __device__ __forceinline__ void attn_phase(const Params& P, char* smem_raw) {
;     ...
;     for (int ck = 0; ck < 6; ++ck) {
;       int lane_c = lane;
;       asm volatile("" : "+v"(lane_c));
;       __syncthreads();
; #pragma unroll
;       for (int i = 0; i < 4; ++i) {
;         const int idx = tid + 256 * i;
;         *reinterpret_cast<uint4*>(&sm_k[(idx >> 3) * LDSS + (idx & 7) * 8]) = kreg[i];
;         *reinterpret_cast<uint4*>(&sm_vt[(idx >> 4) * 136 + (idx & 15) * 8]) = vreg[i];
;       }
;       __syncthreads();
;       f32x4 sacc[8];
; #pragma unroll
;       for (int t8 = 0; t8 < 8; ++t8) sacc[t8] = f32x4{0.f, 0.f, 0.f, 0.f};
; #pragma unroll
;       for (int s = 0; s < 2; ++s)
; #pragma unroll
;         for (int t8 = 0; t8 < 8; ++t8) {
;           const bf16x8 kf = *reinterpret_cast<const bf16x8*>(&sm_k[(t8 * 16 + (lane_c & 15)) * LDSS + s * 32 + (lane_c >> 4) * 8]);
;           sacc[t8] = __builtin_amdgcn_mfma_f32_16x16x32_bf16(qf[s], kf, sacc[t8], 0, 0, 0);
;         }
;       if (ck < 5) {
;         ATT_ISSUE(t, ck + 1)
;       } else if (t + VGRID < 8192) {
;         ATT_ISSUE(t + VGRID, 0)
;         ATT_QLOAD(t + VGRID)
;       }
;       if (ck < 4) {
;         const float* rb0 = sm_rpb + (rs + ck * 2 - r + 7) * 31;
; #pragma unroll
;         for (int t8 = 0; t8 < 8; ++t8)
; #pragma unroll
;           for (int reg = 0; reg < 4; ++reg)
;             sacc[t8][reg] += rb0[(t8 >> 2) * 31 + dco[reg][t8 & 3]];
;       }
; #pragma unroll
;       for (int reg = 0; reg < 4; ++reg) {
;         float mx = sacc[0][reg];
; #pragma unroll
;         for (int t8 = 1; t8 < 8; ++t8) mx = fmaxf(mx, sacc[t8][reg]);
;         mx = row16_max(mx);
;         const float mnew = fmaxf(mrow[reg], mx);
;         const float alpha = __builtin_amdgcn_exp2f(mrow[reg] - mnew);
;         mrow[reg] = mnew;
;         float rsum = 0.f;
; #pragma unroll
;         for (int t8 = 0; t8 < 8; ++t8) {
;           const float p = __builtin_amdgcn_exp2f(sacc[t8][reg] - mnew);
;           rsum += p;
;           sm_p[(wid * 16 + (lane_c >> 4) * 4 + reg) * 136 + t8 * 16 + (lane_c & 15)] = f2bf(p);
;         }
;         rsum = row16_sum(rsum);
;         lrow[reg] = lrow[reg] * alpha + rsum;
; #pragma unroll
;         for (int td = 0; td < 4; ++td) o[td][reg] *= alpha;
;       }
;       asm volatile("s_waitcnt lgkmcnt(0)" ::: "memory");
; #pragma unroll
;       for (int s4 = 0; s4 < 4; ++s4) {
	v_pk_add_f32 v[250:251], v[250:251], v[24:25]
	v_pk_add_f32 v[222:223], v[222:223], v[10:11]
	v_pk_add_f32 v[250:251], v[250:251], v[26:27]
	v_pk_add_f32 v[222:223], v[222:223], v[12:13]
	v_pk_add_f32 v[250:251], v[250:251], v[28:29]
	v_pk_add_f32 v[222:223], v[222:223], v[14:15]
	v_pk_add_f32 v[250:251], v[250:251], v[30:31]
	v_pk_mul_f32 v[32:33], v[32:33], v[220:221]
	v_pk_mul_f32 v[34:35], v[34:35], v[220:221]
	v_pk_mul_f32 v[176:177], v[176:177], v[248:249]
	v_pk_mul_f32 v[178:179], v[178:179], v[248:249]
	v_pk_mul_f32 v[36:37], v[36:37], v[220:221]
	v_pk_mul_f32 v[38:39], v[38:39], v[220:221]
	v_pk_mul_f32 v[180:181], v[180:181], v[248:249]
	v_pk_mul_f32 v[182:183], v[182:183], v[248:249]
	v_pk_mul_f32 v[40:41], v[40:41], v[220:221]
	v_pk_mul_f32 v[42:43], v[42:43], v[220:221]
	v_pk_mul_f32 v[192:193], v[192:193], v[248:249]
	v_pk_mul_f32 v[194:195], v[194:195], v[248:249]
	v_pk_mul_f32 v[44:45], v[44:45], v[220:221]
	v_pk_mul_f32 v[46:47], v[46:47], v[220:221]
	v_pk_mul_f32 v[196:197], v[196:197], v[248:249]
	v_pk_mul_f32 v[198:199], v[198:199], v[248:249]
	v_add_f32_e32 v203, v222, v223
	v_add_f32_e32 v206, v250, v251
	v_fma_f32 v201, v201, v220, v203
	v_fma_f32 v247, v247, v248, v206
	v_cvt_pk_bf16_f32 v48, v0, v1
	v_cvt_pk_bf16_f32 v49, v2, v3
	v_cvt_pk_bf16_f32 v50, v4, v5
	v_cvt_pk_bf16_f32 v51, v6, v7
	v_cvt_pk_bf16_f32 v56, v16, v17
	v_cvt_pk_bf16_f32 v57, v18, v19
	v_cvt_pk_bf16_f32 v58, v20, v21
	v_cvt_pk_bf16_f32 v59, v22, v23
	v_cvt_pk_bf16_f32 v52, v8, v9
	v_cvt_pk_bf16_f32 v53, v10, v11
	v_cvt_pk_bf16_f32 v54, v12, v13
	v_cvt_pk_bf16_f32 v55, v14, v15
	v_cvt_pk_bf16_f32 v60, v24, v25
	v_cvt_pk_bf16_f32 v61, v26, v27
	v_cvt_pk_bf16_f32 v62, v28, v29
	v_cvt_pk_bf16_f32 v63, v30, v31
	s_waitcnt lgkmcnt(7)
	v_mfma_f32_16x16x32_bf16 v[32:35], v[112:115], v[48:51], v[32:35]
	v_mfma_f32_16x16x32_bf16 v[176:179], v[112:115], v[56:59], v[176:179]
	s_waitcnt lgkmcnt(6)
	v_mfma_f32_16x16x32_bf16 v[36:39], v[116:119], v[48:51], v[36:39]
	v_mfma_f32_16x16x32_bf16 v[180:183], v[116:119], v[56:59], v[180:183]
	s_waitcnt lgkmcnt(5)
	v_mfma_f32_16x16x32_bf16 v[40:43], v[120:123], v[48:51], v[40:43]
	v_mfma_f32_16x16x32_bf16 v[192:195], v[120:123], v[56:59], v[192:195]
	s_waitcnt lgkmcnt(4)
	v_mfma_f32_16x16x32_bf16 v[44:47], v[124:127], v[48:51], v[44:47]
	v_mfma_f32_16x16x32_bf16 v[196:199], v[124:127], v[56:59], v[196:199]
	s_waitcnt lgkmcnt(3)
	v_mfma_f32_16x16x32_bf16 v[32:35], v[128:131], v[52:55], v[32:35]
	v_mfma_f32_16x16x32_bf16 v[176:179], v[128:131], v[60:63], v[176:179]
	s_waitcnt lgkmcnt(2)
	v_mfma_f32_16x16x32_bf16 v[36:39], v[132:135], v[52:55], v[36:39]
	v_mfma_f32_16x16x32_bf16 v[180:183], v[132:135], v[60:63], v[180:183]
	s_waitcnt lgkmcnt(1)
	v_mfma_f32_16x16x32_bf16 v[40:43], v[136:139], v[52:55], v[40:43]
	v_mfma_f32_16x16x32_bf16 v[192:195], v[136:139], v[60:63], v[192:195]
	s_waitcnt lgkmcnt(0)
	v_mfma_f32_16x16x32_bf16 v[44:47], v[140:143], v[52:55], v[44:47]
	v_mfma_f32_16x16x32_bf16 v[196:199], v[140:143], v[60:63], v[196:199]
	ds_read_b32 v0, v184 offset:640
	ds_read_b32 v1, v185 offset:640
	ds_read_b32 v2, v186 offset:640
	ds_read_b32 v3, v187 offset:640
	ds_read_b32 v4, v184 offset:768
	ds_read_b32 v5, v185 offset:768
	ds_read_b32 v6, v186 offset:768
	ds_read_b32 v7, v187 offset:768
	ds_read_b32 v8, v188 offset:640
	ds_read_b32 v9, v189 offset:640
	ds_read_b32 v10, v190 offset:640
	ds_read_b32 v11, v191 offset:640
	ds_read_b32 v12, v188 offset:768
	ds_read_b32 v13, v189 offset:768
	ds_read_b32 v14, v190 offset:768
	ds_read_b32 v15, v191 offset:768
	ds_read_b32 v16, v184 offset:512
	ds_read_b32 v17, v185 offset:512
	ds_read_b32 v18, v186 offset:512
	ds_read_b32 v19, v187 offset:512
	ds_read_b32 v20, v184 offset:640
	ds_read_b32 v21, v185 offset:640
	ds_read_b32 v22, v186 offset:640
	ds_read_b32 v23, v187 offset:640
	ds_read_b32 v24, v188 offset:512
	ds_read_b32 v25, v189 offset:512
	ds_read_b32 v26, v190 offset:512
	ds_read_b32 v27, v191 offset:512
	ds_read_b32 v28, v188 offset:640
	ds_read_b32 v29, v189 offset:640
	ds_read_b32 v30, v190 offset:640
	ds_read_b32 v31, v191 offset:640
	s_waitcnt lgkmcnt(0)
	s_barrier
	ds_read_b128 v[112:115], v144 offset:0
	ds_read_b128 v[116:119], v145 offset:0
	ds_read_b128 v[120:123], v144 offset:8192
	ds_read_b128 v[124:127], v145 offset:8192
	ds_read_b128 v[128:131], v144 offset:2048
	ds_read_b128 v[132:135], v145 offset:2048
	ds_read_b128 v[136:139], v144 offset:10240
	ds_read_b128 v[140:143], v145 offset:10240
	s_waitcnt lgkmcnt(7)
	v_mfma_f32_16x16x32_bf16 v[0:3], v[112:115], v[64:67], v[0:3]
	v_mfma_f32_16x16x32_bf16 v[16:19], v[112:115], v[230:233], v[16:19]
	s_waitcnt lgkmcnt(6)
	v_mfma_f32_16x16x32_bf16 v[0:3], v[116:119], v[68:71], v[0:3]
	v_mfma_f32_16x16x32_bf16 v[16:19], v[116:119], v[234:237], v[16:19]
	s_waitcnt lgkmcnt(5)
	v_mfma_f32_16x16x32_bf16 v[4:7], v[120:123], v[64:67], v[4:7]
	v_mfma_f32_16x16x32_bf16 v[20:23], v[120:123], v[230:233], v[20:23]
	s_waitcnt lgkmcnt(4)
	v_mfma_f32_16x16x32_bf16 v[4:7], v[124:127], v[68:71], v[4:7]
	v_mfma_f32_16x16x32_bf16 v[20:23], v[124:127], v[234:237], v[20:23]
	s_waitcnt lgkmcnt(3)
	v_mfma_f32_16x16x32_bf16 v[8:11], v[128:131], v[64:67], v[8:11]
	v_mfma_f32_16x16x32_bf16 v[24:27], v[128:131], v[230:233], v[24:27]
	s_waitcnt lgkmcnt(2)
	v_mfma_f32_16x16x32_bf16 v[8:11], v[132:135], v[68:71], v[8:11]
	v_mfma_f32_16x16x32_bf16 v[24:27], v[132:135], v[234:237], v[24:27]
	s_waitcnt lgkmcnt(1)
	v_mfma_f32_16x16x32_bf16 v[12:15], v[136:139], v[64:67], v[12:15]
	v_mfma_f32_16x16x32_bf16 v[28:31], v[136:139], v[230:233], v[28:31]
	s_waitcnt lgkmcnt(0)
; __device__ __forceinline__ void attn_phase(const Params& P, char* smem_raw) {
;     ...
; #pragma unroll
;       for (int reg = 0; reg < 4; ++reg) {
;         float mx = sacc[0][reg];
; #pragma unroll
;         for (int t8 = 1; t8 < 8; ++t8) mx = fmaxf(mx, sacc[t8][reg]);
;         mx = row16_max(mx);
;         const float mnew = fmaxf(mrow[reg], mx);
;         const float alpha = __builtin_amdgcn_exp2f(mrow[reg] - mnew);
;         mrow[reg] = mnew;
;         float rsum = 0.f;
; #pragma unroll
;         for (int t8 = 0; t8 < 8; ++t8) {
;           const float p = __builtin_amdgcn_exp2f(sacc[t8][reg] - mnew);
;           rsum += p;
;           sm_p[(wid * 16 + (lane_c >> 4) * 4 + reg) * 136 + t8 * 16 + (lane_c & 15)] = f2bf(p);
;         }
;         rsum = row16_sum(rsum);
;         lrow[reg] = lrow[reg] * alpha + rsum;
; #pragma unroll
;         for (int td = 0; td < 4; ++td) o[td][reg] *= alpha;
;       }
;       asm volatile("s_waitcnt lgkmcnt(0)" ::: "memory");
; #pragma unroll
;       for (int s4 = 0; s4 < 4; ++s4) {
;         const bf16x8 pf = *reinterpret_cast<const bf16x8*>(&sm_p[(wid * 16 + (lane_c & 15)) * 136 + s4 * 32 + (lane_c >> 4) * 8]);
; #pragma unroll
;         for (int td = 0; td < 4; ++td) {
;           const bf16x8 vf = *reinterpret_cast<const bf16x8*>(&sm_vt[(td * 16 + (lane_c & 15)) * 136 + s4 * 32 + (lane_c >> 4) * 8]);
;           o[td] = __builtin_amdgcn_mfma_f32_16x16x32_bf16(pf, vf, o[td], 0, 0, 0);
;         }
;       }
	v_mfma_f32_16x16x32_bf16 v[12:15], v[140:143], v[68:71], v[12:15]
	v_mfma_f32_16x16x32_bf16 v[28:31], v[140:143], v[234:237], v[28:31]
	s_nop 7
	v_max3_f32 v203, v0, v1, v2
	v_max3_f32 v206, v16, v17, v18
	v_max3_f32 v203, v203, v3, v4
	v_max3_f32 v206, v206, v19, v20
	v_max3_f32 v203, v203, v5, v6
	v_max3_f32 v206, v206, v21, v22
	v_max3_f32 v203, v203, v7, v8
	v_max3_f32 v206, v206, v23, v24
	v_max3_f32 v203, v203, v9, v10
	v_max3_f32 v206, v206, v25, v26
	v_max3_f32 v203, v203, v11, v12
	v_max3_f32 v206, v206, v27, v28
	v_max3_f32 v203, v203, v13, v14
	v_max3_f32 v206, v206, v29, v30
	v_max_f32_e32 v203, v203, v15
	v_max_f32_e32 v206, v206, v31
	v_mov_b32_e32 v205, v203
	v_mov_b32_e32 v207, v206
	s_nop 1
	v_permlane16_swap_b32_e32 v203, v205
	v_permlane16_swap_b32_e32 v206, v207
	v_max_f32_e32 v203, v203, v205
	v_max_f32_e32 v206, v206, v207
	v_mov_b32_e32 v205, v203
	v_mov_b32_e32 v207, v206
	s_nop 1
	v_permlane32_swap_b32_e32 v203, v205
	v_permlane32_swap_b32_e32 v206, v207
	v_max_f32_e32 v203, v203, v205
	v_max_f32_e32 v206, v206, v207
	v_max_f32_e32 v218, v200, v203
	v_max_f32_e32 v208, v246, v206
	v_sub_f32_e32 v220, v200, v218
	v_sub_f32_e32 v248, v246, v208
	v_mov_b32_e32 v219, v218
	v_mov_b32_e32 v209, v208
	v_exp_f32_e32 v220, v220
	v_exp_f32_e32 v248, v248
	v_mov_b32_e32 v200, v218
	v_mov_b32_e32 v246, v208
	v_pk_add_f32 v[0:1], v[0:1], v[218:219] neg_lo:[0,1] neg_hi:[0,1]
	v_pk_add_f32 v[16:17], v[16:17], v[208:209] neg_lo:[0,1] neg_hi:[0,1]
	v_pk_add_f32 v[2:3], v[2:3], v[218:219] neg_lo:[0,1] neg_hi:[0,1]
	v_pk_add_f32 v[18:19], v[18:19], v[208:209] neg_lo:[0,1] neg_hi:[0,1]
	v_pk_add_f32 v[4:5], v[4:5], v[218:219] neg_lo:[0,1] neg_hi:[0,1]
	v_pk_add_f32 v[20:21], v[20:21], v[208:209] neg_lo:[0,1] neg_hi:[0,1]
	v_pk_add_f32 v[6:7], v[6:7], v[218:219] neg_lo:[0,1] neg_hi:[0,1]
	v_pk_add_f32 v[22:23], v[22:23], v[208:209] neg_lo:[0,1] neg_hi:[0,1]
	v_pk_add_f32 v[8:9], v[8:9], v[218:219] neg_lo:[0,1] neg_hi:[0,1]
	v_pk_add_f32 v[24:25], v[24:25], v[208:209] neg_lo:[0,1] neg_hi:[0,1]
	v_pk_add_f32 v[10:11], v[10:11], v[218:219] neg_lo:[0,1] neg_hi:[0,1]
	v_pk_add_f32 v[26:27], v[26:27], v[208:209] neg_lo:[0,1] neg_hi:[0,1]
	v_pk_add_f32 v[12:13], v[12:13], v[218:219] neg_lo:[0,1] neg_hi:[0,1]
	v_pk_add_f32 v[28:29], v[28:29], v[208:209] neg_lo:[0,1] neg_hi:[0,1]
	v_pk_add_f32 v[14:15], v[14:15], v[218:219] neg_lo:[0,1] neg_hi:[0,1]
	v_pk_add_f32 v[30:31], v[30:31], v[208:209] neg_lo:[0,1] neg_hi:[0,1]
	v_exp_f32_e32 v0, v0
	s_waitcnt vmcnt(0)
	v_exp_f32_e32 v1, v1
	ds_write_b128 v150, v[80:83] offset:32768
	v_exp_f32_e32 v2, v2
	ds_write_b128 v150, v[84:87] offset:36864
	v_exp_f32_e32 v3, v3
	ds_write_b128 v150, v[88:91] offset:40960
	v_exp_f32_e32 v4, v4
	ds_write_b128 v150, v[92:95] offset:45056
	v_exp_f32_e32 v5, v5
	ds_write_b64 v151, v[96:97] offset:32768
	v_exp_f32_e32 v6, v6
	ds_write_b64 v229, v[98:99] offset:32768
	v_exp_f32_e32 v7, v7
	ds_write_b64 v151, v[100:101] offset:36864
	v_exp_f32_e32 v8, v8
	ds_write_b64 v229, v[102:103] offset:36864
	v_exp_f32_e32 v9, v9
	ds_write_b64 v151, v[104:105] offset:40960
	v_exp_f32_e32 v10, v10
	ds_write_b64 v229, v[106:107] offset:40960
	v_exp_f32_e32 v11, v11
	ds_write_b64 v151, v[108:109] offset:45056
	v_exp_f32_e32 v12, v12
	ds_write_b64 v229, v[110:111] offset:45056
	v_exp_f32_e32 v13, v13
	s_add_u32 s100, s12, 0x240000
	v_exp_f32_e32 v14, v14
	s_addc_u32 s101, s13, 0
	v_exp_f32_e32 v15, v15
	s_add_u32 s0, s14, 0x300
	v_exp_f32_e32 v16, v16
	s_addc_u32 s1, s15, 0
	v_exp_f32_e32 v17, v17
	global_load_dwordx4 v[80:83], v154, s[100:101] offset:2048
	v_exp_f32_e32 v18, v18
	global_load_dwordx4 v[96:99], v158, s[0:1]
	v_exp_f32_e32 v19, v19
	global_load_dwordx4 v[84:87], v155, s[100:101] offset:2048
	v_exp_f32_e32 v20, v20
	global_load_dwordx4 v[100:103], v159, s[0:1]
	v_exp_f32_e32 v21, v21
	global_load_dwordx4 v[88:91], v156, s[100:101] offset:2048
	v_exp_f32_e32 v22, v22
	global_load_dwordx4 v[104:107], v160, s[0:1]
	v_exp_f32_e32 v23, v23
	global_load_dwordx4 v[92:95], v157, s[100:101] offset:2048
	v_exp_f32_e32 v24, v24
	global_load_dwordx4 v[108:111], v161, s[0:1]
	v_exp_f32_e32 v25, v25
	v_exp_f32_e32 v26, v26
	v_exp_f32_e32 v27, v27
	v_exp_f32_e32 v28, v28
	v_exp_f32_e32 v29, v29
	v_exp_f32_e32 v30, v30
	v_exp_f32_e32 v31, v31
	ds_read_b128 v[112:115], v146 offset:0
	ds_read_b128 v[116:119], v146 offset:4096
	ds_read_b128 v[120:123], v146 offset:8192
	ds_read_b128 v[124:127], v146 offset:12288
	ds_read_b128 v[128:131], v147 offset:0
	ds_read_b128 v[132:135], v147 offset:4096
	ds_read_b128 v[136:139], v147 offset:8192
	ds_read_b128 v[140:143], v147 offset:12288
	v_mov_b32_e32 v221, v220
	v_mov_b32_e32 v249, v248
	v_pk_add_f32 v[222:223], v[0:1], v[2:3]
	v_pk_add_f32 v[250:251], v[16:17], v[18:19]
	v_pk_add_f32 v[222:223], v[222:223], v[4:5]
	v_pk_add_f32 v[250:251], v[250:251], v[20:21]
	v_pk_add_f32 v[222:223], v[222:223], v[6:7]
	v_pk_add_f32 v[250:251], v[250:251], v[22:23]
	v_pk_add_f32 v[222:223], v[222:223], v[8:9]
	v_pk_add_f32 v[250:251], v[250:251], v[24:25]
	v_pk_add_f32 v[222:223], v[222:223], v[10:11]
	v_pk_add_f32 v[250:251], v[250:251], v[26:27]
	v_pk_add_f32 v[222:223], v[222:223], v[12:13]
	v_pk_add_f32 v[250:251], v[250:251], v[28:29]
	v_pk_add_f32 v[222:223], v[222:223], v[14:15]
	v_pk_add_f32 v[250:251], v[250:251], v[30:31]
	v_pk_mul_f32 v[32:33], v[32:33], v[220:221]
	v_pk_mul_f32 v[34:35], v[34:35], v[220:221]
	v_pk_mul_f32 v[176:177], v[176:177], v[248:249]
	v_pk_mul_f32 v[178:179], v[178:179], v[248:249]
	v_pk_mul_f32 v[36:37], v[36:37], v[220:221]
	v_pk_mul_f32 v[38:39], v[38:39], v[220:221]
	v_pk_mul_f32 v[180:181], v[180:181], v[248:249]
	v_pk_mul_f32 v[182:183], v[182:183], v[248:249]
	v_pk_mul_f32 v[40:41], v[40:41], v[220:221]
	v_pk_mul_f32 v[42:43], v[42:43], v[220:221]
	v_pk_mul_f32 v[192:193], v[192:193], v[248:249]
	v_pk_mul_f32 v[194:195], v[194:195], v[248:249]
	v_pk_mul_f32 v[44:45], v[44:45], v[220:221]
	v_pk_mul_f32 v[46:47], v[46:47], v[220:221]
	v_pk_mul_f32 v[196:197], v[196:197], v[248:249]
	v_pk_mul_f32 v[198:199], v[198:199], v[248:249]
	v_add_f32_e32 v203, v222, v223
	v_add_f32_e32 v206, v250, v251
	v_fma_f32 v201, v201, v220, v203
	v_fma_f32 v247, v247, v248, v206
	v_cvt_pk_bf16_f32 v48, v0, v1
	v_cvt_pk_bf16_f32 v49, v2, v3
	v_cvt_pk_bf16_f32 v50, v4, v5
	v_cvt_pk_bf16_f32 v51, v6, v7
	v_cvt_pk_bf16_f32 v56, v16, v17
	v_cvt_pk_bf16_f32 v57, v18, v19
	v_cvt_pk_bf16_f32 v58, v20, v21
	v_cvt_pk_bf16_f32 v59, v22, v23
	v_cvt_pk_bf16_f32 v52, v8, v9
	v_cvt_pk_bf16_f32 v53, v10, v11
	v_cvt_pk_bf16_f32 v54, v12, v13
	v_cvt_pk_bf16_f32 v55, v14, v15
	v_cvt_pk_bf16_f32 v60, v24, v25
	v_cvt_pk_bf16_f32 v61, v26, v27
	v_cvt_pk_bf16_f32 v62, v28, v29
	v_cvt_pk_bf16_f32 v63, v30, v31
	s_waitcnt lgkmcnt(7)
; __device__ __forceinline__ void attn_phase(const Params& P, char* smem_raw) {
;     ...
;       if (ck < 4) {
;         const float* rb0 = sm_rpb + (rs + ck * 2 - r + 7) * 31;
; #pragma unroll
;         for (int t8 = 0; t8 < 8; ++t8)
; #pragma unroll
;           for (int reg = 0; reg < 4; ++reg)
;             sacc[t8][reg] += rb0[(t8 >> 2) * 31 + dco[reg][t8 & 3]];
;     ...
; #pragma unroll
;       for (int s4 = 0; s4 < 4; ++s4) {
;         const bf16x8 pf = *reinterpret_cast<const bf16x8*>(&sm_p[(wid * 16 + (lane_c & 15)) * 136 + s4 * 32 + (lane_c >> 4) * 8]);
; #pragma unroll
;         for (int td = 0; td < 4; ++td) {
;           const bf16x8 vf = *reinterpret_cast<const bf16x8*>(&sm_vt[(td * 16 + (lane_c & 15)) * 136 + s4 * 32 + (lane_c >> 4) * 8]);
;           o[td] = __builtin_amdgcn_mfma_f32_16x16x32_bf16(pf, vf, o[td], 0, 0, 0);
;         }
;       }
	v_mfma_f32_16x16x32_bf16 v[32:35], v[112:115], v[48:51], v[32:35]
	v_mfma_f32_16x16x32_bf16 v[176:179], v[112:115], v[56:59], v[176:179]
	s_waitcnt lgkmcnt(6)
	v_mfma_f32_16x16x32_bf16 v[36:39], v[116:119], v[48:51], v[36:39]
	v_mfma_f32_16x16x32_bf16 v[180:183], v[116:119], v[56:59], v[180:183]
	s_waitcnt lgkmcnt(5)
	v_mfma_f32_16x16x32_bf16 v[40:43], v[120:123], v[48:51], v[40:43]
	v_mfma_f32_16x16x32_bf16 v[192:195], v[120:123], v[56:59], v[192:195]
	s_waitcnt lgkmcnt(4)
	v_mfma_f32_16x16x32_bf16 v[44:47], v[124:127], v[48:51], v[44:47]
	v_mfma_f32_16x16x32_bf16 v[196:199], v[124:127], v[56:59], v[196:199]
	s_waitcnt lgkmcnt(3)
	v_mfma_f32_16x16x32_bf16 v[32:35], v[128:131], v[52:55], v[32:35]
	v_mfma_f32_16x16x32_bf16 v[176:179], v[128:131], v[60:63], v[176:179]
	s_waitcnt lgkmcnt(2)
	v_mfma_f32_16x16x32_bf16 v[36:39], v[132:135], v[52:55], v[36:39]
	v_mfma_f32_16x16x32_bf16 v[180:183], v[132:135], v[60:63], v[180:183]
	s_waitcnt lgkmcnt(1)
	v_mfma_f32_16x16x32_bf16 v[40:43], v[136:139], v[52:55], v[40:43]
	v_mfma_f32_16x16x32_bf16 v[192:195], v[136:139], v[60:63], v[192:195]
	s_waitcnt lgkmcnt(0)
	v_mfma_f32_16x16x32_bf16 v[44:47], v[140:143], v[52:55], v[44:47]
	v_mfma_f32_16x16x32_bf16 v[196:199], v[140:143], v[60:63], v[196:199]
	ds_read_b32 v0, v184 offset:896
	ds_read_b32 v1, v185 offset:896
	ds_read_b32 v2, v186 offset:896
	ds_read_b32 v3, v187 offset:896
	ds_read_b32 v4, v184 offset:1024
	ds_read_b32 v5, v185 offset:1024
	ds_read_b32 v6, v186 offset:1024
	ds_read_b32 v7, v187 offset:1024
	ds_read_b32 v8, v188 offset:896
	ds_read_b32 v9, v189 offset:896
	ds_read_b32 v10, v190 offset:896
	ds_read_b32 v11, v191 offset:896
	ds_read_b32 v12, v188 offset:1024
	ds_read_b32 v13, v189 offset:1024
	ds_read_b32 v14, v190 offset:1024
	ds_read_b32 v15, v191 offset:1024
	ds_read_b32 v16, v184 offset:768
	ds_read_b32 v17, v185 offset:768
	ds_read_b32 v18, v186 offset:768
	ds_read_b32 v19, v187 offset:768
	ds_read_b32 v20, v184 offset:896
	ds_read_b32 v21, v185 offset:896
	ds_read_b32 v22, v186 offset:896
	ds_read_b32 v23, v187 offset:896
	ds_read_b32 v24, v188 offset:768
	ds_read_b32 v25, v189 offset:768
	ds_read_b32 v26, v190 offset:768
	ds_read_b32 v27, v191 offset:768
	ds_read_b32 v28, v188 offset:896
	ds_read_b32 v29, v189 offset:896
	ds_read_b32 v30, v190 offset:896
	ds_read_b32 v31, v191 offset:896
	s_waitcnt lgkmcnt(0)
	s_barrier
	ds_read_b128 v[112:115], v144 offset:32768
	ds_read_b128 v[116:119], v145 offset:32768
	ds_read_b128 v[120:123], v144 offset:40960
	ds_read_b128 v[124:127], v145 offset:40960
	ds_read_b128 v[128:131], v144 offset:34816
	ds_read_b128 v[132:135], v145 offset:34816
	ds_read_b128 v[136:139], v144 offset:43008
	ds_read_b128 v[140:143], v145 offset:43008
	s_waitcnt lgkmcnt(7)
	v_mfma_f32_16x16x32_bf16 v[0:3], v[112:115], v[64:67], v[0:3]
	v_mfma_f32_16x16x32_bf16 v[16:19], v[112:115], v[230:233], v[16:19]
	s_waitcnt lgkmcnt(6)
	v_mfma_f32_16x16x32_bf16 v[0:3], v[116:119], v[68:71], v[0:3]
	v_mfma_f32_16x16x32_bf16 v[16:19], v[116:119], v[234:237], v[16:19]
	s_waitcnt lgkmcnt(5)
	v_mfma_f32_16x16x32_bf16 v[4:7], v[120:123], v[64:67], v[4:7]
	v_mfma_f32_16x16x32_bf16 v[20:23], v[120:123], v[230:233], v[20:23]
	s_waitcnt lgkmcnt(4)
	v_mfma_f32_16x16x32_bf16 v[4:7], v[124:127], v[68:71], v[4:7]
	v_mfma_f32_16x16x32_bf16 v[20:23], v[124:127], v[234:237], v[20:23]
	s_waitcnt lgkmcnt(3)
	v_mfma_f32_16x16x32_bf16 v[8:11], v[128:131], v[64:67], v[8:11]
	v_mfma_f32_16x16x32_bf16 v[24:27], v[128:131], v[230:233], v[24:27]
	s_waitcnt lgkmcnt(2)
	v_mfma_f32_16x16x32_bf16 v[8:11], v[132:135], v[68:71], v[8:11]
	v_mfma_f32_16x16x32_bf16 v[24:27], v[132:135], v[234:237], v[24:27]
	s_waitcnt lgkmcnt(1)
	v_mfma_f32_16x16x32_bf16 v[12:15], v[136:139], v[64:67], v[12:15]
	v_mfma_f32_16x16x32_bf16 v[28:31], v[136:139], v[230:233], v[28:31]
	s_waitcnt lgkmcnt(0)
	v_mfma_f32_16x16x32_bf16 v[12:15], v[140:143], v[68:71], v[12:15]
	v_mfma_f32_16x16x32_bf16 v[28:31], v[140:143], v[234:237], v[28:31]
	s_nop 7
	v_max3_f32 v203, v0, v1, v2
	v_max3_f32 v206, v16, v17, v18
	v_max3_f32 v203, v203, v3, v4
	v_max3_f32 v206, v206, v19, v20
	v_max3_f32 v203, v203, v5, v6
	v_max3_f32 v206, v206, v21, v22
	v_max3_f32 v203, v203, v7, v8
	v_max3_f32 v206, v206, v23, v24
	v_max3_f32 v203, v203, v9, v10
	v_max3_f32 v206, v206, v25, v26
	v_max3_f32 v203, v203, v11, v12
	v_max3_f32 v206, v206, v27, v28
	v_max3_f32 v203, v203, v13, v14
	v_max3_f32 v206, v206, v29, v30
	v_max_f32_e32 v203, v203, v15
	v_max_f32_e32 v206, v206, v31
	v_mov_b32_e32 v205, v203
	v_mov_b32_e32 v207, v206
	s_nop 1
	v_permlane16_swap_b32_e32 v203, v205
	v_permlane16_swap_b32_e32 v206, v207
	v_max_f32_e32 v203, v203, v205
	v_max_f32_e32 v206, v206, v207
	v_mov_b32_e32 v205, v203
	v_mov_b32_e32 v207, v206
	s_nop 1
	v_permlane32_swap_b32_e32 v203, v205
	v_permlane32_swap_b32_e32 v206, v207
	v_max_f32_e32 v203, v203, v205
	v_max_f32_e32 v206, v206, v207
	v_max_f32_e32 v218, v200, v203
	v_max_f32_e32 v208, v246, v206
	v_sub_f32_e32 v220, v200, v218
	v_sub_f32_e32 v248, v246, v208
	v_mov_b32_e32 v219, v218
	v_mov_b32_e32 v209, v208
	v_exp_f32_e32 v220, v220
	v_exp_f32_e32 v248, v248
	v_mov_b32_e32 v200, v218
	v_mov_b32_e32 v246, v208
	v_pk_add_f32 v[0:1], v[0:1], v[218:219] neg_lo:[0,1] neg_hi:[0,1]
	v_pk_add_f32 v[16:17], v[16:17], v[208:209] neg_lo:[0,1] neg_hi:[0,1]
	v_pk_add_f32 v[2:3], v[2:3], v[218:219] neg_lo:[0,1] neg_hi:[0,1]
	v_pk_add_f32 v[18:19], v[18:19], v[208:209] neg_lo:[0,1] neg_hi:[0,1]
	v_pk_add_f32 v[4:5], v[4:5], v[218:219] neg_lo:[0,1] neg_hi:[0,1]
	v_pk_add_f32 v[20:21], v[20:21], v[208:209] neg_lo:[0,1] neg_hi:[0,1]
	v_pk_add_f32 v[6:7], v[6:7], v[218:219] neg_lo:[0,1] neg_hi:[0,1]
	v_pk_add_f32 v[22:23], v[22:23], v[208:209] neg_lo:[0,1] neg_hi:[0,1]
	v_pk_add_f32 v[8:9], v[8:9], v[218:219] neg_lo:[0,1] neg_hi:[0,1]
	v_pk_add_f32 v[24:25], v[24:25], v[208:209] neg_lo:[0,1] neg_hi:[0,1]
	v_pk_add_f32 v[10:11], v[10:11], v[218:219] neg_lo:[0,1] neg_hi:[0,1]
	v_pk_add_f32 v[26:27], v[26:27], v[208:209] neg_lo:[0,1] neg_hi:[0,1]
	v_pk_add_f32 v[12:13], v[12:13], v[218:219] neg_lo:[0,1] neg_hi:[0,1]
	v_pk_add_f32 v[28:29], v[28:29], v[208:209] neg_lo:[0,1] neg_hi:[0,1]
	v_pk_add_f32 v[14:15], v[14:15], v[218:219] neg_lo:[0,1] neg_hi:[0,1]
	v_pk_add_f32 v[30:31], v[30:31], v[208:209] neg_lo:[0,1] neg_hi:[0,1]
	v_exp_f32_e32 v0, v0
	s_waitcnt vmcnt(0)
; __device__ __forceinline__ void attn_phase(const Params& P, char* smem_raw) {
;     ...
;       if (ck < 4) {
;         const float* rb0 = sm_rpb + (rs + ck * 2 - r + 7) * 31;
; #pragma unroll
;         for (int t8 = 0; t8 < 8; ++t8)
; #pragma unroll
;           for (int reg = 0; reg < 4; ++reg)
;             sacc[t8][reg] += rb0[(t8 >> 2) * 31 + dco[reg][t8 & 3]];
;     ...
; #pragma unroll
;       for (int reg = 0; reg < 4; ++reg) {
;         float mx = sacc[0][reg];
; #pragma unroll
;         for (int t8 = 1; t8 < 8; ++t8) mx = fmaxf(mx, sacc[t8][reg]);
;         mx = row16_max(mx);
;         const float mnew = fmaxf(mrow[reg], mx);
;         const float alpha = __builtin_amdgcn_exp2f(mrow[reg] - mnew);
;         mrow[reg] = mnew;
;         float rsum = 0.f;
; #pragma unroll
;         for (int t8 = 0; t8 < 8; ++t8) {
;           const float p = __builtin_amdgcn_exp2f(sacc[t8][reg] - mnew);
;           rsum += p;
;           sm_p[(wid * 16 + (lane_c >> 4) * 4 + reg) * 136 + t8 * 16 + (lane_c & 15)] = f2bf(p);
;         }
;         rsum = row16_sum(rsum);
;         lrow[reg] = lrow[reg] * alpha + rsum;
; #pragma unroll
;         for (int td = 0; td < 4; ++td) o[td][reg] *= alpha;
;       }
;       asm volatile("s_waitcnt lgkmcnt(0)" ::: "memory");
; #pragma unroll
;       for (int s4 = 0; s4 < 4; ++s4) {
;         const bf16x8 pf = *reinterpret_cast<const bf16x8*>(&sm_p[(wid * 16 + (lane_c & 15)) * 136 + s4 * 32 + (lane_c >> 4) * 8]);
; #pragma unroll
;         for (int td = 0; td < 4; ++td) {
;           const bf16x8 vf = *reinterpret_cast<const bf16x8*>(&sm_vt[(td * 16 + (lane_c & 15)) * 136 + s4 * 32 + (lane_c >> 4) * 8]);
;           o[td] = __builtin_amdgcn_mfma_f32_16x16x32_bf16(pf, vf, o[td], 0, 0, 0);
;         }
;       }
	v_exp_f32_e32 v1, v1
	ds_write_b128 v150, v[80:83] offset:0
	v_exp_f32_e32 v2, v2
	ds_write_b128 v150, v[84:87] offset:4096
	v_exp_f32_e32 v3, v3
	ds_write_b128 v150, v[88:91] offset:8192
	v_exp_f32_e32 v4, v4
	ds_write_b128 v150, v[92:95] offset:12288
	v_exp_f32_e32 v5, v5
	ds_write_b64 v151, v[96:97] offset:0
	v_exp_f32_e32 v6, v6
	ds_write_b64 v229, v[98:99] offset:0
	v_exp_f32_e32 v7, v7
	ds_write_b64 v151, v[100:101] offset:4096
	v_exp_f32_e32 v8, v8
	ds_write_b64 v229, v[102:103] offset:4096
	v_exp_f32_e32 v9, v9
	ds_write_b64 v151, v[104:105] offset:8192
	v_exp_f32_e32 v10, v10
	ds_write_b64 v229, v[106:107] offset:8192
	v_exp_f32_e32 v11, v11
	ds_write_b64 v151, v[108:109] offset:12288
	v_exp_f32_e32 v12, v12
	ds_write_b64 v229, v[110:111] offset:12288
	v_exp_f32_e32 v13, v13
	s_add_u32 s100, s12, s20
	v_exp_f32_e32 v14, v14
	s_addc_u32 s101, s13, 0
	v_exp_f32_e32 v15, v15
	s_add_u32 s0, s14, s21
	v_exp_f32_e32 v16, v16
	s_addc_u32 s1, s15, 0
	v_exp_f32_e32 v17, v17
	global_load_dwordx4 v[80:83], v154, s[100:101] offset:2048
	v_exp_f32_e32 v18, v18
	global_load_dwordx4 v[96:99], v158, s[0:1]
	v_exp_f32_e32 v19, v19
	global_load_dwordx4 v[84:87], v155, s[100:101] offset:2048
	v_exp_f32_e32 v20, v20
	global_load_dwordx4 v[100:103], v159, s[0:1]
	v_exp_f32_e32 v21, v21
	global_load_dwordx4 v[88:91], v156, s[100:101] offset:2048
	v_exp_f32_e32 v22, v22
	global_load_dwordx4 v[104:107], v160, s[0:1]
	v_exp_f32_e32 v23, v23
	global_load_dwordx4 v[92:95], v157, s[100:101] offset:2048
	v_exp_f32_e32 v24, v24
	global_load_dwordx4 v[108:111], v161, s[0:1]
	v_exp_f32_e32 v25, v25
	v_exp_f32_e32 v26, v26
	v_exp_f32_e32 v27, v27
	v_exp_f32_e32 v28, v28
	v_exp_f32_e32 v29, v29
	v_exp_f32_e32 v30, v30
	v_exp_f32_e32 v31, v31
	ds_read_b128 v[112:115], v146 offset:32768
	ds_read_b128 v[116:119], v146 offset:36864
	ds_read_b128 v[120:123], v146 offset:40960
	ds_read_b128 v[124:127], v146 offset:45056
	ds_read_b128 v[128:131], v147 offset:32768
	ds_read_b128 v[132:135], v147 offset:36864
	ds_read_b128 v[136:139], v147 offset:40960
	ds_read_b128 v[140:143], v147 offset:45056
	v_mov_b32_e32 v221, v220
	v_mov_b32_e32 v249, v248
	v_pk_add_f32 v[222:223], v[0:1], v[2:3]
	v_pk_add_f32 v[250:251], v[16:17], v[18:19]
	v_pk_add_f32 v[222:223], v[222:223], v[4:5]
	v_pk_add_f32 v[250:251], v[250:251], v[20:21]
	v_pk_add_f32 v[222:223], v[222:223], v[6:7]
	v_pk_add_f32 v[250:251], v[250:251], v[22:23]
	v_pk_add_f32 v[222:223], v[222:223], v[8:9]
	v_pk_add_f32 v[250:251], v[250:251], v[24:25]
	v_pk_add_f32 v[222:223], v[222:223], v[10:11]
	v_pk_add_f32 v[250:251], v[250:251], v[26:27]
	v_pk_add_f32 v[222:223], v[222:223], v[12:13]
	v_pk_add_f32 v[250:251], v[250:251], v[28:29]
	v_pk_add_f32 v[222:223], v[222:223], v[14:15]
	v_pk_add_f32 v[250:251], v[250:251], v[30:31]
	v_pk_mul_f32 v[32:33], v[32:33], v[220:221]
	v_pk_mul_f32 v[34:35], v[34:35], v[220:221]
	v_pk_mul_f32 v[176:177], v[176:177], v[248:249]
	v_pk_mul_f32 v[178:179], v[178:179], v[248:249]
	v_pk_mul_f32 v[36:37], v[36:37], v[220:221]
	v_pk_mul_f32 v[38:39], v[38:39], v[220:221]
	v_pk_mul_f32 v[180:181], v[180:181], v[248:249]
	v_pk_mul_f32 v[182:183], v[182:183], v[248:249]
	v_pk_mul_f32 v[40:41], v[40:41], v[220:221]
	v_pk_mul_f32 v[42:43], v[42:43], v[220:221]
	v_pk_mul_f32 v[192:193], v[192:193], v[248:249]
	v_pk_mul_f32 v[194:195], v[194:195], v[248:249]
	v_pk_mul_f32 v[44:45], v[44:45], v[220:221]
	v_pk_mul_f32 v[46:47], v[46:47], v[220:221]
	v_pk_mul_f32 v[196:197], v[196:197], v[248:249]
	v_pk_mul_f32 v[198:199], v[198:199], v[248:249]
	v_add_f32_e32 v203, v222, v223
	v_add_f32_e32 v206, v250, v251
	v_fma_f32 v201, v201, v220, v203
	v_fma_f32 v247, v247, v248, v206
	v_cvt_pk_bf16_f32 v48, v0, v1
	v_cvt_pk_bf16_f32 v49, v2, v3
	v_cvt_pk_bf16_f32 v50, v4, v5
	v_cvt_pk_bf16_f32 v51, v6, v7
	v_cvt_pk_bf16_f32 v56, v16, v17
	v_cvt_pk_bf16_f32 v57, v18, v19
	v_cvt_pk_bf16_f32 v58, v20, v21
	v_cvt_pk_bf16_f32 v59, v22, v23
	v_cvt_pk_bf16_f32 v52, v8, v9
	v_cvt_pk_bf16_f32 v53, v10, v11
	v_cvt_pk_bf16_f32 v54, v12, v13
	v_cvt_pk_bf16_f32 v55, v14, v15
	v_cvt_pk_bf16_f32 v60, v24, v25
	v_cvt_pk_bf16_f32 v61, v26, v27
	v_cvt_pk_bf16_f32 v62, v28, v29
	v_cvt_pk_bf16_f32 v63, v30, v31
	s_waitcnt lgkmcnt(7)
	v_mfma_f32_16x16x32_bf16 v[32:35], v[112:115], v[48:51], v[32:35]
	v_mfma_f32_16x16x32_bf16 v[176:179], v[112:115], v[56:59], v[176:179]
	s_waitcnt lgkmcnt(6)
	v_mfma_f32_16x16x32_bf16 v[36:39], v[116:119], v[48:51], v[36:39]
	v_mfma_f32_16x16x32_bf16 v[180:183], v[116:119], v[56:59], v[180:183]
	s_waitcnt lgkmcnt(5)
	v_mfma_f32_16x16x32_bf16 v[40:43], v[120:123], v[48:51], v[40:43]
	v_mfma_f32_16x16x32_bf16 v[192:195], v[120:123], v[56:59], v[192:195]
	s_waitcnt lgkmcnt(4)
	v_mfma_f32_16x16x32_bf16 v[44:47], v[124:127], v[48:51], v[44:47]
	v_mfma_f32_16x16x32_bf16 v[196:199], v[124:127], v[56:59], v[196:199]
	s_waitcnt lgkmcnt(3)
	v_mfma_f32_16x16x32_bf16 v[32:35], v[128:131], v[52:55], v[32:35]
	v_mfma_f32_16x16x32_bf16 v[176:179], v[128:131], v[60:63], v[176:179]
	s_waitcnt lgkmcnt(2)
	v_mfma_f32_16x16x32_bf16 v[36:39], v[132:135], v[52:55], v[36:39]
	v_mfma_f32_16x16x32_bf16 v[180:183], v[132:135], v[60:63], v[180:183]
	s_waitcnt lgkmcnt(1)
	v_mfma_f32_16x16x32_bf16 v[40:43], v[136:139], v[52:55], v[40:43]
	v_mfma_f32_16x16x32_bf16 v[192:195], v[136:139], v[60:63], v[192:195]
	s_waitcnt lgkmcnt(0)
	v_mfma_f32_16x16x32_bf16 v[44:47], v[140:143], v[52:55], v[44:47]
	v_mfma_f32_16x16x32_bf16 v[196:199], v[140:143], v[60:63], v[196:199]
	ds_read_b32 v0, v184 offset:1152
	ds_read_b32 v1, v185 offset:1152
	ds_read_b32 v2, v186 offset:1152
	ds_read_b32 v3, v187 offset:1152
	ds_read_b32 v4, v184 offset:1280
	ds_read_b32 v5, v185 offset:1280
	ds_read_b32 v6, v186 offset:1280
	ds_read_b32 v7, v187 offset:1280
	ds_read_b32 v8, v188 offset:1152
	ds_read_b32 v9, v189 offset:1152
	ds_read_b32 v10, v190 offset:1152
	ds_read_b32 v11, v191 offset:1152
	ds_read_b32 v12, v188 offset:1280
	ds_read_b32 v13, v189 offset:1280
	ds_read_b32 v14, v190 offset:1280
	ds_read_b32 v15, v191 offset:1280
	ds_read_b32 v16, v184 offset:1024
	ds_read_b32 v17, v185 offset:1024
	ds_read_b32 v18, v186 offset:1024
	ds_read_b32 v19, v187 offset:1024
	ds_read_b32 v20, v184 offset:1152
	ds_read_b32 v21, v185 offset:1152
	ds_read_b32 v22, v186 offset:1152
	ds_read_b32 v23, v187 offset:1152
	ds_read_b32 v24, v188 offset:1024
	ds_read_b32 v25, v189 offset:1024
	ds_read_b32 v26, v190 offset:1024
	ds_read_b32 v27, v191 offset:1024
	ds_read_b32 v28, v188 offset:1152
	ds_read_b32 v29, v189 offset:1152
	ds_read_b32 v30, v190 offset:1152
	ds_read_b32 v31, v191 offset:1152
	s_waitcnt lgkmcnt(0)
	s_barrier
; __device__ __forceinline__ void attn_phase(const Params& P, char* smem_raw) {
;     ...
;       f32x4 sacc[8];
; #pragma unroll
;       for (int t8 = 0; t8 < 8; ++t8) sacc[t8] = f32x4{0.f, 0.f, 0.f, 0.f};
; #pragma unroll
;       for (int s = 0; s < 2; ++s)
; #pragma unroll
;         for (int t8 = 0; t8 < 8; ++t8) {
;           const bf16x8 kf = *reinterpret_cast<const bf16x8*>(&sm_k[(t8 * 16 + (lane_c & 15)) * LDSS + s * 32 + (lane_c >> 4) * 8]);
;           sacc[t8] = __builtin_amdgcn_mfma_f32_16x16x32_bf16(qf[s], kf, sacc[t8], 0, 0, 0);
;         }
;       if (ck < 5) {
;         ATT_ISSUE(t, ck + 1)
;       } else if (t + VGRID < 8192) {
;         ATT_ISSUE(t + VGRID, 0)
;         ATT_QLOAD(t + VGRID)
;       }
;       if (ck < 4) {
;         const float* rb0 = sm_rpb + (rs + ck * 2 - r + 7) * 31;
; #pragma unroll
;         for (int t8 = 0; t8 < 8; ++t8)
; #pragma unroll
;           for (int reg = 0; reg < 4; ++reg)
;             sacc[t8][reg] += rb0[(t8 >> 2) * 31 + dco[reg][t8 & 3]];
;       }
; #pragma unroll
;       for (int reg = 0; reg < 4; ++reg) {
;         float mx = sacc[0][reg];
; #pragma unroll
;         for (int t8 = 1; t8 < 8; ++t8) mx = fmaxf(mx, sacc[t8][reg]);
;         mx = row16_max(mx);
;         const float mnew = fmaxf(mrow[reg], mx);
;         const float alpha = __builtin_amdgcn_exp2f(mrow[reg] - mnew);
;         mrow[reg] = mnew;
;         float rsum = 0.f;
; #pragma unroll
;         for (int t8 = 0; t8 < 8; ++t8) {
;           const float p = __builtin_amdgcn_exp2f(sacc[t8][reg] - mnew);
;           rsum += p;
;           sm_p[(wid * 16 + (lane_c >> 4) * 4 + reg) * 136 + t8 * 16 + (lane_c & 15)] = f2bf(p);
;         }
;         rsum = row16_sum(rsum);
;         lrow[reg] = lrow[reg] * alpha + rsum;
; #pragma unroll
;         for (int td = 0; td < 4; ++td) o[td][reg] *= alpha;
;       }
;       asm volatile("s_waitcnt lgkmcnt(0)" ::: "memory");
; #pragma unroll
;       for (int s4 = 0; s4 < 4; ++s4) {
;         const bf16x8 pf = *reinterpret_cast<const bf16x8*>(&sm_p[(wid * 16 + (lane_c & 15)) * 136 + s4 * 32 + (lane_c >> 4) * 8]);
; #pragma unroll
;         for (int td = 0; td < 4; ++td) {
;           const bf16x8 vf = *reinterpret_cast<const bf16x8*>(&sm_vt[(td * 16 + (lane_c & 15)) * 136 + s4 * 32 + (lane_c >> 4) * 8]);
;           o[td] = __builtin_amdgcn_mfma_f32_16x16x32_bf16(pf, vf, o[td], 0, 0, 0);
;         }
;       }
	ds_read_b128 v[112:115], v144 offset:0
	ds_read_b128 v[116:119], v145 offset:0
	ds_read_b128 v[120:123], v144 offset:8192
	ds_read_b128 v[124:127], v145 offset:8192
	ds_read_b128 v[128:131], v144 offset:2048
	ds_read_b128 v[132:135], v145 offset:2048
	ds_read_b128 v[136:139], v144 offset:10240
	ds_read_b128 v[140:143], v145 offset:10240
	s_waitcnt lgkmcnt(7)
	v_mfma_f32_16x16x32_bf16 v[0:3], v[112:115], v[64:67], v[0:3]
	v_mfma_f32_16x16x32_bf16 v[16:19], v[112:115], v[230:233], v[16:19]
	s_waitcnt lgkmcnt(6)
	v_mfma_f32_16x16x32_bf16 v[0:3], v[116:119], v[68:71], v[0:3]
	v_mfma_f32_16x16x32_bf16 v[16:19], v[116:119], v[234:237], v[16:19]
	s_waitcnt lgkmcnt(5)
	v_mfma_f32_16x16x32_bf16 v[4:7], v[120:123], v[64:67], v[4:7]
	v_mfma_f32_16x16x32_bf16 v[20:23], v[120:123], v[230:233], v[20:23]
	s_waitcnt lgkmcnt(4)
	v_mfma_f32_16x16x32_bf16 v[4:7], v[124:127], v[68:71], v[4:7]
	v_mfma_f32_16x16x32_bf16 v[20:23], v[124:127], v[234:237], v[20:23]
	s_waitcnt lgkmcnt(3)
	v_mfma_f32_16x16x32_bf16 v[8:11], v[128:131], v[64:67], v[8:11]
	v_mfma_f32_16x16x32_bf16 v[24:27], v[128:131], v[230:233], v[24:27]
	s_waitcnt lgkmcnt(2)
	v_mfma_f32_16x16x32_bf16 v[8:11], v[132:135], v[68:71], v[8:11]
	v_mfma_f32_16x16x32_bf16 v[24:27], v[132:135], v[234:237], v[24:27]
	s_waitcnt lgkmcnt(1)
	v_mfma_f32_16x16x32_bf16 v[12:15], v[136:139], v[64:67], v[12:15]
	v_mfma_f32_16x16x32_bf16 v[28:31], v[136:139], v[230:233], v[28:31]
	s_waitcnt lgkmcnt(0)
	v_mfma_f32_16x16x32_bf16 v[12:15], v[140:143], v[68:71], v[12:15]
	v_mfma_f32_16x16x32_bf16 v[28:31], v[140:143], v[234:237], v[28:31]
	s_nop 7
	v_max3_f32 v203, v0, v1, v2
	v_max3_f32 v206, v16, v17, v18
	v_max3_f32 v203, v203, v3, v4
	v_max3_f32 v206, v206, v19, v20
	v_max3_f32 v203, v203, v5, v6
	v_max3_f32 v206, v206, v21, v22
	v_max3_f32 v203, v203, v7, v8
	v_max3_f32 v206, v206, v23, v24
	v_max3_f32 v203, v203, v9, v10
	v_max3_f32 v206, v206, v25, v26
	v_max3_f32 v203, v203, v11, v12
	v_max3_f32 v206, v206, v27, v28
	v_max3_f32 v203, v203, v13, v14
	v_max3_f32 v206, v206, v29, v30
	v_max_f32_e32 v203, v203, v15
	v_max_f32_e32 v206, v206, v31
	v_mov_b32_e32 v205, v203
	v_mov_b32_e32 v207, v206
	s_nop 1
	v_permlane16_swap_b32_e32 v203, v205
	v_permlane16_swap_b32_e32 v206, v207
	v_max_f32_e32 v203, v203, v205
	v_max_f32_e32 v206, v206, v207
	v_mov_b32_e32 v205, v203
	v_mov_b32_e32 v207, v206
	s_nop 1
	v_permlane32_swap_b32_e32 v203, v205
	v_permlane32_swap_b32_e32 v206, v207
	v_max_f32_e32 v203, v203, v205
	v_max_f32_e32 v206, v206, v207
	v_max_f32_e32 v218, v200, v203
	v_max_f32_e32 v208, v246, v206
	v_sub_f32_e32 v220, v200, v218
	v_sub_f32_e32 v248, v246, v208
	v_mov_b32_e32 v219, v218
	v_mov_b32_e32 v209, v208
	v_exp_f32_e32 v220, v220
	v_exp_f32_e32 v248, v248
	v_mov_b32_e32 v200, v218
	v_mov_b32_e32 v246, v208
	v_pk_add_f32 v[0:1], v[0:1], v[218:219] neg_lo:[0,1] neg_hi:[0,1]
	v_pk_add_f32 v[16:17], v[16:17], v[208:209] neg_lo:[0,1] neg_hi:[0,1]
	v_pk_add_f32 v[2:3], v[2:3], v[218:219] neg_lo:[0,1] neg_hi:[0,1]
	v_pk_add_f32 v[18:19], v[18:19], v[208:209] neg_lo:[0,1] neg_hi:[0,1]
	v_pk_add_f32 v[4:5], v[4:5], v[218:219] neg_lo:[0,1] neg_hi:[0,1]
	v_pk_add_f32 v[20:21], v[20:21], v[208:209] neg_lo:[0,1] neg_hi:[0,1]
	v_pk_add_f32 v[6:7], v[6:7], v[218:219] neg_lo:[0,1] neg_hi:[0,1]
	v_pk_add_f32 v[22:23], v[22:23], v[208:209] neg_lo:[0,1] neg_hi:[0,1]
	v_pk_add_f32 v[8:9], v[8:9], v[218:219] neg_lo:[0,1] neg_hi:[0,1]
	v_pk_add_f32 v[24:25], v[24:25], v[208:209] neg_lo:[0,1] neg_hi:[0,1]
	v_pk_add_f32 v[10:11], v[10:11], v[218:219] neg_lo:[0,1] neg_hi:[0,1]
	v_pk_add_f32 v[26:27], v[26:27], v[208:209] neg_lo:[0,1] neg_hi:[0,1]
	v_pk_add_f32 v[12:13], v[12:13], v[218:219] neg_lo:[0,1] neg_hi:[0,1]
	v_pk_add_f32 v[28:29], v[28:29], v[208:209] neg_lo:[0,1] neg_hi:[0,1]
	v_pk_add_f32 v[14:15], v[14:15], v[218:219] neg_lo:[0,1] neg_hi:[0,1]
	v_pk_add_f32 v[30:31], v[30:31], v[208:209] neg_lo:[0,1] neg_hi:[0,1]
	v_exp_f32_e32 v0, v0
	s_waitcnt vmcnt(0)
	v_exp_f32_e32 v1, v1
	ds_write_b128 v150, v[80:83] offset:32768
	v_exp_f32_e32 v2, v2
	ds_write_b128 v150, v[84:87] offset:36864
	v_exp_f32_e32 v3, v3
	ds_write_b128 v150, v[88:91] offset:40960
	v_exp_f32_e32 v4, v4
	ds_write_b128 v150, v[92:95] offset:45056
	v_exp_f32_e32 v5, v5
	ds_write_b64 v151, v[96:97] offset:32768
	v_exp_f32_e32 v6, v6
	ds_write_b64 v229, v[98:99] offset:32768
	v_exp_f32_e32 v7, v7
	ds_write_b64 v151, v[100:101] offset:36864
	v_exp_f32_e32 v8, v8
	ds_write_b64 v229, v[102:103] offset:36864
	v_exp_f32_e32 v9, v9
	ds_write_b64 v151, v[104:105] offset:40960
	v_exp_f32_e32 v10, v10
	ds_write_b64 v229, v[106:107] offset:40960
	v_exp_f32_e32 v11, v11
	ds_write_b64 v151, v[108:109] offset:45056
	v_exp_f32_e32 v12, v12
	ds_write_b64 v229, v[110:111] offset:45056
	v_exp_f32_e32 v13, v13
	s_add_u32 s100, s16, 0x0
	v_exp_f32_e32 v14, v14
	s_addc_u32 s101, s17, 0
	v_exp_f32_e32 v15, v15
	s_add_u32 s0, s36, 0x0
	v_exp_f32_e32 v16, v16
	s_addc_u32 s1, s37, 0
	v_exp_f32_e32 v17, v17
	global_load_dwordx4 v[80:83], v154, s[100:101] offset:2048
	v_exp_f32_e32 v18, v18
	global_load_dwordx4 v[96:99], v162, s[0:1]
	v_exp_f32_e32 v19, v19
	global_load_dwordx4 v[84:87], v155, s[100:101] offset:2048
	v_exp_f32_e32 v20, v20
	global_load_dwordx4 v[100:103], v163, s[0:1]
	v_exp_f32_e32 v21, v21
	global_load_dwordx4 v[88:91], v156, s[100:101] offset:2048
	v_exp_f32_e32 v22, v22
	global_load_dwordx4 v[104:107], v164, s[0:1]
	v_exp_f32_e32 v23, v23
	global_load_dwordx4 v[92:95], v157, s[100:101] offset:2048
	v_exp_f32_e32 v24, v24
	global_load_dwordx4 v[108:111], v165, s[0:1]
	v_exp_f32_e32 v25, v25
	v_exp_f32_e32 v26, v26
	v_exp_f32_e32 v27, v27
	v_exp_f32_e32 v28, v28
; __device__ __forceinline__ void attn_phase(const Params& P, char* smem_raw) {
;     ...
; #pragma unroll
;       for (int reg = 0; reg < 4; ++reg) {
;         float mx = sacc[0][reg];
; #pragma unroll
;         for (int t8 = 1; t8 < 8; ++t8) mx = fmaxf(mx, sacc[t8][reg]);
;         mx = row16_max(mx);
;         const float mnew = fmaxf(mrow[reg], mx);
;         const float alpha = __builtin_amdgcn_exp2f(mrow[reg] - mnew);
;         mrow[reg] = mnew;
;         float rsum = 0.f;
; #pragma unroll
;         for (int t8 = 0; t8 < 8; ++t8) {
;           const float p = __builtin_amdgcn_exp2f(sacc[t8][reg] - mnew);
;           rsum += p;
;           sm_p[(wid * 16 + (lane_c >> 4) * 4 + reg) * 136 + t8 * 16 + (lane_c & 15)] = f2bf(p);
;         }
;         rsum = row16_sum(rsum);
;         lrow[reg] = lrow[reg] * alpha + rsum;
; #pragma unroll
;         for (int td = 0; td < 4; ++td) o[td][reg] *= alpha;
;       }
;       asm volatile("s_waitcnt lgkmcnt(0)" ::: "memory");
; #pragma unroll
;       for (int s4 = 0; s4 < 4; ++s4) {
;         const bf16x8 pf = *reinterpret_cast<const bf16x8*>(&sm_p[(wid * 16 + (lane_c & 15)) * 136 + s4 * 32 + (lane_c >> 4) * 8]);
; #pragma unroll
;         for (int td = 0; td < 4; ++td) {
;           const bf16x8 vf = *reinterpret_cast<const bf16x8*>(&sm_vt[(td * 16 + (lane_c & 15)) * 136 + s4 * 32 + (lane_c >> 4) * 8]);
;           o[td] = __builtin_amdgcn_mfma_f32_16x16x32_bf16(pf, vf, o[td], 0, 0, 0);
;         }
;       }
	v_exp_f32_e32 v29, v29
	v_exp_f32_e32 v30, v30
	v_exp_f32_e32 v31, v31
	ds_read_b128 v[112:115], v146 offset:0
	ds_read_b128 v[116:119], v146 offset:4096
	ds_read_b128 v[120:123], v146 offset:8192
	ds_read_b128 v[124:127], v146 offset:12288
	ds_read_b128 v[128:131], v147 offset:0
	ds_read_b128 v[132:135], v147 offset:4096
	ds_read_b128 v[136:139], v147 offset:8192
	ds_read_b128 v[140:143], v147 offset:12288
	v_mov_b32_e32 v221, v220
	v_mov_b32_e32 v249, v248
	v_pk_add_f32 v[222:223], v[0:1], v[2:3]
	v_pk_add_f32 v[250:251], v[16:17], v[18:19]
	v_pk_add_f32 v[222:223], v[222:223], v[4:5]
	v_pk_add_f32 v[250:251], v[250:251], v[20:21]
	v_pk_add_f32 v[222:223], v[222:223], v[6:7]
	v_pk_add_f32 v[250:251], v[250:251], v[22:23]
	v_pk_add_f32 v[222:223], v[222:223], v[8:9]
	v_pk_add_f32 v[250:251], v[250:251], v[24:25]
	v_pk_add_f32 v[222:223], v[222:223], v[10:11]
	v_pk_add_f32 v[250:251], v[250:251], v[26:27]
	v_pk_add_f32 v[222:223], v[222:223], v[12:13]
	v_pk_add_f32 v[250:251], v[250:251], v[28:29]
	v_pk_add_f32 v[222:223], v[222:223], v[14:15]
	v_pk_add_f32 v[250:251], v[250:251], v[30:31]
	v_pk_mul_f32 v[32:33], v[32:33], v[220:221]
	v_pk_mul_f32 v[34:35], v[34:35], v[220:221]
	v_pk_mul_f32 v[176:177], v[176:177], v[248:249]
	v_pk_mul_f32 v[178:179], v[178:179], v[248:249]
	v_pk_mul_f32 v[36:37], v[36:37], v[220:221]
	v_pk_mul_f32 v[38:39], v[38:39], v[220:221]
	v_pk_mul_f32 v[180:181], v[180:181], v[248:249]
	v_pk_mul_f32 v[182:183], v[182:183], v[248:249]
	v_pk_mul_f32 v[40:41], v[40:41], v[220:221]
	v_pk_mul_f32 v[42:43], v[42:43], v[220:221]
	v_pk_mul_f32 v[192:193], v[192:193], v[248:249]
	v_pk_mul_f32 v[194:195], v[194:195], v[248:249]
	v_pk_mul_f32 v[44:45], v[44:45], v[220:221]
	v_pk_mul_f32 v[46:47], v[46:47], v[220:221]
	v_pk_mul_f32 v[196:197], v[196:197], v[248:249]
	v_pk_mul_f32 v[198:199], v[198:199], v[248:249]
	v_add_f32_e32 v203, v222, v223
	v_add_f32_e32 v206, v250, v251
	v_fma_f32 v201, v201, v220, v203
	v_fma_f32 v247, v247, v248, v206
	v_cvt_pk_bf16_f32 v48, v0, v1
	v_cvt_pk_bf16_f32 v49, v2, v3
	v_cvt_pk_bf16_f32 v50, v4, v5
	v_cvt_pk_bf16_f32 v51, v6, v7
	v_cvt_pk_bf16_f32 v56, v16, v17
	v_cvt_pk_bf16_f32 v57, v18, v19
	v_cvt_pk_bf16_f32 v58, v20, v21
	v_cvt_pk_bf16_f32 v59, v22, v23
	v_cvt_pk_bf16_f32 v52, v8, v9
	v_cvt_pk_bf16_f32 v53, v10, v11
	v_cvt_pk_bf16_f32 v54, v12, v13
	v_cvt_pk_bf16_f32 v55, v14, v15
	v_cvt_pk_bf16_f32 v60, v24, v25
	v_cvt_pk_bf16_f32 v61, v26, v27
	v_cvt_pk_bf16_f32 v62, v28, v29
	v_cvt_pk_bf16_f32 v63, v30, v31
	s_waitcnt lgkmcnt(7)
	v_mfma_f32_16x16x32_bf16 v[32:35], v[112:115], v[48:51], v[32:35]
	v_mfma_f32_16x16x32_bf16 v[176:179], v[112:115], v[56:59], v[176:179]
	s_waitcnt lgkmcnt(6)
	v_mfma_f32_16x16x32_bf16 v[36:39], v[116:119], v[48:51], v[36:39]
	v_mfma_f32_16x16x32_bf16 v[180:183], v[116:119], v[56:59], v[180:183]
	s_waitcnt lgkmcnt(5)
	v_mfma_f32_16x16x32_bf16 v[40:43], v[120:123], v[48:51], v[40:43]
	v_mfma_f32_16x16x32_bf16 v[192:195], v[120:123], v[56:59], v[192:195]
	s_waitcnt lgkmcnt(4)
	v_mfma_f32_16x16x32_bf16 v[44:47], v[124:127], v[48:51], v[44:47]
	v_mfma_f32_16x16x32_bf16 v[196:199], v[124:127], v[56:59], v[196:199]
	s_waitcnt lgkmcnt(3)
	v_mfma_f32_16x16x32_bf16 v[32:35], v[128:131], v[52:55], v[32:35]
	v_mfma_f32_16x16x32_bf16 v[176:179], v[128:131], v[60:63], v[176:179]
	s_waitcnt lgkmcnt(2)
	v_mfma_f32_16x16x32_bf16 v[36:39], v[132:135], v[52:55], v[36:39]
	v_mfma_f32_16x16x32_bf16 v[180:183], v[132:135], v[60:63], v[180:183]
	s_waitcnt lgkmcnt(1)
	v_mfma_f32_16x16x32_bf16 v[40:43], v[136:139], v[52:55], v[40:43]
	v_mfma_f32_16x16x32_bf16 v[192:195], v[136:139], v[60:63], v[192:195]
	s_waitcnt lgkmcnt(0)
	v_mfma_f32_16x16x32_bf16 v[44:47], v[140:143], v[52:55], v[44:47]
	v_mfma_f32_16x16x32_bf16 v[196:199], v[140:143], v[60:63], v[196:199]
	s_waitcnt lgkmcnt(0)
	s_barrier
	s_cmp_eq_u32 s19, 0
	s_cbranch_scc1 .Lmy_att_s4_3
	ds_read_b32 v0, v184 offset:1280
	ds_read_b32 v1, v185 offset:1280
	ds_read_b32 v2, v186 offset:1280
	ds_read_b32 v3, v187 offset:1280
	ds_read_b32 v8, v188 offset:1280
	ds_read_b32 v9, v189 offset:1280
	ds_read_b32 v10, v190 offset:1280
	ds_read_b32 v11, v191 offset:1280
	v_mov_b32_e32 v4, 0xf149f2ca
	v_mov_b32_e32 v5, 0xf149f2ca
	v_mov_b32_e32 v6, 0xf149f2ca
	v_mov_b32_e32 v7, 0xf149f2ca
	v_mov_b32_e32 v12, 0xf149f2ca
	v_mov_b32_e32 v13, 0xf149f2ca
	v_mov_b32_e32 v14, 0xf149f2ca
	v_mov_b32_e32 v15, 0xf149f2ca
	ds_read_b128 v[112:115], v144 offset:32768
	ds_read_b128 v[116:119], v145 offset:32768
	ds_read_b128 v[120:123], v144 offset:40960
	ds_read_b128 v[124:127], v145 offset:40960
	ds_read_b128 v[128:131], v144 offset:34816
	ds_read_b128 v[132:135], v145 offset:34816
	ds_read_b128 v[136:139], v144 offset:43008
	ds_read_b128 v[140:143], v145 offset:43008
	s_waitcnt lgkmcnt(7)
	v_mfma_f32_16x16x32_bf16 v[0:3], v[112:115], v[230:233], v[0:3]
	s_waitcnt lgkmcnt(6)
	v_mfma_f32_16x16x32_bf16 v[0:3], v[116:119], v[234:237], v[0:3]
	s_waitcnt lgkmcnt(5)
	v_mfma_f32_16x16x32_bf16 v[4:7], v[120:123], v[230:233], v[4:7]
	s_waitcnt lgkmcnt(4)
	v_mfma_f32_16x16x32_bf16 v[4:7], v[124:127], v[234:237], v[4:7]
	s_waitcnt lgkmcnt(3)
	v_mfma_f32_16x16x32_bf16 v[8:11], v[128:131], v[230:233], v[8:11]
	s_waitcnt lgkmcnt(2)
	v_mfma_f32_16x16x32_bf16 v[8:11], v[132:135], v[234:237], v[8:11]
	s_waitcnt lgkmcnt(1)
	v_mfma_f32_16x16x32_bf16 v[12:15], v[136:139], v[230:233], v[12:15]
	s_waitcnt lgkmcnt(0)
; __device__ __forceinline__ void attn_phase(const Params& P, char* smem_raw) {
;     ...
; #pragma unroll
;       for (int reg = 0; reg < 4; ++reg) {
;         float mx = sacc[0][reg];
; #pragma unroll
;         for (int t8 = 1; t8 < 8; ++t8) mx = fmaxf(mx, sacc[t8][reg]);
;         mx = row16_max(mx);
;         const float mnew = fmaxf(mrow[reg], mx);
;         const float alpha = __builtin_amdgcn_exp2f(mrow[reg] - mnew);
;         mrow[reg] = mnew;
;         float rsum = 0.f;
; #pragma unroll
;         for (int t8 = 0; t8 < 8; ++t8) {
;           const float p = __builtin_amdgcn_exp2f(sacc[t8][reg] - mnew);
;           rsum += p;
;           sm_p[(wid * 16 + (lane_c >> 4) * 4 + reg) * 136 + t8 * 16 + (lane_c & 15)] = f2bf(p);
;         }
;         rsum = row16_sum(rsum);
;         lrow[reg] = lrow[reg] * alpha + rsum;
; #pragma unroll
;         for (int td = 0; td < 4; ++td) o[td][reg] *= alpha;
;       }
;       asm volatile("s_waitcnt lgkmcnt(0)" ::: "memory");
; #pragma unroll
;       for (int s4 = 0; s4 < 4; ++s4) {
;         const bf16x8 pf = *reinterpret_cast<const bf16x8*>(&sm_p[(wid * 16 + (lane_c & 15)) * 136 + s4 * 32 + (lane_c >> 4) * 8]);
; #pragma unroll
;         for (int td = 0; td < 4; ++td) {
;           const bf16x8 vf = *reinterpret_cast<const bf16x8*>(&sm_vt[(td * 16 + (lane_c & 15)) * 136 + s4 * 32 + (lane_c >> 4) * 8]);
;           o[td] = __builtin_amdgcn_mfma_f32_16x16x32_bf16(pf, vf, o[td], 0, 0, 0);
;         }
;       }
	v_mfma_f32_16x16x32_bf16 v[12:15], v[140:143], v[234:237], v[12:15]
	s_nop 7
	v_max3_f32 v203, v0, v1, v2
	v_max3_f32 v203, v203, v3, v4
	v_max3_f32 v203, v203, v5, v6
	v_max3_f32 v203, v203, v7, v8
	v_max3_f32 v203, v203, v9, v10
	v_max3_f32 v203, v203, v11, v12
	v_max3_f32 v203, v203, v13, v14
	v_max_f32_e32 v203, v203, v15
	v_mov_b32_e32 v205, v203
	s_nop 1
	v_permlane16_swap_b32_e32 v203, v205
	v_max_f32_e32 v203, v203, v205
	v_mov_b32_e32 v205, v203
	s_nop 1
	v_permlane32_swap_b32_e32 v203, v205
	v_max_f32_e32 v203, v203, v205
	v_max_f32_e32 v218, v246, v203
	v_sub_f32_e32 v220, v246, v218
	v_mov_b32_e32 v219, v218
	v_exp_f32_e32 v220, v220
	v_mov_b32_e32 v246, v218
	v_pk_add_f32 v[0:1], v[0:1], v[218:219] neg_lo:[0,1] neg_hi:[0,1]
	v_pk_add_f32 v[2:3], v[2:3], v[218:219] neg_lo:[0,1] neg_hi:[0,1]
	v_pk_add_f32 v[4:5], v[4:5], v[218:219] neg_lo:[0,1] neg_hi:[0,1]
	v_pk_add_f32 v[6:7], v[6:7], v[218:219] neg_lo:[0,1] neg_hi:[0,1]
	v_pk_add_f32 v[8:9], v[8:9], v[218:219] neg_lo:[0,1] neg_hi:[0,1]
	v_pk_add_f32 v[10:11], v[10:11], v[218:219] neg_lo:[0,1] neg_hi:[0,1]
	v_pk_add_f32 v[12:13], v[12:13], v[218:219] neg_lo:[0,1] neg_hi:[0,1]
	v_pk_add_f32 v[14:15], v[14:15], v[218:219] neg_lo:[0,1] neg_hi:[0,1]
	v_exp_f32_e32 v0, v0
	s_waitcnt vmcnt(0)
	v_exp_f32_e32 v1, v1
	ds_write_b128 v150, v[80:83] offset:0
	v_exp_f32_e32 v2, v2
	ds_write_b128 v150, v[84:87] offset:4096
	v_exp_f32_e32 v3, v3
	ds_write_b128 v150, v[88:91] offset:8192
	v_exp_f32_e32 v4, v4
	ds_write_b128 v150, v[92:95] offset:12288
	v_exp_f32_e32 v5, v5
	ds_write_b64 v151, v[96:97] offset:0
	v_exp_f32_e32 v6, v6
	ds_write_b64 v229, v[98:99] offset:0
	v_exp_f32_e32 v7, v7
	ds_write_b64 v151, v[100:101] offset:4096
	v_exp_f32_e32 v8, v8
	ds_write_b64 v229, v[102:103] offset:4096
	v_exp_f32_e32 v9, v9
	ds_write_b64 v151, v[104:105] offset:8192
	v_exp_f32_e32 v10, v10
	ds_write_b64 v229, v[106:107] offset:8192
	v_exp_f32_e32 v11, v11
	ds_write_b64 v151, v[108:109] offset:12288
	v_exp_f32_e32 v12, v12
	ds_write_b64 v229, v[110:111] offset:12288
	v_exp_f32_e32 v13, v13
	s_add_u32 s100, s16, 0xc0000
	v_exp_f32_e32 v14, v14
	s_addc_u32 s101, s17, 0
	v_exp_f32_e32 v15, v15
	s_add_u32 s0, s36, 0x100
	s_addc_u32 s1, s37, 0
	global_load_dwordx4 v[80:83], v154, s[100:101] offset:2048
	global_load_dwordx4 v[96:99], v162, s[0:1]
	global_load_dwordx4 v[84:87], v155, s[100:101] offset:2048
	global_load_dwordx4 v[100:103], v163, s[0:1]
	global_load_dwordx4 v[88:91], v156, s[100:101] offset:2048
	global_load_dwordx4 v[104:107], v164, s[0:1]
	global_load_dwordx4 v[92:95], v157, s[100:101] offset:2048
	global_load_dwordx4 v[108:111], v165, s[0:1]
	s_and_b32 s0, s3, 0xff
	s_add_u32 s0, s0, 1
	s_min_u32 s0, s0, 7
	s_lshr_b32 s1, s0, 1
	s_and_b32 s0, s0, 1
	s_lshl_b32 s0, s0, 5
	s_lshr_b32 vcc_lo, s3, 12
	s_add_u32 s0, s0, vcc_lo
	s_lshl_b32 s0, s0, 1
	s_sub_i32 vcc_lo, s0, 4
	s_max_i32 vcc_lo, vcc_lo, 0
	s_min_i32 vcc_lo, vcc_lo, 0x78
	s_lshl_b32 vcc_hi, s1, 13
	s_add_u32 s20, vcc_lo, 8
	s_min_u32 s20, s20, 0x7e
	s_sub_u32 s20, s20, vcc_lo
	s_lshl_b32 s21, s20, 7
	s_mul_i32 s20, s20, 0x60000
	s_lshl_b32 m0, vcc_lo, 6
	s_add_u32 m0, m0, vcc_hi
	s_mul_i32 m0, m0, 0x1800
	s_add_u32 s12, s4, m0
	s_addc_u32 s13, s5, 0
	s_lshl_b32 m0, s1, 24
	s_lshl_b32 s100, vcc_lo, 7
	s_add_u32 m0, m0, s100
	s_add_u32 s14, s6, m0
	s_addc_u32 s15, s7, 0
	s_lshl_b32 m0, s0, 6
	s_add_u32 m0, m0, vcc_hi
	s_mul_i32 m0, m0, 0x1800
	s_add_u32 s100, s4, m0
	s_addc_u32 s101, s5, 0
	global_load_dwordx4 v[72:75], v166, s[100:101]
	global_load_dwordx4 v[76:79], v166, s[100:101] offset:64
	s_add_u32 s100, s100, 0x60000
	s_addc_u32 s101, s101, 0
	global_load_dwordx4 v[238:241], v166, s[100:101]
	global_load_dwordx4 v[242:245], v166, s[100:101] offset:64
	ds_read_b128 v[112:115], v146 offset:32768
	ds_read_b128 v[116:119], v146 offset:36864
	ds_read_b128 v[120:123], v146 offset:40960
	ds_read_b128 v[124:127], v146 offset:45056
	ds_read_b128 v[128:131], v147 offset:32768
	ds_read_b128 v[132:135], v147 offset:36864
	ds_read_b128 v[136:139], v147 offset:40960
	ds_read_b128 v[140:143], v147 offset:45056
	v_mov_b32_e32 v221, v220
	v_pk_add_f32 v[222:223], v[0:1], v[2:3]
	v_pk_add_f32 v[222:223], v[222:223], v[4:5]
	v_pk_add_f32 v[222:223], v[222:223], v[6:7]
	v_pk_add_f32 v[222:223], v[222:223], v[8:9]
	v_pk_add_f32 v[222:223], v[222:223], v[10:11]
	v_pk_add_f32 v[222:223], v[222:223], v[12:13]
	v_pk_add_f32 v[222:223], v[222:223], v[14:15]
	v_pk_mul_f32 v[176:177], v[176:177], v[220:221]
	v_pk_mul_f32 v[178:179], v[178:179], v[220:221]
	v_pk_mul_f32 v[180:181], v[180:181], v[220:221]
	v_pk_mul_f32 v[182:183], v[182:183], v[220:221]
	v_pk_mul_f32 v[192:193], v[192:193], v[220:221]
	v_pk_mul_f32 v[194:195], v[194:195], v[220:221]
	v_pk_mul_f32 v[196:197], v[196:197], v[220:221]
	v_pk_mul_f32 v[198:199], v[198:199], v[220:221]
	v_add_f32_e32 v203, v222, v223
	v_fma_f32 v247, v247, v220, v203
	v_cvt_pk_bf16_f32 v48, v0, v1
	v_cvt_pk_bf16_f32 v49, v2, v3
	v_cvt_pk_bf16_f32 v50, v4, v5
	v_cvt_pk_bf16_f32 v51, v6, v7
	v_cvt_pk_bf16_f32 v52, v8, v9
	v_cvt_pk_bf16_f32 v53, v10, v11
	v_cvt_pk_bf16_f32 v54, v12, v13
	v_cvt_pk_bf16_f32 v55, v14, v15
	s_waitcnt lgkmcnt(7)
	v_mfma_f32_16x16x32_bf16 v[176:179], v[112:115], v[48:51], v[176:179]
	s_waitcnt lgkmcnt(6)
	v_mfma_f32_16x16x32_bf16 v[180:183], v[116:119], v[48:51], v[180:183]
	s_waitcnt lgkmcnt(5)
	v_mfma_f32_16x16x32_bf16 v[192:195], v[120:123], v[48:51], v[192:195]
	s_waitcnt lgkmcnt(4)
	v_mfma_f32_16x16x32_bf16 v[196:199], v[124:127], v[48:51], v[196:199]
	s_waitcnt lgkmcnt(3)
	v_mfma_f32_16x16x32_bf16 v[176:179], v[128:131], v[52:55], v[176:179]
	s_waitcnt lgkmcnt(2)
	v_mfma_f32_16x16x32_bf16 v[180:183], v[132:135], v[52:55], v[180:183]
	s_waitcnt lgkmcnt(1)
	v_mfma_f32_16x16x32_bf16 v[192:195], v[136:139], v[52:55], v[192:195]
	s_waitcnt lgkmcnt(0)
	v_mfma_f32_16x16x32_bf16 v[196:199], v[140:143], v[52:55], v[196:199]
	s_branch .Lmy_att_e4_3

; __device__ __forceinline__ void attn_phase(const Params& P, char* smem_raw) {
;     ...
;     for (int ck = 0; ck < 6; ++ck) {
;       int lane_c = lane;
;       asm volatile("" : "+v"(lane_c));
;       __syncthreads();
; #pragma unroll
;       for (int i = 0; i < 4; ++i) {
;         const int idx = tid + 256 * i;
;         *reinterpret_cast<uint4*>(&sm_k[(idx >> 3) * LDSS + (idx & 7) * 8]) = kreg[i];
;         *reinterpret_cast<uint4*>(&sm_vt[(idx >> 4) * 136 + (idx & 15) * 8]) = vreg[i];
;       }
;       __syncthreads();
;       f32x4 sacc[8];
; #pragma unroll
;       for (int t8 = 0; t8 < 8; ++t8) sacc[t8] = f32x4{0.f, 0.f, 0.f, 0.f};
; #pragma unroll
;       for (int s = 0; s < 2; ++s)
; #pragma unroll
;         for (int t8 = 0; t8 < 8; ++t8) {
;           const bf16x8 kf = *reinterpret_cast<const bf16x8*>(&sm_k[(t8 * 16 + (lane_c & 15)) * LDSS + s * 32 + (lane_c >> 4) * 8]);
;           sacc[t8] = __builtin_amdgcn_mfma_f32_16x16x32_bf16(qf[s], kf, sacc[t8], 0, 0, 0);
;         }
;       if (ck < 5) {
;         ATT_ISSUE(t, ck + 1)
;       } else if (t + VGRID < 8192) {
;         ATT_ISSUE(t + VGRID, 0)
;         ATT_QLOAD(t + VGRID)
;       }
;       if (ck < 4) {
;         const float* rb0 = sm_rpb + (rs + ck * 2 - r + 7) * 31;
; #pragma unroll
;         for (int t8 = 0; t8 < 8; ++t8)
; #pragma unroll
;           for (int reg = 0; reg < 4; ++reg)
;             sacc[t8][reg] += rb0[(t8 >> 2) * 31 + dco[reg][t8 & 3]];
;       }
; #pragma unroll
;       for (int reg = 0; reg < 4; ++reg) {
;         float mx = sacc[0][reg];
; #pragma unroll
;         for (int t8 = 1; t8 < 8; ++t8) mx = fmaxf(mx, sacc[t8][reg]);
;         mx = row16_max(mx);
;         const float mnew = fmaxf(mrow[reg], mx);
;         const float alpha = __builtin_amdgcn_exp2f(mrow[reg] - mnew);
;         mrow[reg] = mnew;
;         float rsum = 0.f;
; #pragma unroll
;         for (int t8 = 0; t8 < 8; ++t8) {
;           const float p = __builtin_amdgcn_exp2f(sacc[t8][reg] - mnew);
;           rsum += p;
;           sm_p[(wid * 16 + (lane_c >> 4) * 4 + reg) * 136 + t8 * 16 + (lane_c & 15)] = f2bf(p);
;         }
;         rsum = row16_sum(rsum);
;         lrow[reg] = lrow[reg] * alpha + rsum;
; #pragma unroll
;         for (int td = 0; td < 4; ++td) o[td][reg] *= alpha;
;       }
;       asm volatile("s_waitcnt lgkmcnt(0)" ::: "memory");
; #pragma unroll
;       for (int s4 = 0; s4 < 4; ++s4) {
.Lmy_att_e4_3:
	s_waitcnt lgkmcnt(0)
	s_barrier
	ds_read_b128 v[112:115], v149 offset:0
	ds_read_b128 v[116:119], v224 offset:0
	ds_read_b128 v[120:123], v149 offset:8192
	ds_read_b128 v[124:127], v224 offset:8192
	ds_read_b128 v[128:131], v149 offset:2048
	ds_read_b128 v[132:135], v224 offset:2048
	ds_read_b128 v[136:139], v149 offset:10240
	ds_read_b128 v[140:143], v224 offset:10240
	s_waitcnt lgkmcnt(7)
	v_mfma_f32_16x16x32_bf16 v[0:3], v[112:115], v[64:67], 0
	ds_read_b128 v[112:115], v149 offset:4096
	s_waitcnt lgkmcnt(7)
	v_mfma_f32_16x16x32_bf16 v[0:3], v[116:119], v[68:71], v[0:3]
	ds_read_b128 v[116:119], v224 offset:4096
	s_waitcnt lgkmcnt(7)
	v_mfma_f32_16x16x32_bf16 v[4:7], v[120:123], v[64:67], 0
	ds_read_b128 v[120:123], v149 offset:12288
	s_waitcnt lgkmcnt(7)
	v_mfma_f32_16x16x32_bf16 v[4:7], v[124:127], v[68:71], v[4:7]
	ds_read_b128 v[124:127], v224 offset:12288
	s_waitcnt lgkmcnt(7)
	v_mfma_f32_16x16x32_bf16 v[8:11], v[128:131], v[64:67], 0
	ds_read_b128 v[128:131], v149 offset:6144
	s_waitcnt lgkmcnt(7)
	v_mfma_f32_16x16x32_bf16 v[8:11], v[132:135], v[68:71], v[8:11]
	ds_read_b128 v[132:135], v224 offset:6144
	s_waitcnt lgkmcnt(7)
	v_mfma_f32_16x16x32_bf16 v[12:15], v[136:139], v[64:67], 0
	ds_read_b128 v[136:139], v149 offset:14336
	s_waitcnt lgkmcnt(7)
	v_mfma_f32_16x16x32_bf16 v[12:15], v[140:143], v[68:71], v[12:15]
	ds_read_b128 v[140:143], v224 offset:14336
	s_waitcnt lgkmcnt(7)
	v_mfma_f32_16x16x32_bf16 v[16:19], v[112:115], v[64:67], 0
	s_waitcnt lgkmcnt(6)
	v_mfma_f32_16x16x32_bf16 v[16:19], v[116:119], v[68:71], v[16:19]
	s_waitcnt lgkmcnt(5)
	v_mfma_f32_16x16x32_bf16 v[20:23], v[120:123], v[64:67], 0
	s_waitcnt lgkmcnt(4)
	v_mfma_f32_16x16x32_bf16 v[20:23], v[124:127], v[68:71], v[20:23]
	s_waitcnt lgkmcnt(3)
	v_mfma_f32_16x16x32_bf16 v[24:27], v[128:131], v[64:67], 0
	s_waitcnt lgkmcnt(2)
	v_mfma_f32_16x16x32_bf16 v[24:27], v[132:135], v[68:71], v[24:27]
	s_waitcnt lgkmcnt(1)
	v_mfma_f32_16x16x32_bf16 v[28:31], v[136:139], v[64:67], 0
	s_waitcnt lgkmcnt(0)
	v_mfma_f32_16x16x32_bf16 v[28:31], v[140:143], v[68:71], v[28:31]
	s_nop 7
	v_max3_f32 v203, v0, v1, v2
	v_max3_f32 v203, v203, v3, v4
	v_max3_f32 v203, v203, v5, v6
	v_max3_f32 v203, v203, v7, v8
	v_max3_f32 v203, v203, v9, v10
	v_max3_f32 v203, v203, v11, v12
	v_max3_f32 v203, v203, v13, v14
	v_max3_f32 v203, v203, v15, v16
	v_max3_f32 v203, v203, v17, v18
	v_max3_f32 v203, v203, v19, v20
	v_max3_f32 v203, v203, v21, v22
	v_max3_f32 v203, v203, v23, v24
	v_max3_f32 v203, v203, v25, v26
	v_max3_f32 v203, v203, v27, v28
	v_max3_f32 v203, v203, v29, v30
	v_max_f32_e32 v203, v203, v31
	v_mov_b32_e32 v205, v203
	s_nop 1
	v_permlane16_swap_b32_e32 v203, v205
	v_max_f32_e32 v203, v203, v205
	v_mov_b32_e32 v205, v203
	s_nop 1
	v_permlane32_swap_b32_e32 v203, v205
	v_max_f32_e32 v203, v203, v205
	v_max_f32_e32 v218, v200, v203
	v_sub_f32_e32 v220, v200, v218
	v_mov_b32_e32 v219, v218
	v_exp_f32_e32 v220, v220
	v_mov_b32_e32 v200, v218
	v_pk_add_f32 v[0:1], v[0:1], v[218:219] neg_lo:[0,1] neg_hi:[0,1]
	v_pk_add_f32 v[2:3], v[2:3], v[218:219] neg_lo:[0,1] neg_hi:[0,1]
	v_pk_add_f32 v[4:5], v[4:5], v[218:219] neg_lo:[0,1] neg_hi:[0,1]
	v_pk_add_f32 v[6:7], v[6:7], v[218:219] neg_lo:[0,1] neg_hi:[0,1]
	v_pk_add_f32 v[8:9], v[8:9], v[218:219] neg_lo:[0,1] neg_hi:[0,1]
	v_pk_add_f32 v[10:11], v[10:11], v[218:219] neg_lo:[0,1] neg_hi:[0,1]
	v_pk_add_f32 v[12:13], v[12:13], v[218:219] neg_lo:[0,1] neg_hi:[0,1]
	v_pk_add_f32 v[14:15], v[14:15], v[218:219] neg_lo:[0,1] neg_hi:[0,1]
	v_pk_add_f32 v[16:17], v[16:17], v[218:219] neg_lo:[0,1] neg_hi:[0,1]
	v_pk_add_f32 v[18:19], v[18:19], v[218:219] neg_lo:[0,1] neg_hi:[0,1]
	v_pk_add_f32 v[20:21], v[20:21], v[218:219] neg_lo:[0,1] neg_hi:[0,1]
	v_pk_add_f32 v[22:23], v[22:23], v[218:219] neg_lo:[0,1] neg_hi:[0,1]
	v_pk_add_f32 v[24:25], v[24:25], v[218:219] neg_lo:[0,1] neg_hi:[0,1]
	v_pk_add_f32 v[26:27], v[26:27], v[218:219] neg_lo:[0,1] neg_hi:[0,1]
	v_pk_add_f32 v[28:29], v[28:29], v[218:219] neg_lo:[0,1] neg_hi:[0,1]
	v_pk_add_f32 v[30:31], v[30:31], v[218:219] neg_lo:[0,1] neg_hi:[0,1]
	v_exp_f32_e32 v0, v0
	s_waitcnt vmcnt(4)
	v_exp_f32_e32 v1, v1
	ds_write_b128 v150, v[80:83] offset:32768
	v_exp_f32_e32 v2, v2
	ds_write_b128 v150, v[84:87] offset:36864
	v_exp_f32_e32 v3, v3
	ds_write_b128 v150, v[88:91] offset:40960
	v_exp_f32_e32 v4, v4
	ds_write_b128 v150, v[92:95] offset:45056
	v_exp_f32_e32 v5, v5
	ds_write_b64 v151, v[96:97] offset:32768
	v_exp_f32_e32 v6, v6
	ds_write_b64 v229, v[98:99] offset:32768
	v_exp_f32_e32 v7, v7
	ds_write_b64 v151, v[100:101] offset:36864
	v_exp_f32_e32 v8, v8
	ds_write_b64 v229, v[102:103] offset:36864
	v_exp_f32_e32 v9, v9
	ds_write_b64 v151, v[104:105] offset:40960
	v_exp_f32_e32 v10, v10
	ds_write_b64 v229, v[106:107] offset:40960
	v_exp_f32_e32 v11, v11
	ds_write_b64 v151, v[108:109] offset:45056
	v_exp_f32_e32 v12, v12
	ds_write_b64 v229, v[110:111] offset:45056
	v_exp_f32_e32 v13, v13
	s_add_u32 s100, s12, 0x0
	v_exp_f32_e32 v14, v14
	s_addc_u32 s101, s13, 0
	v_exp_f32_e32 v15, v15
	s_add_u32 s0, s14, 0x0
	v_exp_f32_e32 v16, v16
	s_addc_u32 s1, s15, 0
	v_exp_f32_e32 v17, v17
	global_load_dwordx4 v[80:83], v154, s[100:101] offset:2048
	v_exp_f32_e32 v18, v18
	global_load_dwordx4 v[96:99], v158, s[0:1]
	v_exp_f32_e32 v19, v19
	global_load_dwordx4 v[84:87], v155, s[100:101] offset:2048
	v_exp_f32_e32 v20, v20
	global_load_dwordx4 v[100:103], v159, s[0:1]
	v_exp_f32_e32 v21, v21
	global_load_dwordx4 v[88:91], v156, s[100:101] offset:2048
	v_exp_f32_e32 v22, v22
	global_load_dwordx4 v[104:107], v160, s[0:1]
	v_exp_f32_e32 v23, v23
	global_load_dwordx4 v[92:95], v157, s[100:101] offset:2048
; __device__ __forceinline__ void attn_phase(const Params& P, char* smem_raw) {
;     ...
;       if (ck < 4) {
;         const float* rb0 = sm_rpb + (rs + ck * 2 - r + 7) * 31;
;     ...
; #pragma unroll
;       for (int reg = 0; reg < 4; ++reg) {
;         float mx = sacc[0][reg];
; #pragma unroll
;         for (int t8 = 1; t8 < 8; ++t8) mx = fmaxf(mx, sacc[t8][reg]);
;         mx = row16_max(mx);
;         const float mnew = fmaxf(mrow[reg], mx);
;         const float alpha = __builtin_amdgcn_exp2f(mrow[reg] - mnew);
;         mrow[reg] = mnew;
;         float rsum = 0.f;
; #pragma unroll
;         for (int t8 = 0; t8 < 8; ++t8) {
;           const float p = __builtin_amdgcn_exp2f(sacc[t8][reg] - mnew);
;           rsum += p;
;           sm_p[(wid * 16 + (lane_c >> 4) * 4 + reg) * 136 + t8 * 16 + (lane_c & 15)] = f2bf(p);
;         }
;         rsum = row16_sum(rsum);
;         lrow[reg] = lrow[reg] * alpha + rsum;
; #pragma unroll
;         for (int td = 0; td < 4; ++td) o[td][reg] *= alpha;
;       }
;       asm volatile("s_waitcnt lgkmcnt(0)" ::: "memory");
; #pragma unroll
;       for (int s4 = 0; s4 < 4; ++s4) {
;         const bf16x8 pf = *reinterpret_cast<const bf16x8*>(&sm_p[(wid * 16 + (lane_c & 15)) * 136 + s4 * 32 + (lane_c >> 4) * 8]);
; #pragma unroll
;         for (int td = 0; td < 4; ++td) {
;           const bf16x8 vf = *reinterpret_cast<const bf16x8*>(&sm_vt[(td * 16 + (lane_c & 15)) * 136 + s4 * 32 + (lane_c >> 4) * 8]);
;           o[td] = __builtin_amdgcn_mfma_f32_16x16x32_bf16(pf, vf, o[td], 0, 0, 0);
;         }
;       }
	v_exp_f32_e32 v24, v24
	global_load_dwordx4 v[108:111], v161, s[0:1]
	v_exp_f32_e32 v25, v25
	v_exp_f32_e32 v26, v26
	v_exp_f32_e32 v27, v27
	v_exp_f32_e32 v28, v28
	v_exp_f32_e32 v29, v29
	v_exp_f32_e32 v30, v30
	v_exp_f32_e32 v31, v31
	s_and_b32 s0, s3, 0xff
	s_add_u32 s0, s0, 1
	s_min_u32 s0, s0, 7
	s_lshr_b32 s1, s0, 1
	s_and_b32 s0, s0, 1
	s_lshl_b32 s0, s0, 5
	s_lshr_b32 vcc_lo, s3, 12
	s_add_u32 s0, s0, vcc_lo
	s_lshl_b32 s0, s0, 1
	s_sub_i32 vcc_lo, s0, 4
	s_max_i32 vcc_lo, vcc_lo, 0
	s_min_i32 vcc_lo, vcc_lo, 0x78
	s_lshl_b32 vcc_hi, s1, 13
	s_sub_i32 vcc_lo, vcc_lo, s0
	s_add_i32 vcc_lo, vcc_lo, 4
	s_lshl_b32 vcc_lo, vcc_lo, 7
	s_bfe_u32 m0, s3, 0x10008
	s_mul_i32 m0, m0, 0x12000
	s_add_i32 vcc_lo, vcc_lo, m0
	s_add_i32 vcc_lo, vcc_lo, 0x10010
	v_add_u32_e32 v184, vcc_lo, v168
	v_add_u32_e32 v185, vcc_lo, v169
	v_add_u32_e32 v186, vcc_lo, v170
	v_add_u32_e32 v187, vcc_lo, v171
	v_add_u32_e32 v188, vcc_lo, v172
	v_add_u32_e32 v189, vcc_lo, v173
	v_add_u32_e32 v190, vcc_lo, v174
	v_add_u32_e32 v191, vcc_lo, v175
	s_and_b32 s0, s3, 0xff
	s_add_u32 s0, s0, 1
	s_min_u32 s0, s0, 7
	s_lshr_b32 s1, s0, 1
	s_and_b32 s0, s0, 1
	s_lshl_b32 s0, s0, 5
	s_lshr_b32 vcc_lo, s3, 12
	s_add_u32 s0, s0, vcc_lo
	s_lshl_b32 s0, s0, 1
	s_sub_i32 vcc_lo, s0, 4
	s_max_i32 vcc_lo, vcc_lo, 0
	s_min_i32 vcc_lo, vcc_lo, 0x78
	s_lshl_b32 vcc_hi, s1, 13
	s_sub_i32 s18, s0, 3
	s_max_i32 s18, s18, 0
	s_min_i32 s18, s18, 0x78
	s_sub_i32 s18, vcc_lo, s18
	ds_read_b128 v[112:115], v225 offset:0
	ds_read_b128 v[116:119], v225 offset:4096
	ds_read_b128 v[120:123], v225 offset:8192
	ds_read_b128 v[124:127], v225 offset:12288
	ds_read_b128 v[128:131], v226 offset:0
	ds_read_b128 v[132:135], v226 offset:4096
	ds_read_b128 v[136:139], v226 offset:8192
	ds_read_b128 v[140:143], v226 offset:12288
	v_mov_b32_e32 v221, v220
	v_pk_add_f32 v[222:223], v[0:1], v[2:3]
	v_pk_add_f32 v[222:223], v[222:223], v[4:5]
	v_pk_add_f32 v[222:223], v[222:223], v[6:7]
	v_pk_add_f32 v[222:223], v[222:223], v[8:9]
	v_pk_add_f32 v[222:223], v[222:223], v[10:11]
	v_pk_add_f32 v[222:223], v[222:223], v[12:13]
	v_pk_add_f32 v[222:223], v[222:223], v[14:15]
	v_pk_add_f32 v[222:223], v[222:223], v[16:17]
	v_pk_add_f32 v[222:223], v[222:223], v[18:19]
	v_pk_add_f32 v[222:223], v[222:223], v[20:21]
	v_pk_add_f32 v[222:223], v[222:223], v[22:23]
	v_pk_add_f32 v[222:223], v[222:223], v[24:25]
	v_pk_add_f32 v[222:223], v[222:223], v[26:27]
	v_pk_add_f32 v[222:223], v[222:223], v[28:29]
	v_pk_add_f32 v[222:223], v[222:223], v[30:31]
	v_pk_mul_f32 v[32:33], v[32:33], v[220:221]
	v_pk_mul_f32 v[34:35], v[34:35], v[220:221]
	v_pk_mul_f32 v[36:37], v[36:37], v[220:221]
	v_pk_mul_f32 v[38:39], v[38:39], v[220:221]
	v_pk_mul_f32 v[40:41], v[40:41], v[220:221]
	v_pk_mul_f32 v[42:43], v[42:43], v[220:221]
	v_pk_mul_f32 v[44:45], v[44:45], v[220:221]
	v_pk_mul_f32 v[46:47], v[46:47], v[220:221]
	v_add_f32_e32 v203, v222, v223
	v_fma_f32 v201, v201, v220, v203
	v_cvt_pk_bf16_f32 v48, v0, v1
	v_cvt_pk_bf16_f32 v49, v2, v3
	v_cvt_pk_bf16_f32 v50, v4, v5
	v_cvt_pk_bf16_f32 v51, v6, v7
	v_cvt_pk_bf16_f32 v52, v8, v9
	v_cvt_pk_bf16_f32 v53, v10, v11
	v_cvt_pk_bf16_f32 v54, v12, v13
	v_cvt_pk_bf16_f32 v55, v14, v15
	v_cvt_pk_bf16_f32 v56, v16, v17
	v_cvt_pk_bf16_f32 v57, v18, v19
	v_cvt_pk_bf16_f32 v58, v20, v21
	v_cvt_pk_bf16_f32 v59, v22, v23
	v_cvt_pk_bf16_f32 v60, v24, v25
	v_cvt_pk_bf16_f32 v61, v26, v27
	v_cvt_pk_bf16_f32 v62, v28, v29
	v_cvt_pk_bf16_f32 v63, v30, v31
	s_waitcnt lgkmcnt(7)
	v_mfma_f32_16x16x32_bf16 v[32:35], v[112:115], v[48:51], v[32:35]
	ds_read_b128 v[112:115], v227 offset:0
	s_waitcnt lgkmcnt(7)
	v_mfma_f32_16x16x32_bf16 v[36:39], v[116:119], v[48:51], v[36:39]
	ds_read_b128 v[116:119], v227 offset:4096
	s_waitcnt lgkmcnt(7)
	v_mfma_f32_16x16x32_bf16 v[40:43], v[120:123], v[48:51], v[40:43]
	ds_read_b128 v[120:123], v227 offset:8192
	s_waitcnt lgkmcnt(7)
	v_mfma_f32_16x16x32_bf16 v[44:47], v[124:127], v[48:51], v[44:47]
	ds_read_b128 v[124:127], v227 offset:12288
	s_waitcnt lgkmcnt(7)
	v_mfma_f32_16x16x32_bf16 v[32:35], v[128:131], v[52:55], v[32:35]
	ds_read_b128 v[128:131], v228 offset:0
	s_waitcnt lgkmcnt(7)
	v_mfma_f32_16x16x32_bf16 v[36:39], v[132:135], v[52:55], v[36:39]
	ds_read_b128 v[132:135], v228 offset:4096
	s_waitcnt lgkmcnt(7)
	v_mfma_f32_16x16x32_bf16 v[40:43], v[136:139], v[52:55], v[40:43]
	ds_read_b128 v[136:139], v228 offset:8192
	s_waitcnt lgkmcnt(7)
	v_mfma_f32_16x16x32_bf16 v[44:47], v[140:143], v[52:55], v[44:47]
	ds_read_b128 v[140:143], v228 offset:12288
	s_waitcnt lgkmcnt(7)
	v_mfma_f32_16x16x32_bf16 v[32:35], v[112:115], v[56:59], v[32:35]
	s_waitcnt lgkmcnt(6)
	v_mfma_f32_16x16x32_bf16 v[36:39], v[116:119], v[56:59], v[36:39]
	s_waitcnt lgkmcnt(5)
	v_mfma_f32_16x16x32_bf16 v[40:43], v[120:123], v[56:59], v[40:43]
	s_waitcnt lgkmcnt(4)
	v_mfma_f32_16x16x32_bf16 v[44:47], v[124:127], v[56:59], v[44:47]
	s_waitcnt lgkmcnt(3)
	v_mfma_f32_16x16x32_bf16 v[32:35], v[128:131], v[60:63], v[32:35]
	s_waitcnt lgkmcnt(2)
	v_mfma_f32_16x16x32_bf16 v[36:39], v[132:135], v[60:63], v[36:39]
	s_waitcnt lgkmcnt(1)
	v_mfma_f32_16x16x32_bf16 v[40:43], v[136:139], v[60:63], v[40:43]
	s_waitcnt lgkmcnt(0)
	v_mfma_f32_16x16x32_bf16 v[44:47], v[140:143], v[60:63], v[44:47]
	ds_read_b128 v[112:115], v149 offset:0
	ds_read_b128 v[116:119], v224 offset:0
	ds_read_b128 v[120:123], v149 offset:8192
	ds_read_b128 v[124:127], v224 offset:8192
	ds_read_b128 v[128:131], v149 offset:2048
	ds_read_b128 v[132:135], v224 offset:2048
	ds_read_b128 v[136:139], v149 offset:10240
	ds_read_b128 v[140:143], v224 offset:10240
	s_waitcnt lgkmcnt(7)
; __device__ __forceinline__ void attn_phase(const Params& P, char* smem_raw) {
;     ...
;     for (int ck = 0; ck < 6; ++ck) {
;       int lane_c = lane;
;       asm volatile("" : "+v"(lane_c));
;       __syncthreads();
; #pragma unroll
;       for (int i = 0; i < 4; ++i) {
;         const int idx = tid + 256 * i;
;         *reinterpret_cast<uint4*>(&sm_k[(idx >> 3) * LDSS + (idx & 7) * 8]) = kreg[i];
;         *reinterpret_cast<uint4*>(&sm_vt[(idx >> 4) * 136 + (idx & 15) * 8]) = vreg[i];
;       }
;       __syncthreads();
;       f32x4 sacc[8];
; #pragma unroll
;       for (int t8 = 0; t8 < 8; ++t8) sacc[t8] = f32x4{0.f, 0.f, 0.f, 0.f};
; #pragma unroll
;       for (int s = 0; s < 2; ++s)
; #pragma unroll
;         for (int t8 = 0; t8 < 8; ++t8) {
;           const bf16x8 kf = *reinterpret_cast<const bf16x8*>(&sm_k[(t8 * 16 + (lane_c & 15)) * LDSS + s * 32 + (lane_c >> 4) * 8]);
;           sacc[t8] = __builtin_amdgcn_mfma_f32_16x16x32_bf16(qf[s], kf, sacc[t8], 0, 0, 0);
;         }
;       if (ck < 5) {
;         ATT_ISSUE(t, ck + 1)
;       } else if (t + VGRID < 8192) {
;         ATT_ISSUE(t + VGRID, 0)
;         ATT_QLOAD(t + VGRID)
;       }
;       if (ck < 4) {
;         const float* rb0 = sm_rpb + (rs + ck * 2 - r + 7) * 31;
; #pragma unroll
;         for (int t8 = 0; t8 < 8; ++t8)
; #pragma unroll
;           for (int reg = 0; reg < 4; ++reg)
;             sacc[t8][reg] += rb0[(t8 >> 2) * 31 + dco[reg][t8 & 3]];
;       }
; #pragma unroll
;       for (int reg = 0; reg < 4; ++reg) {
;         float mx = sacc[0][reg];
; #pragma unroll
;         for (int t8 = 1; t8 < 8; ++t8) mx = fmaxf(mx, sacc[t8][reg]);
;         mx = row16_max(mx);
;         const float mnew = fmaxf(mrow[reg], mx);
;         const float alpha = __builtin_amdgcn_exp2f(mrow[reg] - mnew);
;         mrow[reg] = mnew;
;         float rsum = 0.f;
; #pragma unroll
;         for (int t8 = 0; t8 < 8; ++t8) {
;           const float p = __builtin_amdgcn_exp2f(sacc[t8][reg] - mnew);
;           rsum += p;
;           sm_p[(wid * 16 + (lane_c >> 4) * 4 + reg) * 136 + t8 * 16 + (lane_c & 15)] = f2bf(p);
;         }
;         rsum = row16_sum(rsum);
;         lrow[reg] = lrow[reg] * alpha + rsum;
; #pragma unroll
;         for (int td = 0; td < 4; ++td) o[td][reg] *= alpha;
;       }
;       asm volatile("s_waitcnt lgkmcnt(0)" ::: "memory");
; #pragma unroll
;       for (int s4 = 0; s4 < 4; ++s4) {
	v_mfma_f32_16x16x32_bf16 v[0:3], v[112:115], v[230:233], 0
	ds_read_b128 v[112:115], v149 offset:4096
	s_waitcnt lgkmcnt(7)
	v_mfma_f32_16x16x32_bf16 v[0:3], v[116:119], v[234:237], v[0:3]
	ds_read_b128 v[116:119], v224 offset:4096
	s_waitcnt lgkmcnt(7)
	v_mfma_f32_16x16x32_bf16 v[4:7], v[120:123], v[230:233], 0
	ds_read_b128 v[120:123], v149 offset:12288
	s_waitcnt lgkmcnt(7)
	v_mfma_f32_16x16x32_bf16 v[4:7], v[124:127], v[234:237], v[4:7]
	ds_read_b128 v[124:127], v224 offset:12288
	s_waitcnt lgkmcnt(7)
	v_mfma_f32_16x16x32_bf16 v[8:11], v[128:131], v[230:233], 0
	ds_read_b128 v[128:131], v149 offset:6144
	s_waitcnt lgkmcnt(7)
	v_mfma_f32_16x16x32_bf16 v[8:11], v[132:135], v[234:237], v[8:11]
	ds_read_b128 v[132:135], v224 offset:6144
	s_waitcnt lgkmcnt(7)
	v_mfma_f32_16x16x32_bf16 v[12:15], v[136:139], v[230:233], 0
	ds_read_b128 v[136:139], v149 offset:14336
	s_waitcnt lgkmcnt(7)
	v_mfma_f32_16x16x32_bf16 v[12:15], v[140:143], v[234:237], v[12:15]
	ds_read_b128 v[140:143], v224 offset:14336
	s_waitcnt lgkmcnt(7)
	v_mfma_f32_16x16x32_bf16 v[16:19], v[112:115], v[230:233], 0
	s_waitcnt lgkmcnt(6)
	v_mfma_f32_16x16x32_bf16 v[16:19], v[116:119], v[234:237], v[16:19]
	s_waitcnt lgkmcnt(5)
	v_mfma_f32_16x16x32_bf16 v[20:23], v[120:123], v[230:233], 0
	s_waitcnt lgkmcnt(4)
	v_mfma_f32_16x16x32_bf16 v[20:23], v[124:127], v[234:237], v[20:23]
	s_waitcnt lgkmcnt(3)
	v_mfma_f32_16x16x32_bf16 v[24:27], v[128:131], v[230:233], 0
	s_waitcnt lgkmcnt(2)
	v_mfma_f32_16x16x32_bf16 v[24:27], v[132:135], v[234:237], v[24:27]
	s_waitcnt lgkmcnt(1)
	v_mfma_f32_16x16x32_bf16 v[28:31], v[136:139], v[230:233], 0
	s_waitcnt lgkmcnt(0)
	v_mfma_f32_16x16x32_bf16 v[28:31], v[140:143], v[234:237], v[28:31]
	s_nop 7
	v_max3_f32 v203, v0, v1, v2
	v_max3_f32 v203, v203, v3, v4
	v_max3_f32 v203, v203, v5, v6
	v_max3_f32 v203, v203, v7, v8
	v_max3_f32 v203, v203, v9, v10
	v_max3_f32 v203, v203, v11, v12
	v_max3_f32 v203, v203, v13, v14
	v_max3_f32 v203, v203, v15, v16
	v_max3_f32 v203, v203, v17, v18
	v_max3_f32 v203, v203, v19, v20
	v_max3_f32 v203, v203, v21, v22
	v_max3_f32 v203, v203, v23, v24
	v_max3_f32 v203, v203, v25, v26
	v_max3_f32 v203, v203, v27, v28
	v_max3_f32 v203, v203, v29, v30
	v_max_f32_e32 v203, v203, v31
	v_mov_b32_e32 v205, v203
	s_nop 1
	v_permlane16_swap_b32_e32 v203, v205
	v_max_f32_e32 v203, v203, v205
	v_mov_b32_e32 v205, v203
	s_nop 1
	v_permlane32_swap_b32_e32 v203, v205
	v_max_f32_e32 v203, v203, v205
	v_max_f32_e32 v218, v246, v203
	v_sub_f32_e32 v220, v246, v218
	v_mov_b32_e32 v219, v218
	v_exp_f32_e32 v220, v220
	v_mov_b32_e32 v246, v218
	v_pk_add_f32 v[0:1], v[0:1], v[218:219] neg_lo:[0,1] neg_hi:[0,1]
	v_pk_add_f32 v[2:3], v[2:3], v[218:219] neg_lo:[0,1] neg_hi:[0,1]
	v_pk_add_f32 v[4:5], v[4:5], v[218:219] neg_lo:[0,1] neg_hi:[0,1]
	v_pk_add_f32 v[6:7], v[6:7], v[218:219] neg_lo:[0,1] neg_hi:[0,1]
	v_pk_add_f32 v[8:9], v[8:9], v[218:219] neg_lo:[0,1] neg_hi:[0,1]
	v_pk_add_f32 v[10:11], v[10:11], v[218:219] neg_lo:[0,1] neg_hi:[0,1]
	v_pk_add_f32 v[12:13], v[12:13], v[218:219] neg_lo:[0,1] neg_hi:[0,1]
	v_pk_add_f32 v[14:15], v[14:15], v[218:219] neg_lo:[0,1] neg_hi:[0,1]
	v_pk_add_f32 v[16:17], v[16:17], v[218:219] neg_lo:[0,1] neg_hi:[0,1]
	v_pk_add_f32 v[18:19], v[18:19], v[218:219] neg_lo:[0,1] neg_hi:[0,1]
	v_pk_add_f32 v[20:21], v[20:21], v[218:219] neg_lo:[0,1] neg_hi:[0,1]
	v_pk_add_f32 v[22:23], v[22:23], v[218:219] neg_lo:[0,1] neg_hi:[0,1]
	v_pk_add_f32 v[24:25], v[24:25], v[218:219] neg_lo:[0,1] neg_hi:[0,1]
	v_pk_add_f32 v[26:27], v[26:27], v[218:219] neg_lo:[0,1] neg_hi:[0,1]
	v_pk_add_f32 v[28:29], v[28:29], v[218:219] neg_lo:[0,1] neg_hi:[0,1]
	v_pk_add_f32 v[30:31], v[30:31], v[218:219] neg_lo:[0,1] neg_hi:[0,1]
	v_exp_f32_e32 v0, v0
	v_exp_f32_e32 v1, v1
	v_exp_f32_e32 v2, v2
	v_exp_f32_e32 v3, v3
	v_exp_f32_e32 v4, v4
	v_exp_f32_e32 v5, v5
	v_exp_f32_e32 v6, v6
	v_exp_f32_e32 v7, v7
	v_exp_f32_e32 v8, v8
	v_exp_f32_e32 v9, v9
	v_exp_f32_e32 v10, v10
	v_exp_f32_e32 v11, v11
	v_exp_f32_e32 v12, v12
	v_exp_f32_e32 v13, v13
	v_exp_f32_e32 v14, v14
	v_exp_f32_e32 v15, v15
	v_exp_f32_e32 v16, v16
	v_exp_f32_e32 v17, v17
	v_exp_f32_e32 v18, v18
	v_exp_f32_e32 v19, v19
	v_exp_f32_e32 v20, v20
	v_exp_f32_e32 v21, v21
	v_exp_f32_e32 v22, v22
	v_exp_f32_e32 v23, v23
	v_exp_f32_e32 v24, v24
	v_exp_f32_e32 v25, v25
	v_exp_f32_e32 v26, v26
	v_exp_f32_e32 v27, v27
	v_exp_f32_e32 v28, v28
	v_exp_f32_e32 v29, v29
	v_exp_f32_e32 v30, v30
	v_exp_f32_e32 v31, v31
	ds_read_b128 v[112:115], v225 offset:0
	ds_read_b128 v[116:119], v225 offset:4096
	ds_read_b128 v[120:123], v225 offset:8192
	ds_read_b128 v[124:127], v225 offset:12288
	ds_read_b128 v[128:131], v226 offset:0
	ds_read_b128 v[132:135], v226 offset:4096
	ds_read_b128 v[136:139], v226 offset:8192
	ds_read_b128 v[140:143], v226 offset:12288
	v_mov_b32_e32 v221, v220
	v_pk_add_f32 v[222:223], v[0:1], v[2:3]
	v_pk_add_f32 v[222:223], v[222:223], v[4:5]
	v_pk_add_f32 v[222:223], v[222:223], v[6:7]
	v_pk_add_f32 v[222:223], v[222:223], v[8:9]
	v_pk_add_f32 v[222:223], v[222:223], v[10:11]
	v_pk_add_f32 v[222:223], v[222:223], v[12:13]
	v_pk_add_f32 v[222:223], v[222:223], v[14:15]
	v_pk_add_f32 v[222:223], v[222:223], v[16:17]
	v_pk_add_f32 v[222:223], v[222:223], v[18:19]
	v_pk_add_f32 v[222:223], v[222:223], v[20:21]
	v_pk_add_f32 v[222:223], v[222:223], v[22:23]
	v_pk_add_f32 v[222:223], v[222:223], v[24:25]
	v_pk_add_f32 v[222:223], v[222:223], v[26:27]
	v_pk_add_f32 v[222:223], v[222:223], v[28:29]
	v_pk_add_f32 v[222:223], v[222:223], v[30:31]
	v_pk_mul_f32 v[176:177], v[176:177], v[220:221]
	v_pk_mul_f32 v[178:179], v[178:179], v[220:221]
	v_pk_mul_f32 v[180:181], v[180:181], v[220:221]
	v_pk_mul_f32 v[182:183], v[182:183], v[220:221]
	v_pk_mul_f32 v[192:193], v[192:193], v[220:221]
	v_pk_mul_f32 v[194:195], v[194:195], v[220:221]
	v_pk_mul_f32 v[196:197], v[196:197], v[220:221]
	v_pk_mul_f32 v[198:199], v[198:199], v[220:221]
	v_add_f32_e32 v203, v222, v223
	v_fma_f32 v247, v247, v220, v203
	v_cvt_pk_bf16_f32 v48, v0, v1
	v_cvt_pk_bf16_f32 v49, v2, v3
	v_cvt_pk_bf16_f32 v50, v4, v5
	v_cvt_pk_bf16_f32 v51, v6, v7
	v_cvt_pk_bf16_f32 v52, v8, v9
	v_cvt_pk_bf16_f32 v53, v10, v11
	v_cvt_pk_bf16_f32 v54, v12, v13
	v_cvt_pk_bf16_f32 v55, v14, v15
	v_cvt_pk_bf16_f32 v56, v16, v17
	v_cvt_pk_bf16_f32 v57, v18, v19
	v_cvt_pk_bf16_f32 v58, v20, v21
	v_cvt_pk_bf16_f32 v59, v22, v23
	v_cvt_pk_bf16_f32 v60, v24, v25
	v_cvt_pk_bf16_f32 v61, v26, v27
	v_cvt_pk_bf16_f32 v62, v28, v29
	v_cvt_pk_bf16_f32 v63, v30, v31
	s_waitcnt lgkmcnt(7)
; __device__ __forceinline__ void attn_phase(const Params& P, char* smem_raw) {
;     ...
;       f32x4 sacc[8];
; #pragma unroll
;       for (int t8 = 0; t8 < 8; ++t8) sacc[t8] = f32x4{0.f, 0.f, 0.f, 0.f};
; #pragma unroll
;       for (int s = 0; s < 2; ++s)
; #pragma unroll
;         for (int t8 = 0; t8 < 8; ++t8) {
;           const bf16x8 kf = *reinterpret_cast<const bf16x8*>(&sm_k[(t8 * 16 + (lane_c & 15)) * LDSS + s * 32 + (lane_c >> 4) * 8]);
;           sacc[t8] = __builtin_amdgcn_mfma_f32_16x16x32_bf16(qf[s], kf, sacc[t8], 0, 0, 0);
;         }
;       if (ck < 5) {
;         ATT_ISSUE(t, ck + 1)
;       } else if (t + VGRID < 8192) {
;         ATT_ISSUE(t + VGRID, 0)
;         ATT_QLOAD(t + VGRID)
;       }
;       if (ck < 4) {
;         const float* rb0 = sm_rpb + (rs + ck * 2 - r + 7) * 31;
; #pragma unroll
;         for (int t8 = 0; t8 < 8; ++t8)
; #pragma unroll
;           for (int reg = 0; reg < 4; ++reg)
;             sacc[t8][reg] += rb0[(t8 >> 2) * 31 + dco[reg][t8 & 3]];
;       }
; #pragma unroll
;       for (int reg = 0; reg < 4; ++reg) {
;         float mx = sacc[0][reg];
; #pragma unroll
;         for (int t8 = 1; t8 < 8; ++t8) mx = fmaxf(mx, sacc[t8][reg]);
;         mx = row16_max(mx);
;         const float mnew = fmaxf(mrow[reg], mx);
;         const float alpha = __builtin_amdgcn_exp2f(mrow[reg] - mnew);
;         mrow[reg] = mnew;
;         float rsum = 0.f;
; #pragma unroll
;         for (int t8 = 0; t8 < 8; ++t8) {
;           const float p = __builtin_amdgcn_exp2f(sacc[t8][reg] - mnew);
;           rsum += p;
;           sm_p[(wid * 16 + (lane_c >> 4) * 4 + reg) * 136 + t8 * 16 + (lane_c & 15)] = f2bf(p);
;         }
;         rsum = row16_sum(rsum);
;         lrow[reg] = lrow[reg] * alpha + rsum;
; #pragma unroll
;         for (int td = 0; td < 4; ++td) o[td][reg] *= alpha;
;       }
;       asm volatile("s_waitcnt lgkmcnt(0)" ::: "memory");
; #pragma unroll
;       for (int s4 = 0; s4 < 4; ++s4) {
;         const bf16x8 pf = *reinterpret_cast<const bf16x8*>(&sm_p[(wid * 16 + (lane_c & 15)) * 136 + s4 * 32 + (lane_c >> 4) * 8]);
; #pragma unroll
;         for (int td = 0; td < 4; ++td) {
;           const bf16x8 vf = *reinterpret_cast<const bf16x8*>(&sm_vt[(td * 16 + (lane_c & 15)) * 136 + s4 * 32 + (lane_c >> 4) * 8]);
;           o[td] = __builtin_amdgcn_mfma_f32_16x16x32_bf16(pf, vf, o[td], 0, 0, 0);
;         }
;       }
	v_mfma_f32_16x16x32_bf16 v[176:179], v[112:115], v[48:51], v[176:179]
	ds_read_b128 v[112:115], v227 offset:0
	s_waitcnt lgkmcnt(7)
	v_mfma_f32_16x16x32_bf16 v[180:183], v[116:119], v[48:51], v[180:183]
	ds_read_b128 v[116:119], v227 offset:4096
	s_waitcnt lgkmcnt(7)
	v_mfma_f32_16x16x32_bf16 v[192:195], v[120:123], v[48:51], v[192:195]
	ds_read_b128 v[120:123], v227 offset:8192
	s_waitcnt lgkmcnt(7)
	v_mfma_f32_16x16x32_bf16 v[196:199], v[124:127], v[48:51], v[196:199]
	ds_read_b128 v[124:127], v227 offset:12288
	s_waitcnt lgkmcnt(7)
	v_mfma_f32_16x16x32_bf16 v[176:179], v[128:131], v[52:55], v[176:179]
	ds_read_b128 v[128:131], v228 offset:0
	s_waitcnt lgkmcnt(7)
	v_mfma_f32_16x16x32_bf16 v[180:183], v[132:135], v[52:55], v[180:183]
	ds_read_b128 v[132:135], v228 offset:4096
	s_waitcnt lgkmcnt(7)
	v_mfma_f32_16x16x32_bf16 v[192:195], v[136:139], v[52:55], v[192:195]
	ds_read_b128 v[136:139], v228 offset:8192
	s_waitcnt lgkmcnt(7)
	v_mfma_f32_16x16x32_bf16 v[196:199], v[140:143], v[52:55], v[196:199]
	ds_read_b128 v[140:143], v228 offset:12288
	s_waitcnt lgkmcnt(7)
	v_mfma_f32_16x16x32_bf16 v[176:179], v[112:115], v[56:59], v[176:179]
	s_waitcnt lgkmcnt(6)
	v_mfma_f32_16x16x32_bf16 v[180:183], v[116:119], v[56:59], v[180:183]
	s_waitcnt lgkmcnt(5)
	v_mfma_f32_16x16x32_bf16 v[192:195], v[120:123], v[56:59], v[192:195]
	s_waitcnt lgkmcnt(4)
	v_mfma_f32_16x16x32_bf16 v[196:199], v[124:127], v[56:59], v[196:199]
	s_waitcnt lgkmcnt(3)
	v_mfma_f32_16x16x32_bf16 v[176:179], v[128:131], v[60:63], v[176:179]
	s_waitcnt lgkmcnt(2)
	v_mfma_f32_16x16x32_bf16 v[180:183], v[132:135], v[60:63], v[180:183]
	s_waitcnt lgkmcnt(1)
	v_mfma_f32_16x16x32_bf16 v[192:195], v[136:139], v[60:63], v[192:195]
	s_waitcnt lgkmcnt(0)
	v_mfma_f32_16x16x32_bf16 v[196:199], v[140:143], v[60:63], v[196:199]
	s_waitcnt lgkmcnt(0)
	s_barrier
	ds_read_b128 v[112:115], v149 offset:32768
	ds_read_b128 v[116:119], v224 offset:32768
	ds_read_b128 v[120:123], v149 offset:40960
	ds_read_b128 v[124:127], v224 offset:40960
	ds_read_b128 v[128:131], v149 offset:34816
	ds_read_b128 v[132:135], v224 offset:34816
	ds_read_b128 v[136:139], v149 offset:43008
	ds_read_b128 v[140:143], v224 offset:43008
	s_waitcnt lgkmcnt(7)
	v_mfma_f32_16x16x32_bf16 v[0:3], v[112:115], v[64:67], 0
	ds_read_b128 v[112:115], v149 offset:36864
	s_waitcnt lgkmcnt(7)
	v_mfma_f32_16x16x32_bf16 v[0:3], v[116:119], v[68:71], v[0:3]
	ds_read_b128 v[116:119], v224 offset:36864
	s_waitcnt lgkmcnt(7)
	v_mfma_f32_16x16x32_bf16 v[4:7], v[120:123], v[64:67], 0
	ds_read_b128 v[120:123], v149 offset:45056
	s_waitcnt lgkmcnt(7)
	v_mfma_f32_16x16x32_bf16 v[4:7], v[124:127], v[68:71], v[4:7]
	ds_read_b128 v[124:127], v224 offset:45056
	s_waitcnt lgkmcnt(7)
	v_mfma_f32_16x16x32_bf16 v[8:11], v[128:131], v[64:67], 0
	ds_read_b128 v[128:131], v149 offset:38912
	s_waitcnt lgkmcnt(7)
	v_mfma_f32_16x16x32_bf16 v[8:11], v[132:135], v[68:71], v[8:11]
	ds_read_b128 v[132:135], v224 offset:38912
	s_waitcnt lgkmcnt(7)
	v_mfma_f32_16x16x32_bf16 v[12:15], v[136:139], v[64:67], 0
	ds_read_b128 v[136:139], v149 offset:47104
	s_waitcnt lgkmcnt(7)
	v_mfma_f32_16x16x32_bf16 v[12:15], v[140:143], v[68:71], v[12:15]
	ds_read_b128 v[140:143], v224 offset:47104
	s_waitcnt lgkmcnt(7)
	v_mfma_f32_16x16x32_bf16 v[16:19], v[112:115], v[64:67], 0
	s_waitcnt lgkmcnt(6)
	v_mfma_f32_16x16x32_bf16 v[16:19], v[116:119], v[68:71], v[16:19]
	s_waitcnt lgkmcnt(5)
	v_mfma_f32_16x16x32_bf16 v[20:23], v[120:123], v[64:67], 0
	s_waitcnt lgkmcnt(4)
	v_mfma_f32_16x16x32_bf16 v[20:23], v[124:127], v[68:71], v[20:23]
	s_waitcnt lgkmcnt(3)
	v_mfma_f32_16x16x32_bf16 v[24:27], v[128:131], v[64:67], 0
	s_waitcnt lgkmcnt(2)
	v_mfma_f32_16x16x32_bf16 v[24:27], v[132:135], v[68:71], v[24:27]
	s_waitcnt lgkmcnt(1)
	v_mfma_f32_16x16x32_bf16 v[28:31], v[136:139], v[64:67], 0
	s_waitcnt lgkmcnt(0)
	v_mfma_f32_16x16x32_bf16 v[28:31], v[140:143], v[68:71], v[28:31]
	s_nop 7
	v_max3_f32 v203, v0, v1, v2
	v_max3_f32 v203, v203, v3, v4
	v_max3_f32 v203, v203, v5, v6
	v_max3_f32 v203, v203, v7, v8
	v_max3_f32 v203, v203, v9, v10
	v_max3_f32 v203, v203, v11, v12
	v_max3_f32 v203, v203, v13, v14
	v_max3_f32 v203, v203, v15, v16
	v_max3_f32 v203, v203, v17, v18
	v_max3_f32 v203, v203, v19, v20
	v_max3_f32 v203, v203, v21, v22
	v_max3_f32 v203, v203, v23, v24
	v_max3_f32 v203, v203, v25, v26
	v_max3_f32 v203, v203, v27, v28
	v_max3_f32 v203, v203, v29, v30
	v_max_f32_e32 v203, v203, v31
	v_mov_b32_e32 v205, v203
	s_nop 1
	v_permlane16_swap_b32_e32 v203, v205
	v_max_f32_e32 v203, v203, v205
	v_mov_b32_e32 v205, v203
	s_nop 1
	v_permlane32_swap_b32_e32 v203, v205
	v_max_f32_e32 v203, v203, v205
	v_max_f32_e32 v218, v200, v203
	v_sub_f32_e32 v220, v200, v218
	v_mov_b32_e32 v219, v218
	v_exp_f32_e32 v220, v220
	v_mov_b32_e32 v200, v218
	v_pk_add_f32 v[0:1], v[0:1], v[218:219] neg_lo:[0,1] neg_hi:[0,1]
	v_pk_add_f32 v[2:3], v[2:3], v[218:219] neg_lo:[0,1] neg_hi:[0,1]
	v_pk_add_f32 v[4:5], v[4:5], v[218:219] neg_lo:[0,1] neg_hi:[0,1]
	v_pk_add_f32 v[6:7], v[6:7], v[218:219] neg_lo:[0,1] neg_hi:[0,1]
	v_pk_add_f32 v[8:9], v[8:9], v[218:219] neg_lo:[0,1] neg_hi:[0,1]
	v_pk_add_f32 v[10:11], v[10:11], v[218:219] neg_lo:[0,1] neg_hi:[0,1]
	v_pk_add_f32 v[12:13], v[12:13], v[218:219] neg_lo:[0,1] neg_hi:[0,1]
	v_pk_add_f32 v[14:15], v[14:15], v[218:219] neg_lo:[0,1] neg_hi:[0,1]
	v_pk_add_f32 v[16:17], v[16:17], v[218:219] neg_lo:[0,1] neg_hi:[0,1]
	v_pk_add_f32 v[18:19], v[18:19], v[218:219] neg_lo:[0,1] neg_hi:[0,1]
	v_pk_add_f32 v[20:21], v[20:21], v[218:219] neg_lo:[0,1] neg_hi:[0,1]
	v_pk_add_f32 v[22:23], v[22:23], v[218:219] neg_lo:[0,1] neg_hi:[0,1]
	v_pk_add_f32 v[24:25], v[24:25], v[218:219] neg_lo:[0,1] neg_hi:[0,1]
	v_pk_add_f32 v[26:27], v[26:27], v[218:219] neg_lo:[0,1] neg_hi:[0,1]
	v_pk_add_f32 v[28:29], v[28:29], v[218:219] neg_lo:[0,1] neg_hi:[0,1]
	v_pk_add_f32 v[30:31], v[30:31], v[218:219] neg_lo:[0,1] neg_hi:[0,1]
	v_exp_f32_e32 v0, v0
	s_waitcnt vmcnt(0)
; __device__ __forceinline__ void attn_phase(const Params& P, char* smem_raw) {
;     ...
; #pragma unroll
;       for (int reg = 0; reg < 4; ++reg) {
;         float mx = sacc[0][reg];
; #pragma unroll
;         for (int t8 = 1; t8 < 8; ++t8) mx = fmaxf(mx, sacc[t8][reg]);
;         mx = row16_max(mx);
;         const float mnew = fmaxf(mrow[reg], mx);
;         const float alpha = __builtin_amdgcn_exp2f(mrow[reg] - mnew);
;         mrow[reg] = mnew;
;         float rsum = 0.f;
; #pragma unroll
;         for (int t8 = 0; t8 < 8; ++t8) {
;           const float p = __builtin_amdgcn_exp2f(sacc[t8][reg] - mnew);
;           rsum += p;
;           sm_p[(wid * 16 + (lane_c >> 4) * 4 + reg) * 136 + t8 * 16 + (lane_c & 15)] = f2bf(p);
;         }
;         rsum = row16_sum(rsum);
;         lrow[reg] = lrow[reg] * alpha + rsum;
; #pragma unroll
;         for (int td = 0; td < 4; ++td) o[td][reg] *= alpha;
;       }
;       asm volatile("s_waitcnt lgkmcnt(0)" ::: "memory");
; #pragma unroll
;       for (int s4 = 0; s4 < 4; ++s4) {
;         const bf16x8 pf = *reinterpret_cast<const bf16x8*>(&sm_p[(wid * 16 + (lane_c & 15)) * 136 + s4 * 32 + (lane_c >> 4) * 8]);
; #pragma unroll
;         for (int td = 0; td < 4; ++td) {
;           const bf16x8 vf = *reinterpret_cast<const bf16x8*>(&sm_vt[(td * 16 + (lane_c & 15)) * 136 + s4 * 32 + (lane_c >> 4) * 8]);
;           o[td] = __builtin_amdgcn_mfma_f32_16x16x32_bf16(pf, vf, o[td], 0, 0, 0);
;         }
;       }
	v_exp_f32_e32 v1, v1
	ds_write_b128 v150, v[80:83] offset:0
	v_exp_f32_e32 v2, v2
	ds_write_b128 v150, v[84:87] offset:4096
	v_exp_f32_e32 v3, v3
	ds_write_b128 v150, v[88:91] offset:8192
	v_exp_f32_e32 v4, v4
	ds_write_b128 v150, v[92:95] offset:12288
	v_exp_f32_e32 v5, v5
	ds_write_b64 v151, v[96:97] offset:0
	v_exp_f32_e32 v6, v6
	ds_write_b64 v229, v[98:99] offset:0
	v_exp_f32_e32 v7, v7
	ds_write_b64 v151, v[100:101] offset:4096
	v_exp_f32_e32 v8, v8
	ds_write_b64 v229, v[102:103] offset:4096
	v_exp_f32_e32 v9, v9
	ds_write_b64 v151, v[104:105] offset:8192
	v_exp_f32_e32 v10, v10
	ds_write_b64 v229, v[106:107] offset:8192
	v_exp_f32_e32 v11, v11
	ds_write_b64 v151, v[108:109] offset:12288
	v_exp_f32_e32 v12, v12
	ds_write_b64 v229, v[110:111] offset:12288
	v_exp_f32_e32 v13, v13
	s_add_u32 s100, s12, 0xc0000
	v_exp_f32_e32 v14, v14
	s_addc_u32 s101, s13, 0
	v_exp_f32_e32 v15, v15
	s_add_u32 s0, s14, 0x100
	v_exp_f32_e32 v16, v16
	s_addc_u32 s1, s15, 0
	v_exp_f32_e32 v17, v17
	global_load_dwordx4 v[80:83], v154, s[100:101] offset:2048
	v_exp_f32_e32 v18, v18
	global_load_dwordx4 v[96:99], v158, s[0:1]
	v_exp_f32_e32 v19, v19
	global_load_dwordx4 v[84:87], v155, s[100:101] offset:2048
	v_exp_f32_e32 v20, v20
	global_load_dwordx4 v[100:103], v159, s[0:1]
	v_exp_f32_e32 v21, v21
	global_load_dwordx4 v[88:91], v156, s[100:101] offset:2048
	v_exp_f32_e32 v22, v22
	global_load_dwordx4 v[104:107], v160, s[0:1]
	v_exp_f32_e32 v23, v23
	global_load_dwordx4 v[92:95], v157, s[100:101] offset:2048
	v_exp_f32_e32 v24, v24
	global_load_dwordx4 v[108:111], v161, s[0:1]
	v_exp_f32_e32 v25, v25
	v_exp_f32_e32 v26, v26
	v_exp_f32_e32 v27, v27
	v_exp_f32_e32 v28, v28
	v_exp_f32_e32 v29, v29
	v_exp_f32_e32 v30, v30
	v_exp_f32_e32 v31, v31
	ds_read_b128 v[112:115], v225 offset:32768
	ds_read_b128 v[116:119], v225 offset:36864
	ds_read_b128 v[120:123], v225 offset:40960
	ds_read_b128 v[124:127], v225 offset:45056
	ds_read_b128 v[128:131], v226 offset:32768
	ds_read_b128 v[132:135], v226 offset:36864
	ds_read_b128 v[136:139], v226 offset:40960
	ds_read_b128 v[140:143], v226 offset:45056
	v_mov_b32_e32 v221, v220
	v_pk_add_f32 v[222:223], v[0:1], v[2:3]
	v_pk_add_f32 v[222:223], v[222:223], v[4:5]
	v_pk_add_f32 v[222:223], v[222:223], v[6:7]
	v_pk_add_f32 v[222:223], v[222:223], v[8:9]
	v_pk_add_f32 v[222:223], v[222:223], v[10:11]
	v_pk_add_f32 v[222:223], v[222:223], v[12:13]
	v_pk_add_f32 v[222:223], v[222:223], v[14:15]
	v_pk_add_f32 v[222:223], v[222:223], v[16:17]
	v_pk_add_f32 v[222:223], v[222:223], v[18:19]
	v_pk_add_f32 v[222:223], v[222:223], v[20:21]
	v_pk_add_f32 v[222:223], v[222:223], v[22:23]
	v_pk_add_f32 v[222:223], v[222:223], v[24:25]
	v_pk_add_f32 v[222:223], v[222:223], v[26:27]
	v_pk_add_f32 v[222:223], v[222:223], v[28:29]
	v_pk_add_f32 v[222:223], v[222:223], v[30:31]
	v_pk_mul_f32 v[32:33], v[32:33], v[220:221]
	v_pk_mul_f32 v[34:35], v[34:35], v[220:221]
	v_pk_mul_f32 v[36:37], v[36:37], v[220:221]
	v_pk_mul_f32 v[38:39], v[38:39], v[220:221]
	v_pk_mul_f32 v[40:41], v[40:41], v[220:221]
	v_pk_mul_f32 v[42:43], v[42:43], v[220:221]
	v_pk_mul_f32 v[44:45], v[44:45], v[220:221]
	v_pk_mul_f32 v[46:47], v[46:47], v[220:221]
	v_add_f32_e32 v203, v222, v223
	v_fma_f32 v201, v201, v220, v203
	v_cvt_pk_bf16_f32 v48, v0, v1
	v_cvt_pk_bf16_f32 v49, v2, v3
	v_cvt_pk_bf16_f32 v50, v4, v5
	v_cvt_pk_bf16_f32 v51, v6, v7
	v_cvt_pk_bf16_f32 v52, v8, v9
	v_cvt_pk_bf16_f32 v53, v10, v11
	v_cvt_pk_bf16_f32 v54, v12, v13
	v_cvt_pk_bf16_f32 v55, v14, v15
	v_cvt_pk_bf16_f32 v56, v16, v17
	v_cvt_pk_bf16_f32 v57, v18, v19
	v_cvt_pk_bf16_f32 v58, v20, v21
	v_cvt_pk_bf16_f32 v59, v22, v23
	v_cvt_pk_bf16_f32 v60, v24, v25
	v_cvt_pk_bf16_f32 v61, v26, v27
	v_cvt_pk_bf16_f32 v62, v28, v29
	v_cvt_pk_bf16_f32 v63, v30, v31
	s_waitcnt lgkmcnt(7)
	v_mfma_f32_16x16x32_bf16 v[32:35], v[112:115], v[48:51], v[32:35]
	ds_read_b128 v[112:115], v227 offset:32768
	s_waitcnt lgkmcnt(7)
	v_mfma_f32_16x16x32_bf16 v[36:39], v[116:119], v[48:51], v[36:39]
	ds_read_b128 v[116:119], v227 offset:36864
	s_waitcnt lgkmcnt(7)
	v_mfma_f32_16x16x32_bf16 v[40:43], v[120:123], v[48:51], v[40:43]
	ds_read_b128 v[120:123], v227 offset:40960
	s_waitcnt lgkmcnt(7)
	v_mfma_f32_16x16x32_bf16 v[44:47], v[124:127], v[48:51], v[44:47]
	ds_read_b128 v[124:127], v227 offset:45056
	s_waitcnt lgkmcnt(7)
	v_mfma_f32_16x16x32_bf16 v[32:35], v[128:131], v[52:55], v[32:35]
	ds_read_b128 v[128:131], v228 offset:32768
	s_waitcnt lgkmcnt(7)
	v_mfma_f32_16x16x32_bf16 v[36:39], v[132:135], v[52:55], v[36:39]
	ds_read_b128 v[132:135], v228 offset:36864
	s_waitcnt lgkmcnt(7)
	v_mfma_f32_16x16x32_bf16 v[40:43], v[136:139], v[52:55], v[40:43]
	ds_read_b128 v[136:139], v228 offset:40960
	s_waitcnt lgkmcnt(7)
	v_mfma_f32_16x16x32_bf16 v[44:47], v[140:143], v[52:55], v[44:47]
	ds_read_b128 v[140:143], v228 offset:45056
	s_waitcnt lgkmcnt(7)
	v_mfma_f32_16x16x32_bf16 v[32:35], v[112:115], v[56:59], v[32:35]
	s_waitcnt lgkmcnt(6)
	v_mfma_f32_16x16x32_bf16 v[36:39], v[116:119], v[56:59], v[36:39]
	s_waitcnt lgkmcnt(5)
	v_mfma_f32_16x16x32_bf16 v[40:43], v[120:123], v[56:59], v[40:43]
	s_waitcnt lgkmcnt(4)
	v_mfma_f32_16x16x32_bf16 v[44:47], v[124:127], v[56:59], v[44:47]
	s_waitcnt lgkmcnt(3)
	v_mfma_f32_16x16x32_bf16 v[32:35], v[128:131], v[60:63], v[32:35]
	s_waitcnt lgkmcnt(2)
	v_mfma_f32_16x16x32_bf16 v[36:39], v[132:135], v[60:63], v[36:39]
	s_waitcnt lgkmcnt(1)
	v_mfma_f32_16x16x32_bf16 v[40:43], v[136:139], v[60:63], v[40:43]
	s_waitcnt lgkmcnt(0)
; __device__ __forceinline__ void attn_phase(const Params& P, char* smem_raw) {
;     ...
;       f32x4 sacc[8];
; #pragma unroll
;       for (int t8 = 0; t8 < 8; ++t8) sacc[t8] = f32x4{0.f, 0.f, 0.f, 0.f};
; #pragma unroll
;       for (int s = 0; s < 2; ++s)
; #pragma unroll
;         for (int t8 = 0; t8 < 8; ++t8) {
;           const bf16x8 kf = *reinterpret_cast<const bf16x8*>(&sm_k[(t8 * 16 + (lane_c & 15)) * LDSS + s * 32 + (lane_c >> 4) * 8]);
;           sacc[t8] = __builtin_amdgcn_mfma_f32_16x16x32_bf16(qf[s], kf, sacc[t8], 0, 0, 0);
;         }
;       if (ck < 5) {
;         ATT_ISSUE(t, ck + 1)
;       } else if (t + VGRID < 8192) {
;         ATT_ISSUE(t + VGRID, 0)
;         ATT_QLOAD(t + VGRID)
;       }
;       if (ck < 4) {
;         const float* rb0 = sm_rpb + (rs + ck * 2 - r + 7) * 31;
; #pragma unroll
;         for (int t8 = 0; t8 < 8; ++t8)
; #pragma unroll
;           for (int reg = 0; reg < 4; ++reg)
;             sacc[t8][reg] += rb0[(t8 >> 2) * 31 + dco[reg][t8 & 3]];
;       }
; #pragma unroll
;       for (int reg = 0; reg < 4; ++reg) {
;         float mx = sacc[0][reg];
; #pragma unroll
;         for (int t8 = 1; t8 < 8; ++t8) mx = fmaxf(mx, sacc[t8][reg]);
;         mx = row16_max(mx);
;         const float mnew = fmaxf(mrow[reg], mx);
;         const float alpha = __builtin_amdgcn_exp2f(mrow[reg] - mnew);
;         mrow[reg] = mnew;
;         float rsum = 0.f;
; #pragma unroll
;         for (int t8 = 0; t8 < 8; ++t8) {
;           const float p = __builtin_amdgcn_exp2f(sacc[t8][reg] - mnew);
;           rsum += p;
;           sm_p[(wid * 16 + (lane_c >> 4) * 4 + reg) * 136 + t8 * 16 + (lane_c & 15)] = f2bf(p);
;         }
;         rsum = row16_sum(rsum);
;         lrow[reg] = lrow[reg] * alpha + rsum;
; #pragma unroll
;         for (int td = 0; td < 4; ++td) o[td][reg] *= alpha;
;       }
;       asm volatile("s_waitcnt lgkmcnt(0)" ::: "memory");
; #pragma unroll
;       for (int s4 = 0; s4 < 4; ++s4) {
;         const bf16x8 pf = *reinterpret_cast<const bf16x8*>(&sm_p[(wid * 16 + (lane_c & 15)) * 136 + s4 * 32 + (lane_c >> 4) * 8]);
; #pragma unroll
;         for (int td = 0; td < 4; ++td) {
;           const bf16x8 vf = *reinterpret_cast<const bf16x8*>(&sm_vt[(td * 16 + (lane_c & 15)) * 136 + s4 * 32 + (lane_c >> 4) * 8]);
;           o[td] = __builtin_amdgcn_mfma_f32_16x16x32_bf16(pf, vf, o[td], 0, 0, 0);
;         }
;       }
	v_mfma_f32_16x16x32_bf16 v[44:47], v[140:143], v[60:63], v[44:47]
	ds_read_b128 v[112:115], v149 offset:32768
	ds_read_b128 v[116:119], v224 offset:32768
	ds_read_b128 v[120:123], v149 offset:40960
	ds_read_b128 v[124:127], v224 offset:40960
	ds_read_b128 v[128:131], v149 offset:34816
	ds_read_b128 v[132:135], v224 offset:34816
	ds_read_b128 v[136:139], v149 offset:43008
	ds_read_b128 v[140:143], v224 offset:43008
	s_waitcnt lgkmcnt(7)
	v_mfma_f32_16x16x32_bf16 v[0:3], v[112:115], v[230:233], 0
	ds_read_b128 v[112:115], v149 offset:36864
	s_waitcnt lgkmcnt(7)
	v_mfma_f32_16x16x32_bf16 v[0:3], v[116:119], v[234:237], v[0:3]
	ds_read_b128 v[116:119], v224 offset:36864
	s_waitcnt lgkmcnt(7)
	v_mfma_f32_16x16x32_bf16 v[4:7], v[120:123], v[230:233], 0
	ds_read_b128 v[120:123], v149 offset:45056
	s_waitcnt lgkmcnt(7)
	v_mfma_f32_16x16x32_bf16 v[4:7], v[124:127], v[234:237], v[4:7]
	ds_read_b128 v[124:127], v224 offset:45056
	s_waitcnt lgkmcnt(7)
	v_mfma_f32_16x16x32_bf16 v[8:11], v[128:131], v[230:233], 0
	ds_read_b128 v[128:131], v149 offset:38912
	s_waitcnt lgkmcnt(7)
	v_mfma_f32_16x16x32_bf16 v[8:11], v[132:135], v[234:237], v[8:11]
	ds_read_b128 v[132:135], v224 offset:38912
	s_waitcnt lgkmcnt(7)
	v_mfma_f32_16x16x32_bf16 v[12:15], v[136:139], v[230:233], 0
	ds_read_b128 v[136:139], v149 offset:47104
	s_waitcnt lgkmcnt(7)
	v_mfma_f32_16x16x32_bf16 v[12:15], v[140:143], v[234:237], v[12:15]
	ds_read_b128 v[140:143], v224 offset:47104
	s_waitcnt lgkmcnt(7)
	v_mfma_f32_16x16x32_bf16 v[16:19], v[112:115], v[230:233], 0
	s_waitcnt lgkmcnt(6)
	v_mfma_f32_16x16x32_bf16 v[16:19], v[116:119], v[234:237], v[16:19]
	s_waitcnt lgkmcnt(5)
	v_mfma_f32_16x16x32_bf16 v[20:23], v[120:123], v[230:233], 0
	s_waitcnt lgkmcnt(4)
	v_mfma_f32_16x16x32_bf16 v[20:23], v[124:127], v[234:237], v[20:23]
	s_waitcnt lgkmcnt(3)
	v_mfma_f32_16x16x32_bf16 v[24:27], v[128:131], v[230:233], 0
	s_waitcnt lgkmcnt(2)
	v_mfma_f32_16x16x32_bf16 v[24:27], v[132:135], v[234:237], v[24:27]
	s_waitcnt lgkmcnt(1)
	v_mfma_f32_16x16x32_bf16 v[28:31], v[136:139], v[230:233], 0
	s_waitcnt lgkmcnt(0)
	v_mfma_f32_16x16x32_bf16 v[28:31], v[140:143], v[234:237], v[28:31]
	s_nop 7
	v_max3_f32 v203, v0, v1, v2
	v_max3_f32 v203, v203, v3, v4
	v_max3_f32 v203, v203, v5, v6
	v_max3_f32 v203, v203, v7, v8
	v_max3_f32 v203, v203, v9, v10
	v_max3_f32 v203, v203, v11, v12
	v_max3_f32 v203, v203, v13, v14
	v_max3_f32 v203, v203, v15, v16
	v_max3_f32 v203, v203, v17, v18
	v_max3_f32 v203, v203, v19, v20
	v_max3_f32 v203, v203, v21, v22
	v_max3_f32 v203, v203, v23, v24
	v_max3_f32 v203, v203, v25, v26
	v_max3_f32 v203, v203, v27, v28
	v_max3_f32 v203, v203, v29, v30
	v_max_f32_e32 v203, v203, v31
	v_mov_b32_e32 v205, v203
	s_nop 1
	v_permlane16_swap_b32_e32 v203, v205
	v_max_f32_e32 v203, v203, v205
	v_mov_b32_e32 v205, v203
	s_nop 1
	v_permlane32_swap_b32_e32 v203, v205
	v_max_f32_e32 v203, v203, v205
	v_max_f32_e32 v218, v246, v203
	v_sub_f32_e32 v220, v246, v218
	v_mov_b32_e32 v219, v218
	v_exp_f32_e32 v220, v220
	v_mov_b32_e32 v246, v218
	v_pk_add_f32 v[0:1], v[0:1], v[218:219] neg_lo:[0,1] neg_hi:[0,1]
	v_pk_add_f32 v[2:3], v[2:3], v[218:219] neg_lo:[0,1] neg_hi:[0,1]
	v_pk_add_f32 v[4:5], v[4:5], v[218:219] neg_lo:[0,1] neg_hi:[0,1]
	v_pk_add_f32 v[6:7], v[6:7], v[218:219] neg_lo:[0,1] neg_hi:[0,1]
	v_pk_add_f32 v[8:9], v[8:9], v[218:219] neg_lo:[0,1] neg_hi:[0,1]
	v_pk_add_f32 v[10:11], v[10:11], v[218:219] neg_lo:[0,1] neg_hi:[0,1]
	v_pk_add_f32 v[12:13], v[12:13], v[218:219] neg_lo:[0,1] neg_hi:[0,1]
	v_pk_add_f32 v[14:15], v[14:15], v[218:219] neg_lo:[0,1] neg_hi:[0,1]
	v_pk_add_f32 v[16:17], v[16:17], v[218:219] neg_lo:[0,1] neg_hi:[0,1]
	v_pk_add_f32 v[18:19], v[18:19], v[218:219] neg_lo:[0,1] neg_hi:[0,1]
	v_pk_add_f32 v[20:21], v[20:21], v[218:219] neg_lo:[0,1] neg_hi:[0,1]
	v_pk_add_f32 v[22:23], v[22:23], v[218:219] neg_lo:[0,1] neg_hi:[0,1]
	v_pk_add_f32 v[24:25], v[24:25], v[218:219] neg_lo:[0,1] neg_hi:[0,1]
	v_pk_add_f32 v[26:27], v[26:27], v[218:219] neg_lo:[0,1] neg_hi:[0,1]
	v_pk_add_f32 v[28:29], v[28:29], v[218:219] neg_lo:[0,1] neg_hi:[0,1]
	v_pk_add_f32 v[30:31], v[30:31], v[218:219] neg_lo:[0,1] neg_hi:[0,1]
	v_exp_f32_e32 v0, v0
	v_exp_f32_e32 v1, v1
	v_exp_f32_e32 v2, v2
	v_exp_f32_e32 v3, v3
	v_exp_f32_e32 v4, v4
	v_exp_f32_e32 v5, v5
	v_exp_f32_e32 v6, v6
	v_exp_f32_e32 v7, v7
	v_exp_f32_e32 v8, v8
	v_exp_f32_e32 v9, v9
	v_exp_f32_e32 v10, v10
	v_exp_f32_e32 v11, v11
	v_exp_f32_e32 v12, v12
	v_exp_f32_e32 v13, v13
	v_exp_f32_e32 v14, v14
	v_exp_f32_e32 v15, v15
	v_exp_f32_e32 v16, v16
	v_exp_f32_e32 v17, v17
	v_exp_f32_e32 v18, v18
	v_exp_f32_e32 v19, v19
	v_exp_f32_e32 v20, v20
	v_exp_f32_e32 v21, v21
	v_exp_f32_e32 v22, v22
	v_exp_f32_e32 v23, v23
	v_exp_f32_e32 v24, v24
	v_exp_f32_e32 v25, v25
	v_exp_f32_e32 v26, v26
	v_exp_f32_e32 v27, v27
	v_exp_f32_e32 v28, v28
	v_exp_f32_e32 v29, v29
	v_exp_f32_e32 v30, v30
	v_exp_f32_e32 v31, v31
	ds_read_b128 v[112:115], v225 offset:32768
	ds_read_b128 v[116:119], v225 offset:36864
	ds_read_b128 v[120:123], v225 offset:40960
	ds_read_b128 v[124:127], v225 offset:45056
	ds_read_b128 v[128:131], v226 offset:32768
	ds_read_b128 v[132:135], v226 offset:36864
	ds_read_b128 v[136:139], v226 offset:40960
	ds_read_b128 v[140:143], v226 offset:45056
	v_mov_b32_e32 v221, v220
	v_pk_add_f32 v[222:223], v[0:1], v[2:3]
	v_pk_add_f32 v[222:223], v[222:223], v[4:5]
	v_pk_add_f32 v[222:223], v[222:223], v[6:7]
	v_pk_add_f32 v[222:223], v[222:223], v[8:9]
	v_pk_add_f32 v[222:223], v[222:223], v[10:11]
	v_pk_add_f32 v[222:223], v[222:223], v[12:13]
	v_pk_add_f32 v[222:223], v[222:223], v[14:15]
	v_pk_add_f32 v[222:223], v[222:223], v[16:17]
	v_pk_add_f32 v[222:223], v[222:223], v[18:19]
	v_pk_add_f32 v[222:223], v[222:223], v[20:21]
	v_pk_add_f32 v[222:223], v[222:223], v[22:23]
	v_pk_add_f32 v[222:223], v[222:223], v[24:25]
	v_pk_add_f32 v[222:223], v[222:223], v[26:27]
	v_pk_add_f32 v[222:223], v[222:223], v[28:29]
	v_pk_add_f32 v[222:223], v[222:223], v[30:31]
	v_pk_mul_f32 v[176:177], v[176:177], v[220:221]
	v_pk_mul_f32 v[178:179], v[178:179], v[220:221]
	v_pk_mul_f32 v[180:181], v[180:181], v[220:221]
	v_pk_mul_f32 v[182:183], v[182:183], v[220:221]
	v_pk_mul_f32 v[192:193], v[192:193], v[220:221]
	v_pk_mul_f32 v[194:195], v[194:195], v[220:221]
	v_pk_mul_f32 v[196:197], v[196:197], v[220:221]
	v_pk_mul_f32 v[198:199], v[198:199], v[220:221]
	v_add_f32_e32 v203, v222, v223
	v_fma_f32 v247, v247, v220, v203
	v_cvt_pk_bf16_f32 v48, v0, v1
	v_cvt_pk_bf16_f32 v49, v2, v3
	v_cvt_pk_bf16_f32 v50, v4, v5
	v_cvt_pk_bf16_f32 v51, v6, v7
	v_cvt_pk_bf16_f32 v52, v8, v9
	v_cvt_pk_bf16_f32 v53, v10, v11
	v_cvt_pk_bf16_f32 v54, v12, v13
	v_cvt_pk_bf16_f32 v55, v14, v15
	v_cvt_pk_bf16_f32 v56, v16, v17
	v_cvt_pk_bf16_f32 v57, v18, v19
	v_cvt_pk_bf16_f32 v58, v20, v21
	v_cvt_pk_bf16_f32 v59, v22, v23
	v_cvt_pk_bf16_f32 v60, v24, v25
	v_cvt_pk_bf16_f32 v61, v26, v27
	v_cvt_pk_bf16_f32 v62, v28, v29
	v_cvt_pk_bf16_f32 v63, v30, v31
	s_waitcnt lgkmcnt(7)
; __device__ __forceinline__ void attn_phase(const Params& P, char* smem_raw) {
;     ...
;       if (ck < 4) {
;         const float* rb0 = sm_rpb + (rs + ck * 2 - r + 7) * 31;
; #pragma unroll
;         for (int t8 = 0; t8 < 8; ++t8)
; #pragma unroll
;           for (int reg = 0; reg < 4; ++reg)
;             sacc[t8][reg] += rb0[(t8 >> 2) * 31 + dco[reg][t8 & 3]];
;     ...
;     u16* Ob = P.cat + ((long)b * 8192 + r * 64) * 1024 + h * 64;
; #pragma unroll
;     for (int td = 0; td < 4; ++td)
; #pragma unroll
;       for (int reg = 0; reg < 4; ++reg) {
;         const int rowl = wid * 16 + (lane >> 4) * 4 + reg;
;         Ob[(unsigned)(rowl * 1024 + td * 16 + (lane & 15))] = f2bf(o[td][reg] * __builtin_amdgcn_rcpf(lrow[reg]));
;       }
	v_mfma_f32_16x16x32_bf16 v[176:179], v[112:115], v[48:51], v[176:179]
	ds_read_b128 v[112:115], v227 offset:32768
	s_waitcnt lgkmcnt(7)
	v_mfma_f32_16x16x32_bf16 v[180:183], v[116:119], v[48:51], v[180:183]
	ds_read_b128 v[116:119], v227 offset:36864
	s_waitcnt lgkmcnt(7)
	v_mfma_f32_16x16x32_bf16 v[192:195], v[120:123], v[48:51], v[192:195]
	ds_read_b128 v[120:123], v227 offset:40960
	s_waitcnt lgkmcnt(7)
	v_mfma_f32_16x16x32_bf16 v[196:199], v[124:127], v[48:51], v[196:199]
	ds_read_b128 v[124:127], v227 offset:45056
	s_waitcnt lgkmcnt(7)
	v_mfma_f32_16x16x32_bf16 v[176:179], v[128:131], v[52:55], v[176:179]
	ds_read_b128 v[128:131], v228 offset:32768
	s_waitcnt lgkmcnt(7)
	v_mfma_f32_16x16x32_bf16 v[180:183], v[132:135], v[52:55], v[180:183]
	ds_read_b128 v[132:135], v228 offset:36864
	s_waitcnt lgkmcnt(7)
	v_mfma_f32_16x16x32_bf16 v[192:195], v[136:139], v[52:55], v[192:195]
	ds_read_b128 v[136:139], v228 offset:40960
	s_waitcnt lgkmcnt(7)
	v_mfma_f32_16x16x32_bf16 v[196:199], v[140:143], v[52:55], v[196:199]
	ds_read_b128 v[140:143], v228 offset:45056
	s_waitcnt lgkmcnt(7)
	v_mfma_f32_16x16x32_bf16 v[176:179], v[112:115], v[56:59], v[176:179]
	s_waitcnt lgkmcnt(6)
	v_mfma_f32_16x16x32_bf16 v[180:183], v[116:119], v[56:59], v[180:183]
	s_waitcnt lgkmcnt(5)
	v_mfma_f32_16x16x32_bf16 v[192:195], v[120:123], v[56:59], v[192:195]
	s_waitcnt lgkmcnt(4)
	v_mfma_f32_16x16x32_bf16 v[196:199], v[124:127], v[56:59], v[196:199]
	s_waitcnt lgkmcnt(3)
	v_mfma_f32_16x16x32_bf16 v[176:179], v[128:131], v[60:63], v[176:179]
	s_waitcnt lgkmcnt(2)
	v_mfma_f32_16x16x32_bf16 v[180:183], v[132:135], v[60:63], v[180:183]
	s_waitcnt lgkmcnt(1)
	v_mfma_f32_16x16x32_bf16 v[192:195], v[136:139], v[60:63], v[192:195]
	s_waitcnt lgkmcnt(0)
	v_mfma_f32_16x16x32_bf16 v[196:199], v[140:143], v[60:63], v[196:199]
	ds_read_b32 v0, v184 offset:384
	ds_read_b32 v1, v185 offset:384
	ds_read_b32 v2, v186 offset:384
	ds_read_b32 v3, v187 offset:384
	ds_read_b32 v4, v184 offset:512
	ds_read_b32 v5, v185 offset:512
	ds_read_b32 v6, v186 offset:512
	ds_read_b32 v7, v187 offset:512
	ds_read_b32 v8, v188 offset:384
	ds_read_b32 v9, v189 offset:384
	ds_read_b32 v10, v190 offset:384
	ds_read_b32 v11, v191 offset:384
	ds_read_b32 v12, v188 offset:512
	ds_read_b32 v13, v189 offset:512
	ds_read_b32 v14, v190 offset:512
	ds_read_b32 v15, v191 offset:512
	s_cmp_eq_u32 s18, 0
	s_cbranch_scc1 .Lmy_att_b0_4
	v_mov_b32_e32 v16, 0xf149f2ca
	v_mov_b32_e32 v17, 0xf149f2ca
	v_mov_b32_e32 v18, 0xf149f2ca
	v_mov_b32_e32 v19, 0xf149f2ca
	v_mov_b32_e32 v24, 0xf149f2ca
	v_mov_b32_e32 v25, 0xf149f2ca
	v_mov_b32_e32 v26, 0xf149f2ca
	v_mov_b32_e32 v27, 0xf149f2ca
	s_branch .Lmy_att_b1_4

; __device__ __forceinline__ void attn_phase(const Params& P, char* smem_raw) {
;     ...
;   for (; t < 8192; t += VGRID) {
;     const int h = t & 15, r = (t >> 4) & 127, b = t >> 11;
;     const int rs = min(max(r - 4, 0), 120);
;     bf16x8 qf[2];
;     qf[0] = qn[0]; qf[1] = qn[1];
;     ...
;     u16* Ob = P.cat + ((long)b * 8192 + r * 64) * 1024 + h * 64;
; #pragma unroll
;     for (int td = 0; td < 4; ++td)
; #pragma unroll
;       for (int reg = 0; reg < 4; ++reg) {
;         const int rowl = wid * 16 + (lane >> 4) * 4 + reg;
;         Ob[(unsigned)(rowl * 1024 + td * 16 + (lane & 15))] = f2bf(o[td][reg] * __builtin_amdgcn_rcpf(lrow[reg]));
;       }
.Lmy_att_b1_4:
	ds_read_b32 v20, v184 offset:384
	ds_read_b32 v21, v185 offset:384
	ds_read_b32 v22, v186 offset:384
	ds_read_b32 v23, v187 offset:384
	ds_read_b32 v28, v188 offset:384
	ds_read_b32 v29, v189 offset:384
	ds_read_b32 v30, v190 offset:384
	ds_read_b32 v31, v191 offset:384
	s_waitcnt lgkmcnt(0)
	v_mov_b32_e32 v205, v201
	s_nop 1
	v_permlane16_swap_b32_e32 v201, v205
	v_add_f32_e32 v201, v201, v205
	v_mov_b32_e32 v205, v201
	s_nop 1
	v_permlane32_swap_b32_e32 v201, v205
	v_add_f32_e32 v201, v201, v205
	v_rcp_f32_e32 v203, v201
	s_nop 7
	v_mul_f32_e32 v32, v32, v203
	v_mul_f32_e32 v33, v33, v203
	v_mul_f32_e32 v34, v34, v203
	v_mul_f32_e32 v35, v35, v203
	v_mul_f32_e32 v36, v36, v203
	v_mul_f32_e32 v37, v37, v203
	v_mul_f32_e32 v38, v38, v203
	v_mul_f32_e32 v39, v39, v203
	v_mul_f32_e32 v40, v40, v203
	v_mul_f32_e32 v41, v41, v203
	v_mul_f32_e32 v42, v42, v203
	v_mul_f32_e32 v43, v43, v203
	v_mul_f32_e32 v44, v44, v203
	v_mul_f32_e32 v45, v45, v203
	v_mul_f32_e32 v46, v46, v203
	v_mul_f32_e32 v47, v47, v203
	v_cvt_pk_bf16_f32 v210, v32, v33
	v_cvt_pk_bf16_f32 v211, v34, v35
	v_cvt_pk_bf16_f32 v212, v36, v37
	v_cvt_pk_bf16_f32 v213, v38, v39
	v_cvt_pk_bf16_f32 v214, v40, v41
	v_cvt_pk_bf16_f32 v215, v42, v43
	v_cvt_pk_bf16_f32 v216, v44, v45
	v_cvt_pk_bf16_f32 v217, v46, v47
	global_store_dwordx2 v167, v[210:211], s[98:99] offset:0
	global_store_dwordx2 v167, v[212:213], s[98:99] offset:32
	global_store_dwordx2 v167, v[214:215], s[98:99] offset:64
	global_store_dwordx2 v167, v[216:217], s[98:99] offset:96
	v_mov_b32_e32 v200, 0xf149f2ca
	v_mov_b32_e32 v201, 0
	v_mov_b32_e32 v32, 0
	v_mov_b32_e32 v33, 0
	v_mov_b32_e32 v34, 0
	v_mov_b32_e32 v35, 0
	v_mov_b32_e32 v36, 0
	v_mov_b32_e32 v37, 0
	v_mov_b32_e32 v38, 0
	v_mov_b32_e32 v39, 0
	v_mov_b32_e32 v40, 0
	v_mov_b32_e32 v41, 0
	v_mov_b32_e32 v42, 0
	v_mov_b32_e32 v43, 0
	v_mov_b32_e32 v44, 0
	v_mov_b32_e32 v45, 0
	v_mov_b32_e32 v46, 0
	v_mov_b32_e32 v47, 0
	v_mov_b32_e32 v64, v72
	v_mov_b32_e32 v65, v73
	v_mov_b32_e32 v66, v74
	v_mov_b32_e32 v67, v75
	v_mov_b32_e32 v68, v76
	v_mov_b32_e32 v69, v77
	v_mov_b32_e32 v70, v78
	v_mov_b32_e32 v71, v79
	v_mov_b32_e32 v205, v247
	s_nop 1
	v_permlane16_swap_b32_e32 v247, v205
	v_add_f32_e32 v247, v247, v205
	v_mov_b32_e32 v205, v247
	s_nop 1
	v_permlane32_swap_b32_e32 v247, v205
	v_add_f32_e32 v247, v247, v205
	v_rcp_f32_e32 v203, v247
	s_nop 7
	v_mul_f32_e32 v176, v176, v203
	v_mul_f32_e32 v177, v177, v203
	v_mul_f32_e32 v178, v178, v203
	v_mul_f32_e32 v179, v179, v203
	v_mul_f32_e32 v180, v180, v203
	v_mul_f32_e32 v181, v181, v203
	v_mul_f32_e32 v182, v182, v203
	v_mul_f32_e32 v183, v183, v203
	v_mul_f32_e32 v192, v192, v203
	v_mul_f32_e32 v193, v193, v203
	v_mul_f32_e32 v194, v194, v203
	v_mul_f32_e32 v195, v195, v203
	v_mul_f32_e32 v196, v196, v203
	v_mul_f32_e32 v197, v197, v203
	v_mul_f32_e32 v198, v198, v203
	v_mul_f32_e32 v199, v199, v203
	v_cvt_pk_bf16_f32 v210, v176, v177
	v_cvt_pk_bf16_f32 v211, v178, v179
	v_cvt_pk_bf16_f32 v212, v180, v181
	v_cvt_pk_bf16_f32 v213, v182, v183
	v_cvt_pk_bf16_f32 v214, v192, v193
	v_cvt_pk_bf16_f32 v215, v194, v195
	v_cvt_pk_bf16_f32 v216, v196, v197
	v_cvt_pk_bf16_f32 v217, v198, v199
	s_add_u32 s0, s98, 0x20000
	s_addc_u32 s1, s99, 0
	global_store_dwordx2 v167, v[210:211], s[0:1] offset:0
	global_store_dwordx2 v167, v[212:213], s[0:1] offset:32
	global_store_dwordx2 v167, v[214:215], s[0:1] offset:64
	global_store_dwordx2 v167, v[216:217], s[0:1] offset:96
	v_mov_b32_e32 v246, 0xf149f2ca
	v_mov_b32_e32 v247, 0
	v_mov_b32_e32 v176, 0
	v_mov_b32_e32 v177, 0
	v_mov_b32_e32 v178, 0
	v_mov_b32_e32 v179, 0
	v_mov_b32_e32 v180, 0
	v_mov_b32_e32 v181, 0
	v_mov_b32_e32 v182, 0
	v_mov_b32_e32 v183, 0
	v_mov_b32_e32 v192, 0
	v_mov_b32_e32 v193, 0
	v_mov_b32_e32 v194, 0
	v_mov_b32_e32 v195, 0
	v_mov_b32_e32 v196, 0
	v_mov_b32_e32 v197, 0
	v_mov_b32_e32 v198, 0
	v_mov_b32_e32 v199, 0
	v_mov_b32_e32 v230, v238
	v_mov_b32_e32 v231, v239
	v_mov_b32_e32 v232, v240
	v_mov_b32_e32 v233, v241
	v_mov_b32_e32 v234, v242
	v_mov_b32_e32 v235, v243
	v_mov_b32_e32 v236, v244
	v_mov_b32_e32 v237, v245
	s_add_u32 s3, s3, 1
	s_and_b32 s0, s3, 0xff
	s_cmp_lt_u32 s0, 8
	s_cbranch_scc1 .Lmy_att_tile
	s_waitcnt vmcnt(0)
	s_branch .LBB0_1501
